# MFMA order variant: accumulator chains with the weight-fragment operand held across chain boundaries
# speedup vs baseline: 1.0005x; 1.0005x over previous
.LBB0_74:
	s_ashr_i32 s27, s26, 31
	s_lshl_b64 s[28:29], s[26:27], 19
	s_add_u32 s28, s3, s28
	s_addc_u32 s29, s35, s29
	s_and_b64 s[30:31], s[4:5], exec
	s_cselect_b32 s27, s29, s49
	s_cselect_b32 s68, s28, s48
	s_ashr_i32 s23, s22, 31
	s_lshl_b64 s[30:31], s[22:23], 19
	s_add_u32 s30, s50, s30
	s_addc_u32 s31, s51, s31
	s_and_b64 s[70:71], s[4:5], exec
	s_cselect_b32 s69, s31, s47
	s_cselect_b32 s70, s30, s46
	s_lshl_b32 s23, s44, 8
	v_add_u32_e32 v0, s23, v148
	s_add_u32 s71, s46, 0x100
	v_ashrrev_i32_e32 v1, 31, v0
	s_addc_u32 s74, s47, 0
	v_lshl_add_u64 v[144:145], v[0:1], 4, s[12:13]
	s_add_u32 s44, s48, 0x40080
	s_addc_u32 s45, s49, 0
	s_mov_b32 s75, -2
	s_mov_b64 s[46:47], 0
	s_cmp_eq_u32 s59, 1
	s_cbranch_scc1 .Lfa_0
	v_add_u32_e32 v153, s64, v147
	ds_read_b128 v[160:163], v153
	v_xor_b32_e32 v253, 64, v153
	ds_read_b128 v[164:167], v253
	ds_read_b128 v[168:171], v153 offset:2048
	ds_read_b128 v[172:175], v253 offset:2048
	v_add_u32_e32 v153, s65, v147
	ds_read_b128 v[176:179], v153
	v_xor_b32_e32 v253, 64, v153
	ds_read_b128 v[180:183], v253
	ds_read_b128 v[186:189], v153 offset:2048
	ds_read_b128 v[190:193], v253 offset:2048
	s_add_u32 s48, s44, 0xfffc0080
	s_addc_u32 s49, s45, -1
	s_and_b64 s[46:47], s[46:47], exec
	s_cselect_b32 s49, s27, s49
	s_cselect_b32 s48, s68, s48
	s_cselect_b32 s47, s69, s74
	s_cselect_b32 s46, s70, s71
	v_lshl_add_u64 v[154:155], s[44:45], 0, v[138:139]
	s_add_i32 m0, s55, 0xc000
	ds_read_b128 v[194:197], v150
	v_xor_b32_e32 v253, 64, v150
	ds_read_b128 v[198:201], v253
	ds_read_b128 v[202:205], v150 offset:2048
	ds_read_b128 v[206:209], v253 offset:2048
	ds_read_b128 v[210:213], v150 offset:4096
	ds_read_b128 v[214:217], v253 offset:4096
	ds_read_b128 v[218:221], v150 offset:6144
	ds_read_b128 v[222:225], v253 offset:6144
	global_load_lds_dwordx4 v[154:155], off
	v_lshl_add_u64 v[154:155], s[44:45], 0, v[136:137]
	s_add_i32 m0, s55, 0xe000
	s_nop 0
	global_load_lds_dwordx4 v[154:155], off
	s_waitcnt vmcnt(16)
	s_waitcnt lgkmcnt(0)
	s_barrier
	s_setprio 1
	s_waitcnt lgkmcnt(0)
	v_mfma_f32_16x16x32_bf16 v[124:127], v[160:163], v[194:197], 0
	v_mfma_f32_16x16x32_bf16 v[116:119], v[168:171], v[194:197], 0
	v_mfma_f32_16x16x32_bf16 v[108:111], v[160:163], v[202:205], 0
	v_mfma_f32_16x16x32_bf16 v[100:103], v[168:171], v[202:205], 0
	v_mfma_f32_16x16x32_bf16 v[92:95], v[160:163], v[210:213], 0
	v_mfma_f32_16x16x32_bf16 v[84:87], v[168:171], v[210:213], 0
	v_mfma_f32_16x16x32_bf16 v[76:79], v[160:163], v[218:221], 0
	v_mfma_f32_16x16x32_bf16 v[68:71], v[168:171], v[218:221], 0
	v_mfma_f32_16x16x32_bf16 v[124:127], v[164:167], v[198:201], v[124:127]
	v_mfma_f32_16x16x32_bf16 v[116:119], v[172:175], v[198:201], v[116:119]
	v_mfma_f32_16x16x32_bf16 v[108:111], v[164:167], v[206:209], v[108:111]
	v_mfma_f32_16x16x32_bf16 v[100:103], v[172:175], v[206:209], v[100:103]
	v_mfma_f32_16x16x32_bf16 v[92:95], v[164:167], v[214:217], v[92:95]
	v_mfma_f32_16x16x32_bf16 v[84:87], v[172:175], v[214:217], v[84:87]
	v_mfma_f32_16x16x32_bf16 v[76:79], v[164:167], v[222:225], v[76:79]
	v_mfma_f32_16x16x32_bf16 v[68:71], v[172:175], v[222:225], v[68:71]
	s_setprio 0
	s_setprio 1
	v_mfma_f32_16x16x32_bf16 v[120:123], v[176:179], v[194:197], 0
	v_mfma_f32_16x16x32_bf16 v[112:115], v[186:189], v[194:197], 0
	v_mfma_f32_16x16x32_bf16 v[104:107], v[176:179], v[202:205], 0
	v_mfma_f32_16x16x32_bf16 v[96:99], v[186:189], v[202:205], 0
	v_mfma_f32_16x16x32_bf16 v[88:91], v[176:179], v[210:213], 0
	v_mfma_f32_16x16x32_bf16 v[80:83], v[186:189], v[210:213], 0
	v_mfma_f32_16x16x32_bf16 v[72:75], v[176:179], v[218:221], 0
	v_mfma_f32_16x16x32_bf16 v[64:67], v[186:189], v[218:221], 0
	v_mfma_f32_16x16x32_bf16 v[120:123], v[180:183], v[198:201], v[120:123]
	v_mfma_f32_16x16x32_bf16 v[112:115], v[190:193], v[198:201], v[112:115]
	v_mfma_f32_16x16x32_bf16 v[104:107], v[180:183], v[206:209], v[104:107]
	v_mfma_f32_16x16x32_bf16 v[96:99], v[190:193], v[206:209], v[96:99]
	v_mfma_f32_16x16x32_bf16 v[88:91], v[180:183], v[214:217], v[88:91]
	v_mfma_f32_16x16x32_bf16 v[80:83], v[190:193], v[214:217], v[80:83]
	v_mfma_f32_16x16x32_bf16 v[72:75], v[180:183], v[222:225], v[72:75]
	v_mfma_f32_16x16x32_bf16 v[64:67], v[190:193], v[222:225], v[64:67]
	s_setprio 0
	s_barrier
	s_add_i32 s76, s64, s52
	v_lshl_add_u64 v[154:155], s[46:47], 0, v[132:133]
	s_mov_b32 m0, s76
	ds_read_b128 v[194:197], v150 offset:16384
	v_xor_b32_e32 v253, 64, v150
	ds_read_b128 v[198:201], v253 offset:16384
	ds_read_b128 v[202:205], v150 offset:18432
	ds_read_b128 v[206:209], v253 offset:18432
	ds_read_b128 v[210:213], v150 offset:20480
	ds_read_b128 v[214:217], v253 offset:20480
	ds_read_b128 v[218:221], v150 offset:22528
	ds_read_b128 v[222:225], v253 offset:22528
	global_load_lds_dwordx4 v[154:155], off
	s_add_i32 m0, s76, 0x2000
	s_add_u32 s76, s46, 0x40000
	v_lshl_add_u64 v[226:227], s[46:47], 0, v[128:129]
	s_addc_u32 s77, s47, 0
	s_add_i32 s78, s65, s52
	global_load_lds_dwordx4 v[226:227], off
	v_lshl_add_u64 v[228:229], s[76:77], 0, v[132:133]
	s_mov_b32 m0, s78
	v_lshl_add_u64 v[230:231], s[48:49], 0, v[130:131]
	global_load_lds_dwordx4 v[228:229], off
	v_lshl_add_u64 v[228:229], s[76:77], 0, v[128:129]
	s_add_i32 m0, s78, 0x2000
	s_nop 0
	global_load_lds_dwordx4 v[228:229], off
	v_lshl_add_u64 v[228:229], s[48:49], 0, v[134:135]
	s_mov_b32 m0, s55
	s_nop 0
	global_load_lds_dwordx4 v[228:229], off
	s_mov_b32 m0, s56
	s_nop 0
	global_load_lds_dwordx4 v[230:231], off
	s_waitcnt vmcnt(16)
	s_waitcnt lgkmcnt(0)
	s_barrier
	s_setprio 1
	s_waitcnt lgkmcnt(0)
	v_mfma_f32_16x16x32_bf16 v[60:63], v[160:163], v[194:197], 0
	v_mfma_f32_16x16x32_bf16 v[52:55], v[168:171], v[194:197], 0
	v_mfma_f32_16x16x32_bf16 v[44:47], v[160:163], v[202:205], 0
	v_mfma_f32_16x16x32_bf16 v[36:39], v[168:171], v[202:205], 0
	v_mfma_f32_16x16x32_bf16 v[28:31], v[160:163], v[210:213], 0
	v_mfma_f32_16x16x32_bf16 v[20:23], v[168:171], v[210:213], 0
	v_mfma_f32_16x16x32_bf16 v[12:15], v[160:163], v[218:221], 0
	v_mfma_f32_16x16x32_bf16 v[4:7], v[168:171], v[218:221], 0
	v_mfma_f32_16x16x32_bf16 v[60:63], v[164:167], v[198:201], v[60:63]
	v_mfma_f32_16x16x32_bf16 v[52:55], v[172:175], v[198:201], v[52:55]
	v_mfma_f32_16x16x32_bf16 v[44:47], v[164:167], v[206:209], v[44:47]
	v_mfma_f32_16x16x32_bf16 v[36:39], v[172:175], v[206:209], v[36:39]
	v_mfma_f32_16x16x32_bf16 v[28:31], v[164:167], v[214:217], v[28:31]
	v_mfma_f32_16x16x32_bf16 v[20:23], v[172:175], v[214:217], v[20:23]
	v_mfma_f32_16x16x32_bf16 v[12:15], v[164:167], v[222:225], v[12:15]
	v_mfma_f32_16x16x32_bf16 v[4:7], v[172:175], v[222:225], v[4:7]
	s_setprio 0
	s_setprio 1
	v_mfma_f32_16x16x32_bf16 v[56:59], v[176:179], v[194:197], 0
	v_mfma_f32_16x16x32_bf16 v[48:51], v[186:189], v[194:197], 0
	v_mfma_f32_16x16x32_bf16 v[40:43], v[176:179], v[202:205], 0
	v_mfma_f32_16x16x32_bf16 v[32:35], v[186:189], v[202:205], 0
	v_mfma_f32_16x16x32_bf16 v[24:27], v[176:179], v[210:213], 0
	v_mfma_f32_16x16x32_bf16 v[16:19], v[186:189], v[210:213], 0
	v_mfma_f32_16x16x32_bf16 v[8:11], v[176:179], v[218:221], 0
	v_mfma_f32_16x16x32_bf16 v[0:3], v[186:189], v[218:221], 0
	v_mfma_f32_16x16x32_bf16 v[56:59], v[180:183], v[198:201], v[56:59]
	v_mfma_f32_16x16x32_bf16 v[48:51], v[190:193], v[198:201], v[48:51]
	v_mfma_f32_16x16x32_bf16 v[40:43], v[180:183], v[206:209], v[40:43]
	v_mfma_f32_16x16x32_bf16 v[32:35], v[190:193], v[206:209], v[32:35]
	v_mfma_f32_16x16x32_bf16 v[24:27], v[180:183], v[214:217], v[24:27]
	v_mfma_f32_16x16x32_bf16 v[16:19], v[190:193], v[214:217], v[16:19]
	v_mfma_f32_16x16x32_bf16 v[8:11], v[180:183], v[222:225], v[8:11]
	v_mfma_f32_16x16x32_bf16 v[0:3], v[190:193], v[222:225], v[0:3]
	s_setprio 0
	s_barrier
	s_add_i32 s76, 0, 0x18000
	v_add_u32_e32 v153, s76, v147
	s_add_i32 s77, 0, 0x1c000
	ds_read_b128 v[160:163], v153
	v_xor_b32_e32 v253, 64, v153
	ds_read_b128 v[164:167], v253
	ds_read_b128 v[168:171], v153 offset:2048
	ds_read_b128 v[172:175], v253 offset:2048
	v_add_u32_e32 v153, s77, v147
	ds_read_b128 v[176:179], v153
	v_xor_b32_e32 v253, 64, v153
	ds_read_b128 v[180:183], v253
	ds_read_b128 v[186:189], v153 offset:2048
	ds_read_b128 v[190:193], v253 offset:2048
	s_add_u32 s48, s48, 0x40000
	s_addc_u32 s49, s49, 0
	s_mov_b32 m0, s57
	v_lshl_add_u64 v[232:233], s[48:49], 0, v[134:135]
	ds_read_b128 v[194:197], v150 offset:32768
	v_xor_b32_e32 v253, 64, v150
	ds_read_b128 v[198:201], v253 offset:32768
	ds_read_b128 v[202:205], v150 offset:34816
	ds_read_b128 v[206:209], v253 offset:34816
	ds_read_b128 v[210:213], v150 offset:36864
	ds_read_b128 v[214:217], v253 offset:36864
	ds_read_b128 v[218:221], v150 offset:38912
	ds_read_b128 v[222:225], v253 offset:38912
	global_load_lds_dwordx4 v[232:233], off
	v_lshl_add_u64 v[232:233], s[48:49], 0, v[130:131]
	s_mov_b32 m0, s58
	s_nop 0
	global_load_lds_dwordx4 v[232:233], off
	s_waitcnt vmcnt(8)
	s_waitcnt lgkmcnt(0)
	s_barrier
	s_setprio 1
	s_waitcnt lgkmcnt(0)
	v_mfma_f32_16x16x32_bf16 v[124:127], v[160:163], v[194:197], v[124:127]
	v_mfma_f32_16x16x32_bf16 v[124:127], v[164:167], v[198:201], v[124:127]
	v_mfma_f32_16x16x32_bf16 v[108:111], v[164:167], v[206:209], v[108:111]
	v_mfma_f32_16x16x32_bf16 v[108:111], v[160:163], v[202:205], v[108:111]
	v_mfma_f32_16x16x32_bf16 v[92:95], v[160:163], v[210:213], v[92:95]
	v_mfma_f32_16x16x32_bf16 v[92:95], v[164:167], v[214:217], v[92:95]
	v_mfma_f32_16x16x32_bf16 v[76:79], v[164:167], v[222:225], v[76:79]
	v_mfma_f32_16x16x32_bf16 v[76:79], v[160:163], v[218:221], v[76:79]
	v_mfma_f32_16x16x32_bf16 v[68:71], v[168:171], v[218:221], v[68:71]
	v_mfma_f32_16x16x32_bf16 v[68:71], v[172:175], v[222:225], v[68:71]
	v_mfma_f32_16x16x32_bf16 v[84:87], v[172:175], v[214:217], v[84:87]
	v_mfma_f32_16x16x32_bf16 v[84:87], v[168:171], v[210:213], v[84:87]
	v_mfma_f32_16x16x32_bf16 v[100:103], v[168:171], v[202:205], v[100:103]
	v_mfma_f32_16x16x32_bf16 v[100:103], v[172:175], v[206:209], v[100:103]
	v_mfma_f32_16x16x32_bf16 v[116:119], v[172:175], v[198:201], v[116:119]
	v_mfma_f32_16x16x32_bf16 v[116:119], v[168:171], v[194:197], v[116:119]
	s_setprio 0
	s_setprio 1
	v_mfma_f32_16x16x32_bf16 v[120:123], v[176:179], v[194:197], v[120:123]
	v_mfma_f32_16x16x32_bf16 v[120:123], v[180:183], v[198:201], v[120:123]
	v_mfma_f32_16x16x32_bf16 v[104:107], v[180:183], v[206:209], v[104:107]
	v_mfma_f32_16x16x32_bf16 v[104:107], v[176:179], v[202:205], v[104:107]
	v_mfma_f32_16x16x32_bf16 v[88:91], v[176:179], v[210:213], v[88:91]
	v_mfma_f32_16x16x32_bf16 v[88:91], v[180:183], v[214:217], v[88:91]
	v_mfma_f32_16x16x32_bf16 v[72:75], v[180:183], v[222:225], v[72:75]
	v_mfma_f32_16x16x32_bf16 v[72:75], v[176:179], v[218:221], v[72:75]
	v_mfma_f32_16x16x32_bf16 v[64:67], v[186:189], v[218:221], v[64:67]
	v_mfma_f32_16x16x32_bf16 v[64:67], v[190:193], v[222:225], v[64:67]
	v_mfma_f32_16x16x32_bf16 v[80:83], v[190:193], v[214:217], v[80:83]
	v_mfma_f32_16x16x32_bf16 v[80:83], v[186:189], v[210:213], v[80:83]
	v_mfma_f32_16x16x32_bf16 v[96:99], v[186:189], v[202:205], v[96:99]
	v_mfma_f32_16x16x32_bf16 v[96:99], v[190:193], v[206:209], v[96:99]
	v_mfma_f32_16x16x32_bf16 v[112:115], v[190:193], v[198:201], v[112:115]
	v_mfma_f32_16x16x32_bf16 v[112:115], v[186:189], v[194:197], v[112:115]
	s_setprio 0
	s_barrier
	s_add_i32 s48, s76, s52
	v_lshl_add_u64 v[154:155], v[154:155], 0, s[14:15]
	s_mov_b32 m0, s48
	ds_read_b128 v[194:197], v150 offset:49152
	v_xor_b32_e32 v253, 64, v150
	ds_read_b128 v[198:201], v253 offset:49152
	ds_read_b128 v[202:205], v150 offset:51200
	ds_read_b128 v[206:209], v253 offset:51200
	ds_read_b128 v[210:213], v150 offset:53248
	ds_read_b128 v[214:217], v253 offset:53248
	ds_read_b128 v[218:221], v150 offset:55296
	ds_read_b128 v[222:225], v253 offset:55296
	global_load_lds_dwordx4 v[154:155], off
	s_add_i32 m0, s48, 0x2000
	s_add_u32 s46, s46, 0x40080
	v_lshl_add_u64 v[154:155], v[226:227], 0, s[14:15]
	s_addc_u32 s47, s47, 0
	s_add_i32 s48, s77, s52
	global_load_lds_dwordx4 v[154:155], off
	v_lshl_add_u64 v[154:155], s[46:47], 0, v[132:133]
	s_mov_b32 m0, s48
	s_nop 0
	global_load_lds_dwordx4 v[154:155], off
	v_lshl_add_u64 v[154:155], s[46:47], 0, v[128:129]
	s_add_i32 m0, s48, 0x2000
	s_nop 0
	global_load_lds_dwordx4 v[154:155], off
	v_lshl_add_u64 v[154:155], v[228:229], 0, s[14:15]
	s_mov_b32 m0, s60
	s_nop 0
	global_load_lds_dwordx4 v[154:155], off
	v_lshl_add_u64 v[154:155], v[230:231], 0, s[14:15]
	s_mov_b32 m0, s61
	s_nop 0
	global_load_lds_dwordx4 v[154:155], off
	s_waitcnt vmcnt(8)
	s_waitcnt lgkmcnt(0)
	s_barrier
	s_setprio 1
	s_waitcnt lgkmcnt(0)
	v_mfma_f32_16x16x32_bf16 v[60:63], v[160:163], v[194:197], v[60:63]
	v_mfma_f32_16x16x32_bf16 v[60:63], v[164:167], v[198:201], v[60:63]
	v_mfma_f32_16x16x32_bf16 v[44:47], v[164:167], v[206:209], v[44:47]
	v_mfma_f32_16x16x32_bf16 v[44:47], v[160:163], v[202:205], v[44:47]
	v_mfma_f32_16x16x32_bf16 v[28:31], v[160:163], v[210:213], v[28:31]
	v_mfma_f32_16x16x32_bf16 v[28:31], v[164:167], v[214:217], v[28:31]
	v_mfma_f32_16x16x32_bf16 v[12:15], v[164:167], v[222:225], v[12:15]
	v_mfma_f32_16x16x32_bf16 v[12:15], v[160:163], v[218:221], v[12:15]
	v_mfma_f32_16x16x32_bf16 v[4:7], v[168:171], v[218:221], v[4:7]
	v_mfma_f32_16x16x32_bf16 v[4:7], v[172:175], v[222:225], v[4:7]
	v_mfma_f32_16x16x32_bf16 v[20:23], v[172:175], v[214:217], v[20:23]
	v_mfma_f32_16x16x32_bf16 v[20:23], v[168:171], v[210:213], v[20:23]
	v_mfma_f32_16x16x32_bf16 v[36:39], v[168:171], v[202:205], v[36:39]
	v_mfma_f32_16x16x32_bf16 v[36:39], v[172:175], v[206:209], v[36:39]
	v_mfma_f32_16x16x32_bf16 v[52:55], v[172:175], v[198:201], v[52:55]
	v_mfma_f32_16x16x32_bf16 v[52:55], v[168:171], v[194:197], v[52:55]
	s_setprio 0
	s_setprio 1
	v_mfma_f32_16x16x32_bf16 v[56:59], v[176:179], v[194:197], v[56:59]
	v_mfma_f32_16x16x32_bf16 v[56:59], v[180:183], v[198:201], v[56:59]
	v_mfma_f32_16x16x32_bf16 v[40:43], v[180:183], v[206:209], v[40:43]
	v_mfma_f32_16x16x32_bf16 v[40:43], v[176:179], v[202:205], v[40:43]
	v_mfma_f32_16x16x32_bf16 v[24:27], v[176:179], v[210:213], v[24:27]
	v_mfma_f32_16x16x32_bf16 v[24:27], v[180:183], v[214:217], v[24:27]
	v_mfma_f32_16x16x32_bf16 v[8:11], v[180:183], v[222:225], v[8:11]
	v_mfma_f32_16x16x32_bf16 v[8:11], v[176:179], v[218:221], v[8:11]
	v_mfma_f32_16x16x32_bf16 v[0:3], v[186:189], v[218:221], v[0:3]
	v_mfma_f32_16x16x32_bf16 v[0:3], v[190:193], v[222:225], v[0:3]
	v_mfma_f32_16x16x32_bf16 v[16:19], v[190:193], v[214:217], v[16:19]
	v_mfma_f32_16x16x32_bf16 v[16:19], v[186:189], v[210:213], v[16:19]
	v_mfma_f32_16x16x32_bf16 v[32:35], v[186:189], v[202:205], v[32:35]
	v_mfma_f32_16x16x32_bf16 v[32:35], v[190:193], v[206:209], v[32:35]
	v_mfma_f32_16x16x32_bf16 v[48:51], v[190:193], v[198:201], v[48:51]
	v_mfma_f32_16x16x32_bf16 v[48:51], v[186:189], v[194:197], v[48:51]
	s_setprio 0
	s_barrier
	s_add_i32 s75, s75, 2
	s_add_u32 s71, s71, 0x100
	s_addc_u32 s74, s74, 0
	s_add_u32 s44, s44, 0x100
	s_addc_u32 s45, s45, 0
	s_branch .LBB0_76
.Lfa_0:
	v_add_u32_e32 v153, s64, v147
	ds_read_b128 v[160:163], v153
	v_xor_b32_e32 v253, 64, v153
	ds_read_b128 v[164:167], v253
	ds_read_b128 v[168:171], v153 offset:2048
	ds_read_b128 v[172:175], v253 offset:2048
	v_add_u32_e32 v153, s65, v147
	ds_read_b128 v[176:179], v153
	v_xor_b32_e32 v253, 64, v153
	ds_read_b128 v[180:183], v253
	ds_read_b128 v[186:189], v153 offset:2048
	ds_read_b128 v[190:193], v253 offset:2048
	s_add_u32 s48, s44, 0xfffc0080
	s_addc_u32 s49, s45, -1
	s_and_b64 s[46:47], s[46:47], exec
	s_cselect_b32 s49, s27, s49
	s_cselect_b32 s48, s68, s48
	s_cselect_b32 s47, s69, s74
	s_cselect_b32 s46, s70, s71
	v_lshl_add_u64 v[154:155], s[44:45], 0, v[138:139]
	s_add_i32 m0, s55, 0xc000
	ds_read_b128 v[194:197], v150
	v_xor_b32_e32 v253, 64, v150
	ds_read_b128 v[198:201], v253
	ds_read_b128 v[202:205], v150 offset:2048
	ds_read_b128 v[206:209], v253 offset:2048
	ds_read_b128 v[210:213], v150 offset:4096
	ds_read_b128 v[214:217], v253 offset:4096
	ds_read_b128 v[218:221], v150 offset:6144
	ds_read_b128 v[222:225], v253 offset:6144
	global_load_lds_dwordx4 v[154:155], off
	v_lshl_add_u64 v[154:155], s[44:45], 0, v[136:137]
	s_add_i32 m0, s55, 0xe000
	s_nop 0
	global_load_lds_dwordx4 v[154:155], off
	s_waitcnt vmcnt(8)
	s_waitcnt lgkmcnt(0)
	s_barrier
	s_setprio 1
	s_waitcnt lgkmcnt(0)
	v_mfma_f32_16x16x32_bf16 v[124:127], v[160:163], v[194:197], 0
	v_mfma_f32_16x16x32_bf16 v[116:119], v[168:171], v[194:197], 0
	v_mfma_f32_16x16x32_bf16 v[108:111], v[160:163], v[202:205], 0
	v_mfma_f32_16x16x32_bf16 v[100:103], v[168:171], v[202:205], 0
	v_mfma_f32_16x16x32_bf16 v[92:95], v[160:163], v[210:213], 0
	v_mfma_f32_16x16x32_bf16 v[84:87], v[168:171], v[210:213], 0
	v_mfma_f32_16x16x32_bf16 v[76:79], v[160:163], v[218:221], 0
	v_mfma_f32_16x16x32_bf16 v[68:71], v[168:171], v[218:221], 0
	v_mfma_f32_16x16x32_bf16 v[124:127], v[164:167], v[198:201], v[124:127]
	v_mfma_f32_16x16x32_bf16 v[116:119], v[172:175], v[198:201], v[116:119]
	v_mfma_f32_16x16x32_bf16 v[108:111], v[164:167], v[206:209], v[108:111]
	v_mfma_f32_16x16x32_bf16 v[100:103], v[172:175], v[206:209], v[100:103]
	v_mfma_f32_16x16x32_bf16 v[92:95], v[164:167], v[214:217], v[92:95]
	v_mfma_f32_16x16x32_bf16 v[84:87], v[172:175], v[214:217], v[84:87]
	v_mfma_f32_16x16x32_bf16 v[76:79], v[164:167], v[222:225], v[76:79]
	v_mfma_f32_16x16x32_bf16 v[68:71], v[172:175], v[222:225], v[68:71]
	s_setprio 0
	s_setprio 1
	v_mfma_f32_16x16x32_bf16 v[120:123], v[176:179], v[194:197], 0
	v_mfma_f32_16x16x32_bf16 v[112:115], v[186:189], v[194:197], 0
	v_mfma_f32_16x16x32_bf16 v[104:107], v[176:179], v[202:205], 0
	v_mfma_f32_16x16x32_bf16 v[96:99], v[186:189], v[202:205], 0
	v_mfma_f32_16x16x32_bf16 v[88:91], v[176:179], v[210:213], 0
	v_mfma_f32_16x16x32_bf16 v[80:83], v[186:189], v[210:213], 0
	v_mfma_f32_16x16x32_bf16 v[72:75], v[176:179], v[218:221], 0
	v_mfma_f32_16x16x32_bf16 v[64:67], v[186:189], v[218:221], 0
	v_mfma_f32_16x16x32_bf16 v[120:123], v[180:183], v[198:201], v[120:123]
	v_mfma_f32_16x16x32_bf16 v[112:115], v[190:193], v[198:201], v[112:115]
	v_mfma_f32_16x16x32_bf16 v[104:107], v[180:183], v[206:209], v[104:107]
	v_mfma_f32_16x16x32_bf16 v[96:99], v[190:193], v[206:209], v[96:99]
	v_mfma_f32_16x16x32_bf16 v[88:91], v[180:183], v[214:217], v[88:91]
	v_mfma_f32_16x16x32_bf16 v[80:83], v[190:193], v[214:217], v[80:83]
	v_mfma_f32_16x16x32_bf16 v[72:75], v[180:183], v[222:225], v[72:75]
	v_mfma_f32_16x16x32_bf16 v[64:67], v[190:193], v[222:225], v[64:67]
	s_setprio 0
	s_barrier
	s_add_i32 s76, s64, s52
	v_lshl_add_u64 v[154:155], s[46:47], 0, v[132:133]
	s_mov_b32 m0, s76
	ds_read_b128 v[194:197], v150 offset:16384
	v_xor_b32_e32 v253, 64, v150
	ds_read_b128 v[198:201], v253 offset:16384
	ds_read_b128 v[202:205], v150 offset:18432
	ds_read_b128 v[206:209], v253 offset:18432
	ds_read_b128 v[210:213], v150 offset:20480
	ds_read_b128 v[214:217], v253 offset:20480
	ds_read_b128 v[218:221], v150 offset:22528
	ds_read_b128 v[222:225], v253 offset:22528
	global_load_lds_dwordx4 v[154:155], off
	s_add_i32 m0, s76, 0x2000
	s_add_u32 s76, s46, 0x40000
	v_lshl_add_u64 v[226:227], s[46:47], 0, v[128:129]
	s_addc_u32 s77, s47, 0
	s_add_i32 s78, s65, s52
	global_load_lds_dwordx4 v[226:227], off
	v_lshl_add_u64 v[228:229], s[76:77], 0, v[132:133]
	s_mov_b32 m0, s78
	v_lshl_add_u64 v[230:231], s[48:49], 0, v[130:131]
	global_load_lds_dwordx4 v[228:229], off
	v_lshl_add_u64 v[228:229], s[76:77], 0, v[128:129]
	s_add_i32 m0, s78, 0x2000
	s_nop 0
	global_load_lds_dwordx4 v[228:229], off
	v_lshl_add_u64 v[228:229], s[48:49], 0, v[134:135]
	s_mov_b32 m0, s55
	s_nop 0
	global_load_lds_dwordx4 v[228:229], off
	s_mov_b32 m0, s56
	s_nop 0
	global_load_lds_dwordx4 v[230:231], off
	s_waitcnt vmcnt(8)
	s_waitcnt lgkmcnt(0)
	s_barrier
	s_setprio 1
	s_waitcnt lgkmcnt(0)
	v_mfma_f32_16x16x32_bf16 v[60:63], v[160:163], v[194:197], 0
	v_mfma_f32_16x16x32_bf16 v[52:55], v[168:171], v[194:197], 0
	v_mfma_f32_16x16x32_bf16 v[44:47], v[160:163], v[202:205], 0
	v_mfma_f32_16x16x32_bf16 v[36:39], v[168:171], v[202:205], 0
	v_mfma_f32_16x16x32_bf16 v[28:31], v[160:163], v[210:213], 0
	v_mfma_f32_16x16x32_bf16 v[20:23], v[168:171], v[210:213], 0
	v_mfma_f32_16x16x32_bf16 v[12:15], v[160:163], v[218:221], 0
	v_mfma_f32_16x16x32_bf16 v[4:7], v[168:171], v[218:221], 0
	v_mfma_f32_16x16x32_bf16 v[60:63], v[164:167], v[198:201], v[60:63]
	v_mfma_f32_16x16x32_bf16 v[52:55], v[172:175], v[198:201], v[52:55]
	v_mfma_f32_16x16x32_bf16 v[44:47], v[164:167], v[206:209], v[44:47]
	v_mfma_f32_16x16x32_bf16 v[36:39], v[172:175], v[206:209], v[36:39]
	v_mfma_f32_16x16x32_bf16 v[28:31], v[164:167], v[214:217], v[28:31]
	v_mfma_f32_16x16x32_bf16 v[20:23], v[172:175], v[214:217], v[20:23]
	v_mfma_f32_16x16x32_bf16 v[12:15], v[164:167], v[222:225], v[12:15]
	v_mfma_f32_16x16x32_bf16 v[4:7], v[172:175], v[222:225], v[4:7]
	s_setprio 0
	s_setprio 1
	v_mfma_f32_16x16x32_bf16 v[56:59], v[176:179], v[194:197], 0
	v_mfma_f32_16x16x32_bf16 v[48:51], v[186:189], v[194:197], 0
	v_mfma_f32_16x16x32_bf16 v[40:43], v[176:179], v[202:205], 0
	v_mfma_f32_16x16x32_bf16 v[32:35], v[186:189], v[202:205], 0
	v_mfma_f32_16x16x32_bf16 v[24:27], v[176:179], v[210:213], 0
	v_mfma_f32_16x16x32_bf16 v[16:19], v[186:189], v[210:213], 0
	v_mfma_f32_16x16x32_bf16 v[8:11], v[176:179], v[218:221], 0
	v_mfma_f32_16x16x32_bf16 v[0:3], v[186:189], v[218:221], 0
	v_mfma_f32_16x16x32_bf16 v[56:59], v[180:183], v[198:201], v[56:59]
	v_mfma_f32_16x16x32_bf16 v[48:51], v[190:193], v[198:201], v[48:51]
	v_mfma_f32_16x16x32_bf16 v[40:43], v[180:183], v[206:209], v[40:43]
	v_mfma_f32_16x16x32_bf16 v[32:35], v[190:193], v[206:209], v[32:35]
	v_mfma_f32_16x16x32_bf16 v[24:27], v[180:183], v[214:217], v[24:27]
	v_mfma_f32_16x16x32_bf16 v[16:19], v[190:193], v[214:217], v[16:19]
	v_mfma_f32_16x16x32_bf16 v[8:11], v[180:183], v[222:225], v[8:11]
	v_mfma_f32_16x16x32_bf16 v[0:3], v[190:193], v[222:225], v[0:3]
	s_setprio 0
	s_barrier
	s_add_i32 s76, 0, 0x18000
	v_add_u32_e32 v153, s76, v147
	s_add_i32 s77, 0, 0x1c000
	ds_read_b128 v[160:163], v153
	v_xor_b32_e32 v253, 64, v153
	ds_read_b128 v[164:167], v253
	ds_read_b128 v[168:171], v153 offset:2048
	ds_read_b128 v[172:175], v253 offset:2048
	v_add_u32_e32 v153, s77, v147
	ds_read_b128 v[176:179], v153
	v_xor_b32_e32 v253, 64, v153
	ds_read_b128 v[180:183], v253
	ds_read_b128 v[186:189], v153 offset:2048
	ds_read_b128 v[190:193], v253 offset:2048
	s_add_u32 s48, s48, 0x40000
	s_addc_u32 s49, s49, 0
	s_mov_b32 m0, s57
	v_lshl_add_u64 v[232:233], s[48:49], 0, v[134:135]
	ds_read_b128 v[194:197], v150 offset:32768
	v_xor_b32_e32 v253, 64, v150
	ds_read_b128 v[198:201], v253 offset:32768
	ds_read_b128 v[202:205], v150 offset:34816
	ds_read_b128 v[206:209], v253 offset:34816
	ds_read_b128 v[210:213], v150 offset:36864
	ds_read_b128 v[214:217], v253 offset:36864
	ds_read_b128 v[218:221], v150 offset:38912
	ds_read_b128 v[222:225], v253 offset:38912
	global_load_lds_dwordx4 v[232:233], off
	v_lshl_add_u64 v[232:233], s[48:49], 0, v[130:131]
	s_mov_b32 m0, s58
	s_nop 0
	global_load_lds_dwordx4 v[232:233], off
	s_waitcnt vmcnt(8)
	s_waitcnt lgkmcnt(0)
	s_barrier
	s_setprio 1
	s_waitcnt lgkmcnt(0)
	v_mfma_f32_16x16x32_bf16 v[124:127], v[160:163], v[194:197], v[124:127]
	v_mfma_f32_16x16x32_bf16 v[124:127], v[164:167], v[198:201], v[124:127]
	v_mfma_f32_16x16x32_bf16 v[108:111], v[164:167], v[206:209], v[108:111]
	v_mfma_f32_16x16x32_bf16 v[108:111], v[160:163], v[202:205], v[108:111]
	v_mfma_f32_16x16x32_bf16 v[92:95], v[160:163], v[210:213], v[92:95]
	v_mfma_f32_16x16x32_bf16 v[92:95], v[164:167], v[214:217], v[92:95]
	v_mfma_f32_16x16x32_bf16 v[76:79], v[164:167], v[222:225], v[76:79]
	v_mfma_f32_16x16x32_bf16 v[76:79], v[160:163], v[218:221], v[76:79]
	v_mfma_f32_16x16x32_bf16 v[68:71], v[168:171], v[218:221], v[68:71]
	v_mfma_f32_16x16x32_bf16 v[68:71], v[172:175], v[222:225], v[68:71]
	v_mfma_f32_16x16x32_bf16 v[84:87], v[172:175], v[214:217], v[84:87]
	v_mfma_f32_16x16x32_bf16 v[84:87], v[168:171], v[210:213], v[84:87]
	v_mfma_f32_16x16x32_bf16 v[100:103], v[168:171], v[202:205], v[100:103]
	v_mfma_f32_16x16x32_bf16 v[100:103], v[172:175], v[206:209], v[100:103]
	v_mfma_f32_16x16x32_bf16 v[116:119], v[172:175], v[198:201], v[116:119]
	v_mfma_f32_16x16x32_bf16 v[116:119], v[168:171], v[194:197], v[116:119]
	s_setprio 0
	s_setprio 1
	v_mfma_f32_16x16x32_bf16 v[120:123], v[176:179], v[194:197], v[120:123]
	v_mfma_f32_16x16x32_bf16 v[120:123], v[180:183], v[198:201], v[120:123]
	v_mfma_f32_16x16x32_bf16 v[104:107], v[180:183], v[206:209], v[104:107]
	v_mfma_f32_16x16x32_bf16 v[104:107], v[176:179], v[202:205], v[104:107]
	v_mfma_f32_16x16x32_bf16 v[88:91], v[176:179], v[210:213], v[88:91]
	v_mfma_f32_16x16x32_bf16 v[88:91], v[180:183], v[214:217], v[88:91]
	v_mfma_f32_16x16x32_bf16 v[72:75], v[180:183], v[222:225], v[72:75]
	v_mfma_f32_16x16x32_bf16 v[72:75], v[176:179], v[218:221], v[72:75]
	v_mfma_f32_16x16x32_bf16 v[64:67], v[186:189], v[218:221], v[64:67]
	v_mfma_f32_16x16x32_bf16 v[64:67], v[190:193], v[222:225], v[64:67]
	v_mfma_f32_16x16x32_bf16 v[80:83], v[190:193], v[214:217], v[80:83]
	v_mfma_f32_16x16x32_bf16 v[80:83], v[186:189], v[210:213], v[80:83]
	v_mfma_f32_16x16x32_bf16 v[96:99], v[186:189], v[202:205], v[96:99]
	v_mfma_f32_16x16x32_bf16 v[96:99], v[190:193], v[206:209], v[96:99]
	v_mfma_f32_16x16x32_bf16 v[112:115], v[190:193], v[198:201], v[112:115]
	v_mfma_f32_16x16x32_bf16 v[112:115], v[186:189], v[194:197], v[112:115]
	s_setprio 0
	s_barrier
	s_add_i32 s48, s76, s52
	v_lshl_add_u64 v[154:155], v[154:155], 0, s[14:15]
	s_mov_b32 m0, s48
	ds_read_b128 v[194:197], v150 offset:49152
	v_xor_b32_e32 v253, 64, v150
	ds_read_b128 v[198:201], v253 offset:49152
	ds_read_b128 v[202:205], v150 offset:51200
	ds_read_b128 v[206:209], v253 offset:51200
	ds_read_b128 v[210:213], v150 offset:53248
	ds_read_b128 v[214:217], v253 offset:53248
	ds_read_b128 v[218:221], v150 offset:55296
	ds_read_b128 v[222:225], v253 offset:55296
	global_load_lds_dwordx4 v[154:155], off
	s_add_i32 m0, s48, 0x2000
	s_add_u32 s46, s46, 0x40080
	v_lshl_add_u64 v[154:155], v[226:227], 0, s[14:15]
	s_addc_u32 s47, s47, 0
	s_add_i32 s48, s77, s52
	global_load_lds_dwordx4 v[154:155], off
	v_lshl_add_u64 v[154:155], s[46:47], 0, v[132:133]
	s_mov_b32 m0, s48
	s_nop 0
	global_load_lds_dwordx4 v[154:155], off
	v_lshl_add_u64 v[154:155], s[46:47], 0, v[128:129]
	s_add_i32 m0, s48, 0x2000
	s_nop 0
	global_load_lds_dwordx4 v[154:155], off
	v_lshl_add_u64 v[154:155], v[228:229], 0, s[14:15]
	s_mov_b32 m0, s60
	s_nop 0
	global_load_lds_dwordx4 v[154:155], off
	v_lshl_add_u64 v[154:155], v[230:231], 0, s[14:15]
	s_mov_b32 m0, s61
	s_nop 0
	global_load_lds_dwordx4 v[154:155], off
	s_waitcnt vmcnt(8)
	s_waitcnt lgkmcnt(0)
	s_barrier
	s_setprio 1
	s_waitcnt lgkmcnt(0)
	v_mfma_f32_16x16x32_bf16 v[60:63], v[160:163], v[194:197], v[60:63]
	v_mfma_f32_16x16x32_bf16 v[60:63], v[164:167], v[198:201], v[60:63]
	v_mfma_f32_16x16x32_bf16 v[44:47], v[164:167], v[206:209], v[44:47]
	v_mfma_f32_16x16x32_bf16 v[44:47], v[160:163], v[202:205], v[44:47]
	v_mfma_f32_16x16x32_bf16 v[28:31], v[160:163], v[210:213], v[28:31]
	v_mfma_f32_16x16x32_bf16 v[28:31], v[164:167], v[214:217], v[28:31]
	v_mfma_f32_16x16x32_bf16 v[12:15], v[164:167], v[222:225], v[12:15]
	v_mfma_f32_16x16x32_bf16 v[12:15], v[160:163], v[218:221], v[12:15]
	v_mfma_f32_16x16x32_bf16 v[4:7], v[168:171], v[218:221], v[4:7]
	v_mfma_f32_16x16x32_bf16 v[4:7], v[172:175], v[222:225], v[4:7]
	v_mfma_f32_16x16x32_bf16 v[20:23], v[172:175], v[214:217], v[20:23]
	v_mfma_f32_16x16x32_bf16 v[20:23], v[168:171], v[210:213], v[20:23]
	v_mfma_f32_16x16x32_bf16 v[36:39], v[168:171], v[202:205], v[36:39]
	v_mfma_f32_16x16x32_bf16 v[36:39], v[172:175], v[206:209], v[36:39]
	v_mfma_f32_16x16x32_bf16 v[52:55], v[172:175], v[198:201], v[52:55]
	v_mfma_f32_16x16x32_bf16 v[52:55], v[168:171], v[194:197], v[52:55]
	s_setprio 0
	s_setprio 1
	v_mfma_f32_16x16x32_bf16 v[56:59], v[176:179], v[194:197], v[56:59]
	v_mfma_f32_16x16x32_bf16 v[56:59], v[180:183], v[198:201], v[56:59]
	v_mfma_f32_16x16x32_bf16 v[40:43], v[180:183], v[206:209], v[40:43]
	v_mfma_f32_16x16x32_bf16 v[40:43], v[176:179], v[202:205], v[40:43]
	v_mfma_f32_16x16x32_bf16 v[24:27], v[176:179], v[210:213], v[24:27]
	v_mfma_f32_16x16x32_bf16 v[24:27], v[180:183], v[214:217], v[24:27]
	v_mfma_f32_16x16x32_bf16 v[8:11], v[180:183], v[222:225], v[8:11]
	v_mfma_f32_16x16x32_bf16 v[8:11], v[176:179], v[218:221], v[8:11]
	v_mfma_f32_16x16x32_bf16 v[0:3], v[186:189], v[218:221], v[0:3]
	v_mfma_f32_16x16x32_bf16 v[0:3], v[190:193], v[222:225], v[0:3]
	v_mfma_f32_16x16x32_bf16 v[16:19], v[190:193], v[214:217], v[16:19]
	v_mfma_f32_16x16x32_bf16 v[16:19], v[186:189], v[210:213], v[16:19]
	v_mfma_f32_16x16x32_bf16 v[32:35], v[186:189], v[202:205], v[32:35]
	v_mfma_f32_16x16x32_bf16 v[32:35], v[190:193], v[206:209], v[32:35]
	v_mfma_f32_16x16x32_bf16 v[48:51], v[190:193], v[198:201], v[48:51]
	v_mfma_f32_16x16x32_bf16 v[48:51], v[186:189], v[194:197], v[48:51]
	s_setprio 0
	s_barrier
	s_add_i32 s75, s75, 2
	s_add_u32 s71, s71, 0x100
	s_addc_u32 s74, s74, 0
	s_add_u32 s44, s44, 0x100
	s_addc_u32 s45, s45, 0
	s_branch .LBB0_76
.LBB0_75:
	v_add_u32_e32 v153, s64, v147
	ds_read_b128 v[160:163], v153
	v_xor_b32_e32 v253, 64, v153
	ds_read_b128 v[164:167], v253
	ds_read_b128 v[168:171], v153 offset:2048
	ds_read_b128 v[172:175], v253 offset:2048
	v_add_u32_e32 v153, s65, v147
	ds_read_b128 v[176:179], v153
	v_xor_b32_e32 v253, 64, v153
	ds_read_b128 v[180:183], v253
	ds_read_b128 v[186:189], v153 offset:2048
	ds_read_b128 v[190:193], v253 offset:2048
	s_add_u32 s48, s44, 0xfffc0080
	s_addc_u32 s49, s45, -1
	s_and_b64 s[46:47], s[46:47], exec
	s_cselect_b32 s49, s27, s49
	s_cselect_b32 s48, s68, s48
	s_cselect_b32 s47, s69, s74
	s_cselect_b32 s46, s70, s71
	v_lshl_add_u64 v[154:155], s[44:45], 0, v[138:139]
	s_add_i32 m0, s55, 0xc000
	ds_read_b128 v[194:197], v150
	v_xor_b32_e32 v253, 64, v150
	ds_read_b128 v[198:201], v253
	ds_read_b128 v[202:205], v150 offset:2048
	ds_read_b128 v[206:209], v253 offset:2048
	ds_read_b128 v[210:213], v150 offset:4096
	ds_read_b128 v[214:217], v253 offset:4096
	ds_read_b128 v[218:221], v150 offset:6144
	ds_read_b128 v[222:225], v253 offset:6144
	global_load_lds_dwordx4 v[154:155], off
	v_lshl_add_u64 v[154:155], s[44:45], 0, v[136:137]
	s_add_i32 m0, s55, 0xe000
	s_nop 0
	global_load_lds_dwordx4 v[154:155], off
	s_waitcnt vmcnt(8)
	s_waitcnt lgkmcnt(0)
	s_barrier
	s_setprio 1
	s_waitcnt lgkmcnt(0)
	v_mfma_f32_16x16x32_bf16 v[124:127], v[160:163], v[194:197], v[124:127]
	v_mfma_f32_16x16x32_bf16 v[124:127], v[164:167], v[198:201], v[124:127]
	v_mfma_f32_16x16x32_bf16 v[108:111], v[164:167], v[206:209], v[108:111]
	v_mfma_f32_16x16x32_bf16 v[108:111], v[160:163], v[202:205], v[108:111]
	v_mfma_f32_16x16x32_bf16 v[92:95], v[160:163], v[210:213], v[92:95]
	v_mfma_f32_16x16x32_bf16 v[92:95], v[164:167], v[214:217], v[92:95]
	v_mfma_f32_16x16x32_bf16 v[76:79], v[164:167], v[222:225], v[76:79]
	v_mfma_f32_16x16x32_bf16 v[76:79], v[160:163], v[218:221], v[76:79]
	v_mfma_f32_16x16x32_bf16 v[68:71], v[168:171], v[218:221], v[68:71]
	v_mfma_f32_16x16x32_bf16 v[68:71], v[172:175], v[222:225], v[68:71]
	v_mfma_f32_16x16x32_bf16 v[84:87], v[172:175], v[214:217], v[84:87]
	v_mfma_f32_16x16x32_bf16 v[84:87], v[168:171], v[210:213], v[84:87]
	v_mfma_f32_16x16x32_bf16 v[100:103], v[168:171], v[202:205], v[100:103]
	v_mfma_f32_16x16x32_bf16 v[100:103], v[172:175], v[206:209], v[100:103]
	v_mfma_f32_16x16x32_bf16 v[116:119], v[172:175], v[198:201], v[116:119]
	v_mfma_f32_16x16x32_bf16 v[116:119], v[168:171], v[194:197], v[116:119]
	s_setprio 0
	s_setprio 1
	v_mfma_f32_16x16x32_bf16 v[120:123], v[176:179], v[194:197], v[120:123]
	v_mfma_f32_16x16x32_bf16 v[120:123], v[180:183], v[198:201], v[120:123]
	v_mfma_f32_16x16x32_bf16 v[104:107], v[180:183], v[206:209], v[104:107]
	v_mfma_f32_16x16x32_bf16 v[104:107], v[176:179], v[202:205], v[104:107]
	v_mfma_f32_16x16x32_bf16 v[88:91], v[176:179], v[210:213], v[88:91]
	v_mfma_f32_16x16x32_bf16 v[88:91], v[180:183], v[214:217], v[88:91]
	v_mfma_f32_16x16x32_bf16 v[72:75], v[180:183], v[222:225], v[72:75]
	v_mfma_f32_16x16x32_bf16 v[72:75], v[176:179], v[218:221], v[72:75]
	v_mfma_f32_16x16x32_bf16 v[64:67], v[186:189], v[218:221], v[64:67]
	v_mfma_f32_16x16x32_bf16 v[64:67], v[190:193], v[222:225], v[64:67]
	v_mfma_f32_16x16x32_bf16 v[80:83], v[190:193], v[214:217], v[80:83]
	v_mfma_f32_16x16x32_bf16 v[80:83], v[186:189], v[210:213], v[80:83]
	v_mfma_f32_16x16x32_bf16 v[96:99], v[186:189], v[202:205], v[96:99]
	v_mfma_f32_16x16x32_bf16 v[96:99], v[190:193], v[206:209], v[96:99]
	v_mfma_f32_16x16x32_bf16 v[112:115], v[190:193], v[198:201], v[112:115]
	v_mfma_f32_16x16x32_bf16 v[112:115], v[186:189], v[194:197], v[112:115]
	s_setprio 0
	s_barrier
	s_add_i32 s76, s64, s52
	v_lshl_add_u64 v[154:155], s[46:47], 0, v[132:133]
	s_mov_b32 m0, s76
	ds_read_b128 v[194:197], v150 offset:16384
	v_xor_b32_e32 v253, 64, v150
	ds_read_b128 v[198:201], v253 offset:16384
	ds_read_b128 v[202:205], v150 offset:18432
	ds_read_b128 v[206:209], v253 offset:18432
	ds_read_b128 v[210:213], v150 offset:20480
	ds_read_b128 v[214:217], v253 offset:20480
	ds_read_b128 v[218:221], v150 offset:22528
	ds_read_b128 v[222:225], v253 offset:22528
	global_load_lds_dwordx4 v[154:155], off
	s_add_i32 m0, s76, 0x2000
	s_add_u32 s76, s46, 0x40000
	v_lshl_add_u64 v[226:227], s[46:47], 0, v[128:129]
	s_addc_u32 s77, s47, 0
	s_add_i32 s78, s65, s52
	global_load_lds_dwordx4 v[226:227], off
	v_lshl_add_u64 v[228:229], s[76:77], 0, v[132:133]
	s_mov_b32 m0, s78
	v_lshl_add_u64 v[230:231], s[48:49], 0, v[130:131]
	global_load_lds_dwordx4 v[228:229], off
	v_lshl_add_u64 v[228:229], s[76:77], 0, v[128:129]
	s_add_i32 m0, s78, 0x2000
	s_nop 0
	global_load_lds_dwordx4 v[228:229], off
	v_lshl_add_u64 v[228:229], s[48:49], 0, v[134:135]
	s_mov_b32 m0, s55
	s_nop 0
	global_load_lds_dwordx4 v[228:229], off
	s_mov_b32 m0, s56
	s_nop 0
	global_load_lds_dwordx4 v[230:231], off
	s_waitcnt vmcnt(8)
	s_waitcnt lgkmcnt(0)
	s_barrier
	s_setprio 1
	s_waitcnt lgkmcnt(0)
	v_mfma_f32_16x16x32_bf16 v[60:63], v[160:163], v[194:197], v[60:63]
	v_mfma_f32_16x16x32_bf16 v[60:63], v[164:167], v[198:201], v[60:63]
	v_mfma_f32_16x16x32_bf16 v[44:47], v[164:167], v[206:209], v[44:47]
	v_mfma_f32_16x16x32_bf16 v[44:47], v[160:163], v[202:205], v[44:47]
	v_mfma_f32_16x16x32_bf16 v[28:31], v[160:163], v[210:213], v[28:31]
	v_mfma_f32_16x16x32_bf16 v[28:31], v[164:167], v[214:217], v[28:31]
	v_mfma_f32_16x16x32_bf16 v[12:15], v[164:167], v[222:225], v[12:15]
	v_mfma_f32_16x16x32_bf16 v[12:15], v[160:163], v[218:221], v[12:15]
	v_mfma_f32_16x16x32_bf16 v[4:7], v[168:171], v[218:221], v[4:7]
	v_mfma_f32_16x16x32_bf16 v[4:7], v[172:175], v[222:225], v[4:7]
	v_mfma_f32_16x16x32_bf16 v[20:23], v[172:175], v[214:217], v[20:23]
	v_mfma_f32_16x16x32_bf16 v[20:23], v[168:171], v[210:213], v[20:23]
	v_mfma_f32_16x16x32_bf16 v[36:39], v[168:171], v[202:205], v[36:39]
	v_mfma_f32_16x16x32_bf16 v[36:39], v[172:175], v[206:209], v[36:39]
	v_mfma_f32_16x16x32_bf16 v[52:55], v[172:175], v[198:201], v[52:55]
	v_mfma_f32_16x16x32_bf16 v[52:55], v[168:171], v[194:197], v[52:55]
	s_setprio 0
	s_setprio 1
	v_mfma_f32_16x16x32_bf16 v[56:59], v[176:179], v[194:197], v[56:59]
	v_mfma_f32_16x16x32_bf16 v[56:59], v[180:183], v[198:201], v[56:59]
	v_mfma_f32_16x16x32_bf16 v[40:43], v[180:183], v[206:209], v[40:43]
	v_mfma_f32_16x16x32_bf16 v[40:43], v[176:179], v[202:205], v[40:43]
	v_mfma_f32_16x16x32_bf16 v[24:27], v[176:179], v[210:213], v[24:27]
	v_mfma_f32_16x16x32_bf16 v[24:27], v[180:183], v[214:217], v[24:27]
	v_mfma_f32_16x16x32_bf16 v[8:11], v[180:183], v[222:225], v[8:11]
	v_mfma_f32_16x16x32_bf16 v[8:11], v[176:179], v[218:221], v[8:11]
	v_mfma_f32_16x16x32_bf16 v[0:3], v[186:189], v[218:221], v[0:3]
	v_mfma_f32_16x16x32_bf16 v[0:3], v[190:193], v[222:225], v[0:3]
	v_mfma_f32_16x16x32_bf16 v[16:19], v[190:193], v[214:217], v[16:19]
	v_mfma_f32_16x16x32_bf16 v[16:19], v[186:189], v[210:213], v[16:19]
	v_mfma_f32_16x16x32_bf16 v[32:35], v[186:189], v[202:205], v[32:35]
	v_mfma_f32_16x16x32_bf16 v[32:35], v[190:193], v[206:209], v[32:35]
	v_mfma_f32_16x16x32_bf16 v[48:51], v[190:193], v[198:201], v[48:51]
	v_mfma_f32_16x16x32_bf16 v[48:51], v[186:189], v[194:197], v[48:51]
	s_setprio 0
	s_barrier
	s_add_i32 s76, 0, 0x18000
	v_add_u32_e32 v153, s76, v147
	s_add_i32 s77, 0, 0x1c000
	ds_read_b128 v[160:163], v153
	v_xor_b32_e32 v253, 64, v153
	ds_read_b128 v[164:167], v253
	ds_read_b128 v[168:171], v153 offset:2048
	ds_read_b128 v[172:175], v253 offset:2048
	v_add_u32_e32 v153, s77, v147
	ds_read_b128 v[176:179], v153
	v_xor_b32_e32 v253, 64, v153
	ds_read_b128 v[180:183], v253
	ds_read_b128 v[186:189], v153 offset:2048
	ds_read_b128 v[190:193], v253 offset:2048
	s_add_u32 s48, s48, 0x40000
	s_addc_u32 s49, s49, 0
	s_mov_b32 m0, s57
	v_lshl_add_u64 v[232:233], s[48:49], 0, v[134:135]
	ds_read_b128 v[194:197], v150 offset:32768
	v_xor_b32_e32 v253, 64, v150
	ds_read_b128 v[198:201], v253 offset:32768
	ds_read_b128 v[202:205], v150 offset:34816
	ds_read_b128 v[206:209], v253 offset:34816
	ds_read_b128 v[210:213], v150 offset:36864
	ds_read_b128 v[214:217], v253 offset:36864
	ds_read_b128 v[218:221], v150 offset:38912
	ds_read_b128 v[222:225], v253 offset:38912
	global_load_lds_dwordx4 v[232:233], off
	v_lshl_add_u64 v[232:233], s[48:49], 0, v[130:131]
	s_mov_b32 m0, s58
	s_nop 0
	global_load_lds_dwordx4 v[232:233], off
	s_waitcnt vmcnt(8)
	s_waitcnt lgkmcnt(0)
	s_barrier
	s_setprio 1
	s_waitcnt lgkmcnt(0)
	v_mfma_f32_16x16x32_bf16 v[124:127], v[160:163], v[194:197], v[124:127]
	v_mfma_f32_16x16x32_bf16 v[124:127], v[164:167], v[198:201], v[124:127]
	v_mfma_f32_16x16x32_bf16 v[108:111], v[164:167], v[206:209], v[108:111]
	v_mfma_f32_16x16x32_bf16 v[108:111], v[160:163], v[202:205], v[108:111]
	v_mfma_f32_16x16x32_bf16 v[92:95], v[160:163], v[210:213], v[92:95]
	v_mfma_f32_16x16x32_bf16 v[92:95], v[164:167], v[214:217], v[92:95]
	v_mfma_f32_16x16x32_bf16 v[76:79], v[164:167], v[222:225], v[76:79]
	v_mfma_f32_16x16x32_bf16 v[76:79], v[160:163], v[218:221], v[76:79]
	v_mfma_f32_16x16x32_bf16 v[68:71], v[168:171], v[218:221], v[68:71]
	v_mfma_f32_16x16x32_bf16 v[68:71], v[172:175], v[222:225], v[68:71]
	v_mfma_f32_16x16x32_bf16 v[84:87], v[172:175], v[214:217], v[84:87]
	v_mfma_f32_16x16x32_bf16 v[84:87], v[168:171], v[210:213], v[84:87]
	v_mfma_f32_16x16x32_bf16 v[100:103], v[168:171], v[202:205], v[100:103]
	v_mfma_f32_16x16x32_bf16 v[100:103], v[172:175], v[206:209], v[100:103]
	v_mfma_f32_16x16x32_bf16 v[116:119], v[172:175], v[198:201], v[116:119]
	v_mfma_f32_16x16x32_bf16 v[116:119], v[168:171], v[194:197], v[116:119]
	s_setprio 0
	s_setprio 1
	v_mfma_f32_16x16x32_bf16 v[120:123], v[176:179], v[194:197], v[120:123]
	v_mfma_f32_16x16x32_bf16 v[120:123], v[180:183], v[198:201], v[120:123]
	v_mfma_f32_16x16x32_bf16 v[104:107], v[180:183], v[206:209], v[104:107]
	v_mfma_f32_16x16x32_bf16 v[104:107], v[176:179], v[202:205], v[104:107]
	v_mfma_f32_16x16x32_bf16 v[88:91], v[176:179], v[210:213], v[88:91]
	v_mfma_f32_16x16x32_bf16 v[88:91], v[180:183], v[214:217], v[88:91]
	v_mfma_f32_16x16x32_bf16 v[72:75], v[180:183], v[222:225], v[72:75]
	v_mfma_f32_16x16x32_bf16 v[72:75], v[176:179], v[218:221], v[72:75]
	v_mfma_f32_16x16x32_bf16 v[64:67], v[186:189], v[218:221], v[64:67]
	v_mfma_f32_16x16x32_bf16 v[64:67], v[190:193], v[222:225], v[64:67]
	v_mfma_f32_16x16x32_bf16 v[80:83], v[190:193], v[214:217], v[80:83]
	v_mfma_f32_16x16x32_bf16 v[80:83], v[186:189], v[210:213], v[80:83]
	v_mfma_f32_16x16x32_bf16 v[96:99], v[186:189], v[202:205], v[96:99]
	v_mfma_f32_16x16x32_bf16 v[96:99], v[190:193], v[206:209], v[96:99]
	v_mfma_f32_16x16x32_bf16 v[112:115], v[190:193], v[198:201], v[112:115]
	v_mfma_f32_16x16x32_bf16 v[112:115], v[186:189], v[194:197], v[112:115]
	s_setprio 0
	s_barrier
	s_add_i32 s48, s76, s52
	v_lshl_add_u64 v[154:155], v[154:155], 0, s[14:15]
	s_mov_b32 m0, s48
	ds_read_b128 v[194:197], v150 offset:49152
	v_xor_b32_e32 v253, 64, v150
	ds_read_b128 v[198:201], v253 offset:49152
	ds_read_b128 v[202:205], v150 offset:51200
	ds_read_b128 v[206:209], v253 offset:51200
	ds_read_b128 v[210:213], v150 offset:53248
	ds_read_b128 v[214:217], v253 offset:53248
	ds_read_b128 v[218:221], v150 offset:55296
	ds_read_b128 v[222:225], v253 offset:55296
	global_load_lds_dwordx4 v[154:155], off
	s_add_i32 m0, s48, 0x2000
	s_add_u32 s46, s46, 0x40080
	v_lshl_add_u64 v[154:155], v[226:227], 0, s[14:15]
	s_addc_u32 s47, s47, 0
	s_add_i32 s48, s77, s52
	global_load_lds_dwordx4 v[154:155], off
	v_lshl_add_u64 v[154:155], s[46:47], 0, v[132:133]
	s_mov_b32 m0, s48
	s_nop 0
	global_load_lds_dwordx4 v[154:155], off
	v_lshl_add_u64 v[154:155], s[46:47], 0, v[128:129]
	s_add_i32 m0, s48, 0x2000
	s_nop 0
	global_load_lds_dwordx4 v[154:155], off
	v_lshl_add_u64 v[154:155], v[228:229], 0, s[14:15]
	s_mov_b32 m0, s60
	s_nop 0
	global_load_lds_dwordx4 v[154:155], off
	v_lshl_add_u64 v[154:155], v[230:231], 0, s[14:15]
	s_mov_b32 m0, s61
	s_nop 0
	global_load_lds_dwordx4 v[154:155], off
	s_waitcnt vmcnt(8)
	s_waitcnt lgkmcnt(0)
	s_barrier
	s_setprio 1
	s_waitcnt lgkmcnt(0)
	v_mfma_f32_16x16x32_bf16 v[60:63], v[160:163], v[194:197], v[60:63]
	v_mfma_f32_16x16x32_bf16 v[60:63], v[164:167], v[198:201], v[60:63]
	v_mfma_f32_16x16x32_bf16 v[44:47], v[164:167], v[206:209], v[44:47]
	v_mfma_f32_16x16x32_bf16 v[44:47], v[160:163], v[202:205], v[44:47]
	v_mfma_f32_16x16x32_bf16 v[28:31], v[160:163], v[210:213], v[28:31]
	v_mfma_f32_16x16x32_bf16 v[28:31], v[164:167], v[214:217], v[28:31]
	v_mfma_f32_16x16x32_bf16 v[12:15], v[164:167], v[222:225], v[12:15]
	v_mfma_f32_16x16x32_bf16 v[12:15], v[160:163], v[218:221], v[12:15]
	v_mfma_f32_16x16x32_bf16 v[4:7], v[168:171], v[218:221], v[4:7]
	v_mfma_f32_16x16x32_bf16 v[4:7], v[172:175], v[222:225], v[4:7]
	v_mfma_f32_16x16x32_bf16 v[20:23], v[172:175], v[214:217], v[20:23]
	v_mfma_f32_16x16x32_bf16 v[20:23], v[168:171], v[210:213], v[20:23]
	v_mfma_f32_16x16x32_bf16 v[36:39], v[168:171], v[202:205], v[36:39]
	v_mfma_f32_16x16x32_bf16 v[36:39], v[172:175], v[206:209], v[36:39]
	v_mfma_f32_16x16x32_bf16 v[52:55], v[172:175], v[198:201], v[52:55]
	v_mfma_f32_16x16x32_bf16 v[52:55], v[168:171], v[194:197], v[52:55]
	s_setprio 0
	s_setprio 1
	v_mfma_f32_16x16x32_bf16 v[56:59], v[176:179], v[194:197], v[56:59]
	v_mfma_f32_16x16x32_bf16 v[56:59], v[180:183], v[198:201], v[56:59]
	v_mfma_f32_16x16x32_bf16 v[40:43], v[180:183], v[206:209], v[40:43]
	v_mfma_f32_16x16x32_bf16 v[40:43], v[176:179], v[202:205], v[40:43]
	v_mfma_f32_16x16x32_bf16 v[24:27], v[176:179], v[210:213], v[24:27]
	v_mfma_f32_16x16x32_bf16 v[24:27], v[180:183], v[214:217], v[24:27]
	v_mfma_f32_16x16x32_bf16 v[8:11], v[180:183], v[222:225], v[8:11]
	v_mfma_f32_16x16x32_bf16 v[8:11], v[176:179], v[218:221], v[8:11]
	v_mfma_f32_16x16x32_bf16 v[0:3], v[186:189], v[218:221], v[0:3]
	v_mfma_f32_16x16x32_bf16 v[0:3], v[190:193], v[222:225], v[0:3]
	v_mfma_f32_16x16x32_bf16 v[16:19], v[190:193], v[214:217], v[16:19]
	v_mfma_f32_16x16x32_bf16 v[16:19], v[186:189], v[210:213], v[16:19]
	v_mfma_f32_16x16x32_bf16 v[32:35], v[186:189], v[202:205], v[32:35]
	v_mfma_f32_16x16x32_bf16 v[32:35], v[190:193], v[206:209], v[32:35]
	v_mfma_f32_16x16x32_bf16 v[48:51], v[190:193], v[198:201], v[48:51]
	v_mfma_f32_16x16x32_bf16 v[48:51], v[186:189], v[194:197], v[48:51]
	s_setprio 0
	s_barrier
	s_add_i32 s75, s75, 2
	s_add_u32 s71, s71, 0x100
	s_addc_u32 s74, s74, 0
	s_add_u32 s44, s44, 0x100
	s_addc_u32 s45, s45, 0
	s_cmp_gt_u32 s75, 13
	s_cbranch_scc1 .LBB0_78

.Llast_0:
	v_add_u32_e32 v153, s64, v147
	ds_read_b128 v[160:163], v153
	v_xor_b32_e32 v253, 64, v153
	ds_read_b128 v[164:167], v253
	ds_read_b128 v[168:171], v153 offset:2048
	ds_read_b128 v[172:175], v253 offset:2048
	v_add_u32_e32 v153, s65, v147
	ds_read_b128 v[176:179], v153
	v_xor_b32_e32 v253, 64, v153
	ds_read_b128 v[180:183], v253
	ds_read_b128 v[186:189], v153 offset:2048
	ds_read_b128 v[190:193], v253 offset:2048
	s_add_u32 s48, s44, 0xfffc0080
	s_addc_u32 s49, s45, -1
	s_and_b64 s[46:47], s[46:47], exec
	s_cselect_b32 s49, s27, s49
	s_cselect_b32 s48, s68, s48
	s_cselect_b32 s47, s69, s74
	s_cselect_b32 s46, s70, s71
	v_lshl_add_u64 v[154:155], s[44:45], 0, v[138:139]
	s_add_i32 m0, s55, 0xc000
	ds_read_b128 v[194:197], v150
	v_xor_b32_e32 v253, 64, v150
	ds_read_b128 v[198:201], v253
	ds_read_b128 v[202:205], v150 offset:2048
	ds_read_b128 v[206:209], v253 offset:2048
	ds_read_b128 v[210:213], v150 offset:4096
	ds_read_b128 v[214:217], v253 offset:4096
	ds_read_b128 v[218:221], v150 offset:6144
	ds_read_b128 v[222:225], v253 offset:6144
	global_load_lds_dwordx4 v[154:155], off
	v_lshl_add_u64 v[154:155], s[44:45], 0, v[136:137]
	s_add_i32 m0, s55, 0xe000
	s_nop 0
	global_load_lds_dwordx4 v[154:155], off
	s_waitcnt vmcnt(8)
	s_waitcnt lgkmcnt(0)
	s_barrier
	s_setprio 1
	s_waitcnt lgkmcnt(0)
	v_mfma_f32_16x16x32_bf16 v[124:127], v[160:163], v[194:197], v[124:127]
	v_mfma_f32_16x16x32_bf16 v[124:127], v[164:167], v[198:201], v[124:127]
	v_mfma_f32_16x16x32_bf16 v[108:111], v[164:167], v[206:209], v[108:111]
	v_mfma_f32_16x16x32_bf16 v[108:111], v[160:163], v[202:205], v[108:111]
	v_mfma_f32_16x16x32_bf16 v[92:95], v[160:163], v[210:213], v[92:95]
	v_mfma_f32_16x16x32_bf16 v[92:95], v[164:167], v[214:217], v[92:95]
	v_mfma_f32_16x16x32_bf16 v[76:79], v[164:167], v[222:225], v[76:79]
	v_mfma_f32_16x16x32_bf16 v[76:79], v[160:163], v[218:221], v[76:79]
	v_mfma_f32_16x16x32_bf16 v[68:71], v[168:171], v[218:221], v[68:71]
	v_mfma_f32_16x16x32_bf16 v[68:71], v[172:175], v[222:225], v[68:71]
	v_mfma_f32_16x16x32_bf16 v[84:87], v[172:175], v[214:217], v[84:87]
	v_mfma_f32_16x16x32_bf16 v[84:87], v[168:171], v[210:213], v[84:87]
	v_mfma_f32_16x16x32_bf16 v[100:103], v[168:171], v[202:205], v[100:103]
	v_mfma_f32_16x16x32_bf16 v[100:103], v[172:175], v[206:209], v[100:103]
	v_mfma_f32_16x16x32_bf16 v[116:119], v[172:175], v[198:201], v[116:119]
	v_mfma_f32_16x16x32_bf16 v[116:119], v[168:171], v[194:197], v[116:119]
	s_setprio 0
	s_setprio 1
	v_mfma_f32_16x16x32_bf16 v[120:123], v[176:179], v[194:197], v[120:123]
	v_mfma_f32_16x16x32_bf16 v[120:123], v[180:183], v[198:201], v[120:123]
	v_mfma_f32_16x16x32_bf16 v[104:107], v[180:183], v[206:209], v[104:107]
	v_mfma_f32_16x16x32_bf16 v[104:107], v[176:179], v[202:205], v[104:107]
	v_mfma_f32_16x16x32_bf16 v[88:91], v[176:179], v[210:213], v[88:91]
	v_mfma_f32_16x16x32_bf16 v[88:91], v[180:183], v[214:217], v[88:91]
	v_mfma_f32_16x16x32_bf16 v[72:75], v[180:183], v[222:225], v[72:75]
	v_mfma_f32_16x16x32_bf16 v[72:75], v[176:179], v[218:221], v[72:75]
	v_mfma_f32_16x16x32_bf16 v[64:67], v[186:189], v[218:221], v[64:67]
	v_mfma_f32_16x16x32_bf16 v[64:67], v[190:193], v[222:225], v[64:67]
	v_mfma_f32_16x16x32_bf16 v[80:83], v[190:193], v[214:217], v[80:83]
	v_mfma_f32_16x16x32_bf16 v[80:83], v[186:189], v[210:213], v[80:83]
	v_mfma_f32_16x16x32_bf16 v[96:99], v[186:189], v[202:205], v[96:99]
	v_mfma_f32_16x16x32_bf16 v[96:99], v[190:193], v[206:209], v[96:99]
	v_mfma_f32_16x16x32_bf16 v[112:115], v[190:193], v[198:201], v[112:115]
	v_mfma_f32_16x16x32_bf16 v[112:115], v[186:189], v[194:197], v[112:115]
	s_setprio 0
	s_barrier
	s_add_i32 s76, s64, s52
	v_lshl_add_u64 v[154:155], s[46:47], 0, v[132:133]
	s_mov_b32 m0, s76
	ds_read_b128 v[194:197], v150 offset:16384
	v_xor_b32_e32 v253, 64, v150
	ds_read_b128 v[198:201], v253 offset:16384
	ds_read_b128 v[202:205], v150 offset:18432
	ds_read_b128 v[206:209], v253 offset:18432
	ds_read_b128 v[210:213], v150 offset:20480
	ds_read_b128 v[214:217], v253 offset:20480
	ds_read_b128 v[218:221], v150 offset:22528
	ds_read_b128 v[222:225], v253 offset:22528
	global_load_lds_dwordx4 v[154:155], off
	s_add_i32 m0, s76, 0x2000
	s_add_u32 s76, s46, 0x40000
	v_lshl_add_u64 v[226:227], s[46:47], 0, v[128:129]
	s_addc_u32 s77, s47, 0
	s_add_i32 s78, s65, s52
	global_load_lds_dwordx4 v[226:227], off
	v_lshl_add_u64 v[228:229], s[76:77], 0, v[132:133]
	s_mov_b32 m0, s78
	v_lshl_add_u64 v[230:231], s[48:49], 0, v[130:131]
	global_load_lds_dwordx4 v[228:229], off
	v_lshl_add_u64 v[228:229], s[76:77], 0, v[128:129]
	s_add_i32 m0, s78, 0x2000
	s_nop 0
	global_load_lds_dwordx4 v[228:229], off
	v_lshl_add_u64 v[228:229], s[48:49], 0, v[134:135]
	s_mov_b32 m0, s55
	s_nop 0
	global_load_lds_dwordx4 v[228:229], off
	s_mov_b32 m0, s56
	s_nop 0
	global_load_lds_dwordx4 v[230:231], off
	s_waitcnt vmcnt(8)
	s_waitcnt lgkmcnt(0)
	s_barrier
	s_setprio 1
	s_waitcnt lgkmcnt(0)
	v_mfma_f32_16x16x32_bf16 v[60:63], v[160:163], v[194:197], v[60:63]
	v_mfma_f32_16x16x32_bf16 v[60:63], v[164:167], v[198:201], v[60:63]
	v_mfma_f32_16x16x32_bf16 v[44:47], v[164:167], v[206:209], v[44:47]
	v_mfma_f32_16x16x32_bf16 v[44:47], v[160:163], v[202:205], v[44:47]
	v_mfma_f32_16x16x32_bf16 v[28:31], v[160:163], v[210:213], v[28:31]
	v_mfma_f32_16x16x32_bf16 v[28:31], v[164:167], v[214:217], v[28:31]
	v_mfma_f32_16x16x32_bf16 v[12:15], v[164:167], v[222:225], v[12:15]
	v_mfma_f32_16x16x32_bf16 v[12:15], v[160:163], v[218:221], v[12:15]
	v_mfma_f32_16x16x32_bf16 v[4:7], v[168:171], v[218:221], v[4:7]
	v_mfma_f32_16x16x32_bf16 v[4:7], v[172:175], v[222:225], v[4:7]
	v_mfma_f32_16x16x32_bf16 v[20:23], v[172:175], v[214:217], v[20:23]
	v_mfma_f32_16x16x32_bf16 v[20:23], v[168:171], v[210:213], v[20:23]
	v_mfma_f32_16x16x32_bf16 v[36:39], v[168:171], v[202:205], v[36:39]
	v_mfma_f32_16x16x32_bf16 v[36:39], v[172:175], v[206:209], v[36:39]
	v_mfma_f32_16x16x32_bf16 v[52:55], v[172:175], v[198:201], v[52:55]
	v_mfma_f32_16x16x32_bf16 v[52:55], v[168:171], v[194:197], v[52:55]
	s_setprio 0
	s_setprio 1
	v_mfma_f32_16x16x32_bf16 v[56:59], v[176:179], v[194:197], v[56:59]
	v_mfma_f32_16x16x32_bf16 v[56:59], v[180:183], v[198:201], v[56:59]
	v_mfma_f32_16x16x32_bf16 v[40:43], v[180:183], v[206:209], v[40:43]
	v_mfma_f32_16x16x32_bf16 v[40:43], v[176:179], v[202:205], v[40:43]
	v_mfma_f32_16x16x32_bf16 v[24:27], v[176:179], v[210:213], v[24:27]
	v_mfma_f32_16x16x32_bf16 v[24:27], v[180:183], v[214:217], v[24:27]
	v_mfma_f32_16x16x32_bf16 v[8:11], v[180:183], v[222:225], v[8:11]
	v_mfma_f32_16x16x32_bf16 v[8:11], v[176:179], v[218:221], v[8:11]
	v_mfma_f32_16x16x32_bf16 v[0:3], v[186:189], v[218:221], v[0:3]
	v_mfma_f32_16x16x32_bf16 v[0:3], v[190:193], v[222:225], v[0:3]
	v_mfma_f32_16x16x32_bf16 v[16:19], v[190:193], v[214:217], v[16:19]
	v_mfma_f32_16x16x32_bf16 v[16:19], v[186:189], v[210:213], v[16:19]
	v_mfma_f32_16x16x32_bf16 v[32:35], v[186:189], v[202:205], v[32:35]
	v_mfma_f32_16x16x32_bf16 v[32:35], v[190:193], v[206:209], v[32:35]
	v_mfma_f32_16x16x32_bf16 v[48:51], v[190:193], v[198:201], v[48:51]
	v_mfma_f32_16x16x32_bf16 v[48:51], v[186:189], v[194:197], v[48:51]
	s_setprio 0
	s_barrier
	s_add_i32 s76, 0, 0x18000
	v_add_u32_e32 v153, s76, v147
	s_add_i32 s77, 0, 0x1c000
	ds_read_b128 v[160:163], v153
	v_xor_b32_e32 v253, 64, v153
	ds_read_b128 v[164:167], v253
	ds_read_b128 v[168:171], v153 offset:2048
	ds_read_b128 v[172:175], v253 offset:2048
	v_add_u32_e32 v153, s77, v147
	ds_read_b128 v[176:179], v153
	v_xor_b32_e32 v253, 64, v153
	ds_read_b128 v[180:183], v253
	ds_read_b128 v[186:189], v153 offset:2048
	ds_read_b128 v[190:193], v253 offset:2048
	s_add_u32 s48, s48, 0x40000
	s_addc_u32 s49, s49, 0
	s_mov_b32 m0, s57
	v_lshl_add_u64 v[232:233], s[48:49], 0, v[134:135]
	ds_read_b128 v[194:197], v150 offset:32768
	v_xor_b32_e32 v253, 64, v150
	ds_read_b128 v[198:201], v253 offset:32768
	ds_read_b128 v[202:205], v150 offset:34816
	ds_read_b128 v[206:209], v253 offset:34816
	ds_read_b128 v[210:213], v150 offset:36864
	ds_read_b128 v[214:217], v253 offset:36864
	ds_read_b128 v[218:221], v150 offset:38912
	ds_read_b128 v[222:225], v253 offset:38912
	global_load_lds_dwordx4 v[232:233], off
	v_lshl_add_u64 v[232:233], s[48:49], 0, v[130:131]
	s_mov_b32 m0, s58
	s_nop 0
	global_load_lds_dwordx4 v[232:233], off
	s_waitcnt vmcnt(8)
	s_waitcnt lgkmcnt(0)
	s_barrier
	s_setprio 1
	s_waitcnt lgkmcnt(0)
	v_mfma_f32_16x16x32_bf16 v[124:127], v[160:163], v[194:197], v[124:127]
	v_mfma_f32_16x16x32_bf16 v[124:127], v[164:167], v[198:201], v[124:127]
	v_mfma_f32_16x16x32_bf16 v[108:111], v[164:167], v[206:209], v[108:111]
	v_mfma_f32_16x16x32_bf16 v[108:111], v[160:163], v[202:205], v[108:111]
	v_mfma_f32_16x16x32_bf16 v[92:95], v[160:163], v[210:213], v[92:95]
	v_mfma_f32_16x16x32_bf16 v[92:95], v[164:167], v[214:217], v[92:95]
	v_mfma_f32_16x16x32_bf16 v[76:79], v[164:167], v[222:225], v[76:79]
	v_mfma_f32_16x16x32_bf16 v[76:79], v[160:163], v[218:221], v[76:79]
	v_mfma_f32_16x16x32_bf16 v[68:71], v[168:171], v[218:221], v[68:71]
	v_mfma_f32_16x16x32_bf16 v[68:71], v[172:175], v[222:225], v[68:71]
	v_mfma_f32_16x16x32_bf16 v[84:87], v[172:175], v[214:217], v[84:87]
	v_mfma_f32_16x16x32_bf16 v[84:87], v[168:171], v[210:213], v[84:87]
	v_mfma_f32_16x16x32_bf16 v[100:103], v[168:171], v[202:205], v[100:103]
	v_mfma_f32_16x16x32_bf16 v[100:103], v[172:175], v[206:209], v[100:103]
	v_mfma_f32_16x16x32_bf16 v[116:119], v[172:175], v[198:201], v[116:119]
	v_mfma_f32_16x16x32_bf16 v[116:119], v[168:171], v[194:197], v[116:119]
	s_setprio 0
	s_setprio 1
	v_mfma_f32_16x16x32_bf16 v[120:123], v[176:179], v[194:197], v[120:123]
	v_mfma_f32_16x16x32_bf16 v[120:123], v[180:183], v[198:201], v[120:123]
	v_mfma_f32_16x16x32_bf16 v[104:107], v[180:183], v[206:209], v[104:107]
	v_mfma_f32_16x16x32_bf16 v[104:107], v[176:179], v[202:205], v[104:107]
	v_mfma_f32_16x16x32_bf16 v[88:91], v[176:179], v[210:213], v[88:91]
	v_mfma_f32_16x16x32_bf16 v[88:91], v[180:183], v[214:217], v[88:91]
	v_mfma_f32_16x16x32_bf16 v[72:75], v[180:183], v[222:225], v[72:75]
	v_mfma_f32_16x16x32_bf16 v[72:75], v[176:179], v[218:221], v[72:75]
	v_mfma_f32_16x16x32_bf16 v[64:67], v[186:189], v[218:221], v[64:67]
	v_mfma_f32_16x16x32_bf16 v[64:67], v[190:193], v[222:225], v[64:67]
	v_mfma_f32_16x16x32_bf16 v[80:83], v[190:193], v[214:217], v[80:83]
	v_mfma_f32_16x16x32_bf16 v[80:83], v[186:189], v[210:213], v[80:83]
	v_mfma_f32_16x16x32_bf16 v[96:99], v[186:189], v[202:205], v[96:99]
	v_mfma_f32_16x16x32_bf16 v[96:99], v[190:193], v[206:209], v[96:99]
	v_mfma_f32_16x16x32_bf16 v[112:115], v[190:193], v[198:201], v[112:115]
	v_mfma_f32_16x16x32_bf16 v[112:115], v[186:189], v[194:197], v[112:115]
	s_setprio 0
	s_barrier
	v_add_u32_e32 v234, 0x21000, v151
	ds_read_b128 v[236:239], v234
	ds_read_b128 v[240:243], v234 offset:256
	ds_read_b128 v[244:247], v234 offset:512
	ds_read_b128 v[248:251], v234 offset:768
	v_add_u32_e32 v235, s23, v146
	v_mul_u32_u24_e32 v235, 0x1600, v235
	v_lshl_or_b32 v234, s67, 7, v149
	v_lshl_add_u32 v235, v234, 1, v235
	s_add_i32 s48, s76, s52
	v_lshl_add_u64 v[154:155], v[154:155], 0, s[14:15]
	s_mov_b32 m0, s48
	ds_read_b128 v[194:197], v150 offset:49152
	v_xor_b32_e32 v253, 64, v150
	ds_read_b128 v[198:201], v253 offset:49152
	ds_read_b128 v[202:205], v150 offset:51200
	ds_read_b128 v[206:209], v253 offset:51200
	ds_read_b128 v[210:213], v150 offset:53248
	ds_read_b128 v[214:217], v253 offset:53248
	ds_read_b128 v[218:221], v150 offset:55296
	ds_read_b128 v[222:225], v253 offset:55296
	global_load_lds_dwordx4 v[154:155], off
	s_add_i32 m0, s48, 0x2000
	s_add_u32 s46, s46, 0x40080
	v_lshl_add_u64 v[154:155], v[226:227], 0, s[14:15]
	s_addc_u32 s47, s47, 0
	s_add_i32 s48, s77, s52
	global_load_lds_dwordx4 v[154:155], off
	v_lshl_add_u64 v[154:155], s[46:47], 0, v[132:133]
	s_mov_b32 m0, s48
	s_nop 0
	global_load_lds_dwordx4 v[154:155], off
	v_lshl_add_u64 v[154:155], s[46:47], 0, v[128:129]
	s_add_i32 m0, s48, 0x2000
	s_nop 0
	global_load_lds_dwordx4 v[154:155], off
	v_lshl_add_u64 v[154:155], v[228:229], 0, s[14:15]
	s_mov_b32 m0, s60
	s_nop 0
	global_load_lds_dwordx4 v[154:155], off
	v_lshl_add_u64 v[154:155], v[230:231], 0, s[14:15]
	s_mov_b32 m0, s61
	s_nop 0
	global_load_lds_dwordx4 v[154:155], off
	s_waitcnt lgkmcnt(8)
	v_add_f32_e32 v236, v236, v237
	v_add_f32_e32 v238, v238, v239
	v_add_f32_e32 v240, v240, v241
	v_add_f32_e32 v242, v242, v243
	v_add_f32_e32 v244, v244, v245
	v_add_f32_e32 v246, v246, v247
	v_add_f32_e32 v248, v248, v249
	v_add_f32_e32 v250, v250, v251
	v_add_f32_e32 v236, v236, v238
	v_add_f32_e32 v240, v240, v242
	v_add_f32_e32 v244, v244, v246
	v_add_f32_e32 v248, v248, v250
	v_fmamk_f32 v236, v236, 0x3a800000, v152
	v_fmamk_f32 v240, v240, 0x3a800000, v152
	v_fmamk_f32 v244, v244, 0x3a800000, v152
	v_fmamk_f32 v248, v248, 0x3a800000, v152
	v_rsq_f32_e32 v236, v236
	v_rsq_f32_e32 v240, v240
	v_rsq_f32_e32 v244, v244
	v_rsq_f32_e32 v248, v248
	v_mul_f32_e32 v252, 0xbfb8aa3b, v236
	v_mul_f32_e32 v254, v236, v236
	v_pk_mul_f32 v[120:121], v[124:125], v[120:121]
	v_pk_mul_f32 v[122:123], v[126:127], v[122:123]
	v_pk_mul_f32 v[112:113], v[116:117], v[112:113]
	v_pk_mul_f32 v[114:115], v[118:119], v[114:115]
	v_pk_mul_f32 v[124:125], v[124:125], v[252:253] op_sel_hi:[1,0]
	v_pk_mul_f32 v[126:127], v[126:127], v[252:253] op_sel_hi:[1,0]
	v_pk_mul_f32 v[116:117], v[116:117], v[252:253] op_sel_hi:[1,0]
	v_pk_mul_f32 v[118:119], v[118:119], v[252:253] op_sel_hi:[1,0]
	v_exp_f32_e32 v124, v124
	v_exp_f32_e32 v125, v125
	v_exp_f32_e32 v126, v126
	v_exp_f32_e32 v127, v127
	v_exp_f32_e32 v116, v116
	v_exp_f32_e32 v117, v117
	v_exp_f32_e32 v118, v118
	v_exp_f32_e32 v119, v119
	v_pk_add_f32 v[124:125], v[124:125], 1.0 op_sel_hi:[1,0]
	v_pk_add_f32 v[126:127], v[126:127], 1.0 op_sel_hi:[1,0]
	v_pk_add_f32 v[116:117], v[116:117], 1.0 op_sel_hi:[1,0]
	v_pk_add_f32 v[118:119], v[118:119], 1.0 op_sel_hi:[1,0]
	v_rcp_f32_e32 v124, v124
	v_rcp_f32_e32 v125, v125
	v_rcp_f32_e32 v126, v126
	v_rcp_f32_e32 v127, v127
	v_rcp_f32_e32 v116, v116
	v_rcp_f32_e32 v117, v117
	v_rcp_f32_e32 v118, v118
	v_rcp_f32_e32 v119, v119
	v_pk_mul_f32 v[120:121], v[120:121], v[254:255] op_sel_hi:[1,0]
	v_pk_mul_f32 v[122:123], v[122:123], v[254:255] op_sel_hi:[1,0]
	v_pk_mul_f32 v[112:113], v[112:113], v[254:255] op_sel_hi:[1,0]
	v_pk_mul_f32 v[114:115], v[114:115], v[254:255] op_sel_hi:[1,0]
	v_pk_mul_f32 v[120:121], v[120:121], v[124:125]
	v_pk_mul_f32 v[122:123], v[122:123], v[126:127]
	v_pk_mul_f32 v[112:113], v[112:113], v[116:117]
	v_pk_mul_f32 v[114:115], v[114:115], v[118:119]
	v_cvt_pk_bf16_f32 v120, v120, v121
	v_cvt_pk_bf16_f32 v121, v122, v123
	v_cvt_pk_bf16_f32 v122, v112, v113
	v_cvt_pk_bf16_f32 v123, v114, v115
	global_store_dwordx4 v235, v[120:123], s[10:11]
	v_add_u32_e32 v234, 0x16000, v235
	v_mul_f32_e32 v252, 0xbfb8aa3b, v240
	v_mul_f32_e32 v254, v240, v240
	v_pk_mul_f32 v[104:105], v[108:109], v[104:105]
	v_pk_mul_f32 v[106:107], v[110:111], v[106:107]
	v_pk_mul_f32 v[96:97], v[100:101], v[96:97]
	v_pk_mul_f32 v[98:99], v[102:103], v[98:99]
	v_pk_mul_f32 v[108:109], v[108:109], v[252:253] op_sel_hi:[1,0]
	v_pk_mul_f32 v[110:111], v[110:111], v[252:253] op_sel_hi:[1,0]
	v_pk_mul_f32 v[100:101], v[100:101], v[252:253] op_sel_hi:[1,0]
	v_pk_mul_f32 v[102:103], v[102:103], v[252:253] op_sel_hi:[1,0]
	v_exp_f32_e32 v108, v108
	v_exp_f32_e32 v109, v109
	v_exp_f32_e32 v110, v110
	v_exp_f32_e32 v111, v111
	v_exp_f32_e32 v100, v100
	v_exp_f32_e32 v101, v101
	v_exp_f32_e32 v102, v102
	v_exp_f32_e32 v103, v103
	v_pk_add_f32 v[108:109], v[108:109], 1.0 op_sel_hi:[1,0]
	v_pk_add_f32 v[110:111], v[110:111], 1.0 op_sel_hi:[1,0]
	v_pk_add_f32 v[100:101], v[100:101], 1.0 op_sel_hi:[1,0]
	v_pk_add_f32 v[102:103], v[102:103], 1.0 op_sel_hi:[1,0]
	v_rcp_f32_e32 v108, v108
	v_rcp_f32_e32 v109, v109
	v_rcp_f32_e32 v110, v110
	v_rcp_f32_e32 v111, v111
	v_rcp_f32_e32 v100, v100
	v_rcp_f32_e32 v101, v101
	v_rcp_f32_e32 v102, v102
	v_rcp_f32_e32 v103, v103
	v_pk_mul_f32 v[104:105], v[104:105], v[254:255] op_sel_hi:[1,0]
	v_pk_mul_f32 v[106:107], v[106:107], v[254:255] op_sel_hi:[1,0]
	v_pk_mul_f32 v[96:97], v[96:97], v[254:255] op_sel_hi:[1,0]
	v_pk_mul_f32 v[98:99], v[98:99], v[254:255] op_sel_hi:[1,0]
	v_pk_mul_f32 v[104:105], v[104:105], v[108:109]
	v_pk_mul_f32 v[106:107], v[106:107], v[110:111]
	v_pk_mul_f32 v[96:97], v[96:97], v[100:101]
	v_pk_mul_f32 v[98:99], v[98:99], v[102:103]
	v_cvt_pk_bf16_f32 v104, v104, v105
	v_cvt_pk_bf16_f32 v105, v106, v107
	v_cvt_pk_bf16_f32 v106, v96, v97
	v_cvt_pk_bf16_f32 v107, v98, v99
	global_store_dwordx4 v234, v[104:107], s[10:11]
	v_add_u32_e32 v235, 0x16000, v234
	v_mul_f32_e32 v252, 0xbfb8aa3b, v244
	v_mul_f32_e32 v254, v244, v244
	v_pk_mul_f32 v[88:89], v[92:93], v[88:89]
	v_pk_mul_f32 v[90:91], v[94:95], v[90:91]
	v_pk_mul_f32 v[80:81], v[84:85], v[80:81]
	v_pk_mul_f32 v[82:83], v[86:87], v[82:83]
	v_pk_mul_f32 v[92:93], v[92:93], v[252:253] op_sel_hi:[1,0]
	v_pk_mul_f32 v[94:95], v[94:95], v[252:253] op_sel_hi:[1,0]
	v_pk_mul_f32 v[84:85], v[84:85], v[252:253] op_sel_hi:[1,0]
	v_pk_mul_f32 v[86:87], v[86:87], v[252:253] op_sel_hi:[1,0]
	v_exp_f32_e32 v92, v92
	v_exp_f32_e32 v93, v93
	v_exp_f32_e32 v94, v94
	v_exp_f32_e32 v95, v95
	v_exp_f32_e32 v84, v84
	v_exp_f32_e32 v85, v85
	v_exp_f32_e32 v86, v86
	v_exp_f32_e32 v87, v87
	v_pk_add_f32 v[92:93], v[92:93], 1.0 op_sel_hi:[1,0]
	v_pk_add_f32 v[94:95], v[94:95], 1.0 op_sel_hi:[1,0]
	v_pk_add_f32 v[84:85], v[84:85], 1.0 op_sel_hi:[1,0]
	v_pk_add_f32 v[86:87], v[86:87], 1.0 op_sel_hi:[1,0]
	v_rcp_f32_e32 v92, v92
	v_rcp_f32_e32 v93, v93
	v_rcp_f32_e32 v94, v94
	v_rcp_f32_e32 v95, v95
	v_rcp_f32_e32 v84, v84
	v_rcp_f32_e32 v85, v85
	v_rcp_f32_e32 v86, v86
	v_rcp_f32_e32 v87, v87
	v_pk_mul_f32 v[88:89], v[88:89], v[254:255] op_sel_hi:[1,0]
	v_pk_mul_f32 v[90:91], v[90:91], v[254:255] op_sel_hi:[1,0]
	v_pk_mul_f32 v[80:81], v[80:81], v[254:255] op_sel_hi:[1,0]
	v_pk_mul_f32 v[82:83], v[82:83], v[254:255] op_sel_hi:[1,0]
	v_pk_mul_f32 v[88:89], v[88:89], v[92:93]
	v_pk_mul_f32 v[90:91], v[90:91], v[94:95]
	v_pk_mul_f32 v[80:81], v[80:81], v[84:85]
	v_pk_mul_f32 v[82:83], v[82:83], v[86:87]
	v_cvt_pk_bf16_f32 v88, v88, v89
	v_cvt_pk_bf16_f32 v89, v90, v91
	v_cvt_pk_bf16_f32 v90, v80, v81
	v_cvt_pk_bf16_f32 v91, v82, v83
	global_store_dwordx4 v235, v[88:91], s[10:11]
	v_add_u32_e32 v234, 0x16000, v235
	v_mul_f32_e32 v252, 0xbfb8aa3b, v248
	v_mul_f32_e32 v254, v248, v248
	v_pk_mul_f32 v[72:73], v[76:77], v[72:73]
	v_pk_mul_f32 v[74:75], v[78:79], v[74:75]
	v_pk_mul_f32 v[64:65], v[68:69], v[64:65]
	v_pk_mul_f32 v[66:67], v[70:71], v[66:67]
	v_pk_mul_f32 v[76:77], v[76:77], v[252:253] op_sel_hi:[1,0]
	v_pk_mul_f32 v[78:79], v[78:79], v[252:253] op_sel_hi:[1,0]
	v_pk_mul_f32 v[68:69], v[68:69], v[252:253] op_sel_hi:[1,0]
	v_pk_mul_f32 v[70:71], v[70:71], v[252:253] op_sel_hi:[1,0]
	v_exp_f32_e32 v76, v76
	v_exp_f32_e32 v77, v77
	v_exp_f32_e32 v78, v78
	v_exp_f32_e32 v79, v79
	v_exp_f32_e32 v68, v68
	v_exp_f32_e32 v69, v69
	v_exp_f32_e32 v70, v70
	v_exp_f32_e32 v71, v71
	v_pk_add_f32 v[76:77], v[76:77], 1.0 op_sel_hi:[1,0]
	v_pk_add_f32 v[78:79], v[78:79], 1.0 op_sel_hi:[1,0]
	v_pk_add_f32 v[68:69], v[68:69], 1.0 op_sel_hi:[1,0]
	v_pk_add_f32 v[70:71], v[70:71], 1.0 op_sel_hi:[1,0]
	v_rcp_f32_e32 v76, v76
	v_rcp_f32_e32 v77, v77
	v_rcp_f32_e32 v78, v78
	v_rcp_f32_e32 v79, v79
	v_rcp_f32_e32 v68, v68
	v_rcp_f32_e32 v69, v69
	v_rcp_f32_e32 v70, v70
	v_rcp_f32_e32 v71, v71
	v_pk_mul_f32 v[72:73], v[72:73], v[254:255] op_sel_hi:[1,0]
	v_pk_mul_f32 v[74:75], v[74:75], v[254:255] op_sel_hi:[1,0]
	v_pk_mul_f32 v[64:65], v[64:65], v[254:255] op_sel_hi:[1,0]
	v_pk_mul_f32 v[66:67], v[66:67], v[254:255] op_sel_hi:[1,0]
	v_pk_mul_f32 v[72:73], v[72:73], v[76:77]
	v_pk_mul_f32 v[74:75], v[74:75], v[78:79]
	v_pk_mul_f32 v[64:65], v[64:65], v[68:69]
	v_pk_mul_f32 v[66:67], v[66:67], v[70:71]
	v_cvt_pk_bf16_f32 v72, v72, v73
	v_cvt_pk_bf16_f32 v73, v74, v75
	v_cvt_pk_bf16_f32 v74, v64, v65
	v_cvt_pk_bf16_f32 v75, v66, v67
	global_store_dwordx4 v234, v[72:75], s[10:11]
	s_waitcnt vmcnt(12)
	s_waitcnt lgkmcnt(0)
	s_barrier
	s_setprio 1
	s_waitcnt lgkmcnt(0)
	v_mfma_f32_16x16x32_bf16 v[60:63], v[160:163], v[194:197], v[60:63]
	v_mfma_f32_16x16x32_bf16 v[60:63], v[164:167], v[198:201], v[60:63]
	v_mfma_f32_16x16x32_bf16 v[44:47], v[164:167], v[206:209], v[44:47]
	v_mfma_f32_16x16x32_bf16 v[44:47], v[160:163], v[202:205], v[44:47]
	v_mfma_f32_16x16x32_bf16 v[28:31], v[160:163], v[210:213], v[28:31]
	v_mfma_f32_16x16x32_bf16 v[28:31], v[164:167], v[214:217], v[28:31]
	v_mfma_f32_16x16x32_bf16 v[12:15], v[164:167], v[222:225], v[12:15]
	v_mfma_f32_16x16x32_bf16 v[12:15], v[160:163], v[218:221], v[12:15]
	v_mfma_f32_16x16x32_bf16 v[4:7], v[168:171], v[218:221], v[4:7]
	v_mfma_f32_16x16x32_bf16 v[4:7], v[172:175], v[222:225], v[4:7]
	v_mfma_f32_16x16x32_bf16 v[20:23], v[172:175], v[214:217], v[20:23]
	v_mfma_f32_16x16x32_bf16 v[20:23], v[168:171], v[210:213], v[20:23]
	v_mfma_f32_16x16x32_bf16 v[36:39], v[168:171], v[202:205], v[36:39]
	v_mfma_f32_16x16x32_bf16 v[36:39], v[172:175], v[206:209], v[36:39]
	v_mfma_f32_16x16x32_bf16 v[52:55], v[172:175], v[198:201], v[52:55]
	v_mfma_f32_16x16x32_bf16 v[52:55], v[168:171], v[194:197], v[52:55]
	s_setprio 0
	s_setprio 1
	v_mfma_f32_16x16x32_bf16 v[56:59], v[176:179], v[194:197], v[56:59]
	v_mfma_f32_16x16x32_bf16 v[56:59], v[180:183], v[198:201], v[56:59]
	v_mfma_f32_16x16x32_bf16 v[40:43], v[180:183], v[206:209], v[40:43]
	v_mfma_f32_16x16x32_bf16 v[40:43], v[176:179], v[202:205], v[40:43]
	v_mfma_f32_16x16x32_bf16 v[24:27], v[176:179], v[210:213], v[24:27]
	v_mfma_f32_16x16x32_bf16 v[24:27], v[180:183], v[214:217], v[24:27]
	v_mfma_f32_16x16x32_bf16 v[8:11], v[180:183], v[222:225], v[8:11]
	v_mfma_f32_16x16x32_bf16 v[8:11], v[176:179], v[218:221], v[8:11]
	v_mfma_f32_16x16x32_bf16 v[0:3], v[186:189], v[218:221], v[0:3]
	v_mfma_f32_16x16x32_bf16 v[0:3], v[190:193], v[222:225], v[0:3]
	v_mfma_f32_16x16x32_bf16 v[16:19], v[190:193], v[214:217], v[16:19]
	v_mfma_f32_16x16x32_bf16 v[16:19], v[186:189], v[210:213], v[16:19]
	v_mfma_f32_16x16x32_bf16 v[32:35], v[186:189], v[202:205], v[32:35]
	v_mfma_f32_16x16x32_bf16 v[32:35], v[190:193], v[206:209], v[32:35]
	v_mfma_f32_16x16x32_bf16 v[48:51], v[190:193], v[198:201], v[48:51]
	v_mfma_f32_16x16x32_bf16 v[48:51], v[186:189], v[194:197], v[48:51]
	s_setprio 0
	s_barrier
	s_add_i32 s75, s75, 2
	s_add_u32 s71, s71, 0x100
	s_addc_u32 s74, s74, 0
	s_add_u32 s44, s44, 0x100
	s_addc_u32 s45, s45, 0

.LBB0_158:
	s_add_u32 s81, s56, 0x100
	s_addc_u32 s82, s57, 0
	s_mov_b32 s83, -2
	s_waitcnt lgkmcnt(0)
	s_cmp_eq_u32 s70, 1
	s_cbranch_scc1 .Lfa_1
	ds_read_b128 v[128:131], v189
	v_xor_b32_e32 v253, 64, v189
	ds_read_b128 v[132:135], v253
	ds_read_b128 v[136:139], v189 offset:2048
	ds_read_b128 v[140:143], v253 offset:2048
	ds_read_b128 v[144:147], v190
	v_xor_b32_e32 v253, 64, v190
	ds_read_b128 v[148:151], v253
	ds_read_b128 v[172:175], v190 offset:2048
	ds_read_b128 v[176:179], v253 offset:2048
	s_add_u32 s56, s54, 0x100
	s_addc_u32 s57, s55, 0
	s_cmp_eq_u32 s83, 40
	s_cselect_b32 s61, s15, s57
	s_cselect_b32 s60, s14, s56
	s_cselect_b32 s59, s53, s82
	s_cselect_b32 s58, s52, s81
	v_lshl_add_u64 v[222:223], s[54:55], 0, v[166:167]
	s_add_i32 m0, s66, 0xc000
	ds_read_b128 v[180:183], v191
	v_xor_b32_e32 v253, 64, v191
	ds_read_b128 v[194:197], v253
	ds_read_b128 v[198:201], v191 offset:2048
	ds_read_b128 v[202:205], v253 offset:2048
	ds_read_b128 v[206:209], v191 offset:4096
	ds_read_b128 v[210:213], v253 offset:4096
	ds_read_b128 v[214:217], v191 offset:6144
	ds_read_b128 v[218:221], v253 offset:6144
	global_load_lds_dwordx4 v[222:223], off
	v_lshl_add_u64 v[222:223], s[54:55], 0, v[164:165]
	s_add_i32 m0, s66, 0xe000
	s_nop 0
	global_load_lds_dwordx4 v[222:223], off
	s_waitcnt vmcnt(24)
	s_waitcnt lgkmcnt(0)
	s_barrier
	s_setprio 1
	s_waitcnt lgkmcnt(0)
	v_mfma_f32_16x16x32_bf16 v[124:127], v[128:131], v[180:183], 0
	v_mfma_f32_16x16x32_bf16 v[120:123], v[136:139], v[180:183], 0
	v_mfma_f32_16x16x32_bf16 v[108:111], v[128:131], v[198:201], 0
	v_mfma_f32_16x16x32_bf16 v[104:107], v[136:139], v[198:201], 0
	v_mfma_f32_16x16x32_bf16 v[92:95], v[128:131], v[206:209], 0
	v_mfma_f32_16x16x32_bf16 v[88:91], v[136:139], v[206:209], 0
	v_mfma_f32_16x16x32_bf16 v[76:79], v[128:131], v[214:217], 0
	v_mfma_f32_16x16x32_bf16 v[72:75], v[136:139], v[214:217], 0
	v_mfma_f32_16x16x32_bf16 v[124:127], v[132:135], v[194:197], v[124:127]
	v_mfma_f32_16x16x32_bf16 v[120:123], v[140:143], v[194:197], v[120:123]
	v_mfma_f32_16x16x32_bf16 v[108:111], v[132:135], v[202:205], v[108:111]
	v_mfma_f32_16x16x32_bf16 v[104:107], v[140:143], v[202:205], v[104:107]
	v_mfma_f32_16x16x32_bf16 v[92:95], v[132:135], v[210:213], v[92:95]
	v_mfma_f32_16x16x32_bf16 v[88:91], v[140:143], v[210:213], v[88:91]
	v_mfma_f32_16x16x32_bf16 v[76:79], v[132:135], v[218:221], v[76:79]
	v_mfma_f32_16x16x32_bf16 v[72:75], v[140:143], v[218:221], v[72:75]
	s_setprio 0
	s_setprio 1
	v_mfma_f32_16x16x32_bf16 v[116:119], v[144:147], v[180:183], 0
	v_mfma_f32_16x16x32_bf16 v[112:115], v[172:175], v[180:183], 0
	v_mfma_f32_16x16x32_bf16 v[100:103], v[144:147], v[198:201], 0
	v_mfma_f32_16x16x32_bf16 v[96:99], v[172:175], v[198:201], 0
	v_mfma_f32_16x16x32_bf16 v[84:87], v[144:147], v[206:209], 0
	v_mfma_f32_16x16x32_bf16 v[80:83], v[172:175], v[206:209], 0
	v_mfma_f32_16x16x32_bf16 v[68:71], v[144:147], v[214:217], 0
	v_mfma_f32_16x16x32_bf16 v[64:67], v[172:175], v[214:217], 0
	v_mfma_f32_16x16x32_bf16 v[116:119], v[148:151], v[194:197], v[116:119]
	v_mfma_f32_16x16x32_bf16 v[112:115], v[176:179], v[194:197], v[112:115]
	v_mfma_f32_16x16x32_bf16 v[100:103], v[148:151], v[202:205], v[100:103]
	v_mfma_f32_16x16x32_bf16 v[96:99], v[176:179], v[202:205], v[96:99]
	v_mfma_f32_16x16x32_bf16 v[84:87], v[148:151], v[210:213], v[84:87]
	v_mfma_f32_16x16x32_bf16 v[80:83], v[176:179], v[210:213], v[80:83]
	v_mfma_f32_16x16x32_bf16 v[68:71], v[148:151], v[218:221], v[68:71]
	v_mfma_f32_16x16x32_bf16 v[64:67], v[176:179], v[218:221], v[64:67]
	s_setprio 0
	s_barrier
	s_add_i32 s54, s77, s65
	v_lshl_add_u64 v[222:223], s[58:59], 0, v[154:155]
	s_mov_b32 m0, s54
	ds_read_b128 v[180:183], v191 offset:16384
	v_xor_b32_e32 v253, 64, v191
	ds_read_b128 v[194:197], v253 offset:16384
	ds_read_b128 v[198:201], v191 offset:18432
	ds_read_b128 v[202:205], v253 offset:18432
	ds_read_b128 v[206:209], v191 offset:20480
	ds_read_b128 v[210:213], v253 offset:20480
	ds_read_b128 v[214:217], v191 offset:22528
	ds_read_b128 v[218:221], v253 offset:22528
	global_load_lds_dwordx4 v[222:223], off
	s_add_i32 m0, s54, 0x2000
	s_add_u32 s54, s58, 0xb0000
	v_lshl_add_u64 v[224:225], s[58:59], 0, v[162:163]
	s_addc_u32 s55, s59, 0
	s_add_i32 s84, s78, s65
	global_load_lds_dwordx4 v[224:225], off
	v_lshl_add_u64 v[226:227], s[54:55], 0, v[154:155]
	s_mov_b32 m0, s84
	v_lshl_add_u64 v[228:229], s[60:61], 0, v[160:161]
	global_load_lds_dwordx4 v[226:227], off
	v_lshl_add_u64 v[226:227], s[54:55], 0, v[162:163]
	s_add_i32 m0, s84, 0x2000
	s_nop 0
	global_load_lds_dwordx4 v[226:227], off
	v_lshl_add_u64 v[226:227], s[60:61], 0, v[152:153]
	s_mov_b32 m0, s66
	s_nop 0
	global_load_lds_dwordx4 v[226:227], off
	s_mov_b32 m0, s67
	s_nop 0
	global_load_lds_dwordx4 v[228:229], off
	s_waitcnt vmcnt(24)
	s_waitcnt lgkmcnt(0)
	s_barrier
	s_setprio 1
	s_waitcnt lgkmcnt(0)
	v_mfma_f32_16x16x32_bf16 v[60:63], v[128:131], v[180:183], 0
	v_mfma_f32_16x16x32_bf16 v[56:59], v[136:139], v[180:183], 0
	v_mfma_f32_16x16x32_bf16 v[44:47], v[128:131], v[198:201], 0
	v_mfma_f32_16x16x32_bf16 v[40:43], v[136:139], v[198:201], 0
	v_mfma_f32_16x16x32_bf16 v[28:31], v[128:131], v[206:209], 0
	v_mfma_f32_16x16x32_bf16 v[24:27], v[136:139], v[206:209], 0
	v_mfma_f32_16x16x32_bf16 v[12:15], v[128:131], v[214:217], 0
	v_mfma_f32_16x16x32_bf16 v[8:11], v[136:139], v[214:217], 0
	v_mfma_f32_16x16x32_bf16 v[60:63], v[132:135], v[194:197], v[60:63]
	v_mfma_f32_16x16x32_bf16 v[56:59], v[140:143], v[194:197], v[56:59]
	v_mfma_f32_16x16x32_bf16 v[44:47], v[132:135], v[202:205], v[44:47]
	v_mfma_f32_16x16x32_bf16 v[40:43], v[140:143], v[202:205], v[40:43]
	v_mfma_f32_16x16x32_bf16 v[28:31], v[132:135], v[210:213], v[28:31]
	v_mfma_f32_16x16x32_bf16 v[24:27], v[140:143], v[210:213], v[24:27]
	v_mfma_f32_16x16x32_bf16 v[12:15], v[132:135], v[218:221], v[12:15]
	v_mfma_f32_16x16x32_bf16 v[8:11], v[140:143], v[218:221], v[8:11]
	s_setprio 0
	s_setprio 1
	v_mfma_f32_16x16x32_bf16 v[52:55], v[144:147], v[180:183], 0
	v_mfma_f32_16x16x32_bf16 v[48:51], v[172:175], v[180:183], 0
	v_mfma_f32_16x16x32_bf16 v[36:39], v[144:147], v[198:201], 0
	v_mfma_f32_16x16x32_bf16 v[32:35], v[172:175], v[198:201], 0
	v_mfma_f32_16x16x32_bf16 v[20:23], v[144:147], v[206:209], 0
	v_mfma_f32_16x16x32_bf16 v[16:19], v[172:175], v[206:209], 0
	v_mfma_f32_16x16x32_bf16 v[4:7], v[144:147], v[214:217], 0
	v_mfma_f32_16x16x32_bf16 v[0:3], v[172:175], v[214:217], 0
	v_mfma_f32_16x16x32_bf16 v[52:55], v[148:151], v[194:197], v[52:55]
	v_mfma_f32_16x16x32_bf16 v[48:51], v[176:179], v[194:197], v[48:51]
	v_mfma_f32_16x16x32_bf16 v[36:39], v[148:151], v[202:205], v[36:39]
	v_mfma_f32_16x16x32_bf16 v[32:35], v[176:179], v[202:205], v[32:35]
	v_mfma_f32_16x16x32_bf16 v[20:23], v[148:151], v[210:213], v[20:23]
	v_mfma_f32_16x16x32_bf16 v[16:19], v[176:179], v[210:213], v[16:19]
	v_mfma_f32_16x16x32_bf16 v[4:7], v[148:151], v[218:221], v[4:7]
	v_mfma_f32_16x16x32_bf16 v[0:3], v[176:179], v[218:221], v[0:3]
	s_setprio 0
	s_barrier
	s_add_i32 s84, 0, 0x18000
	s_add_i32 s85, 0, 0x1c000
	v_add_u32_e32 v140, s84, v186
	v_add_u32_e32 v176, s85, v186
	ds_read_b128 v[128:131], v140
	v_xor_b32_e32 v253, 64, v140
	ds_read_b128 v[132:135], v253
	ds_read_b128 v[136:139], v140 offset:2048
	ds_read_b128 v[140:143], v253 offset:2048
	ds_read_b128 v[144:147], v176
	v_xor_b32_e32 v253, 64, v176
	ds_read_b128 v[148:151], v253
	ds_read_b128 v[172:175], v176 offset:2048
	ds_read_b128 v[176:179], v253 offset:2048
	s_add_u32 s54, s60, 0xb0000
	s_addc_u32 s55, s61, 0
	s_mov_b32 m0, s68
	v_lshl_add_u64 v[230:231], s[54:55], 0, v[152:153]
	ds_read_b128 v[180:183], v191 offset:32768
	v_xor_b32_e32 v253, 64, v191
	ds_read_b128 v[194:197], v253 offset:32768
	ds_read_b128 v[198:201], v191 offset:34816
	ds_read_b128 v[202:205], v253 offset:34816
	ds_read_b128 v[206:209], v191 offset:36864
	ds_read_b128 v[210:213], v253 offset:36864
	ds_read_b128 v[214:217], v191 offset:38912
	ds_read_b128 v[218:221], v253 offset:38912
	global_load_lds_dwordx4 v[230:231], off
	v_lshl_add_u64 v[230:231], s[54:55], 0, v[160:161]
	s_mov_b32 m0, s69
	s_nop 0
	global_load_lds_dwordx4 v[230:231], off
	s_waitcnt vmcnt(8)
	s_waitcnt lgkmcnt(0)
	s_barrier
	s_setprio 1
	s_waitcnt lgkmcnt(0)
	v_mfma_f32_16x16x32_bf16 v[124:127], v[128:131], v[180:183], v[124:127]
	v_mfma_f32_16x16x32_bf16 v[124:127], v[132:135], v[194:197], v[124:127]
	v_mfma_f32_16x16x32_bf16 v[108:111], v[132:135], v[202:205], v[108:111]
	v_mfma_f32_16x16x32_bf16 v[108:111], v[128:131], v[198:201], v[108:111]
	v_mfma_f32_16x16x32_bf16 v[92:95], v[128:131], v[206:209], v[92:95]
	v_mfma_f32_16x16x32_bf16 v[92:95], v[132:135], v[210:213], v[92:95]
	v_mfma_f32_16x16x32_bf16 v[76:79], v[132:135], v[218:221], v[76:79]
	v_mfma_f32_16x16x32_bf16 v[76:79], v[128:131], v[214:217], v[76:79]
	v_mfma_f32_16x16x32_bf16 v[72:75], v[136:139], v[214:217], v[72:75]
	v_mfma_f32_16x16x32_bf16 v[72:75], v[140:143], v[218:221], v[72:75]
	v_mfma_f32_16x16x32_bf16 v[88:91], v[140:143], v[210:213], v[88:91]
	v_mfma_f32_16x16x32_bf16 v[88:91], v[136:139], v[206:209], v[88:91]
	v_mfma_f32_16x16x32_bf16 v[104:107], v[136:139], v[198:201], v[104:107]
	v_mfma_f32_16x16x32_bf16 v[104:107], v[140:143], v[202:205], v[104:107]
	v_mfma_f32_16x16x32_bf16 v[120:123], v[140:143], v[194:197], v[120:123]
	v_mfma_f32_16x16x32_bf16 v[120:123], v[136:139], v[180:183], v[120:123]
	s_setprio 0
	s_setprio 1
	v_mfma_f32_16x16x32_bf16 v[116:119], v[144:147], v[180:183], v[116:119]
	v_mfma_f32_16x16x32_bf16 v[116:119], v[148:151], v[194:197], v[116:119]
	v_mfma_f32_16x16x32_bf16 v[100:103], v[148:151], v[202:205], v[100:103]
	v_mfma_f32_16x16x32_bf16 v[100:103], v[144:147], v[198:201], v[100:103]
	v_mfma_f32_16x16x32_bf16 v[84:87], v[144:147], v[206:209], v[84:87]
	v_mfma_f32_16x16x32_bf16 v[84:87], v[148:151], v[210:213], v[84:87]
	v_mfma_f32_16x16x32_bf16 v[68:71], v[148:151], v[218:221], v[68:71]
	v_mfma_f32_16x16x32_bf16 v[68:71], v[144:147], v[214:217], v[68:71]
	v_mfma_f32_16x16x32_bf16 v[64:67], v[172:175], v[214:217], v[64:67]
	v_mfma_f32_16x16x32_bf16 v[64:67], v[176:179], v[218:221], v[64:67]
	v_mfma_f32_16x16x32_bf16 v[80:83], v[176:179], v[210:213], v[80:83]
	v_mfma_f32_16x16x32_bf16 v[80:83], v[172:175], v[206:209], v[80:83]
	v_mfma_f32_16x16x32_bf16 v[96:99], v[172:175], v[198:201], v[96:99]
	v_mfma_f32_16x16x32_bf16 v[96:99], v[176:179], v[202:205], v[96:99]
	v_mfma_f32_16x16x32_bf16 v[112:115], v[176:179], v[194:197], v[112:115]
	v_mfma_f32_16x16x32_bf16 v[112:115], v[172:175], v[180:183], v[112:115]
	s_setprio 0
	s_barrier
	s_add_i32 s54, s84, s65
	v_lshl_add_u64 v[222:223], v[222:223], 0, s[28:29]
	s_mov_b32 m0, s54
	ds_read_b128 v[180:183], v191 offset:49152
	v_xor_b32_e32 v253, 64, v191
	ds_read_b128 v[194:197], v253 offset:49152
	ds_read_b128 v[198:201], v191 offset:51200
	ds_read_b128 v[202:205], v253 offset:51200
	ds_read_b128 v[206:209], v191 offset:53248
	ds_read_b128 v[210:213], v253 offset:53248
	ds_read_b128 v[214:217], v191 offset:55296
	ds_read_b128 v[218:221], v253 offset:55296
	global_load_lds_dwordx4 v[222:223], off
	s_add_i32 m0, s54, 0x2000
	s_add_u32 s54, s58, 0xb0080
	v_lshl_add_u64 v[222:223], v[224:225], 0, s[28:29]
	s_addc_u32 s55, s59, 0
	s_add_i32 s58, s85, s65
	global_load_lds_dwordx4 v[222:223], off
	v_lshl_add_u64 v[222:223], s[54:55], 0, v[154:155]
	s_mov_b32 m0, s58
	s_nop 0
	global_load_lds_dwordx4 v[222:223], off
	v_lshl_add_u64 v[222:223], s[54:55], 0, v[162:163]
	s_add_i32 m0, s58, 0x2000
	s_nop 0
	global_load_lds_dwordx4 v[222:223], off
	v_lshl_add_u64 v[222:223], v[226:227], 0, s[28:29]
	s_mov_b32 m0, s3
	s_nop 0
	global_load_lds_dwordx4 v[222:223], off
	v_lshl_add_u64 v[222:223], v[228:229], 0, s[28:29]
	s_mov_b32 m0, s71
	s_nop 0
	global_load_lds_dwordx4 v[222:223], off
	s_waitcnt vmcnt(8)
	s_waitcnt lgkmcnt(0)
	s_barrier
	s_setprio 1
	s_waitcnt lgkmcnt(0)
	v_mfma_f32_16x16x32_bf16 v[60:63], v[128:131], v[180:183], v[60:63]
	v_mfma_f32_16x16x32_bf16 v[60:63], v[132:135], v[194:197], v[60:63]
	v_mfma_f32_16x16x32_bf16 v[44:47], v[132:135], v[202:205], v[44:47]
	v_mfma_f32_16x16x32_bf16 v[44:47], v[128:131], v[198:201], v[44:47]
	v_mfma_f32_16x16x32_bf16 v[28:31], v[128:131], v[206:209], v[28:31]
	v_mfma_f32_16x16x32_bf16 v[28:31], v[132:135], v[210:213], v[28:31]
	v_mfma_f32_16x16x32_bf16 v[12:15], v[132:135], v[218:221], v[12:15]
	v_mfma_f32_16x16x32_bf16 v[12:15], v[128:131], v[214:217], v[12:15]
	v_mfma_f32_16x16x32_bf16 v[8:11], v[136:139], v[214:217], v[8:11]
	v_mfma_f32_16x16x32_bf16 v[8:11], v[140:143], v[218:221], v[8:11]
	v_mfma_f32_16x16x32_bf16 v[24:27], v[140:143], v[210:213], v[24:27]
	v_mfma_f32_16x16x32_bf16 v[24:27], v[136:139], v[206:209], v[24:27]
	v_mfma_f32_16x16x32_bf16 v[40:43], v[136:139], v[198:201], v[40:43]
	v_mfma_f32_16x16x32_bf16 v[40:43], v[140:143], v[202:205], v[40:43]
	v_mfma_f32_16x16x32_bf16 v[56:59], v[140:143], v[194:197], v[56:59]
	v_mfma_f32_16x16x32_bf16 v[56:59], v[136:139], v[180:183], v[56:59]
	s_setprio 0
	s_setprio 1
	v_mfma_f32_16x16x32_bf16 v[52:55], v[144:147], v[180:183], v[52:55]
	v_mfma_f32_16x16x32_bf16 v[52:55], v[148:151], v[194:197], v[52:55]
	v_mfma_f32_16x16x32_bf16 v[36:39], v[148:151], v[202:205], v[36:39]
	v_mfma_f32_16x16x32_bf16 v[36:39], v[144:147], v[198:201], v[36:39]
	v_mfma_f32_16x16x32_bf16 v[20:23], v[144:147], v[206:209], v[20:23]
	v_mfma_f32_16x16x32_bf16 v[20:23], v[148:151], v[210:213], v[20:23]
	v_mfma_f32_16x16x32_bf16 v[4:7], v[148:151], v[218:221], v[4:7]
	v_mfma_f32_16x16x32_bf16 v[4:7], v[144:147], v[214:217], v[4:7]
	v_mfma_f32_16x16x32_bf16 v[0:3], v[172:175], v[214:217], v[0:3]
	v_mfma_f32_16x16x32_bf16 v[0:3], v[176:179], v[218:221], v[0:3]
	v_mfma_f32_16x16x32_bf16 v[16:19], v[176:179], v[210:213], v[16:19]
	v_mfma_f32_16x16x32_bf16 v[16:19], v[172:175], v[206:209], v[16:19]
	v_mfma_f32_16x16x32_bf16 v[32:35], v[172:175], v[198:201], v[32:35]
	v_mfma_f32_16x16x32_bf16 v[32:35], v[176:179], v[202:205], v[32:35]
	v_mfma_f32_16x16x32_bf16 v[48:51], v[176:179], v[194:197], v[48:51]
	v_mfma_f32_16x16x32_bf16 v[48:51], v[172:175], v[180:183], v[48:51]
	s_setprio 0
	s_barrier
	s_add_i32 s83, s83, 2
	s_add_u32 s81, s81, 0x100
	s_addc_u32 s82, s82, 0
	s_cmp_gt_u32 s83, 41
	s_mov_b64 s[54:55], s[56:57]
	s_branch .LBB0_159
.Lfa_1:
	ds_read_b128 v[128:131], v189
	v_xor_b32_e32 v253, 64, v189
	ds_read_b128 v[132:135], v253
	ds_read_b128 v[136:139], v189 offset:2048
	ds_read_b128 v[140:143], v253 offset:2048
	ds_read_b128 v[144:147], v190
	v_xor_b32_e32 v253, 64, v190
	ds_read_b128 v[148:151], v253
	ds_read_b128 v[172:175], v190 offset:2048
	ds_read_b128 v[176:179], v253 offset:2048
	s_add_u32 s56, s54, 0x100
	s_addc_u32 s57, s55, 0
	s_cmp_eq_u32 s83, 40
	s_cselect_b32 s61, s15, s57
	s_cselect_b32 s60, s14, s56
	s_cselect_b32 s59, s53, s82
	s_cselect_b32 s58, s52, s81
	v_lshl_add_u64 v[222:223], s[54:55], 0, v[166:167]
	s_add_i32 m0, s66, 0xc000
	ds_read_b128 v[180:183], v191
	v_xor_b32_e32 v253, 64, v191
	ds_read_b128 v[194:197], v253
	ds_read_b128 v[198:201], v191 offset:2048
	ds_read_b128 v[202:205], v253 offset:2048
	ds_read_b128 v[206:209], v191 offset:4096
	ds_read_b128 v[210:213], v253 offset:4096
	ds_read_b128 v[214:217], v191 offset:6144
	ds_read_b128 v[218:221], v253 offset:6144
	global_load_lds_dwordx4 v[222:223], off
	v_lshl_add_u64 v[222:223], s[54:55], 0, v[164:165]
	s_add_i32 m0, s66, 0xe000
	s_nop 0
	global_load_lds_dwordx4 v[222:223], off
	s_waitcnt vmcnt(8)
	s_waitcnt lgkmcnt(0)
	s_barrier
	s_setprio 1
	s_waitcnt lgkmcnt(0)
	v_mfma_f32_16x16x32_bf16 v[124:127], v[128:131], v[180:183], 0
	v_mfma_f32_16x16x32_bf16 v[120:123], v[136:139], v[180:183], 0
	v_mfma_f32_16x16x32_bf16 v[108:111], v[128:131], v[198:201], 0
	v_mfma_f32_16x16x32_bf16 v[104:107], v[136:139], v[198:201], 0
	v_mfma_f32_16x16x32_bf16 v[92:95], v[128:131], v[206:209], 0
	v_mfma_f32_16x16x32_bf16 v[88:91], v[136:139], v[206:209], 0
	v_mfma_f32_16x16x32_bf16 v[76:79], v[128:131], v[214:217], 0
	v_mfma_f32_16x16x32_bf16 v[72:75], v[136:139], v[214:217], 0
	v_mfma_f32_16x16x32_bf16 v[124:127], v[132:135], v[194:197], v[124:127]
	v_mfma_f32_16x16x32_bf16 v[120:123], v[140:143], v[194:197], v[120:123]
	v_mfma_f32_16x16x32_bf16 v[108:111], v[132:135], v[202:205], v[108:111]
	v_mfma_f32_16x16x32_bf16 v[104:107], v[140:143], v[202:205], v[104:107]
	v_mfma_f32_16x16x32_bf16 v[92:95], v[132:135], v[210:213], v[92:95]
	v_mfma_f32_16x16x32_bf16 v[88:91], v[140:143], v[210:213], v[88:91]
	v_mfma_f32_16x16x32_bf16 v[76:79], v[132:135], v[218:221], v[76:79]
	v_mfma_f32_16x16x32_bf16 v[72:75], v[140:143], v[218:221], v[72:75]
	s_setprio 0
	s_setprio 1
	v_mfma_f32_16x16x32_bf16 v[116:119], v[144:147], v[180:183], 0
	v_mfma_f32_16x16x32_bf16 v[112:115], v[172:175], v[180:183], 0
	v_mfma_f32_16x16x32_bf16 v[100:103], v[144:147], v[198:201], 0
	v_mfma_f32_16x16x32_bf16 v[96:99], v[172:175], v[198:201], 0
	v_mfma_f32_16x16x32_bf16 v[84:87], v[144:147], v[206:209], 0
	v_mfma_f32_16x16x32_bf16 v[80:83], v[172:175], v[206:209], 0
	v_mfma_f32_16x16x32_bf16 v[68:71], v[144:147], v[214:217], 0
	v_mfma_f32_16x16x32_bf16 v[64:67], v[172:175], v[214:217], 0
	v_mfma_f32_16x16x32_bf16 v[116:119], v[148:151], v[194:197], v[116:119]
	v_mfma_f32_16x16x32_bf16 v[112:115], v[176:179], v[194:197], v[112:115]
	v_mfma_f32_16x16x32_bf16 v[100:103], v[148:151], v[202:205], v[100:103]
	v_mfma_f32_16x16x32_bf16 v[96:99], v[176:179], v[202:205], v[96:99]
	v_mfma_f32_16x16x32_bf16 v[84:87], v[148:151], v[210:213], v[84:87]
	v_mfma_f32_16x16x32_bf16 v[80:83], v[176:179], v[210:213], v[80:83]
	v_mfma_f32_16x16x32_bf16 v[68:71], v[148:151], v[218:221], v[68:71]
	v_mfma_f32_16x16x32_bf16 v[64:67], v[176:179], v[218:221], v[64:67]
	s_setprio 0
	s_barrier
	s_add_i32 s54, s77, s65
	v_lshl_add_u64 v[222:223], s[58:59], 0, v[154:155]
	s_mov_b32 m0, s54
	ds_read_b128 v[180:183], v191 offset:16384
	v_xor_b32_e32 v253, 64, v191
	ds_read_b128 v[194:197], v253 offset:16384
	ds_read_b128 v[198:201], v191 offset:18432
	ds_read_b128 v[202:205], v253 offset:18432
	ds_read_b128 v[206:209], v191 offset:20480
	ds_read_b128 v[210:213], v253 offset:20480
	ds_read_b128 v[214:217], v191 offset:22528
	ds_read_b128 v[218:221], v253 offset:22528
	global_load_lds_dwordx4 v[222:223], off
	s_add_i32 m0, s54, 0x2000
	s_add_u32 s54, s58, 0xb0000
	v_lshl_add_u64 v[224:225], s[58:59], 0, v[162:163]
	s_addc_u32 s55, s59, 0
	s_add_i32 s84, s78, s65
	global_load_lds_dwordx4 v[224:225], off
	v_lshl_add_u64 v[226:227], s[54:55], 0, v[154:155]
	s_mov_b32 m0, s84
	v_lshl_add_u64 v[228:229], s[60:61], 0, v[160:161]
	global_load_lds_dwordx4 v[226:227], off
	v_lshl_add_u64 v[226:227], s[54:55], 0, v[162:163]
	s_add_i32 m0, s84, 0x2000
	s_nop 0
	global_load_lds_dwordx4 v[226:227], off
	v_lshl_add_u64 v[226:227], s[60:61], 0, v[152:153]
	s_mov_b32 m0, s66
	s_nop 0
	global_load_lds_dwordx4 v[226:227], off
	s_mov_b32 m0, s67
	s_nop 0
	global_load_lds_dwordx4 v[228:229], off
	s_waitcnt vmcnt(8)
	s_waitcnt lgkmcnt(0)
	s_barrier
	s_setprio 1
	s_waitcnt lgkmcnt(0)
	v_mfma_f32_16x16x32_bf16 v[60:63], v[128:131], v[180:183], 0
	v_mfma_f32_16x16x32_bf16 v[56:59], v[136:139], v[180:183], 0
	v_mfma_f32_16x16x32_bf16 v[44:47], v[128:131], v[198:201], 0
	v_mfma_f32_16x16x32_bf16 v[40:43], v[136:139], v[198:201], 0
	v_mfma_f32_16x16x32_bf16 v[28:31], v[128:131], v[206:209], 0
	v_mfma_f32_16x16x32_bf16 v[24:27], v[136:139], v[206:209], 0
	v_mfma_f32_16x16x32_bf16 v[12:15], v[128:131], v[214:217], 0
	v_mfma_f32_16x16x32_bf16 v[8:11], v[136:139], v[214:217], 0
	v_mfma_f32_16x16x32_bf16 v[60:63], v[132:135], v[194:197], v[60:63]
	v_mfma_f32_16x16x32_bf16 v[56:59], v[140:143], v[194:197], v[56:59]
	v_mfma_f32_16x16x32_bf16 v[44:47], v[132:135], v[202:205], v[44:47]
	v_mfma_f32_16x16x32_bf16 v[40:43], v[140:143], v[202:205], v[40:43]
	v_mfma_f32_16x16x32_bf16 v[28:31], v[132:135], v[210:213], v[28:31]
	v_mfma_f32_16x16x32_bf16 v[24:27], v[140:143], v[210:213], v[24:27]
	v_mfma_f32_16x16x32_bf16 v[12:15], v[132:135], v[218:221], v[12:15]
	v_mfma_f32_16x16x32_bf16 v[8:11], v[140:143], v[218:221], v[8:11]
	s_setprio 0
	s_setprio 1
	v_mfma_f32_16x16x32_bf16 v[52:55], v[144:147], v[180:183], 0
	v_mfma_f32_16x16x32_bf16 v[48:51], v[172:175], v[180:183], 0
	v_mfma_f32_16x16x32_bf16 v[36:39], v[144:147], v[198:201], 0
	v_mfma_f32_16x16x32_bf16 v[32:35], v[172:175], v[198:201], 0
	v_mfma_f32_16x16x32_bf16 v[20:23], v[144:147], v[206:209], 0
	v_mfma_f32_16x16x32_bf16 v[16:19], v[172:175], v[206:209], 0
	v_mfma_f32_16x16x32_bf16 v[4:7], v[144:147], v[214:217], 0
	v_mfma_f32_16x16x32_bf16 v[0:3], v[172:175], v[214:217], 0
	v_mfma_f32_16x16x32_bf16 v[52:55], v[148:151], v[194:197], v[52:55]
	v_mfma_f32_16x16x32_bf16 v[48:51], v[176:179], v[194:197], v[48:51]
	v_mfma_f32_16x16x32_bf16 v[36:39], v[148:151], v[202:205], v[36:39]
	v_mfma_f32_16x16x32_bf16 v[32:35], v[176:179], v[202:205], v[32:35]
	v_mfma_f32_16x16x32_bf16 v[20:23], v[148:151], v[210:213], v[20:23]
	v_mfma_f32_16x16x32_bf16 v[16:19], v[176:179], v[210:213], v[16:19]
	v_mfma_f32_16x16x32_bf16 v[4:7], v[148:151], v[218:221], v[4:7]
	v_mfma_f32_16x16x32_bf16 v[0:3], v[176:179], v[218:221], v[0:3]
	s_setprio 0
	s_barrier
	s_add_i32 s84, 0, 0x18000
	s_add_i32 s85, 0, 0x1c000
	v_add_u32_e32 v140, s84, v186
	v_add_u32_e32 v176, s85, v186
	ds_read_b128 v[128:131], v140
	v_xor_b32_e32 v253, 64, v140
	ds_read_b128 v[132:135], v253
	ds_read_b128 v[136:139], v140 offset:2048
	ds_read_b128 v[140:143], v253 offset:2048
	ds_read_b128 v[144:147], v176
	v_xor_b32_e32 v253, 64, v176
	ds_read_b128 v[148:151], v253
	ds_read_b128 v[172:175], v176 offset:2048
	ds_read_b128 v[176:179], v253 offset:2048
	s_add_u32 s54, s60, 0xb0000
	s_addc_u32 s55, s61, 0
	s_mov_b32 m0, s68
	v_lshl_add_u64 v[230:231], s[54:55], 0, v[152:153]
	ds_read_b128 v[180:183], v191 offset:32768
	v_xor_b32_e32 v253, 64, v191
	ds_read_b128 v[194:197], v253 offset:32768
	ds_read_b128 v[198:201], v191 offset:34816
	ds_read_b128 v[202:205], v253 offset:34816
	ds_read_b128 v[206:209], v191 offset:36864
	ds_read_b128 v[210:213], v253 offset:36864
	ds_read_b128 v[214:217], v191 offset:38912
	ds_read_b128 v[218:221], v253 offset:38912
	global_load_lds_dwordx4 v[230:231], off
	v_lshl_add_u64 v[230:231], s[54:55], 0, v[160:161]
	s_mov_b32 m0, s69
	s_nop 0
	global_load_lds_dwordx4 v[230:231], off
	s_waitcnt vmcnt(8)
	s_waitcnt lgkmcnt(0)
	s_barrier
	s_setprio 1
	s_waitcnt lgkmcnt(0)
	v_mfma_f32_16x16x32_bf16 v[124:127], v[128:131], v[180:183], v[124:127]
	v_mfma_f32_16x16x32_bf16 v[124:127], v[132:135], v[194:197], v[124:127]
	v_mfma_f32_16x16x32_bf16 v[108:111], v[132:135], v[202:205], v[108:111]
	v_mfma_f32_16x16x32_bf16 v[108:111], v[128:131], v[198:201], v[108:111]
	v_mfma_f32_16x16x32_bf16 v[92:95], v[128:131], v[206:209], v[92:95]
	v_mfma_f32_16x16x32_bf16 v[92:95], v[132:135], v[210:213], v[92:95]
	v_mfma_f32_16x16x32_bf16 v[76:79], v[132:135], v[218:221], v[76:79]
	v_mfma_f32_16x16x32_bf16 v[76:79], v[128:131], v[214:217], v[76:79]
	v_mfma_f32_16x16x32_bf16 v[72:75], v[136:139], v[214:217], v[72:75]
	v_mfma_f32_16x16x32_bf16 v[72:75], v[140:143], v[218:221], v[72:75]
	v_mfma_f32_16x16x32_bf16 v[88:91], v[140:143], v[210:213], v[88:91]
	v_mfma_f32_16x16x32_bf16 v[88:91], v[136:139], v[206:209], v[88:91]
	v_mfma_f32_16x16x32_bf16 v[104:107], v[136:139], v[198:201], v[104:107]
	v_mfma_f32_16x16x32_bf16 v[104:107], v[140:143], v[202:205], v[104:107]
	v_mfma_f32_16x16x32_bf16 v[120:123], v[140:143], v[194:197], v[120:123]
	v_mfma_f32_16x16x32_bf16 v[120:123], v[136:139], v[180:183], v[120:123]
	s_setprio 0
	s_setprio 1
	v_mfma_f32_16x16x32_bf16 v[116:119], v[144:147], v[180:183], v[116:119]
	v_mfma_f32_16x16x32_bf16 v[116:119], v[148:151], v[194:197], v[116:119]
	v_mfma_f32_16x16x32_bf16 v[100:103], v[148:151], v[202:205], v[100:103]
	v_mfma_f32_16x16x32_bf16 v[100:103], v[144:147], v[198:201], v[100:103]
	v_mfma_f32_16x16x32_bf16 v[84:87], v[144:147], v[206:209], v[84:87]
	v_mfma_f32_16x16x32_bf16 v[84:87], v[148:151], v[210:213], v[84:87]
	v_mfma_f32_16x16x32_bf16 v[68:71], v[148:151], v[218:221], v[68:71]
	v_mfma_f32_16x16x32_bf16 v[68:71], v[144:147], v[214:217], v[68:71]
	v_mfma_f32_16x16x32_bf16 v[64:67], v[172:175], v[214:217], v[64:67]
	v_mfma_f32_16x16x32_bf16 v[64:67], v[176:179], v[218:221], v[64:67]
	v_mfma_f32_16x16x32_bf16 v[80:83], v[176:179], v[210:213], v[80:83]
	v_mfma_f32_16x16x32_bf16 v[80:83], v[172:175], v[206:209], v[80:83]
	v_mfma_f32_16x16x32_bf16 v[96:99], v[172:175], v[198:201], v[96:99]
	v_mfma_f32_16x16x32_bf16 v[96:99], v[176:179], v[202:205], v[96:99]
	v_mfma_f32_16x16x32_bf16 v[112:115], v[176:179], v[194:197], v[112:115]
	v_mfma_f32_16x16x32_bf16 v[112:115], v[172:175], v[180:183], v[112:115]
	s_setprio 0
	s_barrier
	s_add_i32 s54, s84, s65
	v_lshl_add_u64 v[222:223], v[222:223], 0, s[28:29]
	s_mov_b32 m0, s54
	ds_read_b128 v[180:183], v191 offset:49152
	v_xor_b32_e32 v253, 64, v191
	ds_read_b128 v[194:197], v253 offset:49152
	ds_read_b128 v[198:201], v191 offset:51200
	ds_read_b128 v[202:205], v253 offset:51200
	ds_read_b128 v[206:209], v191 offset:53248
	ds_read_b128 v[210:213], v253 offset:53248
	ds_read_b128 v[214:217], v191 offset:55296
	ds_read_b128 v[218:221], v253 offset:55296
	global_load_lds_dwordx4 v[222:223], off
	s_add_i32 m0, s54, 0x2000
	s_add_u32 s54, s58, 0xb0080
	v_lshl_add_u64 v[222:223], v[224:225], 0, s[28:29]
	s_addc_u32 s55, s59, 0
	s_add_i32 s58, s85, s65
	global_load_lds_dwordx4 v[222:223], off
	v_lshl_add_u64 v[222:223], s[54:55], 0, v[154:155]
	s_mov_b32 m0, s58
	s_nop 0
	global_load_lds_dwordx4 v[222:223], off
	v_lshl_add_u64 v[222:223], s[54:55], 0, v[162:163]
	s_add_i32 m0, s58, 0x2000
	s_nop 0
	global_load_lds_dwordx4 v[222:223], off
	v_lshl_add_u64 v[222:223], v[226:227], 0, s[28:29]
	s_mov_b32 m0, s3
	s_nop 0
	global_load_lds_dwordx4 v[222:223], off
	v_lshl_add_u64 v[222:223], v[228:229], 0, s[28:29]
	s_mov_b32 m0, s71
	s_nop 0
	global_load_lds_dwordx4 v[222:223], off
	s_waitcnt vmcnt(8)
	s_waitcnt lgkmcnt(0)
	s_barrier
	s_setprio 1
	s_waitcnt lgkmcnt(0)
	v_mfma_f32_16x16x32_bf16 v[60:63], v[128:131], v[180:183], v[60:63]
	v_mfma_f32_16x16x32_bf16 v[60:63], v[132:135], v[194:197], v[60:63]
	v_mfma_f32_16x16x32_bf16 v[44:47], v[132:135], v[202:205], v[44:47]
	v_mfma_f32_16x16x32_bf16 v[44:47], v[128:131], v[198:201], v[44:47]
	v_mfma_f32_16x16x32_bf16 v[28:31], v[128:131], v[206:209], v[28:31]
	v_mfma_f32_16x16x32_bf16 v[28:31], v[132:135], v[210:213], v[28:31]
	v_mfma_f32_16x16x32_bf16 v[12:15], v[132:135], v[218:221], v[12:15]
	v_mfma_f32_16x16x32_bf16 v[12:15], v[128:131], v[214:217], v[12:15]
	v_mfma_f32_16x16x32_bf16 v[8:11], v[136:139], v[214:217], v[8:11]
	v_mfma_f32_16x16x32_bf16 v[8:11], v[140:143], v[218:221], v[8:11]
	v_mfma_f32_16x16x32_bf16 v[24:27], v[140:143], v[210:213], v[24:27]
	v_mfma_f32_16x16x32_bf16 v[24:27], v[136:139], v[206:209], v[24:27]
	v_mfma_f32_16x16x32_bf16 v[40:43], v[136:139], v[198:201], v[40:43]
	v_mfma_f32_16x16x32_bf16 v[40:43], v[140:143], v[202:205], v[40:43]
	v_mfma_f32_16x16x32_bf16 v[56:59], v[140:143], v[194:197], v[56:59]
	v_mfma_f32_16x16x32_bf16 v[56:59], v[136:139], v[180:183], v[56:59]
	s_setprio 0
	s_setprio 1
	v_mfma_f32_16x16x32_bf16 v[52:55], v[144:147], v[180:183], v[52:55]
	v_mfma_f32_16x16x32_bf16 v[52:55], v[148:151], v[194:197], v[52:55]
	v_mfma_f32_16x16x32_bf16 v[36:39], v[148:151], v[202:205], v[36:39]
	v_mfma_f32_16x16x32_bf16 v[36:39], v[144:147], v[198:201], v[36:39]
	v_mfma_f32_16x16x32_bf16 v[20:23], v[144:147], v[206:209], v[20:23]
	v_mfma_f32_16x16x32_bf16 v[20:23], v[148:151], v[210:213], v[20:23]
	v_mfma_f32_16x16x32_bf16 v[4:7], v[148:151], v[218:221], v[4:7]
	v_mfma_f32_16x16x32_bf16 v[4:7], v[144:147], v[214:217], v[4:7]
	v_mfma_f32_16x16x32_bf16 v[0:3], v[172:175], v[214:217], v[0:3]
	v_mfma_f32_16x16x32_bf16 v[0:3], v[176:179], v[218:221], v[0:3]
	v_mfma_f32_16x16x32_bf16 v[16:19], v[176:179], v[210:213], v[16:19]
	v_mfma_f32_16x16x32_bf16 v[16:19], v[172:175], v[206:209], v[16:19]
	v_mfma_f32_16x16x32_bf16 v[32:35], v[172:175], v[198:201], v[32:35]
	v_mfma_f32_16x16x32_bf16 v[32:35], v[176:179], v[202:205], v[32:35]
	v_mfma_f32_16x16x32_bf16 v[48:51], v[176:179], v[194:197], v[48:51]
	v_mfma_f32_16x16x32_bf16 v[48:51], v[172:175], v[180:183], v[48:51]
	s_setprio 0
	s_barrier
	s_add_i32 s83, s83, 2
	s_add_u32 s81, s81, 0x100
	s_addc_u32 s82, s82, 0
	s_cmp_gt_u32 s83, 41
	s_mov_b64 s[54:55], s[56:57]
.LBB0_159:
	ds_read_b128 v[128:131], v189
	v_xor_b32_e32 v253, 64, v189
	ds_read_b128 v[132:135], v253
	ds_read_b128 v[136:139], v189 offset:2048
	ds_read_b128 v[140:143], v253 offset:2048
	ds_read_b128 v[144:147], v190
	v_xor_b32_e32 v253, 64, v190
	ds_read_b128 v[148:151], v253
	ds_read_b128 v[172:175], v190 offset:2048
	ds_read_b128 v[176:179], v253 offset:2048
	s_add_u32 s56, s54, 0x100
	s_addc_u32 s57, s55, 0
	s_cmp_eq_u32 s83, 40
	s_cselect_b32 s61, s15, s57
	s_cselect_b32 s60, s14, s56
	s_cselect_b32 s59, s53, s82
	s_cselect_b32 s58, s52, s81
	v_lshl_add_u64 v[222:223], s[54:55], 0, v[166:167]
	s_add_i32 m0, s66, 0xc000
	ds_read_b128 v[180:183], v191
	v_xor_b32_e32 v253, 64, v191
	ds_read_b128 v[194:197], v253
	ds_read_b128 v[198:201], v191 offset:2048
	ds_read_b128 v[202:205], v253 offset:2048
	ds_read_b128 v[206:209], v191 offset:4096
	ds_read_b128 v[210:213], v253 offset:4096
	ds_read_b128 v[214:217], v191 offset:6144
	ds_read_b128 v[218:221], v253 offset:6144
	global_load_lds_dwordx4 v[222:223], off
	v_lshl_add_u64 v[222:223], s[54:55], 0, v[164:165]
	s_add_i32 m0, s66, 0xe000
	s_nop 0
	global_load_lds_dwordx4 v[222:223], off
	s_waitcnt vmcnt(8)
	s_waitcnt lgkmcnt(0)
	s_barrier
	s_setprio 1
	s_waitcnt lgkmcnt(0)
	v_mfma_f32_16x16x32_bf16 v[124:127], v[128:131], v[180:183], v[124:127]
	v_mfma_f32_16x16x32_bf16 v[124:127], v[132:135], v[194:197], v[124:127]
	v_mfma_f32_16x16x32_bf16 v[108:111], v[132:135], v[202:205], v[108:111]
	v_mfma_f32_16x16x32_bf16 v[108:111], v[128:131], v[198:201], v[108:111]
	v_mfma_f32_16x16x32_bf16 v[92:95], v[128:131], v[206:209], v[92:95]
	v_mfma_f32_16x16x32_bf16 v[92:95], v[132:135], v[210:213], v[92:95]
	v_mfma_f32_16x16x32_bf16 v[76:79], v[132:135], v[218:221], v[76:79]
	v_mfma_f32_16x16x32_bf16 v[76:79], v[128:131], v[214:217], v[76:79]
	v_mfma_f32_16x16x32_bf16 v[72:75], v[136:139], v[214:217], v[72:75]
	v_mfma_f32_16x16x32_bf16 v[72:75], v[140:143], v[218:221], v[72:75]
	v_mfma_f32_16x16x32_bf16 v[88:91], v[140:143], v[210:213], v[88:91]
	v_mfma_f32_16x16x32_bf16 v[88:91], v[136:139], v[206:209], v[88:91]
	v_mfma_f32_16x16x32_bf16 v[104:107], v[136:139], v[198:201], v[104:107]
	v_mfma_f32_16x16x32_bf16 v[104:107], v[140:143], v[202:205], v[104:107]
	v_mfma_f32_16x16x32_bf16 v[120:123], v[140:143], v[194:197], v[120:123]
	v_mfma_f32_16x16x32_bf16 v[120:123], v[136:139], v[180:183], v[120:123]
	s_setprio 0
	s_setprio 1
	v_mfma_f32_16x16x32_bf16 v[116:119], v[144:147], v[180:183], v[116:119]
	v_mfma_f32_16x16x32_bf16 v[116:119], v[148:151], v[194:197], v[116:119]
	v_mfma_f32_16x16x32_bf16 v[100:103], v[148:151], v[202:205], v[100:103]
	v_mfma_f32_16x16x32_bf16 v[100:103], v[144:147], v[198:201], v[100:103]
	v_mfma_f32_16x16x32_bf16 v[84:87], v[144:147], v[206:209], v[84:87]
	v_mfma_f32_16x16x32_bf16 v[84:87], v[148:151], v[210:213], v[84:87]
	v_mfma_f32_16x16x32_bf16 v[68:71], v[148:151], v[218:221], v[68:71]
	v_mfma_f32_16x16x32_bf16 v[68:71], v[144:147], v[214:217], v[68:71]
	v_mfma_f32_16x16x32_bf16 v[64:67], v[172:175], v[214:217], v[64:67]
	v_mfma_f32_16x16x32_bf16 v[64:67], v[176:179], v[218:221], v[64:67]
	v_mfma_f32_16x16x32_bf16 v[80:83], v[176:179], v[210:213], v[80:83]
	v_mfma_f32_16x16x32_bf16 v[80:83], v[172:175], v[206:209], v[80:83]
	v_mfma_f32_16x16x32_bf16 v[96:99], v[172:175], v[198:201], v[96:99]
	v_mfma_f32_16x16x32_bf16 v[96:99], v[176:179], v[202:205], v[96:99]
	v_mfma_f32_16x16x32_bf16 v[112:115], v[176:179], v[194:197], v[112:115]
	v_mfma_f32_16x16x32_bf16 v[112:115], v[172:175], v[180:183], v[112:115]
	s_setprio 0
	s_barrier
	s_add_i32 s54, s77, s65
	v_lshl_add_u64 v[222:223], s[58:59], 0, v[154:155]
	s_mov_b32 m0, s54
	ds_read_b128 v[180:183], v191 offset:16384
	v_xor_b32_e32 v253, 64, v191
	ds_read_b128 v[194:197], v253 offset:16384
	ds_read_b128 v[198:201], v191 offset:18432
	ds_read_b128 v[202:205], v253 offset:18432
	ds_read_b128 v[206:209], v191 offset:20480
	ds_read_b128 v[210:213], v253 offset:20480
	ds_read_b128 v[214:217], v191 offset:22528
	ds_read_b128 v[218:221], v253 offset:22528
	global_load_lds_dwordx4 v[222:223], off
	s_add_i32 m0, s54, 0x2000
	s_add_u32 s54, s58, 0xb0000
	v_lshl_add_u64 v[224:225], s[58:59], 0, v[162:163]
	s_addc_u32 s55, s59, 0
	s_add_i32 s84, s78, s65
	global_load_lds_dwordx4 v[224:225], off
	v_lshl_add_u64 v[226:227], s[54:55], 0, v[154:155]
	s_mov_b32 m0, s84
	v_lshl_add_u64 v[228:229], s[60:61], 0, v[160:161]
	global_load_lds_dwordx4 v[226:227], off
	v_lshl_add_u64 v[226:227], s[54:55], 0, v[162:163]
	s_add_i32 m0, s84, 0x2000
	s_nop 0
	global_load_lds_dwordx4 v[226:227], off
	v_lshl_add_u64 v[226:227], s[60:61], 0, v[152:153]
	s_mov_b32 m0, s66
	s_nop 0
	global_load_lds_dwordx4 v[226:227], off
	s_mov_b32 m0, s67
	s_nop 0
	global_load_lds_dwordx4 v[228:229], off
	s_waitcnt vmcnt(8)
	s_waitcnt lgkmcnt(0)
	s_barrier
	s_setprio 1
	s_waitcnt lgkmcnt(0)
	v_mfma_f32_16x16x32_bf16 v[60:63], v[128:131], v[180:183], v[60:63]
	v_mfma_f32_16x16x32_bf16 v[60:63], v[132:135], v[194:197], v[60:63]
	v_mfma_f32_16x16x32_bf16 v[44:47], v[132:135], v[202:205], v[44:47]
	v_mfma_f32_16x16x32_bf16 v[44:47], v[128:131], v[198:201], v[44:47]
	v_mfma_f32_16x16x32_bf16 v[28:31], v[128:131], v[206:209], v[28:31]
	v_mfma_f32_16x16x32_bf16 v[28:31], v[132:135], v[210:213], v[28:31]
	v_mfma_f32_16x16x32_bf16 v[12:15], v[132:135], v[218:221], v[12:15]
	v_mfma_f32_16x16x32_bf16 v[12:15], v[128:131], v[214:217], v[12:15]
	v_mfma_f32_16x16x32_bf16 v[8:11], v[136:139], v[214:217], v[8:11]
	v_mfma_f32_16x16x32_bf16 v[8:11], v[140:143], v[218:221], v[8:11]
	v_mfma_f32_16x16x32_bf16 v[24:27], v[140:143], v[210:213], v[24:27]
	v_mfma_f32_16x16x32_bf16 v[24:27], v[136:139], v[206:209], v[24:27]
	v_mfma_f32_16x16x32_bf16 v[40:43], v[136:139], v[198:201], v[40:43]
	v_mfma_f32_16x16x32_bf16 v[40:43], v[140:143], v[202:205], v[40:43]
	v_mfma_f32_16x16x32_bf16 v[56:59], v[140:143], v[194:197], v[56:59]
	v_mfma_f32_16x16x32_bf16 v[56:59], v[136:139], v[180:183], v[56:59]
	s_setprio 0
	s_setprio 1
	v_mfma_f32_16x16x32_bf16 v[52:55], v[144:147], v[180:183], v[52:55]
	v_mfma_f32_16x16x32_bf16 v[52:55], v[148:151], v[194:197], v[52:55]
	v_mfma_f32_16x16x32_bf16 v[36:39], v[148:151], v[202:205], v[36:39]
	v_mfma_f32_16x16x32_bf16 v[36:39], v[144:147], v[198:201], v[36:39]
	v_mfma_f32_16x16x32_bf16 v[20:23], v[144:147], v[206:209], v[20:23]
	v_mfma_f32_16x16x32_bf16 v[20:23], v[148:151], v[210:213], v[20:23]
	v_mfma_f32_16x16x32_bf16 v[4:7], v[148:151], v[218:221], v[4:7]
	v_mfma_f32_16x16x32_bf16 v[4:7], v[144:147], v[214:217], v[4:7]
	v_mfma_f32_16x16x32_bf16 v[0:3], v[172:175], v[214:217], v[0:3]
	v_mfma_f32_16x16x32_bf16 v[0:3], v[176:179], v[218:221], v[0:3]
	v_mfma_f32_16x16x32_bf16 v[16:19], v[176:179], v[210:213], v[16:19]
	v_mfma_f32_16x16x32_bf16 v[16:19], v[172:175], v[206:209], v[16:19]
	v_mfma_f32_16x16x32_bf16 v[32:35], v[172:175], v[198:201], v[32:35]
	v_mfma_f32_16x16x32_bf16 v[32:35], v[176:179], v[202:205], v[32:35]
	v_mfma_f32_16x16x32_bf16 v[48:51], v[176:179], v[194:197], v[48:51]
	v_mfma_f32_16x16x32_bf16 v[48:51], v[172:175], v[180:183], v[48:51]
	s_setprio 0
	s_barrier
	s_add_i32 s84, 0, 0x18000
	s_add_i32 s85, 0, 0x1c000
	v_add_u32_e32 v140, s84, v186
	v_add_u32_e32 v176, s85, v186
	ds_read_b128 v[128:131], v140
	v_xor_b32_e32 v253, 64, v140
	ds_read_b128 v[132:135], v253
	ds_read_b128 v[136:139], v140 offset:2048
	ds_read_b128 v[140:143], v253 offset:2048
	ds_read_b128 v[144:147], v176
	v_xor_b32_e32 v253, 64, v176
	ds_read_b128 v[148:151], v253
	ds_read_b128 v[172:175], v176 offset:2048
	ds_read_b128 v[176:179], v253 offset:2048
	s_add_u32 s54, s60, 0xb0000
	s_addc_u32 s55, s61, 0
	s_mov_b32 m0, s68
	v_lshl_add_u64 v[230:231], s[54:55], 0, v[152:153]
	ds_read_b128 v[180:183], v191 offset:32768
	v_xor_b32_e32 v253, 64, v191
	ds_read_b128 v[194:197], v253 offset:32768
	ds_read_b128 v[198:201], v191 offset:34816
	ds_read_b128 v[202:205], v253 offset:34816
	ds_read_b128 v[206:209], v191 offset:36864
	ds_read_b128 v[210:213], v253 offset:36864
	ds_read_b128 v[214:217], v191 offset:38912
	ds_read_b128 v[218:221], v253 offset:38912
	global_load_lds_dwordx4 v[230:231], off
	v_lshl_add_u64 v[230:231], s[54:55], 0, v[160:161]
	s_mov_b32 m0, s69
	s_nop 0
	global_load_lds_dwordx4 v[230:231], off
	s_waitcnt vmcnt(8)
	s_waitcnt lgkmcnt(0)
	s_barrier
	s_setprio 1
	s_waitcnt lgkmcnt(0)
	v_mfma_f32_16x16x32_bf16 v[124:127], v[128:131], v[180:183], v[124:127]
	v_mfma_f32_16x16x32_bf16 v[124:127], v[132:135], v[194:197], v[124:127]
	v_mfma_f32_16x16x32_bf16 v[108:111], v[132:135], v[202:205], v[108:111]
	v_mfma_f32_16x16x32_bf16 v[108:111], v[128:131], v[198:201], v[108:111]
	v_mfma_f32_16x16x32_bf16 v[92:95], v[128:131], v[206:209], v[92:95]
	v_mfma_f32_16x16x32_bf16 v[92:95], v[132:135], v[210:213], v[92:95]
	v_mfma_f32_16x16x32_bf16 v[76:79], v[132:135], v[218:221], v[76:79]
	v_mfma_f32_16x16x32_bf16 v[76:79], v[128:131], v[214:217], v[76:79]
	v_mfma_f32_16x16x32_bf16 v[72:75], v[136:139], v[214:217], v[72:75]
	v_mfma_f32_16x16x32_bf16 v[72:75], v[140:143], v[218:221], v[72:75]
	v_mfma_f32_16x16x32_bf16 v[88:91], v[140:143], v[210:213], v[88:91]
	v_mfma_f32_16x16x32_bf16 v[88:91], v[136:139], v[206:209], v[88:91]
	v_mfma_f32_16x16x32_bf16 v[104:107], v[136:139], v[198:201], v[104:107]
	v_mfma_f32_16x16x32_bf16 v[104:107], v[140:143], v[202:205], v[104:107]
	v_mfma_f32_16x16x32_bf16 v[120:123], v[140:143], v[194:197], v[120:123]
	v_mfma_f32_16x16x32_bf16 v[120:123], v[136:139], v[180:183], v[120:123]
	s_setprio 0
	s_setprio 1
	v_mfma_f32_16x16x32_bf16 v[116:119], v[144:147], v[180:183], v[116:119]
	v_mfma_f32_16x16x32_bf16 v[116:119], v[148:151], v[194:197], v[116:119]
	v_mfma_f32_16x16x32_bf16 v[100:103], v[148:151], v[202:205], v[100:103]
	v_mfma_f32_16x16x32_bf16 v[100:103], v[144:147], v[198:201], v[100:103]
	v_mfma_f32_16x16x32_bf16 v[84:87], v[144:147], v[206:209], v[84:87]
	v_mfma_f32_16x16x32_bf16 v[84:87], v[148:151], v[210:213], v[84:87]
	v_mfma_f32_16x16x32_bf16 v[68:71], v[148:151], v[218:221], v[68:71]
	v_mfma_f32_16x16x32_bf16 v[68:71], v[144:147], v[214:217], v[68:71]
	v_mfma_f32_16x16x32_bf16 v[64:67], v[172:175], v[214:217], v[64:67]
	v_mfma_f32_16x16x32_bf16 v[64:67], v[176:179], v[218:221], v[64:67]
	v_mfma_f32_16x16x32_bf16 v[80:83], v[176:179], v[210:213], v[80:83]
	v_mfma_f32_16x16x32_bf16 v[80:83], v[172:175], v[206:209], v[80:83]
	v_mfma_f32_16x16x32_bf16 v[96:99], v[172:175], v[198:201], v[96:99]
	v_mfma_f32_16x16x32_bf16 v[96:99], v[176:179], v[202:205], v[96:99]
	v_mfma_f32_16x16x32_bf16 v[112:115], v[176:179], v[194:197], v[112:115]
	v_mfma_f32_16x16x32_bf16 v[112:115], v[172:175], v[180:183], v[112:115]
	s_setprio 0
	s_barrier
	s_add_i32 s54, s84, s65
	v_lshl_add_u64 v[222:223], v[222:223], 0, s[28:29]
	s_mov_b32 m0, s54
	ds_read_b128 v[180:183], v191 offset:49152
	v_xor_b32_e32 v253, 64, v191
	ds_read_b128 v[194:197], v253 offset:49152
	ds_read_b128 v[198:201], v191 offset:51200
	ds_read_b128 v[202:205], v253 offset:51200
	ds_read_b128 v[206:209], v191 offset:53248
	ds_read_b128 v[210:213], v253 offset:53248
	ds_read_b128 v[214:217], v191 offset:55296
	ds_read_b128 v[218:221], v253 offset:55296
	global_load_lds_dwordx4 v[222:223], off
	s_add_i32 m0, s54, 0x2000
	s_add_u32 s54, s58, 0xb0080
	v_lshl_add_u64 v[222:223], v[224:225], 0, s[28:29]
	s_addc_u32 s55, s59, 0
	s_add_i32 s58, s85, s65
	global_load_lds_dwordx4 v[222:223], off
	v_lshl_add_u64 v[222:223], s[54:55], 0, v[154:155]
	s_mov_b32 m0, s58
	s_nop 0
	global_load_lds_dwordx4 v[222:223], off
	v_lshl_add_u64 v[222:223], s[54:55], 0, v[162:163]
	s_add_i32 m0, s58, 0x2000
	s_nop 0
	global_load_lds_dwordx4 v[222:223], off
	v_lshl_add_u64 v[222:223], v[226:227], 0, s[28:29]
	s_mov_b32 m0, s3
	s_nop 0
	global_load_lds_dwordx4 v[222:223], off
	v_lshl_add_u64 v[222:223], v[228:229], 0, s[28:29]
	s_mov_b32 m0, s71
	s_nop 0
	global_load_lds_dwordx4 v[222:223], off
	s_waitcnt vmcnt(8)
	s_waitcnt lgkmcnt(0)
	s_barrier
	s_setprio 1
	s_waitcnt lgkmcnt(0)
	v_mfma_f32_16x16x32_bf16 v[60:63], v[128:131], v[180:183], v[60:63]
	v_mfma_f32_16x16x32_bf16 v[60:63], v[132:135], v[194:197], v[60:63]
	v_mfma_f32_16x16x32_bf16 v[44:47], v[132:135], v[202:205], v[44:47]
	v_mfma_f32_16x16x32_bf16 v[44:47], v[128:131], v[198:201], v[44:47]
	v_mfma_f32_16x16x32_bf16 v[28:31], v[128:131], v[206:209], v[28:31]
	v_mfma_f32_16x16x32_bf16 v[28:31], v[132:135], v[210:213], v[28:31]
	v_mfma_f32_16x16x32_bf16 v[12:15], v[132:135], v[218:221], v[12:15]
	v_mfma_f32_16x16x32_bf16 v[12:15], v[128:131], v[214:217], v[12:15]
	v_mfma_f32_16x16x32_bf16 v[8:11], v[136:139], v[214:217], v[8:11]
	v_mfma_f32_16x16x32_bf16 v[8:11], v[140:143], v[218:221], v[8:11]
	v_mfma_f32_16x16x32_bf16 v[24:27], v[140:143], v[210:213], v[24:27]
	v_mfma_f32_16x16x32_bf16 v[24:27], v[136:139], v[206:209], v[24:27]
	v_mfma_f32_16x16x32_bf16 v[40:43], v[136:139], v[198:201], v[40:43]
	v_mfma_f32_16x16x32_bf16 v[40:43], v[140:143], v[202:205], v[40:43]
	v_mfma_f32_16x16x32_bf16 v[56:59], v[140:143], v[194:197], v[56:59]
	v_mfma_f32_16x16x32_bf16 v[56:59], v[136:139], v[180:183], v[56:59]
	s_setprio 0
	s_setprio 1
	v_mfma_f32_16x16x32_bf16 v[52:55], v[144:147], v[180:183], v[52:55]
	v_mfma_f32_16x16x32_bf16 v[52:55], v[148:151], v[194:197], v[52:55]
	v_mfma_f32_16x16x32_bf16 v[36:39], v[148:151], v[202:205], v[36:39]
	v_mfma_f32_16x16x32_bf16 v[36:39], v[144:147], v[198:201], v[36:39]
	v_mfma_f32_16x16x32_bf16 v[20:23], v[144:147], v[206:209], v[20:23]
	v_mfma_f32_16x16x32_bf16 v[20:23], v[148:151], v[210:213], v[20:23]
	v_mfma_f32_16x16x32_bf16 v[4:7], v[148:151], v[218:221], v[4:7]
	v_mfma_f32_16x16x32_bf16 v[4:7], v[144:147], v[214:217], v[4:7]
	v_mfma_f32_16x16x32_bf16 v[0:3], v[172:175], v[214:217], v[0:3]
	v_mfma_f32_16x16x32_bf16 v[0:3], v[176:179], v[218:221], v[0:3]
	v_mfma_f32_16x16x32_bf16 v[16:19], v[176:179], v[210:213], v[16:19]
	v_mfma_f32_16x16x32_bf16 v[16:19], v[172:175], v[206:209], v[16:19]
	v_mfma_f32_16x16x32_bf16 v[32:35], v[172:175], v[198:201], v[32:35]
	v_mfma_f32_16x16x32_bf16 v[32:35], v[176:179], v[202:205], v[32:35]
	v_mfma_f32_16x16x32_bf16 v[48:51], v[176:179], v[194:197], v[48:51]
	v_mfma_f32_16x16x32_bf16 v[48:51], v[172:175], v[180:183], v[48:51]
	s_setprio 0
	s_barrier
	s_add_i32 s83, s83, 2
	s_add_u32 s81, s81, 0x100
	s_addc_u32 s82, s82, 0
	s_cmp_gt_u32 s83, 41
	s_mov_b64 s[54:55], s[56:57]
	s_cbranch_scc0 .LBB0_159
	s_and_b64 vcc, exec, s[30:31]
	s_cbranch_vccz .LBB0_162
	s_barrier

.LBB0_254:
	s_ashr_i32 s61, s60, 31
	s_lshl_b64 s[62:63], s[60:61], 19
	s_add_u32 s62, s35, s62
	s_addc_u32 s63, s47, s63
	s_and_b64 s[64:65], s[12:13], exec
	s_cselect_b32 s3, s63, s69
	s_cselect_b32 s61, s62, s68
	s_ashr_i32 s59, s58, 31
	s_lshl_b64 s[64:65], s[58:59], 19
	s_add_u32 s64, s49, s64
	s_addc_u32 s65, s70, s65
	s_and_b64 s[92:93], s[12:13], exec
	s_cselect_b32 s91, s65, s67
	s_cselect_b32 s92, s64, s66
	s_lshl_b32 s59, s14, 8
	v_add_u32_e32 v0, s59, v182
	s_add_u32 s93, s66, 0x100
	s_waitcnt lgkmcnt(0)
	v_ashrrev_i32_e32 v1, 31, v0
	s_addc_u32 s94, s67, 0
	v_lshl_add_u64 v[72:73], v[0:1], 4, s[26:27]
	s_add_u32 s14, s68, 0x40080
	s_addc_u32 s15, s69, 0
	s_mov_b32 s95, -2
	s_mov_b64 s[66:67], 0
	s_cmp_eq_u32 s90, 1
	s_cbranch_scc1 .Lfa_2
	v_add_u32_e32 v74, s83, v181
	ds_read_b128 v[88:91], v74
	v_xor_b32_e32 v253, 64, v74
	ds_read_b128 v[108:111], v253
	ds_read_b128 v[128:131], v74 offset:2048
	ds_read_b128 v[144:147], v253 offset:2048
	v_add_u32_e32 v74, s84, v181
	ds_read_b128 v[148:151], v74
	v_xor_b32_e32 v253, 64, v74
	ds_read_b128 v[152:155], v253
	ds_read_b128 v[176:179], v74 offset:2048
	ds_read_b128 v[190:193], v253 offset:2048
	s_add_u32 s68, s14, 0xfffc0080
	s_addc_u32 s69, s15, -1
	s_and_b64 s[66:67], s[66:67], exec
	s_cselect_b32 s69, s3, s69
	s_cselect_b32 s68, s61, s68
	s_cselect_b32 s67, s91, s94
	s_cselect_b32 s66, s92, s93
	v_lshl_add_u64 v[74:75], s[14:15], 0, v[170:171]
	s_add_i32 m0, s74, 0xc000
	ds_read_b128 v[194:197], v187
	v_xor_b32_e32 v253, 64, v187
	ds_read_b128 v[198:201], v253
	ds_read_b128 v[202:205], v187 offset:2048
	ds_read_b128 v[206:209], v253 offset:2048
	ds_read_b128 v[210:213], v187 offset:4096
	ds_read_b128 v[214:217], v253 offset:4096
	ds_read_b128 v[218:221], v187 offset:6144
	ds_read_b128 v[222:225], v253 offset:6144
	global_load_lds_dwordx4 v[74:75], off
	v_lshl_add_u64 v[74:75], s[14:15], 0, v[168:169]
	s_add_i32 m0, s74, 0xe000
	s_nop 0
	global_load_lds_dwordx4 v[74:75], off
	s_waitcnt vmcnt(24)
	s_waitcnt lgkmcnt(0)
	s_barrier
	s_setprio 1
	s_waitcnt lgkmcnt(0)
	v_mfma_f32_16x16x32_bf16 v[140:143], v[88:91], v[194:197], 0
	v_mfma_f32_16x16x32_bf16 v[136:139], v[128:131], v[194:197], 0
	v_mfma_f32_16x16x32_bf16 v[120:123], v[88:91], v[202:205], 0
	v_mfma_f32_16x16x32_bf16 v[116:119], v[128:131], v[202:205], 0
	v_mfma_f32_16x16x32_bf16 v[100:103], v[88:91], v[210:213], 0
	v_mfma_f32_16x16x32_bf16 v[96:99], v[128:131], v[210:213], 0
	v_mfma_f32_16x16x32_bf16 v[80:83], v[88:91], v[218:221], 0
	v_mfma_f32_16x16x32_bf16 v[74:77], v[128:131], v[218:221], 0
	v_mfma_f32_16x16x32_bf16 v[140:143], v[108:111], v[198:201], v[140:143]
	v_mfma_f32_16x16x32_bf16 v[136:139], v[144:147], v[198:201], v[136:139]
	v_mfma_f32_16x16x32_bf16 v[120:123], v[108:111], v[206:209], v[120:123]
	v_mfma_f32_16x16x32_bf16 v[116:119], v[144:147], v[206:209], v[116:119]
	v_mfma_f32_16x16x32_bf16 v[100:103], v[108:111], v[214:217], v[100:103]
	v_mfma_f32_16x16x32_bf16 v[96:99], v[144:147], v[214:217], v[96:99]
	v_mfma_f32_16x16x32_bf16 v[80:83], v[108:111], v[222:225], v[80:83]
	v_mfma_f32_16x16x32_bf16 v[74:77], v[144:147], v[222:225], v[74:77]
	s_setprio 0
	s_setprio 1
	v_mfma_f32_16x16x32_bf16 v[132:135], v[148:151], v[194:197], 0
	v_mfma_f32_16x16x32_bf16 v[124:127], v[176:179], v[194:197], 0
	v_mfma_f32_16x16x32_bf16 v[112:115], v[148:151], v[202:205], 0
	v_mfma_f32_16x16x32_bf16 v[104:107], v[176:179], v[202:205], 0
	v_mfma_f32_16x16x32_bf16 v[92:95], v[148:151], v[210:213], 0
	v_mfma_f32_16x16x32_bf16 v[84:87], v[176:179], v[210:213], 0
	v_mfma_f32_16x16x32_bf16 v[68:71], v[148:151], v[218:221], 0
	v_mfma_f32_16x16x32_bf16 v[64:67], v[176:179], v[218:221], 0
	v_mfma_f32_16x16x32_bf16 v[132:135], v[152:155], v[198:201], v[132:135]
	v_mfma_f32_16x16x32_bf16 v[124:127], v[190:193], v[198:201], v[124:127]
	v_mfma_f32_16x16x32_bf16 v[112:115], v[152:155], v[206:209], v[112:115]
	v_mfma_f32_16x16x32_bf16 v[104:107], v[190:193], v[206:209], v[104:107]
	v_mfma_f32_16x16x32_bf16 v[92:95], v[152:155], v[214:217], v[92:95]
	v_mfma_f32_16x16x32_bf16 v[84:87], v[190:193], v[214:217], v[84:87]
	v_mfma_f32_16x16x32_bf16 v[68:71], v[152:155], v[222:225], v[68:71]
	v_mfma_f32_16x16x32_bf16 v[64:67], v[190:193], v[222:225], v[64:67]
	s_setprio 0
	s_barrier
	s_add_i32 s96, s83, s71
	v_lshl_add_u64 v[226:227], s[66:67], 0, v[162:163]
	s_mov_b32 m0, s96
	ds_read_b128 v[194:197], v187 offset:16384
	v_xor_b32_e32 v253, 64, v187
	ds_read_b128 v[198:201], v253 offset:16384
	ds_read_b128 v[202:205], v187 offset:18432
	ds_read_b128 v[206:209], v253 offset:18432
	ds_read_b128 v[210:213], v187 offset:20480
	ds_read_b128 v[214:217], v253 offset:20480
	ds_read_b128 v[218:221], v187 offset:22528
	ds_read_b128 v[222:225], v253 offset:22528
	global_load_lds_dwordx4 v[226:227], off
	s_add_i32 m0, s96, 0x2000
	s_add_u32 s96, s66, 0x40000
	v_lshl_add_u64 v[228:229], s[66:67], 0, v[166:167]
	s_addc_u32 s97, s67, 0
	s_add_i32 vcc_lo, s84, s71
	global_load_lds_dwordx4 v[228:229], off
	v_lshl_add_u64 v[78:79], s[96:97], 0, v[162:163]
	s_mov_b32 m0, vcc_lo
	v_lshl_add_u64 v[230:231], s[68:69], 0, v[160:161]
	global_load_lds_dwordx4 v[78:79], off
	v_lshl_add_u64 v[78:79], s[96:97], 0, v[166:167]
	s_add_i32 m0, vcc_lo, 0x2000
	v_lshl_add_u64 v[232:233], s[68:69], 0, v[164:165]
	global_load_lds_dwordx4 v[78:79], off
	s_mov_b32 m0, s74
	s_nop 0
	global_load_lds_dwordx4 v[230:231], off
	s_mov_b32 m0, s75
	s_nop 0
	global_load_lds_dwordx4 v[232:233], off
	s_waitcnt vmcnt(24)
	s_waitcnt lgkmcnt(0)
	s_barrier
	s_setprio 1
	s_waitcnt lgkmcnt(0)
	v_mfma_f32_16x16x32_bf16 v[60:63], v[88:91], v[194:197], 0
	v_mfma_f32_16x16x32_bf16 v[56:59], v[128:131], v[194:197], 0
	v_mfma_f32_16x16x32_bf16 v[44:47], v[88:91], v[202:205], 0
	v_mfma_f32_16x16x32_bf16 v[40:43], v[128:131], v[202:205], 0
	v_mfma_f32_16x16x32_bf16 v[28:31], v[88:91], v[210:213], 0
	v_mfma_f32_16x16x32_bf16 v[24:27], v[128:131], v[210:213], 0
	v_mfma_f32_16x16x32_bf16 v[12:15], v[88:91], v[218:221], 0
	v_mfma_f32_16x16x32_bf16 v[8:11], v[128:131], v[218:221], 0
	v_mfma_f32_16x16x32_bf16 v[60:63], v[108:111], v[198:201], v[60:63]
	v_mfma_f32_16x16x32_bf16 v[56:59], v[144:147], v[198:201], v[56:59]
	v_mfma_f32_16x16x32_bf16 v[44:47], v[108:111], v[206:209], v[44:47]
	v_mfma_f32_16x16x32_bf16 v[40:43], v[144:147], v[206:209], v[40:43]
	v_mfma_f32_16x16x32_bf16 v[28:31], v[108:111], v[214:217], v[28:31]
	v_mfma_f32_16x16x32_bf16 v[24:27], v[144:147], v[214:217], v[24:27]
	v_mfma_f32_16x16x32_bf16 v[12:15], v[108:111], v[222:225], v[12:15]
	v_mfma_f32_16x16x32_bf16 v[8:11], v[144:147], v[222:225], v[8:11]
	s_setprio 0
	s_setprio 1
	v_mfma_f32_16x16x32_bf16 v[52:55], v[148:151], v[194:197], 0
	v_mfma_f32_16x16x32_bf16 v[48:51], v[176:179], v[194:197], 0
	v_mfma_f32_16x16x32_bf16 v[36:39], v[148:151], v[202:205], 0
	v_mfma_f32_16x16x32_bf16 v[32:35], v[176:179], v[202:205], 0
	v_mfma_f32_16x16x32_bf16 v[20:23], v[148:151], v[210:213], 0
	v_mfma_f32_16x16x32_bf16 v[16:19], v[176:179], v[210:213], 0
	v_mfma_f32_16x16x32_bf16 v[4:7], v[148:151], v[218:221], 0
	v_mfma_f32_16x16x32_bf16 v[0:3], v[176:179], v[218:221], 0
	v_mfma_f32_16x16x32_bf16 v[52:55], v[152:155], v[198:201], v[52:55]
	v_mfma_f32_16x16x32_bf16 v[48:51], v[190:193], v[198:201], v[48:51]
	v_mfma_f32_16x16x32_bf16 v[36:39], v[152:155], v[206:209], v[36:39]
	v_mfma_f32_16x16x32_bf16 v[32:35], v[190:193], v[206:209], v[32:35]
	v_mfma_f32_16x16x32_bf16 v[20:23], v[152:155], v[214:217], v[20:23]
	v_mfma_f32_16x16x32_bf16 v[16:19], v[190:193], v[214:217], v[16:19]
	v_mfma_f32_16x16x32_bf16 v[4:7], v[152:155], v[222:225], v[4:7]
	v_mfma_f32_16x16x32_bf16 v[0:3], v[190:193], v[222:225], v[0:3]
	s_setprio 0
	s_barrier
	s_add_i32 s96, 0, 0x18000
	v_add_u32_e32 v78, s96, v181
	s_add_i32 s97, 0, 0x1c000
	ds_read_b128 v[88:91], v78
	v_xor_b32_e32 v253, 64, v78
	ds_read_b128 v[108:111], v253
	ds_read_b128 v[128:131], v78 offset:2048
	ds_read_b128 v[144:147], v253 offset:2048
	v_add_u32_e32 v78, s97, v181
	ds_read_b128 v[148:151], v78
	v_xor_b32_e32 v253, 64, v78
	ds_read_b128 v[152:155], v253
	ds_read_b128 v[176:179], v78 offset:2048
	ds_read_b128 v[190:193], v253 offset:2048
	s_add_u32 s68, s68, 0x40000
	s_addc_u32 s69, s69, 0
	s_mov_b32 m0, s76
	v_lshl_add_u64 v[78:79], s[68:69], 0, v[160:161]
	ds_read_b128 v[194:197], v187 offset:32768
	v_xor_b32_e32 v253, 64, v187
	ds_read_b128 v[198:201], v253 offset:32768
	ds_read_b128 v[202:205], v187 offset:34816
	ds_read_b128 v[206:209], v253 offset:34816
	ds_read_b128 v[210:213], v187 offset:36864
	ds_read_b128 v[214:217], v253 offset:36864
	ds_read_b128 v[218:221], v187 offset:38912
	ds_read_b128 v[222:225], v253 offset:38912
	global_load_lds_dwordx4 v[78:79], off
	v_lshl_add_u64 v[78:79], s[68:69], 0, v[164:165]
	s_mov_b32 m0, s77
	s_nop 0
	global_load_lds_dwordx4 v[78:79], off
	s_waitcnt vmcnt(8)
	s_waitcnt lgkmcnt(0)
	s_barrier
	s_setprio 1
	s_waitcnt lgkmcnt(0)
	v_mfma_f32_16x16x32_bf16 v[140:143], v[88:91], v[194:197], v[140:143]
	v_mfma_f32_16x16x32_bf16 v[136:139], v[128:131], v[194:197], v[136:139]
	v_mfma_f32_16x16x32_bf16 v[120:123], v[88:91], v[202:205], v[120:123]
	v_mfma_f32_16x16x32_bf16 v[116:119], v[128:131], v[202:205], v[116:119]
	v_mfma_f32_16x16x32_bf16 v[100:103], v[88:91], v[210:213], v[100:103]
	v_mfma_f32_16x16x32_bf16 v[96:99], v[128:131], v[210:213], v[96:99]
	v_mfma_f32_16x16x32_bf16 v[78:81], v[88:91], v[218:221], v[80:83]
	v_mfma_f32_16x16x32_bf16 v[74:77], v[128:131], v[218:221], v[74:77]
	v_mfma_f32_16x16x32_bf16 v[140:143], v[108:111], v[198:201], v[140:143]
	v_mfma_f32_16x16x32_bf16 v[136:139], v[144:147], v[198:201], v[136:139]
	v_mfma_f32_16x16x32_bf16 v[120:123], v[108:111], v[206:209], v[120:123]
	v_mfma_f32_16x16x32_bf16 v[116:119], v[144:147], v[206:209], v[116:119]
	v_mfma_f32_16x16x32_bf16 v[100:103], v[108:111], v[214:217], v[100:103]
	v_mfma_f32_16x16x32_bf16 v[96:99], v[144:147], v[214:217], v[96:99]
	v_mfma_f32_16x16x32_bf16 v[80:83], v[108:111], v[222:225], v[78:81]
	v_mfma_f32_16x16x32_bf16 v[76:79], v[144:147], v[222:225], v[74:77]
	s_setprio 0
	s_setprio 1
	v_mfma_f32_16x16x32_bf16 v[132:135], v[148:151], v[194:197], v[132:135]
	v_mfma_f32_16x16x32_bf16 v[132:135], v[152:155], v[198:201], v[132:135]
	v_mfma_f32_16x16x32_bf16 v[112:115], v[152:155], v[206:209], v[112:115]
	v_mfma_f32_16x16x32_bf16 v[112:115], v[148:151], v[202:205], v[112:115]
	v_mfma_f32_16x16x32_bf16 v[92:95], v[148:151], v[210:213], v[92:95]
	v_mfma_f32_16x16x32_bf16 v[92:95], v[152:155], v[214:217], v[92:95]
	v_mfma_f32_16x16x32_bf16 v[68:71], v[152:155], v[222:225], v[68:71]
	v_mfma_f32_16x16x32_bf16 v[68:71], v[148:151], v[218:221], v[68:71]
	v_mfma_f32_16x16x32_bf16 v[64:67], v[176:179], v[218:221], v[64:67]
	v_mfma_f32_16x16x32_bf16 v[64:67], v[190:193], v[222:225], v[64:67]
	v_mfma_f32_16x16x32_bf16 v[84:87], v[190:193], v[214:217], v[84:87]
	v_mfma_f32_16x16x32_bf16 v[84:87], v[176:179], v[210:213], v[84:87]
	v_mfma_f32_16x16x32_bf16 v[104:107], v[176:179], v[202:205], v[104:107]
	v_mfma_f32_16x16x32_bf16 v[104:107], v[190:193], v[206:209], v[104:107]
	v_mfma_f32_16x16x32_bf16 v[124:127], v[190:193], v[198:201], v[124:127]
	v_mfma_f32_16x16x32_bf16 v[124:127], v[176:179], v[194:197], v[124:127]
	s_setprio 0
	s_barrier
	s_add_i32 s68, s96, s71
	v_lshl_add_u64 v[74:75], v[226:227], 0, s[28:29]
	s_mov_b32 m0, s68
	ds_read_b128 v[194:197], v187 offset:49152
	v_xor_b32_e32 v253, 64, v187
	ds_read_b128 v[198:201], v253 offset:49152
	ds_read_b128 v[202:205], v187 offset:51200
	ds_read_b128 v[206:209], v253 offset:51200
	ds_read_b128 v[210:213], v187 offset:53248
	ds_read_b128 v[214:217], v253 offset:53248
	ds_read_b128 v[218:221], v187 offset:55296
	ds_read_b128 v[222:225], v253 offset:55296
	global_load_lds_dwordx4 v[74:75], off
	s_add_i32 m0, s68, 0x2000
	s_add_u32 s66, s66, 0x40080
	v_lshl_add_u64 v[74:75], v[228:229], 0, s[28:29]
	s_addc_u32 s67, s67, 0
	s_add_i32 s68, s97, s71
	global_load_lds_dwordx4 v[74:75], off
	v_lshl_add_u64 v[74:75], s[66:67], 0, v[162:163]
	s_mov_b32 m0, s68
	s_nop 0
	global_load_lds_dwordx4 v[74:75], off
	v_lshl_add_u64 v[74:75], s[66:67], 0, v[166:167]
	s_add_i32 m0, s68, 0x2000
	s_nop 0
	global_load_lds_dwordx4 v[74:75], off
	v_lshl_add_u64 v[74:75], v[230:231], 0, s[28:29]
	s_mov_b32 m0, s78
	s_nop 0
	global_load_lds_dwordx4 v[74:75], off
	v_lshl_add_u64 v[74:75], v[232:233], 0, s[28:29]
	s_mov_b32 m0, s79
	s_nop 0
	global_load_lds_dwordx4 v[74:75], off
	s_waitcnt vmcnt(8)
	s_waitcnt lgkmcnt(0)
	s_barrier
	s_setprio 1
	s_waitcnt lgkmcnt(0)
	v_mfma_f32_16x16x32_bf16 v[60:63], v[88:91], v[194:197], v[60:63]
	v_mfma_f32_16x16x32_bf16 v[60:63], v[108:111], v[198:201], v[60:63]
	v_mfma_f32_16x16x32_bf16 v[44:47], v[108:111], v[206:209], v[44:47]
	v_mfma_f32_16x16x32_bf16 v[44:47], v[88:91], v[202:205], v[44:47]
	v_mfma_f32_16x16x32_bf16 v[28:31], v[88:91], v[210:213], v[28:31]
	v_mfma_f32_16x16x32_bf16 v[28:31], v[108:111], v[214:217], v[28:31]
	v_mfma_f32_16x16x32_bf16 v[12:15], v[108:111], v[222:225], v[12:15]
	v_mfma_f32_16x16x32_bf16 v[12:15], v[88:91], v[218:221], v[12:15]
	v_mfma_f32_16x16x32_bf16 v[8:11], v[128:131], v[218:221], v[8:11]
	v_mfma_f32_16x16x32_bf16 v[8:11], v[144:147], v[222:225], v[8:11]
	v_mfma_f32_16x16x32_bf16 v[24:27], v[144:147], v[214:217], v[24:27]
	v_mfma_f32_16x16x32_bf16 v[24:27], v[128:131], v[210:213], v[24:27]
	v_mfma_f32_16x16x32_bf16 v[40:43], v[128:131], v[202:205], v[40:43]
	v_mfma_f32_16x16x32_bf16 v[40:43], v[144:147], v[206:209], v[40:43]
	v_mfma_f32_16x16x32_bf16 v[56:59], v[144:147], v[198:201], v[56:59]
	v_mfma_f32_16x16x32_bf16 v[56:59], v[128:131], v[194:197], v[56:59]
	s_setprio 0
	s_setprio 1
	v_mfma_f32_16x16x32_bf16 v[52:55], v[148:151], v[194:197], v[52:55]
	v_mfma_f32_16x16x32_bf16 v[52:55], v[152:155], v[198:201], v[52:55]
	v_mfma_f32_16x16x32_bf16 v[36:39], v[152:155], v[206:209], v[36:39]
	v_mfma_f32_16x16x32_bf16 v[36:39], v[148:151], v[202:205], v[36:39]
	v_mfma_f32_16x16x32_bf16 v[20:23], v[148:151], v[210:213], v[20:23]
	v_mfma_f32_16x16x32_bf16 v[20:23], v[152:155], v[214:217], v[20:23]
	v_mfma_f32_16x16x32_bf16 v[4:7], v[152:155], v[222:225], v[4:7]
	v_mfma_f32_16x16x32_bf16 v[4:7], v[148:151], v[218:221], v[4:7]
	v_mfma_f32_16x16x32_bf16 v[0:3], v[176:179], v[218:221], v[0:3]
	v_mfma_f32_16x16x32_bf16 v[0:3], v[190:193], v[222:225], v[0:3]
	v_mfma_f32_16x16x32_bf16 v[16:19], v[190:193], v[214:217], v[16:19]
	v_mfma_f32_16x16x32_bf16 v[16:19], v[176:179], v[210:213], v[16:19]
	v_mfma_f32_16x16x32_bf16 v[32:35], v[176:179], v[202:205], v[32:35]
	v_mfma_f32_16x16x32_bf16 v[32:35], v[190:193], v[206:209], v[32:35]
	v_mfma_f32_16x16x32_bf16 v[48:51], v[190:193], v[198:201], v[48:51]
	v_mfma_f32_16x16x32_bf16 v[48:51], v[176:179], v[194:197], v[48:51]
	s_setprio 0
	s_barrier
	s_add_i32 s95, s95, 2
	s_add_u32 s93, s93, 0x100
	s_addc_u32 s94, s94, 0
	s_add_u32 s14, s14, 0x100
	s_addc_u32 s15, s15, 0
	s_branch .LBB0_256
.Lfa_2:
	v_add_u32_e32 v74, s83, v181
	ds_read_b128 v[88:91], v74
	v_xor_b32_e32 v253, 64, v74
	ds_read_b128 v[108:111], v253
	ds_read_b128 v[128:131], v74 offset:2048
	ds_read_b128 v[144:147], v253 offset:2048
	v_add_u32_e32 v74, s84, v181
	ds_read_b128 v[148:151], v74
	v_xor_b32_e32 v253, 64, v74
	ds_read_b128 v[152:155], v253
	ds_read_b128 v[176:179], v74 offset:2048
	ds_read_b128 v[190:193], v253 offset:2048
	s_add_u32 s68, s14, 0xfffc0080
	s_addc_u32 s69, s15, -1
	s_and_b64 s[66:67], s[66:67], exec
	s_cselect_b32 s69, s3, s69
	s_cselect_b32 s68, s61, s68
	s_cselect_b32 s67, s91, s94
	s_cselect_b32 s66, s92, s93
	v_lshl_add_u64 v[74:75], s[14:15], 0, v[170:171]
	s_add_i32 m0, s74, 0xc000
	ds_read_b128 v[194:197], v187
	v_xor_b32_e32 v253, 64, v187
	ds_read_b128 v[198:201], v253
	ds_read_b128 v[202:205], v187 offset:2048
	ds_read_b128 v[206:209], v253 offset:2048
	ds_read_b128 v[210:213], v187 offset:4096
	ds_read_b128 v[214:217], v253 offset:4096
	ds_read_b128 v[218:221], v187 offset:6144
	ds_read_b128 v[222:225], v253 offset:6144
	global_load_lds_dwordx4 v[74:75], off
	v_lshl_add_u64 v[74:75], s[14:15], 0, v[168:169]
	s_add_i32 m0, s74, 0xe000
	s_nop 0
	global_load_lds_dwordx4 v[74:75], off
	s_waitcnt vmcnt(8)
	s_waitcnt lgkmcnt(0)
	s_barrier
	s_setprio 1
	s_waitcnt lgkmcnt(0)
	v_mfma_f32_16x16x32_bf16 v[140:143], v[88:91], v[194:197], 0
	v_mfma_f32_16x16x32_bf16 v[136:139], v[128:131], v[194:197], 0
	v_mfma_f32_16x16x32_bf16 v[120:123], v[88:91], v[202:205], 0
	v_mfma_f32_16x16x32_bf16 v[116:119], v[128:131], v[202:205], 0
	v_mfma_f32_16x16x32_bf16 v[100:103], v[88:91], v[210:213], 0
	v_mfma_f32_16x16x32_bf16 v[96:99], v[128:131], v[210:213], 0
	v_mfma_f32_16x16x32_bf16 v[80:83], v[88:91], v[218:221], 0
	v_mfma_f32_16x16x32_bf16 v[74:77], v[128:131], v[218:221], 0
	v_mfma_f32_16x16x32_bf16 v[140:143], v[108:111], v[198:201], v[140:143]
	v_mfma_f32_16x16x32_bf16 v[136:139], v[144:147], v[198:201], v[136:139]
	v_mfma_f32_16x16x32_bf16 v[120:123], v[108:111], v[206:209], v[120:123]
	v_mfma_f32_16x16x32_bf16 v[116:119], v[144:147], v[206:209], v[116:119]
	v_mfma_f32_16x16x32_bf16 v[100:103], v[108:111], v[214:217], v[100:103]
	v_mfma_f32_16x16x32_bf16 v[96:99], v[144:147], v[214:217], v[96:99]
	v_mfma_f32_16x16x32_bf16 v[80:83], v[108:111], v[222:225], v[80:83]
	v_mfma_f32_16x16x32_bf16 v[74:77], v[144:147], v[222:225], v[74:77]
	s_setprio 0
	s_setprio 1
	v_mfma_f32_16x16x32_bf16 v[132:135], v[148:151], v[194:197], 0
	v_mfma_f32_16x16x32_bf16 v[124:127], v[176:179], v[194:197], 0
	v_mfma_f32_16x16x32_bf16 v[112:115], v[148:151], v[202:205], 0
	v_mfma_f32_16x16x32_bf16 v[104:107], v[176:179], v[202:205], 0
	v_mfma_f32_16x16x32_bf16 v[92:95], v[148:151], v[210:213], 0
	v_mfma_f32_16x16x32_bf16 v[84:87], v[176:179], v[210:213], 0
	v_mfma_f32_16x16x32_bf16 v[68:71], v[148:151], v[218:221], 0
	v_mfma_f32_16x16x32_bf16 v[64:67], v[176:179], v[218:221], 0
	v_mfma_f32_16x16x32_bf16 v[132:135], v[152:155], v[198:201], v[132:135]
	v_mfma_f32_16x16x32_bf16 v[124:127], v[190:193], v[198:201], v[124:127]
	v_mfma_f32_16x16x32_bf16 v[112:115], v[152:155], v[206:209], v[112:115]
	v_mfma_f32_16x16x32_bf16 v[104:107], v[190:193], v[206:209], v[104:107]
	v_mfma_f32_16x16x32_bf16 v[92:95], v[152:155], v[214:217], v[92:95]
	v_mfma_f32_16x16x32_bf16 v[84:87], v[190:193], v[214:217], v[84:87]
	v_mfma_f32_16x16x32_bf16 v[68:71], v[152:155], v[222:225], v[68:71]
	v_mfma_f32_16x16x32_bf16 v[64:67], v[190:193], v[222:225], v[64:67]
	s_setprio 0
	s_barrier
	s_add_i32 s96, s83, s71
	v_lshl_add_u64 v[226:227], s[66:67], 0, v[162:163]
	s_mov_b32 m0, s96
	ds_read_b128 v[194:197], v187 offset:16384
	v_xor_b32_e32 v253, 64, v187
	ds_read_b128 v[198:201], v253 offset:16384
	ds_read_b128 v[202:205], v187 offset:18432
	ds_read_b128 v[206:209], v253 offset:18432
	ds_read_b128 v[210:213], v187 offset:20480
	ds_read_b128 v[214:217], v253 offset:20480
	ds_read_b128 v[218:221], v187 offset:22528
	ds_read_b128 v[222:225], v253 offset:22528
	global_load_lds_dwordx4 v[226:227], off
	s_add_i32 m0, s96, 0x2000
	s_add_u32 s96, s66, 0x40000
	v_lshl_add_u64 v[228:229], s[66:67], 0, v[166:167]
	s_addc_u32 s97, s67, 0
	s_add_i32 vcc_lo, s84, s71
	global_load_lds_dwordx4 v[228:229], off
	v_lshl_add_u64 v[78:79], s[96:97], 0, v[162:163]
	s_mov_b32 m0, vcc_lo
	v_lshl_add_u64 v[230:231], s[68:69], 0, v[160:161]
	global_load_lds_dwordx4 v[78:79], off
	v_lshl_add_u64 v[78:79], s[96:97], 0, v[166:167]
	s_add_i32 m0, vcc_lo, 0x2000
	v_lshl_add_u64 v[232:233], s[68:69], 0, v[164:165]
	global_load_lds_dwordx4 v[78:79], off
	s_mov_b32 m0, s74
	s_nop 0
	global_load_lds_dwordx4 v[230:231], off
	s_mov_b32 m0, s75
	s_nop 0
	global_load_lds_dwordx4 v[232:233], off
	s_waitcnt vmcnt(8)
	s_waitcnt lgkmcnt(0)
	s_barrier
	s_setprio 1
	s_waitcnt lgkmcnt(0)
	v_mfma_f32_16x16x32_bf16 v[60:63], v[88:91], v[194:197], 0
	v_mfma_f32_16x16x32_bf16 v[56:59], v[128:131], v[194:197], 0
	v_mfma_f32_16x16x32_bf16 v[44:47], v[88:91], v[202:205], 0
	v_mfma_f32_16x16x32_bf16 v[40:43], v[128:131], v[202:205], 0
	v_mfma_f32_16x16x32_bf16 v[28:31], v[88:91], v[210:213], 0
	v_mfma_f32_16x16x32_bf16 v[24:27], v[128:131], v[210:213], 0
	v_mfma_f32_16x16x32_bf16 v[12:15], v[88:91], v[218:221], 0
	v_mfma_f32_16x16x32_bf16 v[8:11], v[128:131], v[218:221], 0
	v_mfma_f32_16x16x32_bf16 v[60:63], v[108:111], v[198:201], v[60:63]
	v_mfma_f32_16x16x32_bf16 v[56:59], v[144:147], v[198:201], v[56:59]
	v_mfma_f32_16x16x32_bf16 v[44:47], v[108:111], v[206:209], v[44:47]
	v_mfma_f32_16x16x32_bf16 v[40:43], v[144:147], v[206:209], v[40:43]
	v_mfma_f32_16x16x32_bf16 v[28:31], v[108:111], v[214:217], v[28:31]
	v_mfma_f32_16x16x32_bf16 v[24:27], v[144:147], v[214:217], v[24:27]
	v_mfma_f32_16x16x32_bf16 v[12:15], v[108:111], v[222:225], v[12:15]
	v_mfma_f32_16x16x32_bf16 v[8:11], v[144:147], v[222:225], v[8:11]
	s_setprio 0
	s_setprio 1
	v_mfma_f32_16x16x32_bf16 v[52:55], v[148:151], v[194:197], 0
	v_mfma_f32_16x16x32_bf16 v[48:51], v[176:179], v[194:197], 0
	v_mfma_f32_16x16x32_bf16 v[36:39], v[148:151], v[202:205], 0
	v_mfma_f32_16x16x32_bf16 v[32:35], v[176:179], v[202:205], 0
	v_mfma_f32_16x16x32_bf16 v[20:23], v[148:151], v[210:213], 0
	v_mfma_f32_16x16x32_bf16 v[16:19], v[176:179], v[210:213], 0
	v_mfma_f32_16x16x32_bf16 v[4:7], v[148:151], v[218:221], 0
	v_mfma_f32_16x16x32_bf16 v[0:3], v[176:179], v[218:221], 0
	v_mfma_f32_16x16x32_bf16 v[52:55], v[152:155], v[198:201], v[52:55]
	v_mfma_f32_16x16x32_bf16 v[48:51], v[190:193], v[198:201], v[48:51]
	v_mfma_f32_16x16x32_bf16 v[36:39], v[152:155], v[206:209], v[36:39]
	v_mfma_f32_16x16x32_bf16 v[32:35], v[190:193], v[206:209], v[32:35]
	v_mfma_f32_16x16x32_bf16 v[20:23], v[152:155], v[214:217], v[20:23]
	v_mfma_f32_16x16x32_bf16 v[16:19], v[190:193], v[214:217], v[16:19]
	v_mfma_f32_16x16x32_bf16 v[4:7], v[152:155], v[222:225], v[4:7]
	v_mfma_f32_16x16x32_bf16 v[0:3], v[190:193], v[222:225], v[0:3]
	s_setprio 0
	s_barrier
	s_add_i32 s96, 0, 0x18000
	v_add_u32_e32 v78, s96, v181
	s_add_i32 s97, 0, 0x1c000
	ds_read_b128 v[88:91], v78
	v_xor_b32_e32 v253, 64, v78
	ds_read_b128 v[108:111], v253
	ds_read_b128 v[128:131], v78 offset:2048
	ds_read_b128 v[144:147], v253 offset:2048
	v_add_u32_e32 v78, s97, v181
	ds_read_b128 v[148:151], v78
	v_xor_b32_e32 v253, 64, v78
	ds_read_b128 v[152:155], v253
	ds_read_b128 v[176:179], v78 offset:2048
	ds_read_b128 v[190:193], v253 offset:2048
	s_add_u32 s68, s68, 0x40000
	s_addc_u32 s69, s69, 0
	s_mov_b32 m0, s76
	v_lshl_add_u64 v[78:79], s[68:69], 0, v[160:161]
	ds_read_b128 v[194:197], v187 offset:32768
	v_xor_b32_e32 v253, 64, v187
	ds_read_b128 v[198:201], v253 offset:32768
	ds_read_b128 v[202:205], v187 offset:34816
	ds_read_b128 v[206:209], v253 offset:34816
	ds_read_b128 v[210:213], v187 offset:36864
	ds_read_b128 v[214:217], v253 offset:36864
	ds_read_b128 v[218:221], v187 offset:38912
	ds_read_b128 v[222:225], v253 offset:38912
	global_load_lds_dwordx4 v[78:79], off
	v_lshl_add_u64 v[78:79], s[68:69], 0, v[164:165]
	s_mov_b32 m0, s77
	s_nop 0
	global_load_lds_dwordx4 v[78:79], off
	s_waitcnt vmcnt(8)
	s_waitcnt lgkmcnt(0)
	s_barrier
	s_setprio 1
	s_waitcnt lgkmcnt(0)
	v_mfma_f32_16x16x32_bf16 v[140:143], v[88:91], v[194:197], v[140:143]
	v_mfma_f32_16x16x32_bf16 v[136:139], v[128:131], v[194:197], v[136:139]
	v_mfma_f32_16x16x32_bf16 v[120:123], v[88:91], v[202:205], v[120:123]
	v_mfma_f32_16x16x32_bf16 v[116:119], v[128:131], v[202:205], v[116:119]
	v_mfma_f32_16x16x32_bf16 v[100:103], v[88:91], v[210:213], v[100:103]
	v_mfma_f32_16x16x32_bf16 v[96:99], v[128:131], v[210:213], v[96:99]
	v_mfma_f32_16x16x32_bf16 v[78:81], v[88:91], v[218:221], v[80:83]
	v_mfma_f32_16x16x32_bf16 v[74:77], v[128:131], v[218:221], v[74:77]
	v_mfma_f32_16x16x32_bf16 v[140:143], v[108:111], v[198:201], v[140:143]
	v_mfma_f32_16x16x32_bf16 v[136:139], v[144:147], v[198:201], v[136:139]
	v_mfma_f32_16x16x32_bf16 v[120:123], v[108:111], v[206:209], v[120:123]
	v_mfma_f32_16x16x32_bf16 v[116:119], v[144:147], v[206:209], v[116:119]
	v_mfma_f32_16x16x32_bf16 v[100:103], v[108:111], v[214:217], v[100:103]
	v_mfma_f32_16x16x32_bf16 v[96:99], v[144:147], v[214:217], v[96:99]
	v_mfma_f32_16x16x32_bf16 v[80:83], v[108:111], v[222:225], v[78:81]
	v_mfma_f32_16x16x32_bf16 v[76:79], v[144:147], v[222:225], v[74:77]
	s_setprio 0
	s_setprio 1
	v_mfma_f32_16x16x32_bf16 v[132:135], v[148:151], v[194:197], v[132:135]
	v_mfma_f32_16x16x32_bf16 v[132:135], v[152:155], v[198:201], v[132:135]
	v_mfma_f32_16x16x32_bf16 v[112:115], v[152:155], v[206:209], v[112:115]
	v_mfma_f32_16x16x32_bf16 v[112:115], v[148:151], v[202:205], v[112:115]
	v_mfma_f32_16x16x32_bf16 v[92:95], v[148:151], v[210:213], v[92:95]
	v_mfma_f32_16x16x32_bf16 v[92:95], v[152:155], v[214:217], v[92:95]
	v_mfma_f32_16x16x32_bf16 v[68:71], v[152:155], v[222:225], v[68:71]
	v_mfma_f32_16x16x32_bf16 v[68:71], v[148:151], v[218:221], v[68:71]
	v_mfma_f32_16x16x32_bf16 v[64:67], v[176:179], v[218:221], v[64:67]
	v_mfma_f32_16x16x32_bf16 v[64:67], v[190:193], v[222:225], v[64:67]
	v_mfma_f32_16x16x32_bf16 v[84:87], v[190:193], v[214:217], v[84:87]
	v_mfma_f32_16x16x32_bf16 v[84:87], v[176:179], v[210:213], v[84:87]
	v_mfma_f32_16x16x32_bf16 v[104:107], v[176:179], v[202:205], v[104:107]
	v_mfma_f32_16x16x32_bf16 v[104:107], v[190:193], v[206:209], v[104:107]
	v_mfma_f32_16x16x32_bf16 v[124:127], v[190:193], v[198:201], v[124:127]
	v_mfma_f32_16x16x32_bf16 v[124:127], v[176:179], v[194:197], v[124:127]
	s_setprio 0
	s_barrier
	s_add_i32 s68, s96, s71
	v_lshl_add_u64 v[74:75], v[226:227], 0, s[28:29]
	s_mov_b32 m0, s68
	ds_read_b128 v[194:197], v187 offset:49152
	v_xor_b32_e32 v253, 64, v187
	ds_read_b128 v[198:201], v253 offset:49152
	ds_read_b128 v[202:205], v187 offset:51200
	ds_read_b128 v[206:209], v253 offset:51200
	ds_read_b128 v[210:213], v187 offset:53248
	ds_read_b128 v[214:217], v253 offset:53248
	ds_read_b128 v[218:221], v187 offset:55296
	ds_read_b128 v[222:225], v253 offset:55296
	global_load_lds_dwordx4 v[74:75], off
	s_add_i32 m0, s68, 0x2000
	s_add_u32 s66, s66, 0x40080
	v_lshl_add_u64 v[74:75], v[228:229], 0, s[28:29]
	s_addc_u32 s67, s67, 0
	s_add_i32 s68, s97, s71
	global_load_lds_dwordx4 v[74:75], off
	v_lshl_add_u64 v[74:75], s[66:67], 0, v[162:163]
	s_mov_b32 m0, s68
	s_nop 0
	global_load_lds_dwordx4 v[74:75], off
	v_lshl_add_u64 v[74:75], s[66:67], 0, v[166:167]
	s_add_i32 m0, s68, 0x2000
	s_nop 0
	global_load_lds_dwordx4 v[74:75], off
	v_lshl_add_u64 v[74:75], v[230:231], 0, s[28:29]
	s_mov_b32 m0, s78
	s_nop 0
	global_load_lds_dwordx4 v[74:75], off
	v_lshl_add_u64 v[74:75], v[232:233], 0, s[28:29]
	s_mov_b32 m0, s79
	s_nop 0
	global_load_lds_dwordx4 v[74:75], off
	s_waitcnt vmcnt(8)
	s_waitcnt lgkmcnt(0)
	s_barrier
	s_setprio 1
	s_waitcnt lgkmcnt(0)
	v_mfma_f32_16x16x32_bf16 v[60:63], v[88:91], v[194:197], v[60:63]
	v_mfma_f32_16x16x32_bf16 v[60:63], v[108:111], v[198:201], v[60:63]
	v_mfma_f32_16x16x32_bf16 v[44:47], v[108:111], v[206:209], v[44:47]
	v_mfma_f32_16x16x32_bf16 v[44:47], v[88:91], v[202:205], v[44:47]
	v_mfma_f32_16x16x32_bf16 v[28:31], v[88:91], v[210:213], v[28:31]
	v_mfma_f32_16x16x32_bf16 v[28:31], v[108:111], v[214:217], v[28:31]
	v_mfma_f32_16x16x32_bf16 v[12:15], v[108:111], v[222:225], v[12:15]
	v_mfma_f32_16x16x32_bf16 v[12:15], v[88:91], v[218:221], v[12:15]
	v_mfma_f32_16x16x32_bf16 v[8:11], v[128:131], v[218:221], v[8:11]
	v_mfma_f32_16x16x32_bf16 v[8:11], v[144:147], v[222:225], v[8:11]
	v_mfma_f32_16x16x32_bf16 v[24:27], v[144:147], v[214:217], v[24:27]
	v_mfma_f32_16x16x32_bf16 v[24:27], v[128:131], v[210:213], v[24:27]
	v_mfma_f32_16x16x32_bf16 v[40:43], v[128:131], v[202:205], v[40:43]
	v_mfma_f32_16x16x32_bf16 v[40:43], v[144:147], v[206:209], v[40:43]
	v_mfma_f32_16x16x32_bf16 v[56:59], v[144:147], v[198:201], v[56:59]
	v_mfma_f32_16x16x32_bf16 v[56:59], v[128:131], v[194:197], v[56:59]
	s_setprio 0
	s_setprio 1
	v_mfma_f32_16x16x32_bf16 v[52:55], v[148:151], v[194:197], v[52:55]
	v_mfma_f32_16x16x32_bf16 v[52:55], v[152:155], v[198:201], v[52:55]
	v_mfma_f32_16x16x32_bf16 v[36:39], v[152:155], v[206:209], v[36:39]
	v_mfma_f32_16x16x32_bf16 v[36:39], v[148:151], v[202:205], v[36:39]
	v_mfma_f32_16x16x32_bf16 v[20:23], v[148:151], v[210:213], v[20:23]
	v_mfma_f32_16x16x32_bf16 v[20:23], v[152:155], v[214:217], v[20:23]
	v_mfma_f32_16x16x32_bf16 v[4:7], v[152:155], v[222:225], v[4:7]
	v_mfma_f32_16x16x32_bf16 v[4:7], v[148:151], v[218:221], v[4:7]
	v_mfma_f32_16x16x32_bf16 v[0:3], v[176:179], v[218:221], v[0:3]
	v_mfma_f32_16x16x32_bf16 v[0:3], v[190:193], v[222:225], v[0:3]
	v_mfma_f32_16x16x32_bf16 v[16:19], v[190:193], v[214:217], v[16:19]
	v_mfma_f32_16x16x32_bf16 v[16:19], v[176:179], v[210:213], v[16:19]
	v_mfma_f32_16x16x32_bf16 v[32:35], v[176:179], v[202:205], v[32:35]
	v_mfma_f32_16x16x32_bf16 v[32:35], v[190:193], v[206:209], v[32:35]
	v_mfma_f32_16x16x32_bf16 v[48:51], v[190:193], v[198:201], v[48:51]
	v_mfma_f32_16x16x32_bf16 v[48:51], v[176:179], v[194:197], v[48:51]
	s_setprio 0
	s_barrier
	s_add_i32 s95, s95, 2
	s_add_u32 s93, s93, 0x100
	s_addc_u32 s94, s94, 0
	s_add_u32 s14, s14, 0x100
	s_addc_u32 s15, s15, 0
	s_branch .LBB0_256
.LBB0_255:
	v_add_u32_e32 v74, s83, v181
	ds_read_b128 v[88:91], v74
	v_xor_b32_e32 v253, 64, v74
	ds_read_b128 v[108:111], v253
	ds_read_b128 v[128:131], v74 offset:2048
	ds_read_b128 v[144:147], v253 offset:2048
	v_add_u32_e32 v74, s84, v181
	ds_read_b128 v[148:151], v74
	v_xor_b32_e32 v253, 64, v74
	ds_read_b128 v[152:155], v253
	ds_read_b128 v[176:179], v74 offset:2048
	ds_read_b128 v[190:193], v253 offset:2048
	s_add_u32 s68, s14, 0xfffc0080
	s_addc_u32 s69, s15, -1
	s_and_b64 s[66:67], s[66:67], exec
	s_cselect_b32 s69, s3, s69
	s_cselect_b32 s68, s61, s68
	s_cselect_b32 s67, s91, s94
	s_cselect_b32 s66, s92, s93
	v_lshl_add_u64 v[74:75], s[14:15], 0, v[170:171]
	s_add_i32 m0, s74, 0xc000
	ds_read_b128 v[194:197], v187
	v_xor_b32_e32 v253, 64, v187
	ds_read_b128 v[198:201], v253
	ds_read_b128 v[202:205], v187 offset:2048
	ds_read_b128 v[206:209], v253 offset:2048
	ds_read_b128 v[210:213], v187 offset:4096
	ds_read_b128 v[214:217], v253 offset:4096
	ds_read_b128 v[218:221], v187 offset:6144
	ds_read_b128 v[222:225], v253 offset:6144
	global_load_lds_dwordx4 v[74:75], off
	v_lshl_add_u64 v[74:75], s[14:15], 0, v[168:169]
	s_add_i32 m0, s74, 0xe000
	s_nop 0
	global_load_lds_dwordx4 v[74:75], off
	s_waitcnt vmcnt(8)
	s_waitcnt lgkmcnt(0)
	s_barrier
	s_setprio 1
	s_waitcnt lgkmcnt(0)
	v_mfma_f32_16x16x32_bf16 v[140:143], v[88:91], v[194:197], v[140:143]
	v_mfma_f32_16x16x32_bf16 v[136:139], v[128:131], v[194:197], v[136:139]
	v_mfma_f32_16x16x32_bf16 v[120:123], v[88:91], v[202:205], v[120:123]
	v_mfma_f32_16x16x32_bf16 v[116:119], v[128:131], v[202:205], v[116:119]
	v_mfma_f32_16x16x32_bf16 v[100:103], v[88:91], v[210:213], v[100:103]
	v_mfma_f32_16x16x32_bf16 v[96:99], v[128:131], v[210:213], v[96:99]
	v_mfma_f32_16x16x32_bf16 v[80:83], v[88:91], v[218:221], v[80:83]
	v_mfma_f32_16x16x32_bf16 v[74:77], v[128:131], v[218:221], v[76:79]
	v_mfma_f32_16x16x32_bf16 v[140:143], v[108:111], v[198:201], v[140:143]
	v_mfma_f32_16x16x32_bf16 v[136:139], v[144:147], v[198:201], v[136:139]
	v_mfma_f32_16x16x32_bf16 v[120:123], v[108:111], v[206:209], v[120:123]
	v_mfma_f32_16x16x32_bf16 v[116:119], v[144:147], v[206:209], v[116:119]
	v_mfma_f32_16x16x32_bf16 v[100:103], v[108:111], v[214:217], v[100:103]
	v_mfma_f32_16x16x32_bf16 v[96:99], v[144:147], v[214:217], v[96:99]
	v_mfma_f32_16x16x32_bf16 v[80:83], v[108:111], v[222:225], v[80:83]
	v_mfma_f32_16x16x32_bf16 v[74:77], v[144:147], v[222:225], v[74:77]
	s_setprio 0
	s_setprio 1
	v_mfma_f32_16x16x32_bf16 v[132:135], v[148:151], v[194:197], v[132:135]
	v_mfma_f32_16x16x32_bf16 v[132:135], v[152:155], v[198:201], v[132:135]
	v_mfma_f32_16x16x32_bf16 v[112:115], v[152:155], v[206:209], v[112:115]
	v_mfma_f32_16x16x32_bf16 v[112:115], v[148:151], v[202:205], v[112:115]
	v_mfma_f32_16x16x32_bf16 v[92:95], v[148:151], v[210:213], v[92:95]
	v_mfma_f32_16x16x32_bf16 v[92:95], v[152:155], v[214:217], v[92:95]
	v_mfma_f32_16x16x32_bf16 v[68:71], v[152:155], v[222:225], v[68:71]
	v_mfma_f32_16x16x32_bf16 v[68:71], v[148:151], v[218:221], v[68:71]
	v_mfma_f32_16x16x32_bf16 v[64:67], v[176:179], v[218:221], v[64:67]
	v_mfma_f32_16x16x32_bf16 v[64:67], v[190:193], v[222:225], v[64:67]
	v_mfma_f32_16x16x32_bf16 v[84:87], v[190:193], v[214:217], v[84:87]
	v_mfma_f32_16x16x32_bf16 v[84:87], v[176:179], v[210:213], v[84:87]
	v_mfma_f32_16x16x32_bf16 v[104:107], v[176:179], v[202:205], v[104:107]
	v_mfma_f32_16x16x32_bf16 v[104:107], v[190:193], v[206:209], v[104:107]
	v_mfma_f32_16x16x32_bf16 v[124:127], v[190:193], v[198:201], v[124:127]
	v_mfma_f32_16x16x32_bf16 v[124:127], v[176:179], v[194:197], v[124:127]
	s_setprio 0
	s_barrier
	s_add_i32 s96, s83, s71
	v_lshl_add_u64 v[226:227], s[66:67], 0, v[162:163]
	s_mov_b32 m0, s96
	ds_read_b128 v[194:197], v187 offset:16384
	v_xor_b32_e32 v253, 64, v187
	ds_read_b128 v[198:201], v253 offset:16384
	ds_read_b128 v[202:205], v187 offset:18432
	ds_read_b128 v[206:209], v253 offset:18432
	ds_read_b128 v[210:213], v187 offset:20480
	ds_read_b128 v[214:217], v253 offset:20480
	ds_read_b128 v[218:221], v187 offset:22528
	ds_read_b128 v[222:225], v253 offset:22528
	global_load_lds_dwordx4 v[226:227], off
	s_add_i32 m0, s96, 0x2000
	s_add_u32 s96, s66, 0x40000
	v_lshl_add_u64 v[228:229], s[66:67], 0, v[166:167]
	s_addc_u32 s97, s67, 0
	s_add_i32 vcc_lo, s84, s71
	global_load_lds_dwordx4 v[228:229], off
	v_lshl_add_u64 v[78:79], s[96:97], 0, v[162:163]
	s_mov_b32 m0, vcc_lo
	v_lshl_add_u64 v[230:231], s[68:69], 0, v[160:161]
	global_load_lds_dwordx4 v[78:79], off
	v_lshl_add_u64 v[78:79], s[96:97], 0, v[166:167]
	s_add_i32 m0, vcc_lo, 0x2000
	v_lshl_add_u64 v[232:233], s[68:69], 0, v[164:165]
	global_load_lds_dwordx4 v[78:79], off
	s_mov_b32 m0, s74
	s_nop 0
	global_load_lds_dwordx4 v[230:231], off
	s_mov_b32 m0, s75
	s_nop 0
	global_load_lds_dwordx4 v[232:233], off
	s_waitcnt vmcnt(8)
	s_waitcnt lgkmcnt(0)
	s_barrier
	s_setprio 1
	s_waitcnt lgkmcnt(0)
	v_mfma_f32_16x16x32_bf16 v[60:63], v[88:91], v[194:197], v[60:63]
	v_mfma_f32_16x16x32_bf16 v[60:63], v[108:111], v[198:201], v[60:63]
	v_mfma_f32_16x16x32_bf16 v[44:47], v[108:111], v[206:209], v[44:47]
	v_mfma_f32_16x16x32_bf16 v[44:47], v[88:91], v[202:205], v[44:47]
	v_mfma_f32_16x16x32_bf16 v[28:31], v[88:91], v[210:213], v[28:31]
	v_mfma_f32_16x16x32_bf16 v[28:31], v[108:111], v[214:217], v[28:31]
	v_mfma_f32_16x16x32_bf16 v[12:15], v[108:111], v[222:225], v[12:15]
	v_mfma_f32_16x16x32_bf16 v[12:15], v[88:91], v[218:221], v[12:15]
	v_mfma_f32_16x16x32_bf16 v[8:11], v[128:131], v[218:221], v[8:11]
	v_mfma_f32_16x16x32_bf16 v[8:11], v[144:147], v[222:225], v[8:11]
	v_mfma_f32_16x16x32_bf16 v[24:27], v[144:147], v[214:217], v[24:27]
	v_mfma_f32_16x16x32_bf16 v[24:27], v[128:131], v[210:213], v[24:27]
	v_mfma_f32_16x16x32_bf16 v[40:43], v[128:131], v[202:205], v[40:43]
	v_mfma_f32_16x16x32_bf16 v[40:43], v[144:147], v[206:209], v[40:43]
	v_mfma_f32_16x16x32_bf16 v[56:59], v[144:147], v[198:201], v[56:59]
	v_mfma_f32_16x16x32_bf16 v[56:59], v[128:131], v[194:197], v[56:59]
	s_setprio 0
	s_setprio 1
	v_mfma_f32_16x16x32_bf16 v[52:55], v[148:151], v[194:197], v[52:55]
	v_mfma_f32_16x16x32_bf16 v[52:55], v[152:155], v[198:201], v[52:55]
	v_mfma_f32_16x16x32_bf16 v[36:39], v[152:155], v[206:209], v[36:39]
	v_mfma_f32_16x16x32_bf16 v[36:39], v[148:151], v[202:205], v[36:39]
	v_mfma_f32_16x16x32_bf16 v[20:23], v[148:151], v[210:213], v[20:23]
	v_mfma_f32_16x16x32_bf16 v[20:23], v[152:155], v[214:217], v[20:23]
	v_mfma_f32_16x16x32_bf16 v[4:7], v[152:155], v[222:225], v[4:7]
	v_mfma_f32_16x16x32_bf16 v[4:7], v[148:151], v[218:221], v[4:7]
	v_mfma_f32_16x16x32_bf16 v[0:3], v[176:179], v[218:221], v[0:3]
	v_mfma_f32_16x16x32_bf16 v[0:3], v[190:193], v[222:225], v[0:3]
	v_mfma_f32_16x16x32_bf16 v[16:19], v[190:193], v[214:217], v[16:19]
	v_mfma_f32_16x16x32_bf16 v[16:19], v[176:179], v[210:213], v[16:19]
	v_mfma_f32_16x16x32_bf16 v[32:35], v[176:179], v[202:205], v[32:35]
	v_mfma_f32_16x16x32_bf16 v[32:35], v[190:193], v[206:209], v[32:35]
	v_mfma_f32_16x16x32_bf16 v[48:51], v[190:193], v[198:201], v[48:51]
	v_mfma_f32_16x16x32_bf16 v[48:51], v[176:179], v[194:197], v[48:51]
	s_setprio 0
	s_barrier
	s_add_i32 s96, 0, 0x18000
	v_add_u32_e32 v78, s96, v181
	s_add_i32 s97, 0, 0x1c000
	ds_read_b128 v[88:91], v78
	v_xor_b32_e32 v253, 64, v78
	ds_read_b128 v[108:111], v253
	ds_read_b128 v[128:131], v78 offset:2048
	ds_read_b128 v[144:147], v253 offset:2048
	v_add_u32_e32 v78, s97, v181
	ds_read_b128 v[148:151], v78
	v_xor_b32_e32 v253, 64, v78
	ds_read_b128 v[152:155], v253
	ds_read_b128 v[176:179], v78 offset:2048
	ds_read_b128 v[190:193], v253 offset:2048
	s_add_u32 s68, s68, 0x40000
	s_addc_u32 s69, s69, 0
	s_mov_b32 m0, s76
	v_lshl_add_u64 v[78:79], s[68:69], 0, v[160:161]
	ds_read_b128 v[194:197], v187 offset:32768
	v_xor_b32_e32 v253, 64, v187
	ds_read_b128 v[198:201], v253 offset:32768
	ds_read_b128 v[202:205], v187 offset:34816
	ds_read_b128 v[206:209], v253 offset:34816
	ds_read_b128 v[210:213], v187 offset:36864
	ds_read_b128 v[214:217], v253 offset:36864
	ds_read_b128 v[218:221], v187 offset:38912
	ds_read_b128 v[222:225], v253 offset:38912
	global_load_lds_dwordx4 v[78:79], off
	v_lshl_add_u64 v[78:79], s[68:69], 0, v[164:165]
	s_mov_b32 m0, s77
	s_nop 0
	global_load_lds_dwordx4 v[78:79], off
	s_waitcnt vmcnt(8)
	s_waitcnt lgkmcnt(0)
	s_barrier
	s_setprio 1
	s_waitcnt lgkmcnt(0)
	v_mfma_f32_16x16x32_bf16 v[140:143], v[88:91], v[194:197], v[140:143]
	v_mfma_f32_16x16x32_bf16 v[136:139], v[128:131], v[194:197], v[136:139]
	v_mfma_f32_16x16x32_bf16 v[120:123], v[88:91], v[202:205], v[120:123]
	v_mfma_f32_16x16x32_bf16 v[116:119], v[128:131], v[202:205], v[116:119]
	v_mfma_f32_16x16x32_bf16 v[100:103], v[88:91], v[210:213], v[100:103]
	v_mfma_f32_16x16x32_bf16 v[96:99], v[128:131], v[210:213], v[96:99]
	v_mfma_f32_16x16x32_bf16 v[78:81], v[88:91], v[218:221], v[80:83]
	v_mfma_f32_16x16x32_bf16 v[74:77], v[128:131], v[218:221], v[74:77]
	v_mfma_f32_16x16x32_bf16 v[140:143], v[108:111], v[198:201], v[140:143]
	v_mfma_f32_16x16x32_bf16 v[136:139], v[144:147], v[198:201], v[136:139]
	v_mfma_f32_16x16x32_bf16 v[120:123], v[108:111], v[206:209], v[120:123]
	v_mfma_f32_16x16x32_bf16 v[116:119], v[144:147], v[206:209], v[116:119]
	v_mfma_f32_16x16x32_bf16 v[100:103], v[108:111], v[214:217], v[100:103]
	v_mfma_f32_16x16x32_bf16 v[96:99], v[144:147], v[214:217], v[96:99]
	v_mfma_f32_16x16x32_bf16 v[80:83], v[108:111], v[222:225], v[78:81]
	v_mfma_f32_16x16x32_bf16 v[76:79], v[144:147], v[222:225], v[74:77]
	s_setprio 0
	s_setprio 1
	v_mfma_f32_16x16x32_bf16 v[132:135], v[148:151], v[194:197], v[132:135]
	v_mfma_f32_16x16x32_bf16 v[132:135], v[152:155], v[198:201], v[132:135]
	v_mfma_f32_16x16x32_bf16 v[112:115], v[152:155], v[206:209], v[112:115]
	v_mfma_f32_16x16x32_bf16 v[112:115], v[148:151], v[202:205], v[112:115]
	v_mfma_f32_16x16x32_bf16 v[92:95], v[148:151], v[210:213], v[92:95]
	v_mfma_f32_16x16x32_bf16 v[92:95], v[152:155], v[214:217], v[92:95]
	v_mfma_f32_16x16x32_bf16 v[68:71], v[152:155], v[222:225], v[68:71]
	v_mfma_f32_16x16x32_bf16 v[68:71], v[148:151], v[218:221], v[68:71]
	v_mfma_f32_16x16x32_bf16 v[64:67], v[176:179], v[218:221], v[64:67]
	v_mfma_f32_16x16x32_bf16 v[64:67], v[190:193], v[222:225], v[64:67]
	v_mfma_f32_16x16x32_bf16 v[84:87], v[190:193], v[214:217], v[84:87]
	v_mfma_f32_16x16x32_bf16 v[84:87], v[176:179], v[210:213], v[84:87]
	v_mfma_f32_16x16x32_bf16 v[104:107], v[176:179], v[202:205], v[104:107]
	v_mfma_f32_16x16x32_bf16 v[104:107], v[190:193], v[206:209], v[104:107]
	v_mfma_f32_16x16x32_bf16 v[124:127], v[190:193], v[198:201], v[124:127]
	v_mfma_f32_16x16x32_bf16 v[124:127], v[176:179], v[194:197], v[124:127]
	s_setprio 0
	s_barrier
	s_add_i32 s68, s96, s71
	v_lshl_add_u64 v[74:75], v[226:227], 0, s[28:29]
	s_mov_b32 m0, s68
	ds_read_b128 v[194:197], v187 offset:49152
	v_xor_b32_e32 v253, 64, v187
	ds_read_b128 v[198:201], v253 offset:49152
	ds_read_b128 v[202:205], v187 offset:51200
	ds_read_b128 v[206:209], v253 offset:51200
	ds_read_b128 v[210:213], v187 offset:53248
	ds_read_b128 v[214:217], v253 offset:53248
	ds_read_b128 v[218:221], v187 offset:55296
	ds_read_b128 v[222:225], v253 offset:55296
	global_load_lds_dwordx4 v[74:75], off
	s_add_i32 m0, s68, 0x2000
	s_add_u32 s66, s66, 0x40080
	v_lshl_add_u64 v[74:75], v[228:229], 0, s[28:29]
	s_addc_u32 s67, s67, 0
	s_add_i32 s68, s97, s71
	global_load_lds_dwordx4 v[74:75], off
	v_lshl_add_u64 v[74:75], s[66:67], 0, v[162:163]
	s_mov_b32 m0, s68
	s_nop 0
	global_load_lds_dwordx4 v[74:75], off
	v_lshl_add_u64 v[74:75], s[66:67], 0, v[166:167]
	s_add_i32 m0, s68, 0x2000
	s_nop 0
	global_load_lds_dwordx4 v[74:75], off
	v_lshl_add_u64 v[74:75], v[230:231], 0, s[28:29]
	s_mov_b32 m0, s78
	s_nop 0
	global_load_lds_dwordx4 v[74:75], off
	v_lshl_add_u64 v[74:75], v[232:233], 0, s[28:29]
	s_mov_b32 m0, s79
	s_nop 0
	global_load_lds_dwordx4 v[74:75], off
	s_waitcnt vmcnt(8)
	s_waitcnt lgkmcnt(0)
	s_barrier
	s_setprio 1
	s_waitcnt lgkmcnt(0)
	v_mfma_f32_16x16x32_bf16 v[60:63], v[88:91], v[194:197], v[60:63]
	v_mfma_f32_16x16x32_bf16 v[60:63], v[108:111], v[198:201], v[60:63]
	v_mfma_f32_16x16x32_bf16 v[44:47], v[108:111], v[206:209], v[44:47]
	v_mfma_f32_16x16x32_bf16 v[44:47], v[88:91], v[202:205], v[44:47]
	v_mfma_f32_16x16x32_bf16 v[28:31], v[88:91], v[210:213], v[28:31]
	v_mfma_f32_16x16x32_bf16 v[28:31], v[108:111], v[214:217], v[28:31]
	v_mfma_f32_16x16x32_bf16 v[12:15], v[108:111], v[222:225], v[12:15]
	v_mfma_f32_16x16x32_bf16 v[12:15], v[88:91], v[218:221], v[12:15]
	v_mfma_f32_16x16x32_bf16 v[8:11], v[128:131], v[218:221], v[8:11]
	v_mfma_f32_16x16x32_bf16 v[8:11], v[144:147], v[222:225], v[8:11]
	v_mfma_f32_16x16x32_bf16 v[24:27], v[144:147], v[214:217], v[24:27]
	v_mfma_f32_16x16x32_bf16 v[24:27], v[128:131], v[210:213], v[24:27]
	v_mfma_f32_16x16x32_bf16 v[40:43], v[128:131], v[202:205], v[40:43]
	v_mfma_f32_16x16x32_bf16 v[40:43], v[144:147], v[206:209], v[40:43]
	v_mfma_f32_16x16x32_bf16 v[56:59], v[144:147], v[198:201], v[56:59]
	v_mfma_f32_16x16x32_bf16 v[56:59], v[128:131], v[194:197], v[56:59]
	s_setprio 0
	s_setprio 1
	v_mfma_f32_16x16x32_bf16 v[52:55], v[148:151], v[194:197], v[52:55]
	v_mfma_f32_16x16x32_bf16 v[52:55], v[152:155], v[198:201], v[52:55]
	v_mfma_f32_16x16x32_bf16 v[36:39], v[152:155], v[206:209], v[36:39]
	v_mfma_f32_16x16x32_bf16 v[36:39], v[148:151], v[202:205], v[36:39]
	v_mfma_f32_16x16x32_bf16 v[20:23], v[148:151], v[210:213], v[20:23]
	v_mfma_f32_16x16x32_bf16 v[20:23], v[152:155], v[214:217], v[20:23]
	v_mfma_f32_16x16x32_bf16 v[4:7], v[152:155], v[222:225], v[4:7]
	v_mfma_f32_16x16x32_bf16 v[4:7], v[148:151], v[218:221], v[4:7]
	v_mfma_f32_16x16x32_bf16 v[0:3], v[176:179], v[218:221], v[0:3]
	v_mfma_f32_16x16x32_bf16 v[0:3], v[190:193], v[222:225], v[0:3]
	v_mfma_f32_16x16x32_bf16 v[16:19], v[190:193], v[214:217], v[16:19]
	v_mfma_f32_16x16x32_bf16 v[16:19], v[176:179], v[210:213], v[16:19]
	v_mfma_f32_16x16x32_bf16 v[32:35], v[176:179], v[202:205], v[32:35]
	v_mfma_f32_16x16x32_bf16 v[32:35], v[190:193], v[206:209], v[32:35]
	v_mfma_f32_16x16x32_bf16 v[48:51], v[190:193], v[198:201], v[48:51]
	v_mfma_f32_16x16x32_bf16 v[48:51], v[176:179], v[194:197], v[48:51]
	s_setprio 0
	s_barrier
	s_add_i32 s95, s95, 2
	s_add_u32 s93, s93, 0x100
	s_addc_u32 s94, s94, 0
	s_add_u32 s14, s14, 0x100
	s_addc_u32 s15, s15, 0
	s_cmp_gt_u32 s95, 13
	s_cbranch_scc1 .LBB0_258

.LBB0_439:
	s_ashr_i32 s53, s52, 31
	s_lshl_b64 s[54:55], s[52:53], 20
	s_add_u32 s54, s35, s54
	s_addc_u32 s55, s66, s55
	s_and_b64 s[56:57], s[12:13], exec
	s_cselect_b32 s15, s55, s63
	s_cselect_b32 s53, s54, s62
	s_ashr_i32 s51, s50, 31
	s_lshl_b64 s[56:57], s[50:51], 20
	s_add_u32 s56, s67, s56
	s_addc_u32 s57, s68, s57
	s_and_b64 s[64:65], s[12:13], exec
	s_cselect_b32 s51, s57, s61
	s_cselect_b32 s59, s56, s60
	s_add_u32 s81, s60, 0x100
	s_addc_u32 s82, s61, 0
	s_add_u32 s60, s62, 0x80080
	s_addc_u32 s61, s63, 0
	s_mov_b32 s83, -2
	s_waitcnt lgkmcnt(0)
	s_cmp_eq_u32 s74, 1
	s_cbranch_scc1 .Lfa_3
	ds_read_b128 v[128:131], v189
	v_xor_b32_e32 v253, 64, v189
	ds_read_b128 v[132:135], v253
	ds_read_b128 v[136:139], v189 offset:2048
	ds_read_b128 v[140:143], v253 offset:2048
	ds_read_b128 v[144:147], v190
	v_xor_b32_e32 v253, 64, v190
	ds_read_b128 v[148:151], v253
	ds_read_b128 v[172:175], v190 offset:2048
	ds_read_b128 v[176:179], v253 offset:2048
	s_add_u32 s62, s60, 0xfff80080
	s_addc_u32 s63, s61, -1
	s_cmp_eq_u32 s83, 28
	s_cselect_b32 s65, s15, s63
	s_cselect_b32 s64, s53, s62
	s_cselect_b32 s63, s51, s82
	s_cselect_b32 s62, s59, s81
	v_lshl_add_u64 v[222:223], s[60:61], 0, v[166:167]
	s_add_i32 m0, s70, 0xc000
	ds_read_b128 v[180:183], v191
	v_xor_b32_e32 v253, 64, v191
	ds_read_b128 v[194:197], v253
	ds_read_b128 v[198:201], v191 offset:2048
	ds_read_b128 v[202:205], v253 offset:2048
	ds_read_b128 v[206:209], v191 offset:4096
	ds_read_b128 v[210:213], v253 offset:4096
	ds_read_b128 v[214:217], v191 offset:6144
	ds_read_b128 v[218:221], v253 offset:6144
	global_load_lds_dwordx4 v[222:223], off
	v_lshl_add_u64 v[222:223], s[60:61], 0, v[164:165]
	s_add_i32 m0, s70, 0xe000
	s_nop 0
	global_load_lds_dwordx4 v[222:223], off
	s_waitcnt vmcnt(24)
	s_waitcnt lgkmcnt(0)
	s_barrier
	s_setprio 1
	s_waitcnt lgkmcnt(0)
	v_mfma_f32_16x16x32_bf16 v[124:127], v[128:131], v[180:183], 0
	v_mfma_f32_16x16x32_bf16 v[120:123], v[136:139], v[180:183], 0
	v_mfma_f32_16x16x32_bf16 v[108:111], v[128:131], v[198:201], 0
	v_mfma_f32_16x16x32_bf16 v[104:107], v[136:139], v[198:201], 0
	v_mfma_f32_16x16x32_bf16 v[92:95], v[128:131], v[206:209], 0
	v_mfma_f32_16x16x32_bf16 v[88:91], v[136:139], v[206:209], 0
	v_mfma_f32_16x16x32_bf16 v[76:79], v[128:131], v[214:217], 0
	v_mfma_f32_16x16x32_bf16 v[72:75], v[136:139], v[214:217], 0
	v_mfma_f32_16x16x32_bf16 v[124:127], v[132:135], v[194:197], v[124:127]
	v_mfma_f32_16x16x32_bf16 v[120:123], v[140:143], v[194:197], v[120:123]
	v_mfma_f32_16x16x32_bf16 v[108:111], v[132:135], v[202:205], v[108:111]
	v_mfma_f32_16x16x32_bf16 v[104:107], v[140:143], v[202:205], v[104:107]
	v_mfma_f32_16x16x32_bf16 v[92:95], v[132:135], v[210:213], v[92:95]
	v_mfma_f32_16x16x32_bf16 v[88:91], v[140:143], v[210:213], v[88:91]
	v_mfma_f32_16x16x32_bf16 v[76:79], v[132:135], v[218:221], v[76:79]
	v_mfma_f32_16x16x32_bf16 v[72:75], v[140:143], v[218:221], v[72:75]
	s_setprio 0
	s_setprio 1
	v_mfma_f32_16x16x32_bf16 v[116:119], v[144:147], v[180:183], 0
	v_mfma_f32_16x16x32_bf16 v[112:115], v[172:175], v[180:183], 0
	v_mfma_f32_16x16x32_bf16 v[100:103], v[144:147], v[198:201], 0
	v_mfma_f32_16x16x32_bf16 v[96:99], v[172:175], v[198:201], 0
	v_mfma_f32_16x16x32_bf16 v[84:87], v[144:147], v[206:209], 0
	v_mfma_f32_16x16x32_bf16 v[80:83], v[172:175], v[206:209], 0
	v_mfma_f32_16x16x32_bf16 v[68:71], v[144:147], v[214:217], 0
	v_mfma_f32_16x16x32_bf16 v[64:67], v[172:175], v[214:217], 0
	v_mfma_f32_16x16x32_bf16 v[116:119], v[148:151], v[194:197], v[116:119]
	v_mfma_f32_16x16x32_bf16 v[112:115], v[176:179], v[194:197], v[112:115]
	v_mfma_f32_16x16x32_bf16 v[100:103], v[148:151], v[202:205], v[100:103]
	v_mfma_f32_16x16x32_bf16 v[96:99], v[176:179], v[202:205], v[96:99]
	v_mfma_f32_16x16x32_bf16 v[84:87], v[148:151], v[210:213], v[84:87]
	v_mfma_f32_16x16x32_bf16 v[80:83], v[176:179], v[210:213], v[80:83]
	v_mfma_f32_16x16x32_bf16 v[68:71], v[148:151], v[218:221], v[68:71]
	v_mfma_f32_16x16x32_bf16 v[64:67], v[176:179], v[218:221], v[64:67]
	s_setprio 0
	s_barrier
	s_add_i32 s84, s79, s69
	v_lshl_add_u64 v[222:223], s[62:63], 0, v[154:155]
	s_mov_b32 m0, s84
	ds_read_b128 v[180:183], v191 offset:16384
	v_xor_b32_e32 v253, 64, v191
	ds_read_b128 v[194:197], v253 offset:16384
	ds_read_b128 v[198:201], v191 offset:18432
	ds_read_b128 v[202:205], v253 offset:18432
	ds_read_b128 v[206:209], v191 offset:20480
	ds_read_b128 v[210:213], v253 offset:20480
	ds_read_b128 v[214:217], v191 offset:22528
	ds_read_b128 v[218:221], v253 offset:22528
	global_load_lds_dwordx4 v[222:223], off
	s_add_i32 m0, s84, 0x2000
	s_add_u32 s84, s62, 0x80000
	v_lshl_add_u64 v[224:225], s[62:63], 0, v[162:163]
	s_addc_u32 s85, s63, 0
	s_add_i32 s86, s80, s69
	global_load_lds_dwordx4 v[224:225], off
	v_lshl_add_u64 v[226:227], s[84:85], 0, v[154:155]
	s_mov_b32 m0, s86
	v_lshl_add_u64 v[228:229], s[64:65], 0, v[160:161]
	global_load_lds_dwordx4 v[226:227], off
	v_lshl_add_u64 v[226:227], s[84:85], 0, v[162:163]
	s_add_i32 m0, s86, 0x2000
	s_nop 0
	global_load_lds_dwordx4 v[226:227], off
	v_lshl_add_u64 v[226:227], s[64:65], 0, v[152:153]
	s_mov_b32 m0, s70
	s_nop 0
	global_load_lds_dwordx4 v[226:227], off
	s_mov_b32 m0, s71
	s_nop 0
	global_load_lds_dwordx4 v[228:229], off
	s_waitcnt vmcnt(24)
	s_waitcnt lgkmcnt(0)
	s_barrier
	s_setprio 1
	s_waitcnt lgkmcnt(0)
	v_mfma_f32_16x16x32_bf16 v[60:63], v[128:131], v[180:183], 0
	v_mfma_f32_16x16x32_bf16 v[56:59], v[136:139], v[180:183], 0
	v_mfma_f32_16x16x32_bf16 v[44:47], v[128:131], v[198:201], 0
	v_mfma_f32_16x16x32_bf16 v[40:43], v[136:139], v[198:201], 0
	v_mfma_f32_16x16x32_bf16 v[28:31], v[128:131], v[206:209], 0
	v_mfma_f32_16x16x32_bf16 v[24:27], v[136:139], v[206:209], 0
	v_mfma_f32_16x16x32_bf16 v[12:15], v[128:131], v[214:217], 0
	v_mfma_f32_16x16x32_bf16 v[8:11], v[136:139], v[214:217], 0
	v_mfma_f32_16x16x32_bf16 v[60:63], v[132:135], v[194:197], v[60:63]
	v_mfma_f32_16x16x32_bf16 v[56:59], v[140:143], v[194:197], v[56:59]
	v_mfma_f32_16x16x32_bf16 v[44:47], v[132:135], v[202:205], v[44:47]
	v_mfma_f32_16x16x32_bf16 v[40:43], v[140:143], v[202:205], v[40:43]
	v_mfma_f32_16x16x32_bf16 v[28:31], v[132:135], v[210:213], v[28:31]
	v_mfma_f32_16x16x32_bf16 v[24:27], v[140:143], v[210:213], v[24:27]
	v_mfma_f32_16x16x32_bf16 v[12:15], v[132:135], v[218:221], v[12:15]
	v_mfma_f32_16x16x32_bf16 v[8:11], v[140:143], v[218:221], v[8:11]
	s_setprio 0
	s_setprio 1
	v_mfma_f32_16x16x32_bf16 v[52:55], v[144:147], v[180:183], 0
	v_mfma_f32_16x16x32_bf16 v[48:51], v[172:175], v[180:183], 0
	v_mfma_f32_16x16x32_bf16 v[36:39], v[144:147], v[198:201], 0
	v_mfma_f32_16x16x32_bf16 v[32:35], v[172:175], v[198:201], 0
	v_mfma_f32_16x16x32_bf16 v[20:23], v[144:147], v[206:209], 0
	v_mfma_f32_16x16x32_bf16 v[16:19], v[172:175], v[206:209], 0
	v_mfma_f32_16x16x32_bf16 v[4:7], v[144:147], v[214:217], 0
	v_mfma_f32_16x16x32_bf16 v[0:3], v[172:175], v[214:217], 0
	v_mfma_f32_16x16x32_bf16 v[52:55], v[148:151], v[194:197], v[52:55]
	v_mfma_f32_16x16x32_bf16 v[48:51], v[176:179], v[194:197], v[48:51]
	v_mfma_f32_16x16x32_bf16 v[36:39], v[148:151], v[202:205], v[36:39]
	v_mfma_f32_16x16x32_bf16 v[32:35], v[176:179], v[202:205], v[32:35]
	v_mfma_f32_16x16x32_bf16 v[20:23], v[148:151], v[210:213], v[20:23]
	v_mfma_f32_16x16x32_bf16 v[16:19], v[176:179], v[210:213], v[16:19]
	v_mfma_f32_16x16x32_bf16 v[4:7], v[148:151], v[218:221], v[4:7]
	v_mfma_f32_16x16x32_bf16 v[0:3], v[176:179], v[218:221], v[0:3]
	s_setprio 0
	s_barrier
	s_add_i32 s84, 0, 0x18000
	s_add_i32 s85, 0, 0x1c000
	v_add_u32_e32 v140, s84, v186
	v_add_u32_e32 v176, s85, v186
	ds_read_b128 v[128:131], v140
	v_xor_b32_e32 v253, 64, v140
	ds_read_b128 v[132:135], v253
	ds_read_b128 v[136:139], v140 offset:2048
	ds_read_b128 v[140:143], v253 offset:2048
	ds_read_b128 v[144:147], v176
	v_xor_b32_e32 v253, 64, v176
	ds_read_b128 v[148:151], v253
	ds_read_b128 v[172:175], v176 offset:2048
	ds_read_b128 v[176:179], v253 offset:2048
	s_add_u32 s64, s64, 0x80000
	s_addc_u32 s65, s65, 0
	s_mov_b32 m0, s72
	v_lshl_add_u64 v[230:231], s[64:65], 0, v[152:153]
	ds_read_b128 v[180:183], v191 offset:32768
	v_xor_b32_e32 v253, 64, v191
	ds_read_b128 v[194:197], v253 offset:32768
	ds_read_b128 v[198:201], v191 offset:34816
	ds_read_b128 v[202:205], v253 offset:34816
	ds_read_b128 v[206:209], v191 offset:36864
	ds_read_b128 v[210:213], v253 offset:36864
	ds_read_b128 v[214:217], v191 offset:38912
	ds_read_b128 v[218:221], v253 offset:38912
	global_load_lds_dwordx4 v[230:231], off
	v_lshl_add_u64 v[230:231], s[64:65], 0, v[160:161]
	s_mov_b32 m0, s73
	s_nop 0
	global_load_lds_dwordx4 v[230:231], off
	s_waitcnt vmcnt(8)
	s_waitcnt lgkmcnt(0)
	s_barrier
	s_setprio 1
	s_waitcnt lgkmcnt(0)
	v_mfma_f32_16x16x32_bf16 v[124:127], v[128:131], v[180:183], v[124:127]
	v_mfma_f32_16x16x32_bf16 v[124:127], v[132:135], v[194:197], v[124:127]
	v_mfma_f32_16x16x32_bf16 v[108:111], v[132:135], v[202:205], v[108:111]
	v_mfma_f32_16x16x32_bf16 v[108:111], v[128:131], v[198:201], v[108:111]
	v_mfma_f32_16x16x32_bf16 v[92:95], v[128:131], v[206:209], v[92:95]
	v_mfma_f32_16x16x32_bf16 v[92:95], v[132:135], v[210:213], v[92:95]
	v_mfma_f32_16x16x32_bf16 v[76:79], v[132:135], v[218:221], v[76:79]
	v_mfma_f32_16x16x32_bf16 v[76:79], v[128:131], v[214:217], v[76:79]
	v_mfma_f32_16x16x32_bf16 v[72:75], v[136:139], v[214:217], v[72:75]
	v_mfma_f32_16x16x32_bf16 v[72:75], v[140:143], v[218:221], v[72:75]
	v_mfma_f32_16x16x32_bf16 v[88:91], v[140:143], v[210:213], v[88:91]
	v_mfma_f32_16x16x32_bf16 v[88:91], v[136:139], v[206:209], v[88:91]
	v_mfma_f32_16x16x32_bf16 v[104:107], v[136:139], v[198:201], v[104:107]
	v_mfma_f32_16x16x32_bf16 v[104:107], v[140:143], v[202:205], v[104:107]
	v_mfma_f32_16x16x32_bf16 v[120:123], v[140:143], v[194:197], v[120:123]
	v_mfma_f32_16x16x32_bf16 v[120:123], v[136:139], v[180:183], v[120:123]
	s_setprio 0
	s_setprio 1
	v_mfma_f32_16x16x32_bf16 v[116:119], v[144:147], v[180:183], v[116:119]
	v_mfma_f32_16x16x32_bf16 v[116:119], v[148:151], v[194:197], v[116:119]
	v_mfma_f32_16x16x32_bf16 v[100:103], v[148:151], v[202:205], v[100:103]
	v_mfma_f32_16x16x32_bf16 v[100:103], v[144:147], v[198:201], v[100:103]
	v_mfma_f32_16x16x32_bf16 v[84:87], v[144:147], v[206:209], v[84:87]
	v_mfma_f32_16x16x32_bf16 v[84:87], v[148:151], v[210:213], v[84:87]
	v_mfma_f32_16x16x32_bf16 v[68:71], v[148:151], v[218:221], v[68:71]
	v_mfma_f32_16x16x32_bf16 v[68:71], v[144:147], v[214:217], v[68:71]
	v_mfma_f32_16x16x32_bf16 v[64:67], v[172:175], v[214:217], v[64:67]
	v_mfma_f32_16x16x32_bf16 v[64:67], v[176:179], v[218:221], v[64:67]
	v_mfma_f32_16x16x32_bf16 v[80:83], v[176:179], v[210:213], v[80:83]
	v_mfma_f32_16x16x32_bf16 v[80:83], v[172:175], v[206:209], v[80:83]
	v_mfma_f32_16x16x32_bf16 v[96:99], v[172:175], v[198:201], v[96:99]
	v_mfma_f32_16x16x32_bf16 v[96:99], v[176:179], v[202:205], v[96:99]
	v_mfma_f32_16x16x32_bf16 v[112:115], v[176:179], v[194:197], v[112:115]
	v_mfma_f32_16x16x32_bf16 v[112:115], v[172:175], v[180:183], v[112:115]
	s_setprio 0
	s_barrier
	s_add_i32 s64, s84, s69
	v_lshl_add_u64 v[222:223], v[222:223], 0, s[26:27]
	s_mov_b32 m0, s64
	ds_read_b128 v[180:183], v191 offset:49152
	v_xor_b32_e32 v253, 64, v191
	ds_read_b128 v[194:197], v253 offset:49152
	ds_read_b128 v[198:201], v191 offset:51200
	ds_read_b128 v[202:205], v253 offset:51200
	ds_read_b128 v[206:209], v191 offset:53248
	ds_read_b128 v[210:213], v253 offset:53248
	ds_read_b128 v[214:217], v191 offset:55296
	ds_read_b128 v[218:221], v253 offset:55296
	global_load_lds_dwordx4 v[222:223], off
	s_add_i32 m0, s64, 0x2000
	s_add_u32 s62, s62, 0x80080
	v_lshl_add_u64 v[222:223], v[224:225], 0, s[26:27]
	s_addc_u32 s63, s63, 0
	s_add_i32 s64, s85, s69
	global_load_lds_dwordx4 v[222:223], off
	v_lshl_add_u64 v[222:223], s[62:63], 0, v[154:155]
	s_mov_b32 m0, s64
	s_nop 0
	global_load_lds_dwordx4 v[222:223], off
	v_lshl_add_u64 v[222:223], s[62:63], 0, v[162:163]
	s_add_i32 m0, s64, 0x2000
	s_nop 0
	global_load_lds_dwordx4 v[222:223], off
	v_lshl_add_u64 v[222:223], v[226:227], 0, s[26:27]
	s_mov_b32 m0, s3
	s_nop 0
	global_load_lds_dwordx4 v[222:223], off
	v_lshl_add_u64 v[222:223], v[228:229], 0, s[26:27]
	s_mov_b32 m0, s75
	s_nop 0
	global_load_lds_dwordx4 v[222:223], off
	s_waitcnt vmcnt(8)
	s_waitcnt lgkmcnt(0)
	s_barrier
	s_setprio 1
	s_waitcnt lgkmcnt(0)
	v_mfma_f32_16x16x32_bf16 v[60:63], v[128:131], v[180:183], v[60:63]
	v_mfma_f32_16x16x32_bf16 v[60:63], v[132:135], v[194:197], v[60:63]
	v_mfma_f32_16x16x32_bf16 v[44:47], v[132:135], v[202:205], v[44:47]
	v_mfma_f32_16x16x32_bf16 v[44:47], v[128:131], v[198:201], v[44:47]
	v_mfma_f32_16x16x32_bf16 v[28:31], v[128:131], v[206:209], v[28:31]
	v_mfma_f32_16x16x32_bf16 v[28:31], v[132:135], v[210:213], v[28:31]
	v_mfma_f32_16x16x32_bf16 v[12:15], v[132:135], v[218:221], v[12:15]
	v_mfma_f32_16x16x32_bf16 v[12:15], v[128:131], v[214:217], v[12:15]
	v_mfma_f32_16x16x32_bf16 v[8:11], v[136:139], v[214:217], v[8:11]
	v_mfma_f32_16x16x32_bf16 v[8:11], v[140:143], v[218:221], v[8:11]
	v_mfma_f32_16x16x32_bf16 v[24:27], v[140:143], v[210:213], v[24:27]
	v_mfma_f32_16x16x32_bf16 v[24:27], v[136:139], v[206:209], v[24:27]
	v_mfma_f32_16x16x32_bf16 v[40:43], v[136:139], v[198:201], v[40:43]
	v_mfma_f32_16x16x32_bf16 v[40:43], v[140:143], v[202:205], v[40:43]
	v_mfma_f32_16x16x32_bf16 v[56:59], v[140:143], v[194:197], v[56:59]
	v_mfma_f32_16x16x32_bf16 v[56:59], v[136:139], v[180:183], v[56:59]
	s_setprio 0
	s_setprio 1
	v_mfma_f32_16x16x32_bf16 v[52:55], v[144:147], v[180:183], v[52:55]
	v_mfma_f32_16x16x32_bf16 v[52:55], v[148:151], v[194:197], v[52:55]
	v_mfma_f32_16x16x32_bf16 v[36:39], v[148:151], v[202:205], v[36:39]
	v_mfma_f32_16x16x32_bf16 v[36:39], v[144:147], v[198:201], v[36:39]
	v_mfma_f32_16x16x32_bf16 v[20:23], v[144:147], v[206:209], v[20:23]
	v_mfma_f32_16x16x32_bf16 v[20:23], v[148:151], v[210:213], v[20:23]
	v_mfma_f32_16x16x32_bf16 v[4:7], v[148:151], v[218:221], v[4:7]
	v_mfma_f32_16x16x32_bf16 v[4:7], v[144:147], v[214:217], v[4:7]
	v_mfma_f32_16x16x32_bf16 v[0:3], v[172:175], v[214:217], v[0:3]
	v_mfma_f32_16x16x32_bf16 v[0:3], v[176:179], v[218:221], v[0:3]
	v_mfma_f32_16x16x32_bf16 v[16:19], v[176:179], v[210:213], v[16:19]
	v_mfma_f32_16x16x32_bf16 v[16:19], v[172:175], v[206:209], v[16:19]
	v_mfma_f32_16x16x32_bf16 v[32:35], v[172:175], v[198:201], v[32:35]
	v_mfma_f32_16x16x32_bf16 v[32:35], v[176:179], v[202:205], v[32:35]
	v_mfma_f32_16x16x32_bf16 v[48:51], v[176:179], v[194:197], v[48:51]
	v_mfma_f32_16x16x32_bf16 v[48:51], v[172:175], v[180:183], v[48:51]
	s_setprio 0
	s_barrier
	s_add_i32 s83, s83, 2
	s_add_u32 s81, s81, 0x100
	s_addc_u32 s82, s82, 0
	s_add_u32 s60, s60, 0x100
	s_addc_u32 s61, s61, 0
	s_cmp_gt_u32 s83, 29
	s_branch .LBB0_440
.Lfa_3:
	ds_read_b128 v[128:131], v189
	v_xor_b32_e32 v253, 64, v189
	ds_read_b128 v[132:135], v253
	ds_read_b128 v[136:139], v189 offset:2048
	ds_read_b128 v[140:143], v253 offset:2048
	ds_read_b128 v[144:147], v190
	v_xor_b32_e32 v253, 64, v190
	ds_read_b128 v[148:151], v253
	ds_read_b128 v[172:175], v190 offset:2048
	ds_read_b128 v[176:179], v253 offset:2048
	s_add_u32 s62, s60, 0xfff80080
	s_addc_u32 s63, s61, -1
	s_cmp_eq_u32 s83, 28
	s_cselect_b32 s65, s15, s63
	s_cselect_b32 s64, s53, s62
	s_cselect_b32 s63, s51, s82
	s_cselect_b32 s62, s59, s81
	v_lshl_add_u64 v[222:223], s[60:61], 0, v[166:167]
	s_add_i32 m0, s70, 0xc000
	ds_read_b128 v[180:183], v191
	v_xor_b32_e32 v253, 64, v191
	ds_read_b128 v[194:197], v253
	ds_read_b128 v[198:201], v191 offset:2048
	ds_read_b128 v[202:205], v253 offset:2048
	ds_read_b128 v[206:209], v191 offset:4096
	ds_read_b128 v[210:213], v253 offset:4096
	ds_read_b128 v[214:217], v191 offset:6144
	ds_read_b128 v[218:221], v253 offset:6144
	global_load_lds_dwordx4 v[222:223], off
	v_lshl_add_u64 v[222:223], s[60:61], 0, v[164:165]
	s_add_i32 m0, s70, 0xe000
	s_nop 0
	global_load_lds_dwordx4 v[222:223], off
	s_waitcnt vmcnt(8)
	s_waitcnt lgkmcnt(0)
	s_barrier
	s_setprio 1
	s_waitcnt lgkmcnt(0)
	v_mfma_f32_16x16x32_bf16 v[124:127], v[128:131], v[180:183], 0
	v_mfma_f32_16x16x32_bf16 v[120:123], v[136:139], v[180:183], 0
	v_mfma_f32_16x16x32_bf16 v[108:111], v[128:131], v[198:201], 0
	v_mfma_f32_16x16x32_bf16 v[104:107], v[136:139], v[198:201], 0
	v_mfma_f32_16x16x32_bf16 v[92:95], v[128:131], v[206:209], 0
	v_mfma_f32_16x16x32_bf16 v[88:91], v[136:139], v[206:209], 0
	v_mfma_f32_16x16x32_bf16 v[76:79], v[128:131], v[214:217], 0
	v_mfma_f32_16x16x32_bf16 v[72:75], v[136:139], v[214:217], 0
	v_mfma_f32_16x16x32_bf16 v[124:127], v[132:135], v[194:197], v[124:127]
	v_mfma_f32_16x16x32_bf16 v[120:123], v[140:143], v[194:197], v[120:123]
	v_mfma_f32_16x16x32_bf16 v[108:111], v[132:135], v[202:205], v[108:111]
	v_mfma_f32_16x16x32_bf16 v[104:107], v[140:143], v[202:205], v[104:107]
	v_mfma_f32_16x16x32_bf16 v[92:95], v[132:135], v[210:213], v[92:95]
	v_mfma_f32_16x16x32_bf16 v[88:91], v[140:143], v[210:213], v[88:91]
	v_mfma_f32_16x16x32_bf16 v[76:79], v[132:135], v[218:221], v[76:79]
	v_mfma_f32_16x16x32_bf16 v[72:75], v[140:143], v[218:221], v[72:75]
	s_setprio 0
	s_setprio 1
	v_mfma_f32_16x16x32_bf16 v[116:119], v[144:147], v[180:183], 0
	v_mfma_f32_16x16x32_bf16 v[112:115], v[172:175], v[180:183], 0
	v_mfma_f32_16x16x32_bf16 v[100:103], v[144:147], v[198:201], 0
	v_mfma_f32_16x16x32_bf16 v[96:99], v[172:175], v[198:201], 0
	v_mfma_f32_16x16x32_bf16 v[84:87], v[144:147], v[206:209], 0
	v_mfma_f32_16x16x32_bf16 v[80:83], v[172:175], v[206:209], 0
	v_mfma_f32_16x16x32_bf16 v[68:71], v[144:147], v[214:217], 0
	v_mfma_f32_16x16x32_bf16 v[64:67], v[172:175], v[214:217], 0
	v_mfma_f32_16x16x32_bf16 v[116:119], v[148:151], v[194:197], v[116:119]
	v_mfma_f32_16x16x32_bf16 v[112:115], v[176:179], v[194:197], v[112:115]
	v_mfma_f32_16x16x32_bf16 v[100:103], v[148:151], v[202:205], v[100:103]
	v_mfma_f32_16x16x32_bf16 v[96:99], v[176:179], v[202:205], v[96:99]
	v_mfma_f32_16x16x32_bf16 v[84:87], v[148:151], v[210:213], v[84:87]
	v_mfma_f32_16x16x32_bf16 v[80:83], v[176:179], v[210:213], v[80:83]
	v_mfma_f32_16x16x32_bf16 v[68:71], v[148:151], v[218:221], v[68:71]
	v_mfma_f32_16x16x32_bf16 v[64:67], v[176:179], v[218:221], v[64:67]
	s_setprio 0
	s_barrier
	s_add_i32 s84, s79, s69
	v_lshl_add_u64 v[222:223], s[62:63], 0, v[154:155]
	s_mov_b32 m0, s84
	ds_read_b128 v[180:183], v191 offset:16384
	v_xor_b32_e32 v253, 64, v191
	ds_read_b128 v[194:197], v253 offset:16384
	ds_read_b128 v[198:201], v191 offset:18432
	ds_read_b128 v[202:205], v253 offset:18432
	ds_read_b128 v[206:209], v191 offset:20480
	ds_read_b128 v[210:213], v253 offset:20480
	ds_read_b128 v[214:217], v191 offset:22528
	ds_read_b128 v[218:221], v253 offset:22528
	global_load_lds_dwordx4 v[222:223], off
	s_add_i32 m0, s84, 0x2000
	s_add_u32 s84, s62, 0x80000
	v_lshl_add_u64 v[224:225], s[62:63], 0, v[162:163]
	s_addc_u32 s85, s63, 0
	s_add_i32 s86, s80, s69
	global_load_lds_dwordx4 v[224:225], off
	v_lshl_add_u64 v[226:227], s[84:85], 0, v[154:155]
	s_mov_b32 m0, s86
	v_lshl_add_u64 v[228:229], s[64:65], 0, v[160:161]
	global_load_lds_dwordx4 v[226:227], off
	v_lshl_add_u64 v[226:227], s[84:85], 0, v[162:163]
	s_add_i32 m0, s86, 0x2000
	s_nop 0
	global_load_lds_dwordx4 v[226:227], off
	v_lshl_add_u64 v[226:227], s[64:65], 0, v[152:153]
	s_mov_b32 m0, s70
	s_nop 0
	global_load_lds_dwordx4 v[226:227], off
	s_mov_b32 m0, s71
	s_nop 0
	global_load_lds_dwordx4 v[228:229], off
	s_waitcnt vmcnt(8)
	s_waitcnt lgkmcnt(0)
	s_barrier
	s_setprio 1
	s_waitcnt lgkmcnt(0)
	v_mfma_f32_16x16x32_bf16 v[60:63], v[128:131], v[180:183], 0
	v_mfma_f32_16x16x32_bf16 v[56:59], v[136:139], v[180:183], 0
	v_mfma_f32_16x16x32_bf16 v[44:47], v[128:131], v[198:201], 0
	v_mfma_f32_16x16x32_bf16 v[40:43], v[136:139], v[198:201], 0
	v_mfma_f32_16x16x32_bf16 v[28:31], v[128:131], v[206:209], 0
	v_mfma_f32_16x16x32_bf16 v[24:27], v[136:139], v[206:209], 0
	v_mfma_f32_16x16x32_bf16 v[12:15], v[128:131], v[214:217], 0
	v_mfma_f32_16x16x32_bf16 v[8:11], v[136:139], v[214:217], 0
	v_mfma_f32_16x16x32_bf16 v[60:63], v[132:135], v[194:197], v[60:63]
	v_mfma_f32_16x16x32_bf16 v[56:59], v[140:143], v[194:197], v[56:59]
	v_mfma_f32_16x16x32_bf16 v[44:47], v[132:135], v[202:205], v[44:47]
	v_mfma_f32_16x16x32_bf16 v[40:43], v[140:143], v[202:205], v[40:43]
	v_mfma_f32_16x16x32_bf16 v[28:31], v[132:135], v[210:213], v[28:31]
	v_mfma_f32_16x16x32_bf16 v[24:27], v[140:143], v[210:213], v[24:27]
	v_mfma_f32_16x16x32_bf16 v[12:15], v[132:135], v[218:221], v[12:15]
	v_mfma_f32_16x16x32_bf16 v[8:11], v[140:143], v[218:221], v[8:11]
	s_setprio 0
	s_setprio 1
	v_mfma_f32_16x16x32_bf16 v[52:55], v[144:147], v[180:183], 0
	v_mfma_f32_16x16x32_bf16 v[48:51], v[172:175], v[180:183], 0
	v_mfma_f32_16x16x32_bf16 v[36:39], v[144:147], v[198:201], 0
	v_mfma_f32_16x16x32_bf16 v[32:35], v[172:175], v[198:201], 0
	v_mfma_f32_16x16x32_bf16 v[20:23], v[144:147], v[206:209], 0
	v_mfma_f32_16x16x32_bf16 v[16:19], v[172:175], v[206:209], 0
	v_mfma_f32_16x16x32_bf16 v[4:7], v[144:147], v[214:217], 0
	v_mfma_f32_16x16x32_bf16 v[0:3], v[172:175], v[214:217], 0
	v_mfma_f32_16x16x32_bf16 v[52:55], v[148:151], v[194:197], v[52:55]
	v_mfma_f32_16x16x32_bf16 v[48:51], v[176:179], v[194:197], v[48:51]
	v_mfma_f32_16x16x32_bf16 v[36:39], v[148:151], v[202:205], v[36:39]
	v_mfma_f32_16x16x32_bf16 v[32:35], v[176:179], v[202:205], v[32:35]
	v_mfma_f32_16x16x32_bf16 v[20:23], v[148:151], v[210:213], v[20:23]
	v_mfma_f32_16x16x32_bf16 v[16:19], v[176:179], v[210:213], v[16:19]
	v_mfma_f32_16x16x32_bf16 v[4:7], v[148:151], v[218:221], v[4:7]
	v_mfma_f32_16x16x32_bf16 v[0:3], v[176:179], v[218:221], v[0:3]
	s_setprio 0
	s_barrier
	s_add_i32 s84, 0, 0x18000
	s_add_i32 s85, 0, 0x1c000
	v_add_u32_e32 v140, s84, v186
	v_add_u32_e32 v176, s85, v186
	ds_read_b128 v[128:131], v140
	v_xor_b32_e32 v253, 64, v140
	ds_read_b128 v[132:135], v253
	ds_read_b128 v[136:139], v140 offset:2048
	ds_read_b128 v[140:143], v253 offset:2048
	ds_read_b128 v[144:147], v176
	v_xor_b32_e32 v253, 64, v176
	ds_read_b128 v[148:151], v253
	ds_read_b128 v[172:175], v176 offset:2048
	ds_read_b128 v[176:179], v253 offset:2048
	s_add_u32 s64, s64, 0x80000
	s_addc_u32 s65, s65, 0
	s_mov_b32 m0, s72
	v_lshl_add_u64 v[230:231], s[64:65], 0, v[152:153]
	ds_read_b128 v[180:183], v191 offset:32768
	v_xor_b32_e32 v253, 64, v191
	ds_read_b128 v[194:197], v253 offset:32768
	ds_read_b128 v[198:201], v191 offset:34816
	ds_read_b128 v[202:205], v253 offset:34816
	ds_read_b128 v[206:209], v191 offset:36864
	ds_read_b128 v[210:213], v253 offset:36864
	ds_read_b128 v[214:217], v191 offset:38912
	ds_read_b128 v[218:221], v253 offset:38912
	global_load_lds_dwordx4 v[230:231], off
	v_lshl_add_u64 v[230:231], s[64:65], 0, v[160:161]
	s_mov_b32 m0, s73
	s_nop 0
	global_load_lds_dwordx4 v[230:231], off
	s_waitcnt vmcnt(8)
	s_waitcnt lgkmcnt(0)
	s_barrier
	s_setprio 1
	s_waitcnt lgkmcnt(0)
	v_mfma_f32_16x16x32_bf16 v[124:127], v[128:131], v[180:183], v[124:127]
	v_mfma_f32_16x16x32_bf16 v[124:127], v[132:135], v[194:197], v[124:127]
	v_mfma_f32_16x16x32_bf16 v[108:111], v[132:135], v[202:205], v[108:111]
	v_mfma_f32_16x16x32_bf16 v[108:111], v[128:131], v[198:201], v[108:111]
	v_mfma_f32_16x16x32_bf16 v[92:95], v[128:131], v[206:209], v[92:95]
	v_mfma_f32_16x16x32_bf16 v[92:95], v[132:135], v[210:213], v[92:95]
	v_mfma_f32_16x16x32_bf16 v[76:79], v[132:135], v[218:221], v[76:79]
	v_mfma_f32_16x16x32_bf16 v[76:79], v[128:131], v[214:217], v[76:79]
	v_mfma_f32_16x16x32_bf16 v[72:75], v[136:139], v[214:217], v[72:75]
	v_mfma_f32_16x16x32_bf16 v[72:75], v[140:143], v[218:221], v[72:75]
	v_mfma_f32_16x16x32_bf16 v[88:91], v[140:143], v[210:213], v[88:91]
	v_mfma_f32_16x16x32_bf16 v[88:91], v[136:139], v[206:209], v[88:91]
	v_mfma_f32_16x16x32_bf16 v[104:107], v[136:139], v[198:201], v[104:107]
	v_mfma_f32_16x16x32_bf16 v[104:107], v[140:143], v[202:205], v[104:107]
	v_mfma_f32_16x16x32_bf16 v[120:123], v[140:143], v[194:197], v[120:123]
	v_mfma_f32_16x16x32_bf16 v[120:123], v[136:139], v[180:183], v[120:123]
	s_setprio 0
	s_setprio 1
	v_mfma_f32_16x16x32_bf16 v[116:119], v[144:147], v[180:183], v[116:119]
	v_mfma_f32_16x16x32_bf16 v[116:119], v[148:151], v[194:197], v[116:119]
	v_mfma_f32_16x16x32_bf16 v[100:103], v[148:151], v[202:205], v[100:103]
	v_mfma_f32_16x16x32_bf16 v[100:103], v[144:147], v[198:201], v[100:103]
	v_mfma_f32_16x16x32_bf16 v[84:87], v[144:147], v[206:209], v[84:87]
	v_mfma_f32_16x16x32_bf16 v[84:87], v[148:151], v[210:213], v[84:87]
	v_mfma_f32_16x16x32_bf16 v[68:71], v[148:151], v[218:221], v[68:71]
	v_mfma_f32_16x16x32_bf16 v[68:71], v[144:147], v[214:217], v[68:71]
	v_mfma_f32_16x16x32_bf16 v[64:67], v[172:175], v[214:217], v[64:67]
	v_mfma_f32_16x16x32_bf16 v[64:67], v[176:179], v[218:221], v[64:67]
	v_mfma_f32_16x16x32_bf16 v[80:83], v[176:179], v[210:213], v[80:83]
	v_mfma_f32_16x16x32_bf16 v[80:83], v[172:175], v[206:209], v[80:83]
	v_mfma_f32_16x16x32_bf16 v[96:99], v[172:175], v[198:201], v[96:99]
	v_mfma_f32_16x16x32_bf16 v[96:99], v[176:179], v[202:205], v[96:99]
	v_mfma_f32_16x16x32_bf16 v[112:115], v[176:179], v[194:197], v[112:115]
	v_mfma_f32_16x16x32_bf16 v[112:115], v[172:175], v[180:183], v[112:115]
	s_setprio 0
	s_barrier
	s_add_i32 s64, s84, s69
	v_lshl_add_u64 v[222:223], v[222:223], 0, s[26:27]
	s_mov_b32 m0, s64
	ds_read_b128 v[180:183], v191 offset:49152
	v_xor_b32_e32 v253, 64, v191
	ds_read_b128 v[194:197], v253 offset:49152
	ds_read_b128 v[198:201], v191 offset:51200
	ds_read_b128 v[202:205], v253 offset:51200
	ds_read_b128 v[206:209], v191 offset:53248
	ds_read_b128 v[210:213], v253 offset:53248
	ds_read_b128 v[214:217], v191 offset:55296
	ds_read_b128 v[218:221], v253 offset:55296
	global_load_lds_dwordx4 v[222:223], off
	s_add_i32 m0, s64, 0x2000
	s_add_u32 s62, s62, 0x80080
	v_lshl_add_u64 v[222:223], v[224:225], 0, s[26:27]
	s_addc_u32 s63, s63, 0
	s_add_i32 s64, s85, s69
	global_load_lds_dwordx4 v[222:223], off
	v_lshl_add_u64 v[222:223], s[62:63], 0, v[154:155]
	s_mov_b32 m0, s64
	s_nop 0
	global_load_lds_dwordx4 v[222:223], off
	v_lshl_add_u64 v[222:223], s[62:63], 0, v[162:163]
	s_add_i32 m0, s64, 0x2000
	s_nop 0
	global_load_lds_dwordx4 v[222:223], off
	v_lshl_add_u64 v[222:223], v[226:227], 0, s[26:27]
	s_mov_b32 m0, s3
	s_nop 0
	global_load_lds_dwordx4 v[222:223], off
	v_lshl_add_u64 v[222:223], v[228:229], 0, s[26:27]
	s_mov_b32 m0, s75
	s_nop 0
	global_load_lds_dwordx4 v[222:223], off
	s_waitcnt vmcnt(8)
	s_waitcnt lgkmcnt(0)
	s_barrier
	s_setprio 1
	s_waitcnt lgkmcnt(0)
	v_mfma_f32_16x16x32_bf16 v[60:63], v[128:131], v[180:183], v[60:63]
	v_mfma_f32_16x16x32_bf16 v[60:63], v[132:135], v[194:197], v[60:63]
	v_mfma_f32_16x16x32_bf16 v[44:47], v[132:135], v[202:205], v[44:47]
	v_mfma_f32_16x16x32_bf16 v[44:47], v[128:131], v[198:201], v[44:47]
	v_mfma_f32_16x16x32_bf16 v[28:31], v[128:131], v[206:209], v[28:31]
	v_mfma_f32_16x16x32_bf16 v[28:31], v[132:135], v[210:213], v[28:31]
	v_mfma_f32_16x16x32_bf16 v[12:15], v[132:135], v[218:221], v[12:15]
	v_mfma_f32_16x16x32_bf16 v[12:15], v[128:131], v[214:217], v[12:15]
	v_mfma_f32_16x16x32_bf16 v[8:11], v[136:139], v[214:217], v[8:11]
	v_mfma_f32_16x16x32_bf16 v[8:11], v[140:143], v[218:221], v[8:11]
	v_mfma_f32_16x16x32_bf16 v[24:27], v[140:143], v[210:213], v[24:27]
	v_mfma_f32_16x16x32_bf16 v[24:27], v[136:139], v[206:209], v[24:27]
	v_mfma_f32_16x16x32_bf16 v[40:43], v[136:139], v[198:201], v[40:43]
	v_mfma_f32_16x16x32_bf16 v[40:43], v[140:143], v[202:205], v[40:43]
	v_mfma_f32_16x16x32_bf16 v[56:59], v[140:143], v[194:197], v[56:59]
	v_mfma_f32_16x16x32_bf16 v[56:59], v[136:139], v[180:183], v[56:59]
	s_setprio 0
	s_setprio 1
	v_mfma_f32_16x16x32_bf16 v[52:55], v[144:147], v[180:183], v[52:55]
	v_mfma_f32_16x16x32_bf16 v[52:55], v[148:151], v[194:197], v[52:55]
	v_mfma_f32_16x16x32_bf16 v[36:39], v[148:151], v[202:205], v[36:39]
	v_mfma_f32_16x16x32_bf16 v[36:39], v[144:147], v[198:201], v[36:39]
	v_mfma_f32_16x16x32_bf16 v[20:23], v[144:147], v[206:209], v[20:23]
	v_mfma_f32_16x16x32_bf16 v[20:23], v[148:151], v[210:213], v[20:23]
	v_mfma_f32_16x16x32_bf16 v[4:7], v[148:151], v[218:221], v[4:7]
	v_mfma_f32_16x16x32_bf16 v[4:7], v[144:147], v[214:217], v[4:7]
	v_mfma_f32_16x16x32_bf16 v[0:3], v[172:175], v[214:217], v[0:3]
	v_mfma_f32_16x16x32_bf16 v[0:3], v[176:179], v[218:221], v[0:3]
	v_mfma_f32_16x16x32_bf16 v[16:19], v[176:179], v[210:213], v[16:19]
	v_mfma_f32_16x16x32_bf16 v[16:19], v[172:175], v[206:209], v[16:19]
	v_mfma_f32_16x16x32_bf16 v[32:35], v[172:175], v[198:201], v[32:35]
	v_mfma_f32_16x16x32_bf16 v[32:35], v[176:179], v[202:205], v[32:35]
	v_mfma_f32_16x16x32_bf16 v[48:51], v[176:179], v[194:197], v[48:51]
	v_mfma_f32_16x16x32_bf16 v[48:51], v[172:175], v[180:183], v[48:51]
	s_setprio 0
	s_barrier
	s_add_i32 s83, s83, 2
	s_add_u32 s81, s81, 0x100
	s_addc_u32 s82, s82, 0
	s_add_u32 s60, s60, 0x100
	s_addc_u32 s61, s61, 0
	s_cmp_gt_u32 s83, 29
.LBB0_440:
	ds_read_b128 v[128:131], v189
	v_xor_b32_e32 v253, 64, v189
	ds_read_b128 v[132:135], v253
	ds_read_b128 v[136:139], v189 offset:2048
	ds_read_b128 v[140:143], v253 offset:2048
	ds_read_b128 v[144:147], v190
	v_xor_b32_e32 v253, 64, v190
	ds_read_b128 v[148:151], v253
	ds_read_b128 v[172:175], v190 offset:2048
	ds_read_b128 v[176:179], v253 offset:2048
	s_add_u32 s62, s60, 0xfff80080
	s_addc_u32 s63, s61, -1
	s_cmp_eq_u32 s83, 28
	s_cselect_b32 s65, s15, s63
	s_cselect_b32 s64, s53, s62
	s_cselect_b32 s63, s51, s82
	s_cselect_b32 s62, s59, s81
	v_lshl_add_u64 v[222:223], s[60:61], 0, v[166:167]
	s_add_i32 m0, s70, 0xc000
	ds_read_b128 v[180:183], v191
	v_xor_b32_e32 v253, 64, v191
	ds_read_b128 v[194:197], v253
	ds_read_b128 v[198:201], v191 offset:2048
	ds_read_b128 v[202:205], v253 offset:2048
	ds_read_b128 v[206:209], v191 offset:4096
	ds_read_b128 v[210:213], v253 offset:4096
	ds_read_b128 v[214:217], v191 offset:6144
	ds_read_b128 v[218:221], v253 offset:6144
	global_load_lds_dwordx4 v[222:223], off
	v_lshl_add_u64 v[222:223], s[60:61], 0, v[164:165]
	s_add_i32 m0, s70, 0xe000
	s_nop 0
	global_load_lds_dwordx4 v[222:223], off
	s_waitcnt vmcnt(8)
	s_waitcnt lgkmcnt(0)
	s_barrier
	s_setprio 1
	s_waitcnt lgkmcnt(0)
	v_mfma_f32_16x16x32_bf16 v[124:127], v[128:131], v[180:183], v[124:127]
	v_mfma_f32_16x16x32_bf16 v[124:127], v[132:135], v[194:197], v[124:127]
	v_mfma_f32_16x16x32_bf16 v[108:111], v[132:135], v[202:205], v[108:111]
	v_mfma_f32_16x16x32_bf16 v[108:111], v[128:131], v[198:201], v[108:111]
	v_mfma_f32_16x16x32_bf16 v[92:95], v[128:131], v[206:209], v[92:95]
	v_mfma_f32_16x16x32_bf16 v[92:95], v[132:135], v[210:213], v[92:95]
	v_mfma_f32_16x16x32_bf16 v[76:79], v[132:135], v[218:221], v[76:79]
	v_mfma_f32_16x16x32_bf16 v[76:79], v[128:131], v[214:217], v[76:79]
	v_mfma_f32_16x16x32_bf16 v[72:75], v[136:139], v[214:217], v[72:75]
	v_mfma_f32_16x16x32_bf16 v[72:75], v[140:143], v[218:221], v[72:75]
	v_mfma_f32_16x16x32_bf16 v[88:91], v[140:143], v[210:213], v[88:91]
	v_mfma_f32_16x16x32_bf16 v[88:91], v[136:139], v[206:209], v[88:91]
	v_mfma_f32_16x16x32_bf16 v[104:107], v[136:139], v[198:201], v[104:107]
	v_mfma_f32_16x16x32_bf16 v[104:107], v[140:143], v[202:205], v[104:107]
	v_mfma_f32_16x16x32_bf16 v[120:123], v[140:143], v[194:197], v[120:123]
	v_mfma_f32_16x16x32_bf16 v[120:123], v[136:139], v[180:183], v[120:123]
	s_setprio 0
	s_setprio 1
	v_mfma_f32_16x16x32_bf16 v[116:119], v[144:147], v[180:183], v[116:119]
	v_mfma_f32_16x16x32_bf16 v[116:119], v[148:151], v[194:197], v[116:119]
	v_mfma_f32_16x16x32_bf16 v[100:103], v[148:151], v[202:205], v[100:103]
	v_mfma_f32_16x16x32_bf16 v[100:103], v[144:147], v[198:201], v[100:103]
	v_mfma_f32_16x16x32_bf16 v[84:87], v[144:147], v[206:209], v[84:87]
	v_mfma_f32_16x16x32_bf16 v[84:87], v[148:151], v[210:213], v[84:87]
	v_mfma_f32_16x16x32_bf16 v[68:71], v[148:151], v[218:221], v[68:71]
	v_mfma_f32_16x16x32_bf16 v[68:71], v[144:147], v[214:217], v[68:71]
	v_mfma_f32_16x16x32_bf16 v[64:67], v[172:175], v[214:217], v[64:67]
	v_mfma_f32_16x16x32_bf16 v[64:67], v[176:179], v[218:221], v[64:67]
	v_mfma_f32_16x16x32_bf16 v[80:83], v[176:179], v[210:213], v[80:83]
	v_mfma_f32_16x16x32_bf16 v[80:83], v[172:175], v[206:209], v[80:83]
	v_mfma_f32_16x16x32_bf16 v[96:99], v[172:175], v[198:201], v[96:99]
	v_mfma_f32_16x16x32_bf16 v[96:99], v[176:179], v[202:205], v[96:99]
	v_mfma_f32_16x16x32_bf16 v[112:115], v[176:179], v[194:197], v[112:115]
	v_mfma_f32_16x16x32_bf16 v[112:115], v[172:175], v[180:183], v[112:115]
	s_setprio 0
	s_barrier
	s_add_i32 s84, s79, s69
	v_lshl_add_u64 v[222:223], s[62:63], 0, v[154:155]
	s_mov_b32 m0, s84
	ds_read_b128 v[180:183], v191 offset:16384
	v_xor_b32_e32 v253, 64, v191
	ds_read_b128 v[194:197], v253 offset:16384
	ds_read_b128 v[198:201], v191 offset:18432
	ds_read_b128 v[202:205], v253 offset:18432
	ds_read_b128 v[206:209], v191 offset:20480
	ds_read_b128 v[210:213], v253 offset:20480
	ds_read_b128 v[214:217], v191 offset:22528
	ds_read_b128 v[218:221], v253 offset:22528
	global_load_lds_dwordx4 v[222:223], off
	s_add_i32 m0, s84, 0x2000
	s_add_u32 s84, s62, 0x80000
	v_lshl_add_u64 v[224:225], s[62:63], 0, v[162:163]
	s_addc_u32 s85, s63, 0
	s_add_i32 s86, s80, s69
	global_load_lds_dwordx4 v[224:225], off
	v_lshl_add_u64 v[226:227], s[84:85], 0, v[154:155]
	s_mov_b32 m0, s86
	v_lshl_add_u64 v[228:229], s[64:65], 0, v[160:161]
	global_load_lds_dwordx4 v[226:227], off
	v_lshl_add_u64 v[226:227], s[84:85], 0, v[162:163]
	s_add_i32 m0, s86, 0x2000
	s_nop 0
	global_load_lds_dwordx4 v[226:227], off
	v_lshl_add_u64 v[226:227], s[64:65], 0, v[152:153]
	s_mov_b32 m0, s70
	s_nop 0
	global_load_lds_dwordx4 v[226:227], off
	s_mov_b32 m0, s71
	s_nop 0
	global_load_lds_dwordx4 v[228:229], off
	s_waitcnt vmcnt(8)
	s_waitcnt lgkmcnt(0)
	s_barrier
	s_setprio 1
	s_waitcnt lgkmcnt(0)
	v_mfma_f32_16x16x32_bf16 v[60:63], v[128:131], v[180:183], v[60:63]
	v_mfma_f32_16x16x32_bf16 v[60:63], v[132:135], v[194:197], v[60:63]
	v_mfma_f32_16x16x32_bf16 v[44:47], v[132:135], v[202:205], v[44:47]
	v_mfma_f32_16x16x32_bf16 v[44:47], v[128:131], v[198:201], v[44:47]
	v_mfma_f32_16x16x32_bf16 v[28:31], v[128:131], v[206:209], v[28:31]
	v_mfma_f32_16x16x32_bf16 v[28:31], v[132:135], v[210:213], v[28:31]
	v_mfma_f32_16x16x32_bf16 v[12:15], v[132:135], v[218:221], v[12:15]
	v_mfma_f32_16x16x32_bf16 v[12:15], v[128:131], v[214:217], v[12:15]
	v_mfma_f32_16x16x32_bf16 v[8:11], v[136:139], v[214:217], v[8:11]
	v_mfma_f32_16x16x32_bf16 v[8:11], v[140:143], v[218:221], v[8:11]
	v_mfma_f32_16x16x32_bf16 v[24:27], v[140:143], v[210:213], v[24:27]
	v_mfma_f32_16x16x32_bf16 v[24:27], v[136:139], v[206:209], v[24:27]
	v_mfma_f32_16x16x32_bf16 v[40:43], v[136:139], v[198:201], v[40:43]
	v_mfma_f32_16x16x32_bf16 v[40:43], v[140:143], v[202:205], v[40:43]
	v_mfma_f32_16x16x32_bf16 v[56:59], v[140:143], v[194:197], v[56:59]
	v_mfma_f32_16x16x32_bf16 v[56:59], v[136:139], v[180:183], v[56:59]
	s_setprio 0
	s_setprio 1
	v_mfma_f32_16x16x32_bf16 v[52:55], v[144:147], v[180:183], v[52:55]
	v_mfma_f32_16x16x32_bf16 v[52:55], v[148:151], v[194:197], v[52:55]
	v_mfma_f32_16x16x32_bf16 v[36:39], v[148:151], v[202:205], v[36:39]
	v_mfma_f32_16x16x32_bf16 v[36:39], v[144:147], v[198:201], v[36:39]
	v_mfma_f32_16x16x32_bf16 v[20:23], v[144:147], v[206:209], v[20:23]
	v_mfma_f32_16x16x32_bf16 v[20:23], v[148:151], v[210:213], v[20:23]
	v_mfma_f32_16x16x32_bf16 v[4:7], v[148:151], v[218:221], v[4:7]
	v_mfma_f32_16x16x32_bf16 v[4:7], v[144:147], v[214:217], v[4:7]
	v_mfma_f32_16x16x32_bf16 v[0:3], v[172:175], v[214:217], v[0:3]
	v_mfma_f32_16x16x32_bf16 v[0:3], v[176:179], v[218:221], v[0:3]
	v_mfma_f32_16x16x32_bf16 v[16:19], v[176:179], v[210:213], v[16:19]
	v_mfma_f32_16x16x32_bf16 v[16:19], v[172:175], v[206:209], v[16:19]
	v_mfma_f32_16x16x32_bf16 v[32:35], v[172:175], v[198:201], v[32:35]
	v_mfma_f32_16x16x32_bf16 v[32:35], v[176:179], v[202:205], v[32:35]
	v_mfma_f32_16x16x32_bf16 v[48:51], v[176:179], v[194:197], v[48:51]
	v_mfma_f32_16x16x32_bf16 v[48:51], v[172:175], v[180:183], v[48:51]
	s_setprio 0
	s_barrier
	s_add_i32 s84, 0, 0x18000
	s_add_i32 s85, 0, 0x1c000
	v_add_u32_e32 v140, s84, v186
	v_add_u32_e32 v176, s85, v186
	ds_read_b128 v[128:131], v140
	v_xor_b32_e32 v253, 64, v140
	ds_read_b128 v[132:135], v253
	ds_read_b128 v[136:139], v140 offset:2048
	ds_read_b128 v[140:143], v253 offset:2048
	ds_read_b128 v[144:147], v176
	v_xor_b32_e32 v253, 64, v176
	ds_read_b128 v[148:151], v253
	ds_read_b128 v[172:175], v176 offset:2048
	ds_read_b128 v[176:179], v253 offset:2048
	s_add_u32 s64, s64, 0x80000
	s_addc_u32 s65, s65, 0
	s_mov_b32 m0, s72
	v_lshl_add_u64 v[230:231], s[64:65], 0, v[152:153]
	ds_read_b128 v[180:183], v191 offset:32768
	v_xor_b32_e32 v253, 64, v191
	ds_read_b128 v[194:197], v253 offset:32768
	ds_read_b128 v[198:201], v191 offset:34816
	ds_read_b128 v[202:205], v253 offset:34816
	ds_read_b128 v[206:209], v191 offset:36864
	ds_read_b128 v[210:213], v253 offset:36864
	ds_read_b128 v[214:217], v191 offset:38912
	ds_read_b128 v[218:221], v253 offset:38912
	global_load_lds_dwordx4 v[230:231], off
	v_lshl_add_u64 v[230:231], s[64:65], 0, v[160:161]
	s_mov_b32 m0, s73
	s_nop 0
	global_load_lds_dwordx4 v[230:231], off
	s_waitcnt vmcnt(8)
	s_waitcnt lgkmcnt(0)
	s_barrier
	s_setprio 1
	s_waitcnt lgkmcnt(0)
	v_mfma_f32_16x16x32_bf16 v[124:127], v[128:131], v[180:183], v[124:127]
	v_mfma_f32_16x16x32_bf16 v[124:127], v[132:135], v[194:197], v[124:127]
	v_mfma_f32_16x16x32_bf16 v[108:111], v[132:135], v[202:205], v[108:111]
	v_mfma_f32_16x16x32_bf16 v[108:111], v[128:131], v[198:201], v[108:111]
	v_mfma_f32_16x16x32_bf16 v[92:95], v[128:131], v[206:209], v[92:95]
	v_mfma_f32_16x16x32_bf16 v[92:95], v[132:135], v[210:213], v[92:95]
	v_mfma_f32_16x16x32_bf16 v[76:79], v[132:135], v[218:221], v[76:79]
	v_mfma_f32_16x16x32_bf16 v[76:79], v[128:131], v[214:217], v[76:79]
	v_mfma_f32_16x16x32_bf16 v[72:75], v[136:139], v[214:217], v[72:75]
	v_mfma_f32_16x16x32_bf16 v[72:75], v[140:143], v[218:221], v[72:75]
	v_mfma_f32_16x16x32_bf16 v[88:91], v[140:143], v[210:213], v[88:91]
	v_mfma_f32_16x16x32_bf16 v[88:91], v[136:139], v[206:209], v[88:91]
	v_mfma_f32_16x16x32_bf16 v[104:107], v[136:139], v[198:201], v[104:107]
	v_mfma_f32_16x16x32_bf16 v[104:107], v[140:143], v[202:205], v[104:107]
	v_mfma_f32_16x16x32_bf16 v[120:123], v[140:143], v[194:197], v[120:123]
	v_mfma_f32_16x16x32_bf16 v[120:123], v[136:139], v[180:183], v[120:123]
	s_setprio 0
	s_setprio 1
	v_mfma_f32_16x16x32_bf16 v[116:119], v[144:147], v[180:183], v[116:119]
	v_mfma_f32_16x16x32_bf16 v[116:119], v[148:151], v[194:197], v[116:119]
	v_mfma_f32_16x16x32_bf16 v[100:103], v[148:151], v[202:205], v[100:103]
	v_mfma_f32_16x16x32_bf16 v[100:103], v[144:147], v[198:201], v[100:103]
	v_mfma_f32_16x16x32_bf16 v[84:87], v[144:147], v[206:209], v[84:87]
	v_mfma_f32_16x16x32_bf16 v[84:87], v[148:151], v[210:213], v[84:87]
	v_mfma_f32_16x16x32_bf16 v[68:71], v[148:151], v[218:221], v[68:71]
	v_mfma_f32_16x16x32_bf16 v[68:71], v[144:147], v[214:217], v[68:71]
	v_mfma_f32_16x16x32_bf16 v[64:67], v[172:175], v[214:217], v[64:67]
	v_mfma_f32_16x16x32_bf16 v[64:67], v[176:179], v[218:221], v[64:67]
	v_mfma_f32_16x16x32_bf16 v[80:83], v[176:179], v[210:213], v[80:83]
	v_mfma_f32_16x16x32_bf16 v[80:83], v[172:175], v[206:209], v[80:83]
	v_mfma_f32_16x16x32_bf16 v[96:99], v[172:175], v[198:201], v[96:99]
	v_mfma_f32_16x16x32_bf16 v[96:99], v[176:179], v[202:205], v[96:99]
	v_mfma_f32_16x16x32_bf16 v[112:115], v[176:179], v[194:197], v[112:115]
	v_mfma_f32_16x16x32_bf16 v[112:115], v[172:175], v[180:183], v[112:115]
	s_setprio 0
	s_barrier
	s_add_i32 s64, s84, s69
	v_lshl_add_u64 v[222:223], v[222:223], 0, s[26:27]
	s_mov_b32 m0, s64
	ds_read_b128 v[180:183], v191 offset:49152
	v_xor_b32_e32 v253, 64, v191
	ds_read_b128 v[194:197], v253 offset:49152
	ds_read_b128 v[198:201], v191 offset:51200
	ds_read_b128 v[202:205], v253 offset:51200
	ds_read_b128 v[206:209], v191 offset:53248
	ds_read_b128 v[210:213], v253 offset:53248
	ds_read_b128 v[214:217], v191 offset:55296
	ds_read_b128 v[218:221], v253 offset:55296
	global_load_lds_dwordx4 v[222:223], off
	s_add_i32 m0, s64, 0x2000
	s_add_u32 s62, s62, 0x80080
	v_lshl_add_u64 v[222:223], v[224:225], 0, s[26:27]
	s_addc_u32 s63, s63, 0
	s_add_i32 s64, s85, s69
	global_load_lds_dwordx4 v[222:223], off
	v_lshl_add_u64 v[222:223], s[62:63], 0, v[154:155]
	s_mov_b32 m0, s64
	s_nop 0
	global_load_lds_dwordx4 v[222:223], off
	v_lshl_add_u64 v[222:223], s[62:63], 0, v[162:163]
	s_add_i32 m0, s64, 0x2000
	s_nop 0
	global_load_lds_dwordx4 v[222:223], off
	v_lshl_add_u64 v[222:223], v[226:227], 0, s[26:27]
	s_mov_b32 m0, s3
	s_nop 0
	global_load_lds_dwordx4 v[222:223], off
	v_lshl_add_u64 v[222:223], v[228:229], 0, s[26:27]
	s_mov_b32 m0, s75
	s_nop 0
	global_load_lds_dwordx4 v[222:223], off
	s_waitcnt vmcnt(8)
	s_waitcnt lgkmcnt(0)
	s_barrier
	s_setprio 1
	s_waitcnt lgkmcnt(0)
	v_mfma_f32_16x16x32_bf16 v[60:63], v[128:131], v[180:183], v[60:63]
	v_mfma_f32_16x16x32_bf16 v[60:63], v[132:135], v[194:197], v[60:63]
	v_mfma_f32_16x16x32_bf16 v[44:47], v[132:135], v[202:205], v[44:47]
	v_mfma_f32_16x16x32_bf16 v[44:47], v[128:131], v[198:201], v[44:47]
	v_mfma_f32_16x16x32_bf16 v[28:31], v[128:131], v[206:209], v[28:31]
	v_mfma_f32_16x16x32_bf16 v[28:31], v[132:135], v[210:213], v[28:31]
	v_mfma_f32_16x16x32_bf16 v[12:15], v[132:135], v[218:221], v[12:15]
	v_mfma_f32_16x16x32_bf16 v[12:15], v[128:131], v[214:217], v[12:15]
	v_mfma_f32_16x16x32_bf16 v[8:11], v[136:139], v[214:217], v[8:11]
	v_mfma_f32_16x16x32_bf16 v[8:11], v[140:143], v[218:221], v[8:11]
	v_mfma_f32_16x16x32_bf16 v[24:27], v[140:143], v[210:213], v[24:27]
	v_mfma_f32_16x16x32_bf16 v[24:27], v[136:139], v[206:209], v[24:27]
	v_mfma_f32_16x16x32_bf16 v[40:43], v[136:139], v[198:201], v[40:43]
	v_mfma_f32_16x16x32_bf16 v[40:43], v[140:143], v[202:205], v[40:43]
	v_mfma_f32_16x16x32_bf16 v[56:59], v[140:143], v[194:197], v[56:59]
	v_mfma_f32_16x16x32_bf16 v[56:59], v[136:139], v[180:183], v[56:59]
	s_setprio 0
	s_setprio 1
	v_mfma_f32_16x16x32_bf16 v[52:55], v[144:147], v[180:183], v[52:55]
	v_mfma_f32_16x16x32_bf16 v[52:55], v[148:151], v[194:197], v[52:55]
	v_mfma_f32_16x16x32_bf16 v[36:39], v[148:151], v[202:205], v[36:39]
	v_mfma_f32_16x16x32_bf16 v[36:39], v[144:147], v[198:201], v[36:39]
	v_mfma_f32_16x16x32_bf16 v[20:23], v[144:147], v[206:209], v[20:23]
	v_mfma_f32_16x16x32_bf16 v[20:23], v[148:151], v[210:213], v[20:23]
	v_mfma_f32_16x16x32_bf16 v[4:7], v[148:151], v[218:221], v[4:7]
	v_mfma_f32_16x16x32_bf16 v[4:7], v[144:147], v[214:217], v[4:7]
	v_mfma_f32_16x16x32_bf16 v[0:3], v[172:175], v[214:217], v[0:3]
	v_mfma_f32_16x16x32_bf16 v[0:3], v[176:179], v[218:221], v[0:3]
	v_mfma_f32_16x16x32_bf16 v[16:19], v[176:179], v[210:213], v[16:19]
	v_mfma_f32_16x16x32_bf16 v[16:19], v[172:175], v[206:209], v[16:19]
	v_mfma_f32_16x16x32_bf16 v[32:35], v[172:175], v[198:201], v[32:35]
	v_mfma_f32_16x16x32_bf16 v[32:35], v[176:179], v[202:205], v[32:35]
	v_mfma_f32_16x16x32_bf16 v[48:51], v[176:179], v[194:197], v[48:51]
	v_mfma_f32_16x16x32_bf16 v[48:51], v[172:175], v[180:183], v[48:51]
	s_setprio 0
	s_barrier
	s_add_i32 s83, s83, 2
	s_add_u32 s81, s81, 0x100
	s_addc_u32 s82, s82, 0
	s_add_u32 s60, s60, 0x100
	s_addc_u32 s61, s61, 0
	s_cmp_gt_u32 s83, 29
	s_cbranch_scc0 .LBB0_440
	s_and_b64 vcc, exec, s[28:29]
	s_cbranch_vccz .LBB0_443
	s_barrier

.LBB0_525:
	s_ashr_i32 s29, s28, 31
	s_lshl_b64 s[30:31], s[28:29], 19
	s_add_u32 s30, s3, s30
	s_addc_u32 s31, s35, s31
	s_and_b64 s[44:45], s[10:11], exec
	s_cselect_b32 s29, s31, s51
	s_cselect_b32 s70, s30, s50
	s_ashr_i32 s27, s26, 31
	s_lshl_b64 s[44:45], s[26:27], 19
	s_add_u32 s44, s52, s44
	s_addc_u32 s45, s53, s45
	s_and_b64 s[72:73], s[10:11], exec
	s_cselect_b32 s71, s45, s49
	s_cselect_b32 s72, s44, s48
	s_lshl_b32 s27, s46, 8
	v_add_u32_e32 v0, s27, v148
	s_add_u32 s73, s48, 0x100
	v_ashrrev_i32_e32 v1, 31, v0
	s_addc_u32 s74, s49, 0
	v_lshl_add_u64 v[144:145], v[0:1], 4, s[16:17]
	s_add_u32 s46, s50, 0x40080
	s_addc_u32 s47, s51, 0
	s_mov_b32 s75, -2
	s_mov_b64 s[48:49], 0
	s_cmp_eq_u32 s61, 1
	s_cbranch_scc1 .Lfa_4
	v_add_u32_e32 v153, s66, v147
	ds_read_b128 v[160:163], v153
	v_xor_b32_e32 v253, 64, v153
	ds_read_b128 v[164:167], v253
	ds_read_b128 v[168:171], v153 offset:2048
	ds_read_b128 v[172:175], v253 offset:2048
	v_add_u32_e32 v153, s67, v147
	ds_read_b128 v[176:179], v153
	v_xor_b32_e32 v253, 64, v153
	ds_read_b128 v[180:183], v253
	ds_read_b128 v[186:189], v153 offset:2048
	ds_read_b128 v[190:193], v253 offset:2048
	s_add_u32 s50, s46, 0xfffc0080
	s_addc_u32 s51, s47, -1
	s_and_b64 s[48:49], s[48:49], exec
	s_cselect_b32 s51, s29, s51
	s_cselect_b32 s50, s70, s50
	s_cselect_b32 s49, s71, s74
	s_cselect_b32 s48, s72, s73
	v_lshl_add_u64 v[154:155], s[46:47], 0, v[138:139]
	s_add_i32 m0, s57, 0xc000
	ds_read_b128 v[194:197], v150
	v_xor_b32_e32 v253, 64, v150
	ds_read_b128 v[198:201], v253
	ds_read_b128 v[202:205], v150 offset:2048
	ds_read_b128 v[206:209], v253 offset:2048
	ds_read_b128 v[210:213], v150 offset:4096
	ds_read_b128 v[214:217], v253 offset:4096
	ds_read_b128 v[218:221], v150 offset:6144
	ds_read_b128 v[222:225], v253 offset:6144
	global_load_lds_dwordx4 v[154:155], off
	v_lshl_add_u64 v[154:155], s[46:47], 0, v[136:137]
	s_add_i32 m0, s57, 0xe000
	s_nop 0
	global_load_lds_dwordx4 v[154:155], off
	s_waitcnt vmcnt(16)
	s_waitcnt lgkmcnt(0)
	s_barrier
	s_setprio 1
	s_waitcnt lgkmcnt(0)
	v_mfma_f32_16x16x32_bf16 v[124:127], v[160:163], v[194:197], 0
	v_mfma_f32_16x16x32_bf16 v[116:119], v[168:171], v[194:197], 0
	v_mfma_f32_16x16x32_bf16 v[108:111], v[160:163], v[202:205], 0
	v_mfma_f32_16x16x32_bf16 v[100:103], v[168:171], v[202:205], 0
	v_mfma_f32_16x16x32_bf16 v[92:95], v[160:163], v[210:213], 0
	v_mfma_f32_16x16x32_bf16 v[84:87], v[168:171], v[210:213], 0
	v_mfma_f32_16x16x32_bf16 v[76:79], v[160:163], v[218:221], 0
	v_mfma_f32_16x16x32_bf16 v[68:71], v[168:171], v[218:221], 0
	v_mfma_f32_16x16x32_bf16 v[124:127], v[164:167], v[198:201], v[124:127]
	v_mfma_f32_16x16x32_bf16 v[116:119], v[172:175], v[198:201], v[116:119]
	v_mfma_f32_16x16x32_bf16 v[108:111], v[164:167], v[206:209], v[108:111]
	v_mfma_f32_16x16x32_bf16 v[100:103], v[172:175], v[206:209], v[100:103]
	v_mfma_f32_16x16x32_bf16 v[92:95], v[164:167], v[214:217], v[92:95]
	v_mfma_f32_16x16x32_bf16 v[84:87], v[172:175], v[214:217], v[84:87]
	v_mfma_f32_16x16x32_bf16 v[76:79], v[164:167], v[222:225], v[76:79]
	v_mfma_f32_16x16x32_bf16 v[68:71], v[172:175], v[222:225], v[68:71]
	s_setprio 0
	s_setprio 1
	v_mfma_f32_16x16x32_bf16 v[120:123], v[176:179], v[194:197], 0
	v_mfma_f32_16x16x32_bf16 v[112:115], v[186:189], v[194:197], 0
	v_mfma_f32_16x16x32_bf16 v[104:107], v[176:179], v[202:205], 0
	v_mfma_f32_16x16x32_bf16 v[96:99], v[186:189], v[202:205], 0
	v_mfma_f32_16x16x32_bf16 v[88:91], v[176:179], v[210:213], 0
	v_mfma_f32_16x16x32_bf16 v[80:83], v[186:189], v[210:213], 0
	v_mfma_f32_16x16x32_bf16 v[72:75], v[176:179], v[218:221], 0
	v_mfma_f32_16x16x32_bf16 v[64:67], v[186:189], v[218:221], 0
	v_mfma_f32_16x16x32_bf16 v[120:123], v[180:183], v[198:201], v[120:123]
	v_mfma_f32_16x16x32_bf16 v[112:115], v[190:193], v[198:201], v[112:115]
	v_mfma_f32_16x16x32_bf16 v[104:107], v[180:183], v[206:209], v[104:107]
	v_mfma_f32_16x16x32_bf16 v[96:99], v[190:193], v[206:209], v[96:99]
	v_mfma_f32_16x16x32_bf16 v[88:91], v[180:183], v[214:217], v[88:91]
	v_mfma_f32_16x16x32_bf16 v[80:83], v[190:193], v[214:217], v[80:83]
	v_mfma_f32_16x16x32_bf16 v[72:75], v[180:183], v[222:225], v[72:75]
	v_mfma_f32_16x16x32_bf16 v[64:67], v[190:193], v[222:225], v[64:67]
	s_setprio 0
	s_barrier
	s_add_i32 s76, s66, s54
	v_lshl_add_u64 v[154:155], s[48:49], 0, v[132:133]
	s_mov_b32 m0, s76
	ds_read_b128 v[194:197], v150 offset:16384
	v_xor_b32_e32 v253, 64, v150
	ds_read_b128 v[198:201], v253 offset:16384
	ds_read_b128 v[202:205], v150 offset:18432
	ds_read_b128 v[206:209], v253 offset:18432
	ds_read_b128 v[210:213], v150 offset:20480
	ds_read_b128 v[214:217], v253 offset:20480
	ds_read_b128 v[218:221], v150 offset:22528
	ds_read_b128 v[222:225], v253 offset:22528
	global_load_lds_dwordx4 v[154:155], off
	s_add_i32 m0, s76, 0x2000
	s_add_u32 s76, s48, 0x40000
	v_lshl_add_u64 v[226:227], s[48:49], 0, v[128:129]
	s_addc_u32 s77, s49, 0
	s_add_i32 s78, s67, s54
	global_load_lds_dwordx4 v[226:227], off
	v_lshl_add_u64 v[228:229], s[76:77], 0, v[132:133]
	s_mov_b32 m0, s78
	v_lshl_add_u64 v[230:231], s[50:51], 0, v[130:131]
	global_load_lds_dwordx4 v[228:229], off
	v_lshl_add_u64 v[228:229], s[76:77], 0, v[128:129]
	s_add_i32 m0, s78, 0x2000
	s_nop 0
	global_load_lds_dwordx4 v[228:229], off
	v_lshl_add_u64 v[228:229], s[50:51], 0, v[134:135]
	s_mov_b32 m0, s57
	s_nop 0
	global_load_lds_dwordx4 v[228:229], off
	s_mov_b32 m0, s58
	s_nop 0
	global_load_lds_dwordx4 v[230:231], off
	s_waitcnt vmcnt(16)
	s_waitcnt lgkmcnt(0)
	s_barrier
	s_setprio 1
	s_waitcnt lgkmcnt(0)
	v_mfma_f32_16x16x32_bf16 v[60:63], v[160:163], v[194:197], 0
	v_mfma_f32_16x16x32_bf16 v[52:55], v[168:171], v[194:197], 0
	v_mfma_f32_16x16x32_bf16 v[44:47], v[160:163], v[202:205], 0
	v_mfma_f32_16x16x32_bf16 v[36:39], v[168:171], v[202:205], 0
	v_mfma_f32_16x16x32_bf16 v[28:31], v[160:163], v[210:213], 0
	v_mfma_f32_16x16x32_bf16 v[20:23], v[168:171], v[210:213], 0
	v_mfma_f32_16x16x32_bf16 v[12:15], v[160:163], v[218:221], 0
	v_mfma_f32_16x16x32_bf16 v[4:7], v[168:171], v[218:221], 0
	v_mfma_f32_16x16x32_bf16 v[60:63], v[164:167], v[198:201], v[60:63]
	v_mfma_f32_16x16x32_bf16 v[52:55], v[172:175], v[198:201], v[52:55]
	v_mfma_f32_16x16x32_bf16 v[44:47], v[164:167], v[206:209], v[44:47]
	v_mfma_f32_16x16x32_bf16 v[36:39], v[172:175], v[206:209], v[36:39]
	v_mfma_f32_16x16x32_bf16 v[28:31], v[164:167], v[214:217], v[28:31]
	v_mfma_f32_16x16x32_bf16 v[20:23], v[172:175], v[214:217], v[20:23]
	v_mfma_f32_16x16x32_bf16 v[12:15], v[164:167], v[222:225], v[12:15]
	v_mfma_f32_16x16x32_bf16 v[4:7], v[172:175], v[222:225], v[4:7]
	s_setprio 0
	s_setprio 1
	v_mfma_f32_16x16x32_bf16 v[56:59], v[176:179], v[194:197], 0
	v_mfma_f32_16x16x32_bf16 v[48:51], v[186:189], v[194:197], 0
	v_mfma_f32_16x16x32_bf16 v[40:43], v[176:179], v[202:205], 0
	v_mfma_f32_16x16x32_bf16 v[32:35], v[186:189], v[202:205], 0
	v_mfma_f32_16x16x32_bf16 v[24:27], v[176:179], v[210:213], 0
	v_mfma_f32_16x16x32_bf16 v[16:19], v[186:189], v[210:213], 0
	v_mfma_f32_16x16x32_bf16 v[8:11], v[176:179], v[218:221], 0
	v_mfma_f32_16x16x32_bf16 v[0:3], v[186:189], v[218:221], 0
	v_mfma_f32_16x16x32_bf16 v[56:59], v[180:183], v[198:201], v[56:59]
	v_mfma_f32_16x16x32_bf16 v[48:51], v[190:193], v[198:201], v[48:51]
	v_mfma_f32_16x16x32_bf16 v[40:43], v[180:183], v[206:209], v[40:43]
	v_mfma_f32_16x16x32_bf16 v[32:35], v[190:193], v[206:209], v[32:35]
	v_mfma_f32_16x16x32_bf16 v[24:27], v[180:183], v[214:217], v[24:27]
	v_mfma_f32_16x16x32_bf16 v[16:19], v[190:193], v[214:217], v[16:19]
	v_mfma_f32_16x16x32_bf16 v[8:11], v[180:183], v[222:225], v[8:11]
	v_mfma_f32_16x16x32_bf16 v[0:3], v[190:193], v[222:225], v[0:3]
	s_setprio 0
	s_barrier
	s_add_i32 s76, 0, 0x18000
	v_add_u32_e32 v153, s76, v147
	s_add_i32 s77, 0, 0x1c000
	ds_read_b128 v[160:163], v153
	v_xor_b32_e32 v253, 64, v153
	ds_read_b128 v[164:167], v253
	ds_read_b128 v[168:171], v153 offset:2048
	ds_read_b128 v[172:175], v253 offset:2048
	v_add_u32_e32 v153, s77, v147
	ds_read_b128 v[176:179], v153
	v_xor_b32_e32 v253, 64, v153
	ds_read_b128 v[180:183], v253
	ds_read_b128 v[186:189], v153 offset:2048
	ds_read_b128 v[190:193], v253 offset:2048
	s_add_u32 s50, s50, 0x40000
	s_addc_u32 s51, s51, 0
	s_mov_b32 m0, s59
	v_lshl_add_u64 v[232:233], s[50:51], 0, v[134:135]
	ds_read_b128 v[194:197], v150 offset:32768
	v_xor_b32_e32 v253, 64, v150
	ds_read_b128 v[198:201], v253 offset:32768
	ds_read_b128 v[202:205], v150 offset:34816
	ds_read_b128 v[206:209], v253 offset:34816
	ds_read_b128 v[210:213], v150 offset:36864
	ds_read_b128 v[214:217], v253 offset:36864
	ds_read_b128 v[218:221], v150 offset:38912
	ds_read_b128 v[222:225], v253 offset:38912
	global_load_lds_dwordx4 v[232:233], off
	v_lshl_add_u64 v[232:233], s[50:51], 0, v[130:131]
	s_mov_b32 m0, s60
	s_nop 0
	global_load_lds_dwordx4 v[232:233], off
	s_waitcnt vmcnt(8)
	s_waitcnt lgkmcnt(0)
	s_barrier
	s_setprio 1
	s_waitcnt lgkmcnt(0)
	v_mfma_f32_16x16x32_bf16 v[124:127], v[160:163], v[194:197], v[124:127]
	v_mfma_f32_16x16x32_bf16 v[124:127], v[164:167], v[198:201], v[124:127]
	v_mfma_f32_16x16x32_bf16 v[108:111], v[164:167], v[206:209], v[108:111]
	v_mfma_f32_16x16x32_bf16 v[108:111], v[160:163], v[202:205], v[108:111]
	v_mfma_f32_16x16x32_bf16 v[92:95], v[160:163], v[210:213], v[92:95]
	v_mfma_f32_16x16x32_bf16 v[92:95], v[164:167], v[214:217], v[92:95]
	v_mfma_f32_16x16x32_bf16 v[76:79], v[164:167], v[222:225], v[76:79]
	v_mfma_f32_16x16x32_bf16 v[76:79], v[160:163], v[218:221], v[76:79]
	v_mfma_f32_16x16x32_bf16 v[68:71], v[168:171], v[218:221], v[68:71]
	v_mfma_f32_16x16x32_bf16 v[68:71], v[172:175], v[222:225], v[68:71]
	v_mfma_f32_16x16x32_bf16 v[84:87], v[172:175], v[214:217], v[84:87]
	v_mfma_f32_16x16x32_bf16 v[84:87], v[168:171], v[210:213], v[84:87]
	v_mfma_f32_16x16x32_bf16 v[100:103], v[168:171], v[202:205], v[100:103]
	v_mfma_f32_16x16x32_bf16 v[100:103], v[172:175], v[206:209], v[100:103]
	v_mfma_f32_16x16x32_bf16 v[116:119], v[172:175], v[198:201], v[116:119]
	v_mfma_f32_16x16x32_bf16 v[116:119], v[168:171], v[194:197], v[116:119]
	s_setprio 0
	s_setprio 1
	v_mfma_f32_16x16x32_bf16 v[120:123], v[176:179], v[194:197], v[120:123]
	v_mfma_f32_16x16x32_bf16 v[120:123], v[180:183], v[198:201], v[120:123]
	v_mfma_f32_16x16x32_bf16 v[104:107], v[180:183], v[206:209], v[104:107]
	v_mfma_f32_16x16x32_bf16 v[104:107], v[176:179], v[202:205], v[104:107]
	v_mfma_f32_16x16x32_bf16 v[88:91], v[176:179], v[210:213], v[88:91]
	v_mfma_f32_16x16x32_bf16 v[88:91], v[180:183], v[214:217], v[88:91]
	v_mfma_f32_16x16x32_bf16 v[72:75], v[180:183], v[222:225], v[72:75]
	v_mfma_f32_16x16x32_bf16 v[72:75], v[176:179], v[218:221], v[72:75]
	v_mfma_f32_16x16x32_bf16 v[64:67], v[186:189], v[218:221], v[64:67]
	v_mfma_f32_16x16x32_bf16 v[64:67], v[190:193], v[222:225], v[64:67]
	v_mfma_f32_16x16x32_bf16 v[80:83], v[190:193], v[214:217], v[80:83]
	v_mfma_f32_16x16x32_bf16 v[80:83], v[186:189], v[210:213], v[80:83]
	v_mfma_f32_16x16x32_bf16 v[96:99], v[186:189], v[202:205], v[96:99]
	v_mfma_f32_16x16x32_bf16 v[96:99], v[190:193], v[206:209], v[96:99]
	v_mfma_f32_16x16x32_bf16 v[112:115], v[190:193], v[198:201], v[112:115]
	v_mfma_f32_16x16x32_bf16 v[112:115], v[186:189], v[194:197], v[112:115]
	s_setprio 0
	s_barrier
	s_add_i32 s50, s76, s54
	v_lshl_add_u64 v[154:155], v[154:155], 0, s[20:21]
	s_mov_b32 m0, s50
	ds_read_b128 v[194:197], v150 offset:49152
	v_xor_b32_e32 v253, 64, v150
	ds_read_b128 v[198:201], v253 offset:49152
	ds_read_b128 v[202:205], v150 offset:51200
	ds_read_b128 v[206:209], v253 offset:51200
	ds_read_b128 v[210:213], v150 offset:53248
	ds_read_b128 v[214:217], v253 offset:53248
	ds_read_b128 v[218:221], v150 offset:55296
	ds_read_b128 v[222:225], v253 offset:55296
	global_load_lds_dwordx4 v[154:155], off
	s_add_i32 m0, s50, 0x2000
	s_add_u32 s48, s48, 0x40080
	v_lshl_add_u64 v[154:155], v[226:227], 0, s[20:21]
	s_addc_u32 s49, s49, 0
	s_add_i32 s50, s77, s54
	global_load_lds_dwordx4 v[154:155], off
	v_lshl_add_u64 v[154:155], s[48:49], 0, v[132:133]
	s_mov_b32 m0, s50
	s_nop 0
	global_load_lds_dwordx4 v[154:155], off
	v_lshl_add_u64 v[154:155], s[48:49], 0, v[128:129]
	s_add_i32 m0, s50, 0x2000
	s_nop 0
	global_load_lds_dwordx4 v[154:155], off
	v_lshl_add_u64 v[154:155], v[228:229], 0, s[20:21]
	s_mov_b32 m0, s62
	s_nop 0
	global_load_lds_dwordx4 v[154:155], off
	v_lshl_add_u64 v[154:155], v[230:231], 0, s[20:21]
	s_mov_b32 m0, s63
	s_nop 0
	global_load_lds_dwordx4 v[154:155], off
	s_waitcnt vmcnt(8)
	s_waitcnt lgkmcnt(0)
	s_barrier
	s_setprio 1
	s_waitcnt lgkmcnt(0)
	v_mfma_f32_16x16x32_bf16 v[60:63], v[160:163], v[194:197], v[60:63]
	v_mfma_f32_16x16x32_bf16 v[60:63], v[164:167], v[198:201], v[60:63]
	v_mfma_f32_16x16x32_bf16 v[44:47], v[164:167], v[206:209], v[44:47]
	v_mfma_f32_16x16x32_bf16 v[44:47], v[160:163], v[202:205], v[44:47]
	v_mfma_f32_16x16x32_bf16 v[28:31], v[160:163], v[210:213], v[28:31]
	v_mfma_f32_16x16x32_bf16 v[28:31], v[164:167], v[214:217], v[28:31]
	v_mfma_f32_16x16x32_bf16 v[12:15], v[164:167], v[222:225], v[12:15]
	v_mfma_f32_16x16x32_bf16 v[12:15], v[160:163], v[218:221], v[12:15]
	v_mfma_f32_16x16x32_bf16 v[4:7], v[168:171], v[218:221], v[4:7]
	v_mfma_f32_16x16x32_bf16 v[4:7], v[172:175], v[222:225], v[4:7]
	v_mfma_f32_16x16x32_bf16 v[20:23], v[172:175], v[214:217], v[20:23]
	v_mfma_f32_16x16x32_bf16 v[20:23], v[168:171], v[210:213], v[20:23]
	v_mfma_f32_16x16x32_bf16 v[36:39], v[168:171], v[202:205], v[36:39]
	v_mfma_f32_16x16x32_bf16 v[36:39], v[172:175], v[206:209], v[36:39]
	v_mfma_f32_16x16x32_bf16 v[52:55], v[172:175], v[198:201], v[52:55]
	v_mfma_f32_16x16x32_bf16 v[52:55], v[168:171], v[194:197], v[52:55]
	s_setprio 0
	s_setprio 1
	v_mfma_f32_16x16x32_bf16 v[56:59], v[176:179], v[194:197], v[56:59]
	v_mfma_f32_16x16x32_bf16 v[56:59], v[180:183], v[198:201], v[56:59]
	v_mfma_f32_16x16x32_bf16 v[40:43], v[180:183], v[206:209], v[40:43]
	v_mfma_f32_16x16x32_bf16 v[40:43], v[176:179], v[202:205], v[40:43]
	v_mfma_f32_16x16x32_bf16 v[24:27], v[176:179], v[210:213], v[24:27]
	v_mfma_f32_16x16x32_bf16 v[24:27], v[180:183], v[214:217], v[24:27]
	v_mfma_f32_16x16x32_bf16 v[8:11], v[180:183], v[222:225], v[8:11]
	v_mfma_f32_16x16x32_bf16 v[8:11], v[176:179], v[218:221], v[8:11]
	v_mfma_f32_16x16x32_bf16 v[0:3], v[186:189], v[218:221], v[0:3]
	v_mfma_f32_16x16x32_bf16 v[0:3], v[190:193], v[222:225], v[0:3]
	v_mfma_f32_16x16x32_bf16 v[16:19], v[190:193], v[214:217], v[16:19]
	v_mfma_f32_16x16x32_bf16 v[16:19], v[186:189], v[210:213], v[16:19]
	v_mfma_f32_16x16x32_bf16 v[32:35], v[186:189], v[202:205], v[32:35]
	v_mfma_f32_16x16x32_bf16 v[32:35], v[190:193], v[206:209], v[32:35]
	v_mfma_f32_16x16x32_bf16 v[48:51], v[190:193], v[198:201], v[48:51]
	v_mfma_f32_16x16x32_bf16 v[48:51], v[186:189], v[194:197], v[48:51]
	s_setprio 0
	s_barrier
	s_add_i32 s75, s75, 2
	s_add_u32 s73, s73, 0x100
	s_addc_u32 s74, s74, 0
	s_add_u32 s46, s46, 0x100
	s_addc_u32 s47, s47, 0
	s_branch .LBB0_527
.Lfa_4:
	v_add_u32_e32 v153, s66, v147
	ds_read_b128 v[160:163], v153
	v_xor_b32_e32 v253, 64, v153
	ds_read_b128 v[164:167], v253
	ds_read_b128 v[168:171], v153 offset:2048
	ds_read_b128 v[172:175], v253 offset:2048
	v_add_u32_e32 v153, s67, v147
	ds_read_b128 v[176:179], v153
	v_xor_b32_e32 v253, 64, v153
	ds_read_b128 v[180:183], v253
	ds_read_b128 v[186:189], v153 offset:2048
	ds_read_b128 v[190:193], v253 offset:2048
	s_add_u32 s50, s46, 0xfffc0080
	s_addc_u32 s51, s47, -1
	s_and_b64 s[48:49], s[48:49], exec
	s_cselect_b32 s51, s29, s51
	s_cselect_b32 s50, s70, s50
	s_cselect_b32 s49, s71, s74
	s_cselect_b32 s48, s72, s73
	v_lshl_add_u64 v[154:155], s[46:47], 0, v[138:139]
	s_add_i32 m0, s57, 0xc000
	ds_read_b128 v[194:197], v150
	v_xor_b32_e32 v253, 64, v150
	ds_read_b128 v[198:201], v253
	ds_read_b128 v[202:205], v150 offset:2048
	ds_read_b128 v[206:209], v253 offset:2048
	ds_read_b128 v[210:213], v150 offset:4096
	ds_read_b128 v[214:217], v253 offset:4096
	ds_read_b128 v[218:221], v150 offset:6144
	ds_read_b128 v[222:225], v253 offset:6144
	global_load_lds_dwordx4 v[154:155], off
	v_lshl_add_u64 v[154:155], s[46:47], 0, v[136:137]
	s_add_i32 m0, s57, 0xe000
	s_nop 0
	global_load_lds_dwordx4 v[154:155], off
	s_waitcnt vmcnt(8)
	s_waitcnt lgkmcnt(0)
	s_barrier
	s_setprio 1
	s_waitcnt lgkmcnt(0)
	v_mfma_f32_16x16x32_bf16 v[124:127], v[160:163], v[194:197], 0
	v_mfma_f32_16x16x32_bf16 v[116:119], v[168:171], v[194:197], 0
	v_mfma_f32_16x16x32_bf16 v[108:111], v[160:163], v[202:205], 0
	v_mfma_f32_16x16x32_bf16 v[100:103], v[168:171], v[202:205], 0
	v_mfma_f32_16x16x32_bf16 v[92:95], v[160:163], v[210:213], 0
	v_mfma_f32_16x16x32_bf16 v[84:87], v[168:171], v[210:213], 0
	v_mfma_f32_16x16x32_bf16 v[76:79], v[160:163], v[218:221], 0
	v_mfma_f32_16x16x32_bf16 v[68:71], v[168:171], v[218:221], 0
	v_mfma_f32_16x16x32_bf16 v[124:127], v[164:167], v[198:201], v[124:127]
	v_mfma_f32_16x16x32_bf16 v[116:119], v[172:175], v[198:201], v[116:119]
	v_mfma_f32_16x16x32_bf16 v[108:111], v[164:167], v[206:209], v[108:111]
	v_mfma_f32_16x16x32_bf16 v[100:103], v[172:175], v[206:209], v[100:103]
	v_mfma_f32_16x16x32_bf16 v[92:95], v[164:167], v[214:217], v[92:95]
	v_mfma_f32_16x16x32_bf16 v[84:87], v[172:175], v[214:217], v[84:87]
	v_mfma_f32_16x16x32_bf16 v[76:79], v[164:167], v[222:225], v[76:79]
	v_mfma_f32_16x16x32_bf16 v[68:71], v[172:175], v[222:225], v[68:71]
	s_setprio 0
	s_setprio 1
	v_mfma_f32_16x16x32_bf16 v[120:123], v[176:179], v[194:197], 0
	v_mfma_f32_16x16x32_bf16 v[112:115], v[186:189], v[194:197], 0
	v_mfma_f32_16x16x32_bf16 v[104:107], v[176:179], v[202:205], 0
	v_mfma_f32_16x16x32_bf16 v[96:99], v[186:189], v[202:205], 0
	v_mfma_f32_16x16x32_bf16 v[88:91], v[176:179], v[210:213], 0
	v_mfma_f32_16x16x32_bf16 v[80:83], v[186:189], v[210:213], 0
	v_mfma_f32_16x16x32_bf16 v[72:75], v[176:179], v[218:221], 0
	v_mfma_f32_16x16x32_bf16 v[64:67], v[186:189], v[218:221], 0
	v_mfma_f32_16x16x32_bf16 v[120:123], v[180:183], v[198:201], v[120:123]
	v_mfma_f32_16x16x32_bf16 v[112:115], v[190:193], v[198:201], v[112:115]
	v_mfma_f32_16x16x32_bf16 v[104:107], v[180:183], v[206:209], v[104:107]
	v_mfma_f32_16x16x32_bf16 v[96:99], v[190:193], v[206:209], v[96:99]
	v_mfma_f32_16x16x32_bf16 v[88:91], v[180:183], v[214:217], v[88:91]
	v_mfma_f32_16x16x32_bf16 v[80:83], v[190:193], v[214:217], v[80:83]
	v_mfma_f32_16x16x32_bf16 v[72:75], v[180:183], v[222:225], v[72:75]
	v_mfma_f32_16x16x32_bf16 v[64:67], v[190:193], v[222:225], v[64:67]
	s_setprio 0
	s_barrier
	s_add_i32 s76, s66, s54
	v_lshl_add_u64 v[154:155], s[48:49], 0, v[132:133]
	s_mov_b32 m0, s76
	ds_read_b128 v[194:197], v150 offset:16384
	v_xor_b32_e32 v253, 64, v150
	ds_read_b128 v[198:201], v253 offset:16384
	ds_read_b128 v[202:205], v150 offset:18432
	ds_read_b128 v[206:209], v253 offset:18432
	ds_read_b128 v[210:213], v150 offset:20480
	ds_read_b128 v[214:217], v253 offset:20480
	ds_read_b128 v[218:221], v150 offset:22528
	ds_read_b128 v[222:225], v253 offset:22528
	global_load_lds_dwordx4 v[154:155], off
	s_add_i32 m0, s76, 0x2000
	s_add_u32 s76, s48, 0x40000
	v_lshl_add_u64 v[226:227], s[48:49], 0, v[128:129]
	s_addc_u32 s77, s49, 0
	s_add_i32 s78, s67, s54
	global_load_lds_dwordx4 v[226:227], off
	v_lshl_add_u64 v[228:229], s[76:77], 0, v[132:133]
	s_mov_b32 m0, s78
	v_lshl_add_u64 v[230:231], s[50:51], 0, v[130:131]
	global_load_lds_dwordx4 v[228:229], off
	v_lshl_add_u64 v[228:229], s[76:77], 0, v[128:129]
	s_add_i32 m0, s78, 0x2000
	s_nop 0
	global_load_lds_dwordx4 v[228:229], off
	v_lshl_add_u64 v[228:229], s[50:51], 0, v[134:135]
	s_mov_b32 m0, s57
	s_nop 0
	global_load_lds_dwordx4 v[228:229], off
	s_mov_b32 m0, s58
	s_nop 0
	global_load_lds_dwordx4 v[230:231], off
	s_waitcnt vmcnt(8)
	s_waitcnt lgkmcnt(0)
	s_barrier
	s_setprio 1
	s_waitcnt lgkmcnt(0)
	v_mfma_f32_16x16x32_bf16 v[60:63], v[160:163], v[194:197], 0
	v_mfma_f32_16x16x32_bf16 v[52:55], v[168:171], v[194:197], 0
	v_mfma_f32_16x16x32_bf16 v[44:47], v[160:163], v[202:205], 0
	v_mfma_f32_16x16x32_bf16 v[36:39], v[168:171], v[202:205], 0
	v_mfma_f32_16x16x32_bf16 v[28:31], v[160:163], v[210:213], 0
	v_mfma_f32_16x16x32_bf16 v[20:23], v[168:171], v[210:213], 0
	v_mfma_f32_16x16x32_bf16 v[12:15], v[160:163], v[218:221], 0
	v_mfma_f32_16x16x32_bf16 v[4:7], v[168:171], v[218:221], 0
	v_mfma_f32_16x16x32_bf16 v[60:63], v[164:167], v[198:201], v[60:63]
	v_mfma_f32_16x16x32_bf16 v[52:55], v[172:175], v[198:201], v[52:55]
	v_mfma_f32_16x16x32_bf16 v[44:47], v[164:167], v[206:209], v[44:47]
	v_mfma_f32_16x16x32_bf16 v[36:39], v[172:175], v[206:209], v[36:39]
	v_mfma_f32_16x16x32_bf16 v[28:31], v[164:167], v[214:217], v[28:31]
	v_mfma_f32_16x16x32_bf16 v[20:23], v[172:175], v[214:217], v[20:23]
	v_mfma_f32_16x16x32_bf16 v[12:15], v[164:167], v[222:225], v[12:15]
	v_mfma_f32_16x16x32_bf16 v[4:7], v[172:175], v[222:225], v[4:7]
	s_setprio 0
	s_setprio 1
	v_mfma_f32_16x16x32_bf16 v[56:59], v[176:179], v[194:197], 0
	v_mfma_f32_16x16x32_bf16 v[48:51], v[186:189], v[194:197], 0
	v_mfma_f32_16x16x32_bf16 v[40:43], v[176:179], v[202:205], 0
	v_mfma_f32_16x16x32_bf16 v[32:35], v[186:189], v[202:205], 0
	v_mfma_f32_16x16x32_bf16 v[24:27], v[176:179], v[210:213], 0
	v_mfma_f32_16x16x32_bf16 v[16:19], v[186:189], v[210:213], 0
	v_mfma_f32_16x16x32_bf16 v[8:11], v[176:179], v[218:221], 0
	v_mfma_f32_16x16x32_bf16 v[0:3], v[186:189], v[218:221], 0
	v_mfma_f32_16x16x32_bf16 v[56:59], v[180:183], v[198:201], v[56:59]
	v_mfma_f32_16x16x32_bf16 v[48:51], v[190:193], v[198:201], v[48:51]
	v_mfma_f32_16x16x32_bf16 v[40:43], v[180:183], v[206:209], v[40:43]
	v_mfma_f32_16x16x32_bf16 v[32:35], v[190:193], v[206:209], v[32:35]
	v_mfma_f32_16x16x32_bf16 v[24:27], v[180:183], v[214:217], v[24:27]
	v_mfma_f32_16x16x32_bf16 v[16:19], v[190:193], v[214:217], v[16:19]
	v_mfma_f32_16x16x32_bf16 v[8:11], v[180:183], v[222:225], v[8:11]
	v_mfma_f32_16x16x32_bf16 v[0:3], v[190:193], v[222:225], v[0:3]
	s_setprio 0
	s_barrier
	s_add_i32 s76, 0, 0x18000
	v_add_u32_e32 v153, s76, v147
	s_add_i32 s77, 0, 0x1c000
	ds_read_b128 v[160:163], v153
	v_xor_b32_e32 v253, 64, v153
	ds_read_b128 v[164:167], v253
	ds_read_b128 v[168:171], v153 offset:2048
	ds_read_b128 v[172:175], v253 offset:2048
	v_add_u32_e32 v153, s77, v147
	ds_read_b128 v[176:179], v153
	v_xor_b32_e32 v253, 64, v153
	ds_read_b128 v[180:183], v253
	ds_read_b128 v[186:189], v153 offset:2048
	ds_read_b128 v[190:193], v253 offset:2048
	s_add_u32 s50, s50, 0x40000
	s_addc_u32 s51, s51, 0
	s_mov_b32 m0, s59
	v_lshl_add_u64 v[232:233], s[50:51], 0, v[134:135]
	ds_read_b128 v[194:197], v150 offset:32768
	v_xor_b32_e32 v253, 64, v150
	ds_read_b128 v[198:201], v253 offset:32768
	ds_read_b128 v[202:205], v150 offset:34816
	ds_read_b128 v[206:209], v253 offset:34816
	ds_read_b128 v[210:213], v150 offset:36864
	ds_read_b128 v[214:217], v253 offset:36864
	ds_read_b128 v[218:221], v150 offset:38912
	ds_read_b128 v[222:225], v253 offset:38912
	global_load_lds_dwordx4 v[232:233], off
	v_lshl_add_u64 v[232:233], s[50:51], 0, v[130:131]
	s_mov_b32 m0, s60
	s_nop 0
	global_load_lds_dwordx4 v[232:233], off
	s_waitcnt vmcnt(8)
	s_waitcnt lgkmcnt(0)
	s_barrier
	s_setprio 1
	s_waitcnt lgkmcnt(0)
	v_mfma_f32_16x16x32_bf16 v[124:127], v[160:163], v[194:197], v[124:127]
	v_mfma_f32_16x16x32_bf16 v[124:127], v[164:167], v[198:201], v[124:127]
	v_mfma_f32_16x16x32_bf16 v[108:111], v[164:167], v[206:209], v[108:111]
	v_mfma_f32_16x16x32_bf16 v[108:111], v[160:163], v[202:205], v[108:111]
	v_mfma_f32_16x16x32_bf16 v[92:95], v[160:163], v[210:213], v[92:95]
	v_mfma_f32_16x16x32_bf16 v[92:95], v[164:167], v[214:217], v[92:95]
	v_mfma_f32_16x16x32_bf16 v[76:79], v[164:167], v[222:225], v[76:79]
	v_mfma_f32_16x16x32_bf16 v[76:79], v[160:163], v[218:221], v[76:79]
	v_mfma_f32_16x16x32_bf16 v[68:71], v[168:171], v[218:221], v[68:71]
	v_mfma_f32_16x16x32_bf16 v[68:71], v[172:175], v[222:225], v[68:71]
	v_mfma_f32_16x16x32_bf16 v[84:87], v[172:175], v[214:217], v[84:87]
	v_mfma_f32_16x16x32_bf16 v[84:87], v[168:171], v[210:213], v[84:87]
	v_mfma_f32_16x16x32_bf16 v[100:103], v[168:171], v[202:205], v[100:103]
	v_mfma_f32_16x16x32_bf16 v[100:103], v[172:175], v[206:209], v[100:103]
	v_mfma_f32_16x16x32_bf16 v[116:119], v[172:175], v[198:201], v[116:119]
	v_mfma_f32_16x16x32_bf16 v[116:119], v[168:171], v[194:197], v[116:119]
	s_setprio 0
	s_setprio 1
	v_mfma_f32_16x16x32_bf16 v[120:123], v[176:179], v[194:197], v[120:123]
	v_mfma_f32_16x16x32_bf16 v[120:123], v[180:183], v[198:201], v[120:123]
	v_mfma_f32_16x16x32_bf16 v[104:107], v[180:183], v[206:209], v[104:107]
	v_mfma_f32_16x16x32_bf16 v[104:107], v[176:179], v[202:205], v[104:107]
	v_mfma_f32_16x16x32_bf16 v[88:91], v[176:179], v[210:213], v[88:91]
	v_mfma_f32_16x16x32_bf16 v[88:91], v[180:183], v[214:217], v[88:91]
	v_mfma_f32_16x16x32_bf16 v[72:75], v[180:183], v[222:225], v[72:75]
	v_mfma_f32_16x16x32_bf16 v[72:75], v[176:179], v[218:221], v[72:75]
	v_mfma_f32_16x16x32_bf16 v[64:67], v[186:189], v[218:221], v[64:67]
	v_mfma_f32_16x16x32_bf16 v[64:67], v[190:193], v[222:225], v[64:67]
	v_mfma_f32_16x16x32_bf16 v[80:83], v[190:193], v[214:217], v[80:83]
	v_mfma_f32_16x16x32_bf16 v[80:83], v[186:189], v[210:213], v[80:83]
	v_mfma_f32_16x16x32_bf16 v[96:99], v[186:189], v[202:205], v[96:99]
	v_mfma_f32_16x16x32_bf16 v[96:99], v[190:193], v[206:209], v[96:99]
	v_mfma_f32_16x16x32_bf16 v[112:115], v[190:193], v[198:201], v[112:115]
	v_mfma_f32_16x16x32_bf16 v[112:115], v[186:189], v[194:197], v[112:115]
	s_setprio 0
	s_barrier
	s_add_i32 s50, s76, s54
	v_lshl_add_u64 v[154:155], v[154:155], 0, s[20:21]
	s_mov_b32 m0, s50
	ds_read_b128 v[194:197], v150 offset:49152
	v_xor_b32_e32 v253, 64, v150
	ds_read_b128 v[198:201], v253 offset:49152
	ds_read_b128 v[202:205], v150 offset:51200
	ds_read_b128 v[206:209], v253 offset:51200
	ds_read_b128 v[210:213], v150 offset:53248
	ds_read_b128 v[214:217], v253 offset:53248
	ds_read_b128 v[218:221], v150 offset:55296
	ds_read_b128 v[222:225], v253 offset:55296
	global_load_lds_dwordx4 v[154:155], off
	s_add_i32 m0, s50, 0x2000
	s_add_u32 s48, s48, 0x40080
	v_lshl_add_u64 v[154:155], v[226:227], 0, s[20:21]
	s_addc_u32 s49, s49, 0
	s_add_i32 s50, s77, s54
	global_load_lds_dwordx4 v[154:155], off
	v_lshl_add_u64 v[154:155], s[48:49], 0, v[132:133]
	s_mov_b32 m0, s50
	s_nop 0
	global_load_lds_dwordx4 v[154:155], off
	v_lshl_add_u64 v[154:155], s[48:49], 0, v[128:129]
	s_add_i32 m0, s50, 0x2000
	s_nop 0
	global_load_lds_dwordx4 v[154:155], off
	v_lshl_add_u64 v[154:155], v[228:229], 0, s[20:21]
	s_mov_b32 m0, s62
	s_nop 0
	global_load_lds_dwordx4 v[154:155], off
	v_lshl_add_u64 v[154:155], v[230:231], 0, s[20:21]
	s_mov_b32 m0, s63
	s_nop 0
	global_load_lds_dwordx4 v[154:155], off
	s_waitcnt vmcnt(8)
	s_waitcnt lgkmcnt(0)
	s_barrier
	s_setprio 1
	s_waitcnt lgkmcnt(0)
	v_mfma_f32_16x16x32_bf16 v[60:63], v[160:163], v[194:197], v[60:63]
	v_mfma_f32_16x16x32_bf16 v[60:63], v[164:167], v[198:201], v[60:63]
	v_mfma_f32_16x16x32_bf16 v[44:47], v[164:167], v[206:209], v[44:47]
	v_mfma_f32_16x16x32_bf16 v[44:47], v[160:163], v[202:205], v[44:47]
	v_mfma_f32_16x16x32_bf16 v[28:31], v[160:163], v[210:213], v[28:31]
	v_mfma_f32_16x16x32_bf16 v[28:31], v[164:167], v[214:217], v[28:31]
	v_mfma_f32_16x16x32_bf16 v[12:15], v[164:167], v[222:225], v[12:15]
	v_mfma_f32_16x16x32_bf16 v[12:15], v[160:163], v[218:221], v[12:15]
	v_mfma_f32_16x16x32_bf16 v[4:7], v[168:171], v[218:221], v[4:7]
	v_mfma_f32_16x16x32_bf16 v[4:7], v[172:175], v[222:225], v[4:7]
	v_mfma_f32_16x16x32_bf16 v[20:23], v[172:175], v[214:217], v[20:23]
	v_mfma_f32_16x16x32_bf16 v[20:23], v[168:171], v[210:213], v[20:23]
	v_mfma_f32_16x16x32_bf16 v[36:39], v[168:171], v[202:205], v[36:39]
	v_mfma_f32_16x16x32_bf16 v[36:39], v[172:175], v[206:209], v[36:39]
	v_mfma_f32_16x16x32_bf16 v[52:55], v[172:175], v[198:201], v[52:55]
	v_mfma_f32_16x16x32_bf16 v[52:55], v[168:171], v[194:197], v[52:55]
	s_setprio 0
	s_setprio 1
	v_mfma_f32_16x16x32_bf16 v[56:59], v[176:179], v[194:197], v[56:59]
	v_mfma_f32_16x16x32_bf16 v[56:59], v[180:183], v[198:201], v[56:59]
	v_mfma_f32_16x16x32_bf16 v[40:43], v[180:183], v[206:209], v[40:43]
	v_mfma_f32_16x16x32_bf16 v[40:43], v[176:179], v[202:205], v[40:43]
	v_mfma_f32_16x16x32_bf16 v[24:27], v[176:179], v[210:213], v[24:27]
	v_mfma_f32_16x16x32_bf16 v[24:27], v[180:183], v[214:217], v[24:27]
	v_mfma_f32_16x16x32_bf16 v[8:11], v[180:183], v[222:225], v[8:11]
	v_mfma_f32_16x16x32_bf16 v[8:11], v[176:179], v[218:221], v[8:11]
	v_mfma_f32_16x16x32_bf16 v[0:3], v[186:189], v[218:221], v[0:3]
	v_mfma_f32_16x16x32_bf16 v[0:3], v[190:193], v[222:225], v[0:3]
	v_mfma_f32_16x16x32_bf16 v[16:19], v[190:193], v[214:217], v[16:19]
	v_mfma_f32_16x16x32_bf16 v[16:19], v[186:189], v[210:213], v[16:19]
	v_mfma_f32_16x16x32_bf16 v[32:35], v[186:189], v[202:205], v[32:35]
	v_mfma_f32_16x16x32_bf16 v[32:35], v[190:193], v[206:209], v[32:35]
	v_mfma_f32_16x16x32_bf16 v[48:51], v[190:193], v[198:201], v[48:51]
	v_mfma_f32_16x16x32_bf16 v[48:51], v[186:189], v[194:197], v[48:51]
	s_setprio 0
	s_barrier
	s_add_i32 s75, s75, 2
	s_add_u32 s73, s73, 0x100
	s_addc_u32 s74, s74, 0
	s_add_u32 s46, s46, 0x100
	s_addc_u32 s47, s47, 0
	s_branch .LBB0_527
.LBB0_526:
	v_add_u32_e32 v153, s66, v147
	ds_read_b128 v[160:163], v153
	v_xor_b32_e32 v253, 64, v153
	ds_read_b128 v[164:167], v253
	ds_read_b128 v[168:171], v153 offset:2048
	ds_read_b128 v[172:175], v253 offset:2048
	v_add_u32_e32 v153, s67, v147
	ds_read_b128 v[176:179], v153
	v_xor_b32_e32 v253, 64, v153
	ds_read_b128 v[180:183], v253
	ds_read_b128 v[186:189], v153 offset:2048
	ds_read_b128 v[190:193], v253 offset:2048
	s_add_u32 s50, s46, 0xfffc0080
	s_addc_u32 s51, s47, -1
	s_and_b64 s[48:49], s[48:49], exec
	s_cselect_b32 s51, s29, s51
	s_cselect_b32 s50, s70, s50
	s_cselect_b32 s49, s71, s74
	s_cselect_b32 s48, s72, s73
	v_lshl_add_u64 v[154:155], s[46:47], 0, v[138:139]
	s_add_i32 m0, s57, 0xc000
	ds_read_b128 v[194:197], v150
	v_xor_b32_e32 v253, 64, v150
	ds_read_b128 v[198:201], v253
	ds_read_b128 v[202:205], v150 offset:2048
	ds_read_b128 v[206:209], v253 offset:2048
	ds_read_b128 v[210:213], v150 offset:4096
	ds_read_b128 v[214:217], v253 offset:4096
	ds_read_b128 v[218:221], v150 offset:6144
	ds_read_b128 v[222:225], v253 offset:6144
	global_load_lds_dwordx4 v[154:155], off
	v_lshl_add_u64 v[154:155], s[46:47], 0, v[136:137]
	s_add_i32 m0, s57, 0xe000
	s_nop 0
	global_load_lds_dwordx4 v[154:155], off
	s_waitcnt vmcnt(8)
	s_waitcnt lgkmcnt(0)
	s_barrier
	s_setprio 1
	s_waitcnt lgkmcnt(0)
	v_mfma_f32_16x16x32_bf16 v[124:127], v[160:163], v[194:197], v[124:127]
	v_mfma_f32_16x16x32_bf16 v[124:127], v[164:167], v[198:201], v[124:127]
	v_mfma_f32_16x16x32_bf16 v[108:111], v[164:167], v[206:209], v[108:111]
	v_mfma_f32_16x16x32_bf16 v[108:111], v[160:163], v[202:205], v[108:111]
	v_mfma_f32_16x16x32_bf16 v[92:95], v[160:163], v[210:213], v[92:95]
	v_mfma_f32_16x16x32_bf16 v[92:95], v[164:167], v[214:217], v[92:95]
	v_mfma_f32_16x16x32_bf16 v[76:79], v[164:167], v[222:225], v[76:79]
	v_mfma_f32_16x16x32_bf16 v[76:79], v[160:163], v[218:221], v[76:79]
	v_mfma_f32_16x16x32_bf16 v[68:71], v[168:171], v[218:221], v[68:71]
	v_mfma_f32_16x16x32_bf16 v[68:71], v[172:175], v[222:225], v[68:71]
	v_mfma_f32_16x16x32_bf16 v[84:87], v[172:175], v[214:217], v[84:87]
	v_mfma_f32_16x16x32_bf16 v[84:87], v[168:171], v[210:213], v[84:87]
	v_mfma_f32_16x16x32_bf16 v[100:103], v[168:171], v[202:205], v[100:103]
	v_mfma_f32_16x16x32_bf16 v[100:103], v[172:175], v[206:209], v[100:103]
	v_mfma_f32_16x16x32_bf16 v[116:119], v[172:175], v[198:201], v[116:119]
	v_mfma_f32_16x16x32_bf16 v[116:119], v[168:171], v[194:197], v[116:119]
	s_setprio 0
	s_setprio 1
	v_mfma_f32_16x16x32_bf16 v[120:123], v[176:179], v[194:197], v[120:123]
	v_mfma_f32_16x16x32_bf16 v[120:123], v[180:183], v[198:201], v[120:123]
	v_mfma_f32_16x16x32_bf16 v[104:107], v[180:183], v[206:209], v[104:107]
	v_mfma_f32_16x16x32_bf16 v[104:107], v[176:179], v[202:205], v[104:107]
	v_mfma_f32_16x16x32_bf16 v[88:91], v[176:179], v[210:213], v[88:91]
	v_mfma_f32_16x16x32_bf16 v[88:91], v[180:183], v[214:217], v[88:91]
	v_mfma_f32_16x16x32_bf16 v[72:75], v[180:183], v[222:225], v[72:75]
	v_mfma_f32_16x16x32_bf16 v[72:75], v[176:179], v[218:221], v[72:75]
	v_mfma_f32_16x16x32_bf16 v[64:67], v[186:189], v[218:221], v[64:67]
	v_mfma_f32_16x16x32_bf16 v[64:67], v[190:193], v[222:225], v[64:67]
	v_mfma_f32_16x16x32_bf16 v[80:83], v[190:193], v[214:217], v[80:83]
	v_mfma_f32_16x16x32_bf16 v[80:83], v[186:189], v[210:213], v[80:83]
	v_mfma_f32_16x16x32_bf16 v[96:99], v[186:189], v[202:205], v[96:99]
	v_mfma_f32_16x16x32_bf16 v[96:99], v[190:193], v[206:209], v[96:99]
	v_mfma_f32_16x16x32_bf16 v[112:115], v[190:193], v[198:201], v[112:115]
	v_mfma_f32_16x16x32_bf16 v[112:115], v[186:189], v[194:197], v[112:115]
	s_setprio 0
	s_barrier
	s_add_i32 s76, s66, s54
	v_lshl_add_u64 v[154:155], s[48:49], 0, v[132:133]
	s_mov_b32 m0, s76
	ds_read_b128 v[194:197], v150 offset:16384
	v_xor_b32_e32 v253, 64, v150
	ds_read_b128 v[198:201], v253 offset:16384
	ds_read_b128 v[202:205], v150 offset:18432
	ds_read_b128 v[206:209], v253 offset:18432
	ds_read_b128 v[210:213], v150 offset:20480
	ds_read_b128 v[214:217], v253 offset:20480
	ds_read_b128 v[218:221], v150 offset:22528
	ds_read_b128 v[222:225], v253 offset:22528
	global_load_lds_dwordx4 v[154:155], off
	s_add_i32 m0, s76, 0x2000
	s_add_u32 s76, s48, 0x40000
	v_lshl_add_u64 v[226:227], s[48:49], 0, v[128:129]
	s_addc_u32 s77, s49, 0
	s_add_i32 s78, s67, s54
	global_load_lds_dwordx4 v[226:227], off
	v_lshl_add_u64 v[228:229], s[76:77], 0, v[132:133]
	s_mov_b32 m0, s78
	v_lshl_add_u64 v[230:231], s[50:51], 0, v[130:131]
	global_load_lds_dwordx4 v[228:229], off
	v_lshl_add_u64 v[228:229], s[76:77], 0, v[128:129]
	s_add_i32 m0, s78, 0x2000
	s_nop 0
	global_load_lds_dwordx4 v[228:229], off
	v_lshl_add_u64 v[228:229], s[50:51], 0, v[134:135]
	s_mov_b32 m0, s57
	s_nop 0
	global_load_lds_dwordx4 v[228:229], off
	s_mov_b32 m0, s58
	s_nop 0
	global_load_lds_dwordx4 v[230:231], off
	s_waitcnt vmcnt(8)
	s_waitcnt lgkmcnt(0)
	s_barrier
	s_setprio 1
	s_waitcnt lgkmcnt(0)
	v_mfma_f32_16x16x32_bf16 v[60:63], v[160:163], v[194:197], v[60:63]
	v_mfma_f32_16x16x32_bf16 v[60:63], v[164:167], v[198:201], v[60:63]
	v_mfma_f32_16x16x32_bf16 v[44:47], v[164:167], v[206:209], v[44:47]
	v_mfma_f32_16x16x32_bf16 v[44:47], v[160:163], v[202:205], v[44:47]
	v_mfma_f32_16x16x32_bf16 v[28:31], v[160:163], v[210:213], v[28:31]
	v_mfma_f32_16x16x32_bf16 v[28:31], v[164:167], v[214:217], v[28:31]
	v_mfma_f32_16x16x32_bf16 v[12:15], v[164:167], v[222:225], v[12:15]
	v_mfma_f32_16x16x32_bf16 v[12:15], v[160:163], v[218:221], v[12:15]
	v_mfma_f32_16x16x32_bf16 v[4:7], v[168:171], v[218:221], v[4:7]
	v_mfma_f32_16x16x32_bf16 v[4:7], v[172:175], v[222:225], v[4:7]
	v_mfma_f32_16x16x32_bf16 v[20:23], v[172:175], v[214:217], v[20:23]
	v_mfma_f32_16x16x32_bf16 v[20:23], v[168:171], v[210:213], v[20:23]
	v_mfma_f32_16x16x32_bf16 v[36:39], v[168:171], v[202:205], v[36:39]
	v_mfma_f32_16x16x32_bf16 v[36:39], v[172:175], v[206:209], v[36:39]
	v_mfma_f32_16x16x32_bf16 v[52:55], v[172:175], v[198:201], v[52:55]
	v_mfma_f32_16x16x32_bf16 v[52:55], v[168:171], v[194:197], v[52:55]
	s_setprio 0
	s_setprio 1
	v_mfma_f32_16x16x32_bf16 v[56:59], v[176:179], v[194:197], v[56:59]
	v_mfma_f32_16x16x32_bf16 v[56:59], v[180:183], v[198:201], v[56:59]
	v_mfma_f32_16x16x32_bf16 v[40:43], v[180:183], v[206:209], v[40:43]
	v_mfma_f32_16x16x32_bf16 v[40:43], v[176:179], v[202:205], v[40:43]
	v_mfma_f32_16x16x32_bf16 v[24:27], v[176:179], v[210:213], v[24:27]
	v_mfma_f32_16x16x32_bf16 v[24:27], v[180:183], v[214:217], v[24:27]
	v_mfma_f32_16x16x32_bf16 v[8:11], v[180:183], v[222:225], v[8:11]
	v_mfma_f32_16x16x32_bf16 v[8:11], v[176:179], v[218:221], v[8:11]
	v_mfma_f32_16x16x32_bf16 v[0:3], v[186:189], v[218:221], v[0:3]
	v_mfma_f32_16x16x32_bf16 v[0:3], v[190:193], v[222:225], v[0:3]
	v_mfma_f32_16x16x32_bf16 v[16:19], v[190:193], v[214:217], v[16:19]
	v_mfma_f32_16x16x32_bf16 v[16:19], v[186:189], v[210:213], v[16:19]
	v_mfma_f32_16x16x32_bf16 v[32:35], v[186:189], v[202:205], v[32:35]
	v_mfma_f32_16x16x32_bf16 v[32:35], v[190:193], v[206:209], v[32:35]
	v_mfma_f32_16x16x32_bf16 v[48:51], v[190:193], v[198:201], v[48:51]
	v_mfma_f32_16x16x32_bf16 v[48:51], v[186:189], v[194:197], v[48:51]
	s_setprio 0
	s_barrier
	s_add_i32 s76, 0, 0x18000
	v_add_u32_e32 v153, s76, v147
	s_add_i32 s77, 0, 0x1c000
	ds_read_b128 v[160:163], v153
	v_xor_b32_e32 v253, 64, v153
	ds_read_b128 v[164:167], v253
	ds_read_b128 v[168:171], v153 offset:2048
	ds_read_b128 v[172:175], v253 offset:2048
	v_add_u32_e32 v153, s77, v147
	ds_read_b128 v[176:179], v153
	v_xor_b32_e32 v253, 64, v153
	ds_read_b128 v[180:183], v253
	ds_read_b128 v[186:189], v153 offset:2048
	ds_read_b128 v[190:193], v253 offset:2048
	s_add_u32 s50, s50, 0x40000
	s_addc_u32 s51, s51, 0
	s_mov_b32 m0, s59
	v_lshl_add_u64 v[232:233], s[50:51], 0, v[134:135]
	ds_read_b128 v[194:197], v150 offset:32768
	v_xor_b32_e32 v253, 64, v150
	ds_read_b128 v[198:201], v253 offset:32768
	ds_read_b128 v[202:205], v150 offset:34816
	ds_read_b128 v[206:209], v253 offset:34816
	ds_read_b128 v[210:213], v150 offset:36864
	ds_read_b128 v[214:217], v253 offset:36864
	ds_read_b128 v[218:221], v150 offset:38912
	ds_read_b128 v[222:225], v253 offset:38912
	global_load_lds_dwordx4 v[232:233], off
	v_lshl_add_u64 v[232:233], s[50:51], 0, v[130:131]
	s_mov_b32 m0, s60
	s_nop 0
	global_load_lds_dwordx4 v[232:233], off
	s_waitcnt vmcnt(8)
	s_waitcnt lgkmcnt(0)
	s_barrier
	s_setprio 1
	s_waitcnt lgkmcnt(0)
	v_mfma_f32_16x16x32_bf16 v[124:127], v[160:163], v[194:197], v[124:127]
	v_mfma_f32_16x16x32_bf16 v[124:127], v[164:167], v[198:201], v[124:127]
	v_mfma_f32_16x16x32_bf16 v[108:111], v[164:167], v[206:209], v[108:111]
	v_mfma_f32_16x16x32_bf16 v[108:111], v[160:163], v[202:205], v[108:111]
	v_mfma_f32_16x16x32_bf16 v[92:95], v[160:163], v[210:213], v[92:95]
	v_mfma_f32_16x16x32_bf16 v[92:95], v[164:167], v[214:217], v[92:95]
	v_mfma_f32_16x16x32_bf16 v[76:79], v[164:167], v[222:225], v[76:79]
	v_mfma_f32_16x16x32_bf16 v[76:79], v[160:163], v[218:221], v[76:79]
	v_mfma_f32_16x16x32_bf16 v[68:71], v[168:171], v[218:221], v[68:71]
	v_mfma_f32_16x16x32_bf16 v[68:71], v[172:175], v[222:225], v[68:71]
	v_mfma_f32_16x16x32_bf16 v[84:87], v[172:175], v[214:217], v[84:87]
	v_mfma_f32_16x16x32_bf16 v[84:87], v[168:171], v[210:213], v[84:87]
	v_mfma_f32_16x16x32_bf16 v[100:103], v[168:171], v[202:205], v[100:103]
	v_mfma_f32_16x16x32_bf16 v[100:103], v[172:175], v[206:209], v[100:103]
	v_mfma_f32_16x16x32_bf16 v[116:119], v[172:175], v[198:201], v[116:119]
	v_mfma_f32_16x16x32_bf16 v[116:119], v[168:171], v[194:197], v[116:119]
	s_setprio 0
	s_setprio 1
	v_mfma_f32_16x16x32_bf16 v[120:123], v[176:179], v[194:197], v[120:123]
	v_mfma_f32_16x16x32_bf16 v[120:123], v[180:183], v[198:201], v[120:123]
	v_mfma_f32_16x16x32_bf16 v[104:107], v[180:183], v[206:209], v[104:107]
	v_mfma_f32_16x16x32_bf16 v[104:107], v[176:179], v[202:205], v[104:107]
	v_mfma_f32_16x16x32_bf16 v[88:91], v[176:179], v[210:213], v[88:91]
	v_mfma_f32_16x16x32_bf16 v[88:91], v[180:183], v[214:217], v[88:91]
	v_mfma_f32_16x16x32_bf16 v[72:75], v[180:183], v[222:225], v[72:75]
	v_mfma_f32_16x16x32_bf16 v[72:75], v[176:179], v[218:221], v[72:75]
	v_mfma_f32_16x16x32_bf16 v[64:67], v[186:189], v[218:221], v[64:67]
	v_mfma_f32_16x16x32_bf16 v[64:67], v[190:193], v[222:225], v[64:67]
	v_mfma_f32_16x16x32_bf16 v[80:83], v[190:193], v[214:217], v[80:83]
	v_mfma_f32_16x16x32_bf16 v[80:83], v[186:189], v[210:213], v[80:83]
	v_mfma_f32_16x16x32_bf16 v[96:99], v[186:189], v[202:205], v[96:99]
	v_mfma_f32_16x16x32_bf16 v[96:99], v[190:193], v[206:209], v[96:99]
	v_mfma_f32_16x16x32_bf16 v[112:115], v[190:193], v[198:201], v[112:115]
	v_mfma_f32_16x16x32_bf16 v[112:115], v[186:189], v[194:197], v[112:115]
	s_setprio 0
	s_barrier
	s_add_i32 s50, s76, s54
	v_lshl_add_u64 v[154:155], v[154:155], 0, s[20:21]
	s_mov_b32 m0, s50
	ds_read_b128 v[194:197], v150 offset:49152
	v_xor_b32_e32 v253, 64, v150
	ds_read_b128 v[198:201], v253 offset:49152
	ds_read_b128 v[202:205], v150 offset:51200
	ds_read_b128 v[206:209], v253 offset:51200
	ds_read_b128 v[210:213], v150 offset:53248
	ds_read_b128 v[214:217], v253 offset:53248
	ds_read_b128 v[218:221], v150 offset:55296
	ds_read_b128 v[222:225], v253 offset:55296
	global_load_lds_dwordx4 v[154:155], off
	s_add_i32 m0, s50, 0x2000
	s_add_u32 s48, s48, 0x40080
	v_lshl_add_u64 v[154:155], v[226:227], 0, s[20:21]
	s_addc_u32 s49, s49, 0
	s_add_i32 s50, s77, s54
	global_load_lds_dwordx4 v[154:155], off
	v_lshl_add_u64 v[154:155], s[48:49], 0, v[132:133]
	s_mov_b32 m0, s50
	s_nop 0
	global_load_lds_dwordx4 v[154:155], off
	v_lshl_add_u64 v[154:155], s[48:49], 0, v[128:129]
	s_add_i32 m0, s50, 0x2000
	s_nop 0
	global_load_lds_dwordx4 v[154:155], off
	v_lshl_add_u64 v[154:155], v[228:229], 0, s[20:21]
	s_mov_b32 m0, s62
	s_nop 0
	global_load_lds_dwordx4 v[154:155], off
	v_lshl_add_u64 v[154:155], v[230:231], 0, s[20:21]
	s_mov_b32 m0, s63
	s_nop 0
	global_load_lds_dwordx4 v[154:155], off
	s_waitcnt vmcnt(8)
	s_waitcnt lgkmcnt(0)
	s_barrier
	s_setprio 1
	s_waitcnt lgkmcnt(0)
	v_mfma_f32_16x16x32_bf16 v[60:63], v[160:163], v[194:197], v[60:63]
	v_mfma_f32_16x16x32_bf16 v[60:63], v[164:167], v[198:201], v[60:63]
	v_mfma_f32_16x16x32_bf16 v[44:47], v[164:167], v[206:209], v[44:47]
	v_mfma_f32_16x16x32_bf16 v[44:47], v[160:163], v[202:205], v[44:47]
	v_mfma_f32_16x16x32_bf16 v[28:31], v[160:163], v[210:213], v[28:31]
	v_mfma_f32_16x16x32_bf16 v[28:31], v[164:167], v[214:217], v[28:31]
	v_mfma_f32_16x16x32_bf16 v[12:15], v[164:167], v[222:225], v[12:15]
	v_mfma_f32_16x16x32_bf16 v[12:15], v[160:163], v[218:221], v[12:15]
	v_mfma_f32_16x16x32_bf16 v[4:7], v[168:171], v[218:221], v[4:7]
	v_mfma_f32_16x16x32_bf16 v[4:7], v[172:175], v[222:225], v[4:7]
	v_mfma_f32_16x16x32_bf16 v[20:23], v[172:175], v[214:217], v[20:23]
	v_mfma_f32_16x16x32_bf16 v[20:23], v[168:171], v[210:213], v[20:23]
	v_mfma_f32_16x16x32_bf16 v[36:39], v[168:171], v[202:205], v[36:39]
	v_mfma_f32_16x16x32_bf16 v[36:39], v[172:175], v[206:209], v[36:39]
	v_mfma_f32_16x16x32_bf16 v[52:55], v[172:175], v[198:201], v[52:55]
	v_mfma_f32_16x16x32_bf16 v[52:55], v[168:171], v[194:197], v[52:55]
	s_setprio 0
	s_setprio 1
	v_mfma_f32_16x16x32_bf16 v[56:59], v[176:179], v[194:197], v[56:59]
	v_mfma_f32_16x16x32_bf16 v[56:59], v[180:183], v[198:201], v[56:59]
	v_mfma_f32_16x16x32_bf16 v[40:43], v[180:183], v[206:209], v[40:43]
	v_mfma_f32_16x16x32_bf16 v[40:43], v[176:179], v[202:205], v[40:43]
	v_mfma_f32_16x16x32_bf16 v[24:27], v[176:179], v[210:213], v[24:27]
	v_mfma_f32_16x16x32_bf16 v[24:27], v[180:183], v[214:217], v[24:27]
	v_mfma_f32_16x16x32_bf16 v[8:11], v[180:183], v[222:225], v[8:11]
	v_mfma_f32_16x16x32_bf16 v[8:11], v[176:179], v[218:221], v[8:11]
	v_mfma_f32_16x16x32_bf16 v[0:3], v[186:189], v[218:221], v[0:3]
	v_mfma_f32_16x16x32_bf16 v[0:3], v[190:193], v[222:225], v[0:3]
	v_mfma_f32_16x16x32_bf16 v[16:19], v[190:193], v[214:217], v[16:19]
	v_mfma_f32_16x16x32_bf16 v[16:19], v[186:189], v[210:213], v[16:19]
	v_mfma_f32_16x16x32_bf16 v[32:35], v[186:189], v[202:205], v[32:35]
	v_mfma_f32_16x16x32_bf16 v[32:35], v[190:193], v[206:209], v[32:35]
	v_mfma_f32_16x16x32_bf16 v[48:51], v[190:193], v[198:201], v[48:51]
	v_mfma_f32_16x16x32_bf16 v[48:51], v[186:189], v[194:197], v[48:51]
	s_setprio 0
	s_barrier
	s_add_i32 s75, s75, 2
	s_add_u32 s73, s73, 0x100
	s_addc_u32 s74, s74, 0
	s_add_u32 s46, s46, 0x100
	s_addc_u32 s47, s47, 0
	s_cmp_gt_u32 s75, 13
	s_cbranch_scc1 .LBB0_529

.Llast_4:
	v_add_u32_e32 v153, s66, v147
	ds_read_b128 v[160:163], v153
	v_xor_b32_e32 v253, 64, v153
	ds_read_b128 v[164:167], v253
	ds_read_b128 v[168:171], v153 offset:2048
	ds_read_b128 v[172:175], v253 offset:2048
	v_add_u32_e32 v153, s67, v147
	ds_read_b128 v[176:179], v153
	v_xor_b32_e32 v253, 64, v153
	ds_read_b128 v[180:183], v253
	ds_read_b128 v[186:189], v153 offset:2048
	ds_read_b128 v[190:193], v253 offset:2048
	s_add_u32 s50, s46, 0xfffc0080
	s_addc_u32 s51, s47, -1
	s_and_b64 s[48:49], s[48:49], exec
	s_cselect_b32 s51, s29, s51
	s_cselect_b32 s50, s70, s50
	s_cselect_b32 s49, s71, s74
	s_cselect_b32 s48, s72, s73
	v_lshl_add_u64 v[154:155], s[46:47], 0, v[138:139]
	s_add_i32 m0, s57, 0xc000
	ds_read_b128 v[194:197], v150
	v_xor_b32_e32 v253, 64, v150
	ds_read_b128 v[198:201], v253
	ds_read_b128 v[202:205], v150 offset:2048
	ds_read_b128 v[206:209], v253 offset:2048
	ds_read_b128 v[210:213], v150 offset:4096
	ds_read_b128 v[214:217], v253 offset:4096
	ds_read_b128 v[218:221], v150 offset:6144
	ds_read_b128 v[222:225], v253 offset:6144
	global_load_lds_dwordx4 v[154:155], off
	v_lshl_add_u64 v[154:155], s[46:47], 0, v[136:137]
	s_add_i32 m0, s57, 0xe000
	s_nop 0
	global_load_lds_dwordx4 v[154:155], off
	s_waitcnt vmcnt(8)
	s_waitcnt lgkmcnt(0)
	s_barrier
	s_setprio 1
	s_waitcnt lgkmcnt(0)
	v_mfma_f32_16x16x32_bf16 v[124:127], v[160:163], v[194:197], v[124:127]
	v_mfma_f32_16x16x32_bf16 v[124:127], v[164:167], v[198:201], v[124:127]
	v_mfma_f32_16x16x32_bf16 v[108:111], v[164:167], v[206:209], v[108:111]
	v_mfma_f32_16x16x32_bf16 v[108:111], v[160:163], v[202:205], v[108:111]
	v_mfma_f32_16x16x32_bf16 v[92:95], v[160:163], v[210:213], v[92:95]
	v_mfma_f32_16x16x32_bf16 v[92:95], v[164:167], v[214:217], v[92:95]
	v_mfma_f32_16x16x32_bf16 v[76:79], v[164:167], v[222:225], v[76:79]
	v_mfma_f32_16x16x32_bf16 v[76:79], v[160:163], v[218:221], v[76:79]
	v_mfma_f32_16x16x32_bf16 v[68:71], v[168:171], v[218:221], v[68:71]
	v_mfma_f32_16x16x32_bf16 v[68:71], v[172:175], v[222:225], v[68:71]
	v_mfma_f32_16x16x32_bf16 v[84:87], v[172:175], v[214:217], v[84:87]
	v_mfma_f32_16x16x32_bf16 v[84:87], v[168:171], v[210:213], v[84:87]
	v_mfma_f32_16x16x32_bf16 v[100:103], v[168:171], v[202:205], v[100:103]
	v_mfma_f32_16x16x32_bf16 v[100:103], v[172:175], v[206:209], v[100:103]
	v_mfma_f32_16x16x32_bf16 v[116:119], v[172:175], v[198:201], v[116:119]
	v_mfma_f32_16x16x32_bf16 v[116:119], v[168:171], v[194:197], v[116:119]
	s_setprio 0
	s_setprio 1
	v_mfma_f32_16x16x32_bf16 v[120:123], v[176:179], v[194:197], v[120:123]
	v_mfma_f32_16x16x32_bf16 v[120:123], v[180:183], v[198:201], v[120:123]
	v_mfma_f32_16x16x32_bf16 v[104:107], v[180:183], v[206:209], v[104:107]
	v_mfma_f32_16x16x32_bf16 v[104:107], v[176:179], v[202:205], v[104:107]
	v_mfma_f32_16x16x32_bf16 v[88:91], v[176:179], v[210:213], v[88:91]
	v_mfma_f32_16x16x32_bf16 v[88:91], v[180:183], v[214:217], v[88:91]
	v_mfma_f32_16x16x32_bf16 v[72:75], v[180:183], v[222:225], v[72:75]
	v_mfma_f32_16x16x32_bf16 v[72:75], v[176:179], v[218:221], v[72:75]
	v_mfma_f32_16x16x32_bf16 v[64:67], v[186:189], v[218:221], v[64:67]
	v_mfma_f32_16x16x32_bf16 v[64:67], v[190:193], v[222:225], v[64:67]
	v_mfma_f32_16x16x32_bf16 v[80:83], v[190:193], v[214:217], v[80:83]
	v_mfma_f32_16x16x32_bf16 v[80:83], v[186:189], v[210:213], v[80:83]
	v_mfma_f32_16x16x32_bf16 v[96:99], v[186:189], v[202:205], v[96:99]
	v_mfma_f32_16x16x32_bf16 v[96:99], v[190:193], v[206:209], v[96:99]
	v_mfma_f32_16x16x32_bf16 v[112:115], v[190:193], v[198:201], v[112:115]
	v_mfma_f32_16x16x32_bf16 v[112:115], v[186:189], v[194:197], v[112:115]
	s_setprio 0
	s_barrier
	s_add_i32 s76, s66, s54
	v_lshl_add_u64 v[154:155], s[48:49], 0, v[132:133]
	s_mov_b32 m0, s76
	ds_read_b128 v[194:197], v150 offset:16384
	v_xor_b32_e32 v253, 64, v150
	ds_read_b128 v[198:201], v253 offset:16384
	ds_read_b128 v[202:205], v150 offset:18432
	ds_read_b128 v[206:209], v253 offset:18432
	ds_read_b128 v[210:213], v150 offset:20480
	ds_read_b128 v[214:217], v253 offset:20480
	ds_read_b128 v[218:221], v150 offset:22528
	ds_read_b128 v[222:225], v253 offset:22528
	global_load_lds_dwordx4 v[154:155], off
	s_add_i32 m0, s76, 0x2000
	s_add_u32 s76, s48, 0x40000
	v_lshl_add_u64 v[226:227], s[48:49], 0, v[128:129]
	s_addc_u32 s77, s49, 0
	s_add_i32 s78, s67, s54
	global_load_lds_dwordx4 v[226:227], off
	v_lshl_add_u64 v[228:229], s[76:77], 0, v[132:133]
	s_mov_b32 m0, s78
	v_lshl_add_u64 v[230:231], s[50:51], 0, v[130:131]
	global_load_lds_dwordx4 v[228:229], off
	v_lshl_add_u64 v[228:229], s[76:77], 0, v[128:129]
	s_add_i32 m0, s78, 0x2000
	s_nop 0
	global_load_lds_dwordx4 v[228:229], off
	v_lshl_add_u64 v[228:229], s[50:51], 0, v[134:135]
	s_mov_b32 m0, s57
	s_nop 0
	global_load_lds_dwordx4 v[228:229], off
	s_mov_b32 m0, s58
	s_nop 0
	global_load_lds_dwordx4 v[230:231], off
	s_waitcnt vmcnt(8)
	s_waitcnt lgkmcnt(0)
	s_barrier
	s_setprio 1
	s_waitcnt lgkmcnt(0)
	v_mfma_f32_16x16x32_bf16 v[60:63], v[160:163], v[194:197], v[60:63]
	v_mfma_f32_16x16x32_bf16 v[60:63], v[164:167], v[198:201], v[60:63]
	v_mfma_f32_16x16x32_bf16 v[44:47], v[164:167], v[206:209], v[44:47]
	v_mfma_f32_16x16x32_bf16 v[44:47], v[160:163], v[202:205], v[44:47]
	v_mfma_f32_16x16x32_bf16 v[28:31], v[160:163], v[210:213], v[28:31]
	v_mfma_f32_16x16x32_bf16 v[28:31], v[164:167], v[214:217], v[28:31]
	v_mfma_f32_16x16x32_bf16 v[12:15], v[164:167], v[222:225], v[12:15]
	v_mfma_f32_16x16x32_bf16 v[12:15], v[160:163], v[218:221], v[12:15]
	v_mfma_f32_16x16x32_bf16 v[4:7], v[168:171], v[218:221], v[4:7]
	v_mfma_f32_16x16x32_bf16 v[4:7], v[172:175], v[222:225], v[4:7]
	v_mfma_f32_16x16x32_bf16 v[20:23], v[172:175], v[214:217], v[20:23]
	v_mfma_f32_16x16x32_bf16 v[20:23], v[168:171], v[210:213], v[20:23]
	v_mfma_f32_16x16x32_bf16 v[36:39], v[168:171], v[202:205], v[36:39]
	v_mfma_f32_16x16x32_bf16 v[36:39], v[172:175], v[206:209], v[36:39]
	v_mfma_f32_16x16x32_bf16 v[52:55], v[172:175], v[198:201], v[52:55]
	v_mfma_f32_16x16x32_bf16 v[52:55], v[168:171], v[194:197], v[52:55]
	s_setprio 0
	s_setprio 1
	v_mfma_f32_16x16x32_bf16 v[56:59], v[176:179], v[194:197], v[56:59]
	v_mfma_f32_16x16x32_bf16 v[56:59], v[180:183], v[198:201], v[56:59]
	v_mfma_f32_16x16x32_bf16 v[40:43], v[180:183], v[206:209], v[40:43]
	v_mfma_f32_16x16x32_bf16 v[40:43], v[176:179], v[202:205], v[40:43]
	v_mfma_f32_16x16x32_bf16 v[24:27], v[176:179], v[210:213], v[24:27]
	v_mfma_f32_16x16x32_bf16 v[24:27], v[180:183], v[214:217], v[24:27]
	v_mfma_f32_16x16x32_bf16 v[8:11], v[180:183], v[222:225], v[8:11]
	v_mfma_f32_16x16x32_bf16 v[8:11], v[176:179], v[218:221], v[8:11]
	v_mfma_f32_16x16x32_bf16 v[0:3], v[186:189], v[218:221], v[0:3]
	v_mfma_f32_16x16x32_bf16 v[0:3], v[190:193], v[222:225], v[0:3]
	v_mfma_f32_16x16x32_bf16 v[16:19], v[190:193], v[214:217], v[16:19]
	v_mfma_f32_16x16x32_bf16 v[16:19], v[186:189], v[210:213], v[16:19]
	v_mfma_f32_16x16x32_bf16 v[32:35], v[186:189], v[202:205], v[32:35]
	v_mfma_f32_16x16x32_bf16 v[32:35], v[190:193], v[206:209], v[32:35]
	v_mfma_f32_16x16x32_bf16 v[48:51], v[190:193], v[198:201], v[48:51]
	v_mfma_f32_16x16x32_bf16 v[48:51], v[186:189], v[194:197], v[48:51]
	s_setprio 0
	s_barrier
	s_add_i32 s76, 0, 0x18000
	v_add_u32_e32 v153, s76, v147
	s_add_i32 s77, 0, 0x1c000
	ds_read_b128 v[160:163], v153
	v_xor_b32_e32 v253, 64, v153
	ds_read_b128 v[164:167], v253
	ds_read_b128 v[168:171], v153 offset:2048
	ds_read_b128 v[172:175], v253 offset:2048
	v_add_u32_e32 v153, s77, v147
	ds_read_b128 v[176:179], v153
	v_xor_b32_e32 v253, 64, v153
	ds_read_b128 v[180:183], v253
	ds_read_b128 v[186:189], v153 offset:2048
	ds_read_b128 v[190:193], v253 offset:2048
	s_add_u32 s50, s50, 0x40000
	s_addc_u32 s51, s51, 0
	s_mov_b32 m0, s59
	v_lshl_add_u64 v[232:233], s[50:51], 0, v[134:135]
	ds_read_b128 v[194:197], v150 offset:32768
	v_xor_b32_e32 v253, 64, v150
	ds_read_b128 v[198:201], v253 offset:32768
	ds_read_b128 v[202:205], v150 offset:34816
	ds_read_b128 v[206:209], v253 offset:34816
	ds_read_b128 v[210:213], v150 offset:36864
	ds_read_b128 v[214:217], v253 offset:36864
	ds_read_b128 v[218:221], v150 offset:38912
	ds_read_b128 v[222:225], v253 offset:38912
	global_load_lds_dwordx4 v[232:233], off
	v_lshl_add_u64 v[232:233], s[50:51], 0, v[130:131]
	s_mov_b32 m0, s60
	s_nop 0
	global_load_lds_dwordx4 v[232:233], off
	s_waitcnt vmcnt(8)
	s_waitcnt lgkmcnt(0)
	s_barrier
	s_setprio 1
	s_waitcnt lgkmcnt(0)
	v_mfma_f32_16x16x32_bf16 v[124:127], v[160:163], v[194:197], v[124:127]
	v_mfma_f32_16x16x32_bf16 v[124:127], v[164:167], v[198:201], v[124:127]
	v_mfma_f32_16x16x32_bf16 v[108:111], v[164:167], v[206:209], v[108:111]
	v_mfma_f32_16x16x32_bf16 v[108:111], v[160:163], v[202:205], v[108:111]
	v_mfma_f32_16x16x32_bf16 v[92:95], v[160:163], v[210:213], v[92:95]
	v_mfma_f32_16x16x32_bf16 v[92:95], v[164:167], v[214:217], v[92:95]
	v_mfma_f32_16x16x32_bf16 v[76:79], v[164:167], v[222:225], v[76:79]
	v_mfma_f32_16x16x32_bf16 v[76:79], v[160:163], v[218:221], v[76:79]
	v_mfma_f32_16x16x32_bf16 v[68:71], v[168:171], v[218:221], v[68:71]
	v_mfma_f32_16x16x32_bf16 v[68:71], v[172:175], v[222:225], v[68:71]
	v_mfma_f32_16x16x32_bf16 v[84:87], v[172:175], v[214:217], v[84:87]
	v_mfma_f32_16x16x32_bf16 v[84:87], v[168:171], v[210:213], v[84:87]
	v_mfma_f32_16x16x32_bf16 v[100:103], v[168:171], v[202:205], v[100:103]
	v_mfma_f32_16x16x32_bf16 v[100:103], v[172:175], v[206:209], v[100:103]
	v_mfma_f32_16x16x32_bf16 v[116:119], v[172:175], v[198:201], v[116:119]
	v_mfma_f32_16x16x32_bf16 v[116:119], v[168:171], v[194:197], v[116:119]
	s_setprio 0
	s_setprio 1
	v_mfma_f32_16x16x32_bf16 v[120:123], v[176:179], v[194:197], v[120:123]
	v_mfma_f32_16x16x32_bf16 v[120:123], v[180:183], v[198:201], v[120:123]
	v_mfma_f32_16x16x32_bf16 v[104:107], v[180:183], v[206:209], v[104:107]
	v_mfma_f32_16x16x32_bf16 v[104:107], v[176:179], v[202:205], v[104:107]
	v_mfma_f32_16x16x32_bf16 v[88:91], v[176:179], v[210:213], v[88:91]
	v_mfma_f32_16x16x32_bf16 v[88:91], v[180:183], v[214:217], v[88:91]
	v_mfma_f32_16x16x32_bf16 v[72:75], v[180:183], v[222:225], v[72:75]
	v_mfma_f32_16x16x32_bf16 v[72:75], v[176:179], v[218:221], v[72:75]
	v_mfma_f32_16x16x32_bf16 v[64:67], v[186:189], v[218:221], v[64:67]
	v_mfma_f32_16x16x32_bf16 v[64:67], v[190:193], v[222:225], v[64:67]
	v_mfma_f32_16x16x32_bf16 v[80:83], v[190:193], v[214:217], v[80:83]
	v_mfma_f32_16x16x32_bf16 v[80:83], v[186:189], v[210:213], v[80:83]
	v_mfma_f32_16x16x32_bf16 v[96:99], v[186:189], v[202:205], v[96:99]
	v_mfma_f32_16x16x32_bf16 v[96:99], v[190:193], v[206:209], v[96:99]
	v_mfma_f32_16x16x32_bf16 v[112:115], v[190:193], v[198:201], v[112:115]
	v_mfma_f32_16x16x32_bf16 v[112:115], v[186:189], v[194:197], v[112:115]
	s_setprio 0
	s_barrier
	v_add_u32_e32 v234, 0x21000, v151
	ds_read_b128 v[236:239], v234
	ds_read_b128 v[240:243], v234 offset:256
	ds_read_b128 v[244:247], v234 offset:512
	ds_read_b128 v[248:251], v234 offset:768
	v_add_u32_e32 v235, s27, v146
	v_mul_u32_u24_e32 v235, 0x1600, v235
	v_lshl_or_b32 v234, s69, 7, v149
	v_lshl_add_u32 v235, v234, 1, v235
	s_add_i32 s50, s76, s54
	v_lshl_add_u64 v[154:155], v[154:155], 0, s[20:21]
	s_mov_b32 m0, s50
	ds_read_b128 v[194:197], v150 offset:49152
	v_xor_b32_e32 v253, 64, v150
	ds_read_b128 v[198:201], v253 offset:49152
	ds_read_b128 v[202:205], v150 offset:51200
	ds_read_b128 v[206:209], v253 offset:51200
	ds_read_b128 v[210:213], v150 offset:53248
	ds_read_b128 v[214:217], v253 offset:53248
	ds_read_b128 v[218:221], v150 offset:55296
	ds_read_b128 v[222:225], v253 offset:55296
	global_load_lds_dwordx4 v[154:155], off
	s_add_i32 m0, s50, 0x2000
	s_add_u32 s48, s48, 0x40080
	v_lshl_add_u64 v[154:155], v[226:227], 0, s[20:21]
	s_addc_u32 s49, s49, 0
	s_add_i32 s50, s77, s54
	global_load_lds_dwordx4 v[154:155], off
	v_lshl_add_u64 v[154:155], s[48:49], 0, v[132:133]
	s_mov_b32 m0, s50
	s_nop 0
	global_load_lds_dwordx4 v[154:155], off
	v_lshl_add_u64 v[154:155], s[48:49], 0, v[128:129]
	s_add_i32 m0, s50, 0x2000
	s_nop 0
	global_load_lds_dwordx4 v[154:155], off
	v_lshl_add_u64 v[154:155], v[228:229], 0, s[20:21]
	s_mov_b32 m0, s62
	s_nop 0
	global_load_lds_dwordx4 v[154:155], off
	v_lshl_add_u64 v[154:155], v[230:231], 0, s[20:21]
	s_mov_b32 m0, s63
	s_nop 0
	global_load_lds_dwordx4 v[154:155], off
	s_waitcnt lgkmcnt(8)
	v_add_f32_e32 v236, v236, v237
	v_add_f32_e32 v238, v238, v239
	v_add_f32_e32 v240, v240, v241
	v_add_f32_e32 v242, v242, v243
	v_add_f32_e32 v244, v244, v245
	v_add_f32_e32 v246, v246, v247
	v_add_f32_e32 v248, v248, v249
	v_add_f32_e32 v250, v250, v251
	v_add_f32_e32 v236, v236, v238
	v_add_f32_e32 v240, v240, v242
	v_add_f32_e32 v244, v244, v246
	v_add_f32_e32 v248, v248, v250
	v_fmamk_f32 v236, v236, 0x3a800000, v152
	v_fmamk_f32 v240, v240, 0x3a800000, v152
	v_fmamk_f32 v244, v244, 0x3a800000, v152
	v_fmamk_f32 v248, v248, 0x3a800000, v152
	v_rsq_f32_e32 v236, v236
	v_rsq_f32_e32 v240, v240
	v_rsq_f32_e32 v244, v244
	v_rsq_f32_e32 v248, v248
	v_mul_f32_e32 v252, 0xbfb8aa3b, v236
	v_mul_f32_e32 v254, v236, v236
	v_pk_mul_f32 v[120:121], v[124:125], v[120:121]
	v_pk_mul_f32 v[122:123], v[126:127], v[122:123]
	v_pk_mul_f32 v[112:113], v[116:117], v[112:113]
	v_pk_mul_f32 v[114:115], v[118:119], v[114:115]
	v_pk_mul_f32 v[124:125], v[124:125], v[252:253] op_sel_hi:[1,0]
	v_pk_mul_f32 v[126:127], v[126:127], v[252:253] op_sel_hi:[1,0]
	v_pk_mul_f32 v[116:117], v[116:117], v[252:253] op_sel_hi:[1,0]
	v_pk_mul_f32 v[118:119], v[118:119], v[252:253] op_sel_hi:[1,0]
	v_exp_f32_e32 v124, v124
	v_exp_f32_e32 v125, v125
	v_exp_f32_e32 v126, v126
	v_exp_f32_e32 v127, v127
	v_exp_f32_e32 v116, v116
	v_exp_f32_e32 v117, v117
	v_exp_f32_e32 v118, v118
	v_exp_f32_e32 v119, v119
	v_pk_add_f32 v[124:125], v[124:125], 1.0 op_sel_hi:[1,0]
	v_pk_add_f32 v[126:127], v[126:127], 1.0 op_sel_hi:[1,0]
	v_pk_add_f32 v[116:117], v[116:117], 1.0 op_sel_hi:[1,0]
	v_pk_add_f32 v[118:119], v[118:119], 1.0 op_sel_hi:[1,0]
	v_rcp_f32_e32 v124, v124
	v_rcp_f32_e32 v125, v125
	v_rcp_f32_e32 v126, v126
	v_rcp_f32_e32 v127, v127
	v_rcp_f32_e32 v116, v116
	v_rcp_f32_e32 v117, v117
	v_rcp_f32_e32 v118, v118
	v_rcp_f32_e32 v119, v119
	v_pk_mul_f32 v[120:121], v[120:121], v[254:255] op_sel_hi:[1,0]
	v_pk_mul_f32 v[122:123], v[122:123], v[254:255] op_sel_hi:[1,0]
	v_pk_mul_f32 v[112:113], v[112:113], v[254:255] op_sel_hi:[1,0]
	v_pk_mul_f32 v[114:115], v[114:115], v[254:255] op_sel_hi:[1,0]
	v_pk_mul_f32 v[120:121], v[120:121], v[124:125]
	v_pk_mul_f32 v[122:123], v[122:123], v[126:127]
	v_pk_mul_f32 v[112:113], v[112:113], v[116:117]
	v_pk_mul_f32 v[114:115], v[114:115], v[118:119]
	v_cvt_pk_bf16_f32 v120, v120, v121
	v_cvt_pk_bf16_f32 v121, v122, v123
	v_cvt_pk_bf16_f32 v122, v112, v113
	v_cvt_pk_bf16_f32 v123, v114, v115
	global_store_dwordx4 v235, v[120:123], s[14:15]
	v_add_u32_e32 v234, 0x16000, v235
	v_mul_f32_e32 v252, 0xbfb8aa3b, v240
	v_mul_f32_e32 v254, v240, v240
	v_pk_mul_f32 v[104:105], v[108:109], v[104:105]
	v_pk_mul_f32 v[106:107], v[110:111], v[106:107]
	v_pk_mul_f32 v[96:97], v[100:101], v[96:97]
	v_pk_mul_f32 v[98:99], v[102:103], v[98:99]
	v_pk_mul_f32 v[108:109], v[108:109], v[252:253] op_sel_hi:[1,0]
	v_pk_mul_f32 v[110:111], v[110:111], v[252:253] op_sel_hi:[1,0]
	v_pk_mul_f32 v[100:101], v[100:101], v[252:253] op_sel_hi:[1,0]
	v_pk_mul_f32 v[102:103], v[102:103], v[252:253] op_sel_hi:[1,0]
	v_exp_f32_e32 v108, v108
	v_exp_f32_e32 v109, v109
	v_exp_f32_e32 v110, v110
	v_exp_f32_e32 v111, v111
	v_exp_f32_e32 v100, v100
	v_exp_f32_e32 v101, v101
	v_exp_f32_e32 v102, v102
	v_exp_f32_e32 v103, v103
	v_pk_add_f32 v[108:109], v[108:109], 1.0 op_sel_hi:[1,0]
	v_pk_add_f32 v[110:111], v[110:111], 1.0 op_sel_hi:[1,0]
	v_pk_add_f32 v[100:101], v[100:101], 1.0 op_sel_hi:[1,0]
	v_pk_add_f32 v[102:103], v[102:103], 1.0 op_sel_hi:[1,0]
	v_rcp_f32_e32 v108, v108
	v_rcp_f32_e32 v109, v109
	v_rcp_f32_e32 v110, v110
	v_rcp_f32_e32 v111, v111
	v_rcp_f32_e32 v100, v100
	v_rcp_f32_e32 v101, v101
	v_rcp_f32_e32 v102, v102
	v_rcp_f32_e32 v103, v103
	v_pk_mul_f32 v[104:105], v[104:105], v[254:255] op_sel_hi:[1,0]
	v_pk_mul_f32 v[106:107], v[106:107], v[254:255] op_sel_hi:[1,0]
	v_pk_mul_f32 v[96:97], v[96:97], v[254:255] op_sel_hi:[1,0]
	v_pk_mul_f32 v[98:99], v[98:99], v[254:255] op_sel_hi:[1,0]
	v_pk_mul_f32 v[104:105], v[104:105], v[108:109]
	v_pk_mul_f32 v[106:107], v[106:107], v[110:111]
	v_pk_mul_f32 v[96:97], v[96:97], v[100:101]
	v_pk_mul_f32 v[98:99], v[98:99], v[102:103]
	v_cvt_pk_bf16_f32 v104, v104, v105
	v_cvt_pk_bf16_f32 v105, v106, v107
	v_cvt_pk_bf16_f32 v106, v96, v97
	v_cvt_pk_bf16_f32 v107, v98, v99
	global_store_dwordx4 v234, v[104:107], s[14:15]
	v_add_u32_e32 v235, 0x16000, v234
	v_mul_f32_e32 v252, 0xbfb8aa3b, v244
	v_mul_f32_e32 v254, v244, v244
	v_pk_mul_f32 v[88:89], v[92:93], v[88:89]
	v_pk_mul_f32 v[90:91], v[94:95], v[90:91]
	v_pk_mul_f32 v[80:81], v[84:85], v[80:81]
	v_pk_mul_f32 v[82:83], v[86:87], v[82:83]
	v_pk_mul_f32 v[92:93], v[92:93], v[252:253] op_sel_hi:[1,0]
	v_pk_mul_f32 v[94:95], v[94:95], v[252:253] op_sel_hi:[1,0]
	v_pk_mul_f32 v[84:85], v[84:85], v[252:253] op_sel_hi:[1,0]
	v_pk_mul_f32 v[86:87], v[86:87], v[252:253] op_sel_hi:[1,0]
	v_exp_f32_e32 v92, v92
	v_exp_f32_e32 v93, v93
	v_exp_f32_e32 v94, v94
	v_exp_f32_e32 v95, v95
	v_exp_f32_e32 v84, v84
	v_exp_f32_e32 v85, v85
	v_exp_f32_e32 v86, v86
	v_exp_f32_e32 v87, v87
	v_pk_add_f32 v[92:93], v[92:93], 1.0 op_sel_hi:[1,0]
	v_pk_add_f32 v[94:95], v[94:95], 1.0 op_sel_hi:[1,0]
	v_pk_add_f32 v[84:85], v[84:85], 1.0 op_sel_hi:[1,0]
	v_pk_add_f32 v[86:87], v[86:87], 1.0 op_sel_hi:[1,0]
	v_rcp_f32_e32 v92, v92
	v_rcp_f32_e32 v93, v93
	v_rcp_f32_e32 v94, v94
	v_rcp_f32_e32 v95, v95
	v_rcp_f32_e32 v84, v84
	v_rcp_f32_e32 v85, v85
	v_rcp_f32_e32 v86, v86
	v_rcp_f32_e32 v87, v87
	v_pk_mul_f32 v[88:89], v[88:89], v[254:255] op_sel_hi:[1,0]
	v_pk_mul_f32 v[90:91], v[90:91], v[254:255] op_sel_hi:[1,0]
	v_pk_mul_f32 v[80:81], v[80:81], v[254:255] op_sel_hi:[1,0]
	v_pk_mul_f32 v[82:83], v[82:83], v[254:255] op_sel_hi:[1,0]
	v_pk_mul_f32 v[88:89], v[88:89], v[92:93]
	v_pk_mul_f32 v[90:91], v[90:91], v[94:95]
	v_pk_mul_f32 v[80:81], v[80:81], v[84:85]
	v_pk_mul_f32 v[82:83], v[82:83], v[86:87]
	v_cvt_pk_bf16_f32 v88, v88, v89
	v_cvt_pk_bf16_f32 v89, v90, v91
	v_cvt_pk_bf16_f32 v90, v80, v81
	v_cvt_pk_bf16_f32 v91, v82, v83
	global_store_dwordx4 v235, v[88:91], s[14:15]
	v_add_u32_e32 v234, 0x16000, v235
	v_mul_f32_e32 v252, 0xbfb8aa3b, v248
	v_mul_f32_e32 v254, v248, v248
	v_pk_mul_f32 v[72:73], v[76:77], v[72:73]
	v_pk_mul_f32 v[74:75], v[78:79], v[74:75]
	v_pk_mul_f32 v[64:65], v[68:69], v[64:65]
	v_pk_mul_f32 v[66:67], v[70:71], v[66:67]
	v_pk_mul_f32 v[76:77], v[76:77], v[252:253] op_sel_hi:[1,0]
	v_pk_mul_f32 v[78:79], v[78:79], v[252:253] op_sel_hi:[1,0]
	v_pk_mul_f32 v[68:69], v[68:69], v[252:253] op_sel_hi:[1,0]
	v_pk_mul_f32 v[70:71], v[70:71], v[252:253] op_sel_hi:[1,0]
	v_exp_f32_e32 v76, v76
	v_exp_f32_e32 v77, v77
	v_exp_f32_e32 v78, v78
	v_exp_f32_e32 v79, v79
	v_exp_f32_e32 v68, v68
	v_exp_f32_e32 v69, v69
	v_exp_f32_e32 v70, v70
	v_exp_f32_e32 v71, v71
	v_pk_add_f32 v[76:77], v[76:77], 1.0 op_sel_hi:[1,0]
	v_pk_add_f32 v[78:79], v[78:79], 1.0 op_sel_hi:[1,0]
	v_pk_add_f32 v[68:69], v[68:69], 1.0 op_sel_hi:[1,0]
	v_pk_add_f32 v[70:71], v[70:71], 1.0 op_sel_hi:[1,0]
	v_rcp_f32_e32 v76, v76
	v_rcp_f32_e32 v77, v77
	v_rcp_f32_e32 v78, v78
	v_rcp_f32_e32 v79, v79
	v_rcp_f32_e32 v68, v68
	v_rcp_f32_e32 v69, v69
	v_rcp_f32_e32 v70, v70
	v_rcp_f32_e32 v71, v71
	v_pk_mul_f32 v[72:73], v[72:73], v[254:255] op_sel_hi:[1,0]
	v_pk_mul_f32 v[74:75], v[74:75], v[254:255] op_sel_hi:[1,0]
	v_pk_mul_f32 v[64:65], v[64:65], v[254:255] op_sel_hi:[1,0]
	v_pk_mul_f32 v[66:67], v[66:67], v[254:255] op_sel_hi:[1,0]
	v_pk_mul_f32 v[72:73], v[72:73], v[76:77]
	v_pk_mul_f32 v[74:75], v[74:75], v[78:79]
	v_pk_mul_f32 v[64:65], v[64:65], v[68:69]
	v_pk_mul_f32 v[66:67], v[66:67], v[70:71]
	v_cvt_pk_bf16_f32 v72, v72, v73
	v_cvt_pk_bf16_f32 v73, v74, v75
	v_cvt_pk_bf16_f32 v74, v64, v65
	v_cvt_pk_bf16_f32 v75, v66, v67
	global_store_dwordx4 v234, v[72:75], s[14:15]
	s_waitcnt vmcnt(12)
	s_waitcnt lgkmcnt(0)
	s_barrier
	s_setprio 1
	s_waitcnt lgkmcnt(0)
	v_mfma_f32_16x16x32_bf16 v[60:63], v[160:163], v[194:197], v[60:63]
	v_mfma_f32_16x16x32_bf16 v[60:63], v[164:167], v[198:201], v[60:63]
	v_mfma_f32_16x16x32_bf16 v[44:47], v[164:167], v[206:209], v[44:47]
	v_mfma_f32_16x16x32_bf16 v[44:47], v[160:163], v[202:205], v[44:47]
	v_mfma_f32_16x16x32_bf16 v[28:31], v[160:163], v[210:213], v[28:31]
	v_mfma_f32_16x16x32_bf16 v[28:31], v[164:167], v[214:217], v[28:31]
	v_mfma_f32_16x16x32_bf16 v[12:15], v[164:167], v[222:225], v[12:15]
	v_mfma_f32_16x16x32_bf16 v[12:15], v[160:163], v[218:221], v[12:15]
	v_mfma_f32_16x16x32_bf16 v[4:7], v[168:171], v[218:221], v[4:7]
	v_mfma_f32_16x16x32_bf16 v[4:7], v[172:175], v[222:225], v[4:7]
	v_mfma_f32_16x16x32_bf16 v[20:23], v[172:175], v[214:217], v[20:23]
	v_mfma_f32_16x16x32_bf16 v[20:23], v[168:171], v[210:213], v[20:23]
	v_mfma_f32_16x16x32_bf16 v[36:39], v[168:171], v[202:205], v[36:39]
	v_mfma_f32_16x16x32_bf16 v[36:39], v[172:175], v[206:209], v[36:39]
	v_mfma_f32_16x16x32_bf16 v[52:55], v[172:175], v[198:201], v[52:55]
	v_mfma_f32_16x16x32_bf16 v[52:55], v[168:171], v[194:197], v[52:55]
	s_setprio 0
	s_setprio 1
	v_mfma_f32_16x16x32_bf16 v[56:59], v[176:179], v[194:197], v[56:59]
	v_mfma_f32_16x16x32_bf16 v[56:59], v[180:183], v[198:201], v[56:59]
	v_mfma_f32_16x16x32_bf16 v[40:43], v[180:183], v[206:209], v[40:43]
	v_mfma_f32_16x16x32_bf16 v[40:43], v[176:179], v[202:205], v[40:43]
	v_mfma_f32_16x16x32_bf16 v[24:27], v[176:179], v[210:213], v[24:27]
	v_mfma_f32_16x16x32_bf16 v[24:27], v[180:183], v[214:217], v[24:27]
	v_mfma_f32_16x16x32_bf16 v[8:11], v[180:183], v[222:225], v[8:11]
	v_mfma_f32_16x16x32_bf16 v[8:11], v[176:179], v[218:221], v[8:11]
	v_mfma_f32_16x16x32_bf16 v[0:3], v[186:189], v[218:221], v[0:3]
	v_mfma_f32_16x16x32_bf16 v[0:3], v[190:193], v[222:225], v[0:3]
	v_mfma_f32_16x16x32_bf16 v[16:19], v[190:193], v[214:217], v[16:19]
	v_mfma_f32_16x16x32_bf16 v[16:19], v[186:189], v[210:213], v[16:19]
	v_mfma_f32_16x16x32_bf16 v[32:35], v[186:189], v[202:205], v[32:35]
	v_mfma_f32_16x16x32_bf16 v[32:35], v[190:193], v[206:209], v[32:35]
	v_mfma_f32_16x16x32_bf16 v[48:51], v[190:193], v[198:201], v[48:51]
	v_mfma_f32_16x16x32_bf16 v[48:51], v[186:189], v[194:197], v[48:51]
	s_setprio 0
	s_barrier
	s_add_i32 s75, s75, 2
	s_add_u32 s73, s73, 0x100
	s_addc_u32 s74, s74, 0
	s_add_u32 s46, s46, 0x100
	s_addc_u32 s47, s47, 0

.LBB0_609:
	s_add_u32 s79, s56, 0x100
	s_addc_u32 s80, s57, 0
	s_mov_b32 s81, -2
	s_waitcnt lgkmcnt(0)
	s_cmp_eq_u32 s70, 1
	s_cbranch_scc1 .Lfa_5
	ds_read_b128 v[128:131], v189
	v_xor_b32_e32 v253, 64, v189
	ds_read_b128 v[132:135], v253
	ds_read_b128 v[136:139], v189 offset:2048
	ds_read_b128 v[140:143], v253 offset:2048
	ds_read_b128 v[144:147], v190
	v_xor_b32_e32 v253, 64, v190
	ds_read_b128 v[148:151], v253
	ds_read_b128 v[172:175], v190 offset:2048
	ds_read_b128 v[176:179], v253 offset:2048
	s_add_u32 s56, s54, 0x100
	s_addc_u32 s57, s55, 0
	s_cmp_eq_u32 s81, 40
	s_cselect_b32 s61, s17, s57
	s_cselect_b32 s60, s16, s56
	s_cselect_b32 s59, s53, s80
	s_cselect_b32 s58, s52, s79
	v_lshl_add_u64 v[222:223], s[54:55], 0, v[166:167]
	s_add_i32 m0, s66, 0xc000
	ds_read_b128 v[180:183], v191
	v_xor_b32_e32 v253, 64, v191
	ds_read_b128 v[194:197], v253
	ds_read_b128 v[198:201], v191 offset:2048
	ds_read_b128 v[202:205], v253 offset:2048
	ds_read_b128 v[206:209], v191 offset:4096
	ds_read_b128 v[210:213], v253 offset:4096
	ds_read_b128 v[214:217], v191 offset:6144
	ds_read_b128 v[218:221], v253 offset:6144
	global_load_lds_dwordx4 v[222:223], off
	v_lshl_add_u64 v[222:223], s[54:55], 0, v[164:165]
	s_add_i32 m0, s66, 0xe000
	s_nop 0
	global_load_lds_dwordx4 v[222:223], off
	s_waitcnt vmcnt(24)
	s_waitcnt lgkmcnt(0)
	s_barrier
	s_setprio 1
	s_waitcnt lgkmcnt(0)
	v_mfma_f32_16x16x32_bf16 v[124:127], v[128:131], v[180:183], 0
	v_mfma_f32_16x16x32_bf16 v[120:123], v[136:139], v[180:183], 0
	v_mfma_f32_16x16x32_bf16 v[108:111], v[128:131], v[198:201], 0
	v_mfma_f32_16x16x32_bf16 v[104:107], v[136:139], v[198:201], 0
	v_mfma_f32_16x16x32_bf16 v[92:95], v[128:131], v[206:209], 0
	v_mfma_f32_16x16x32_bf16 v[88:91], v[136:139], v[206:209], 0
	v_mfma_f32_16x16x32_bf16 v[76:79], v[128:131], v[214:217], 0
	v_mfma_f32_16x16x32_bf16 v[72:75], v[136:139], v[214:217], 0
	v_mfma_f32_16x16x32_bf16 v[124:127], v[132:135], v[194:197], v[124:127]
	v_mfma_f32_16x16x32_bf16 v[120:123], v[140:143], v[194:197], v[120:123]
	v_mfma_f32_16x16x32_bf16 v[108:111], v[132:135], v[202:205], v[108:111]
	v_mfma_f32_16x16x32_bf16 v[104:107], v[140:143], v[202:205], v[104:107]
	v_mfma_f32_16x16x32_bf16 v[92:95], v[132:135], v[210:213], v[92:95]
	v_mfma_f32_16x16x32_bf16 v[88:91], v[140:143], v[210:213], v[88:91]
	v_mfma_f32_16x16x32_bf16 v[76:79], v[132:135], v[218:221], v[76:79]
	v_mfma_f32_16x16x32_bf16 v[72:75], v[140:143], v[218:221], v[72:75]
	s_setprio 0
	s_setprio 1
	v_mfma_f32_16x16x32_bf16 v[116:119], v[144:147], v[180:183], 0
	v_mfma_f32_16x16x32_bf16 v[112:115], v[172:175], v[180:183], 0
	v_mfma_f32_16x16x32_bf16 v[100:103], v[144:147], v[198:201], 0
	v_mfma_f32_16x16x32_bf16 v[96:99], v[172:175], v[198:201], 0
	v_mfma_f32_16x16x32_bf16 v[84:87], v[144:147], v[206:209], 0
	v_mfma_f32_16x16x32_bf16 v[80:83], v[172:175], v[206:209], 0
	v_mfma_f32_16x16x32_bf16 v[68:71], v[144:147], v[214:217], 0
	v_mfma_f32_16x16x32_bf16 v[64:67], v[172:175], v[214:217], 0
	v_mfma_f32_16x16x32_bf16 v[116:119], v[148:151], v[194:197], v[116:119]
	v_mfma_f32_16x16x32_bf16 v[112:115], v[176:179], v[194:197], v[112:115]
	v_mfma_f32_16x16x32_bf16 v[100:103], v[148:151], v[202:205], v[100:103]
	v_mfma_f32_16x16x32_bf16 v[96:99], v[176:179], v[202:205], v[96:99]
	v_mfma_f32_16x16x32_bf16 v[84:87], v[148:151], v[210:213], v[84:87]
	v_mfma_f32_16x16x32_bf16 v[80:83], v[176:179], v[210:213], v[80:83]
	v_mfma_f32_16x16x32_bf16 v[68:71], v[148:151], v[218:221], v[68:71]
	v_mfma_f32_16x16x32_bf16 v[64:67], v[176:179], v[218:221], v[64:67]
	s_setprio 0
	s_barrier
	s_add_i32 s54, s75, s65
	v_lshl_add_u64 v[222:223], s[58:59], 0, v[154:155]
	s_mov_b32 m0, s54
	ds_read_b128 v[180:183], v191 offset:16384
	v_xor_b32_e32 v253, 64, v191
	ds_read_b128 v[194:197], v253 offset:16384
	ds_read_b128 v[198:201], v191 offset:18432
	ds_read_b128 v[202:205], v253 offset:18432
	ds_read_b128 v[206:209], v191 offset:20480
	ds_read_b128 v[210:213], v253 offset:20480
	ds_read_b128 v[214:217], v191 offset:22528
	ds_read_b128 v[218:221], v253 offset:22528
	global_load_lds_dwordx4 v[222:223], off
	s_add_i32 m0, s54, 0x2000
	s_add_u32 s54, s58, 0xb0000
	v_lshl_add_u64 v[224:225], s[58:59], 0, v[162:163]
	s_addc_u32 s55, s59, 0
	s_add_i32 s82, s76, s65
	global_load_lds_dwordx4 v[224:225], off
	v_lshl_add_u64 v[226:227], s[54:55], 0, v[154:155]
	s_mov_b32 m0, s82
	v_lshl_add_u64 v[228:229], s[60:61], 0, v[160:161]
	global_load_lds_dwordx4 v[226:227], off
	v_lshl_add_u64 v[226:227], s[54:55], 0, v[162:163]
	s_add_i32 m0, s82, 0x2000
	s_nop 0
	global_load_lds_dwordx4 v[226:227], off
	v_lshl_add_u64 v[226:227], s[60:61], 0, v[152:153]
	s_mov_b32 m0, s66
	s_nop 0
	global_load_lds_dwordx4 v[226:227], off
	s_mov_b32 m0, s67
	s_nop 0
	global_load_lds_dwordx4 v[228:229], off
	s_waitcnt vmcnt(24)
	s_waitcnt lgkmcnt(0)
	s_barrier
	s_setprio 1
	s_waitcnt lgkmcnt(0)
	v_mfma_f32_16x16x32_bf16 v[60:63], v[128:131], v[180:183], 0
	v_mfma_f32_16x16x32_bf16 v[56:59], v[136:139], v[180:183], 0
	v_mfma_f32_16x16x32_bf16 v[44:47], v[128:131], v[198:201], 0
	v_mfma_f32_16x16x32_bf16 v[40:43], v[136:139], v[198:201], 0
	v_mfma_f32_16x16x32_bf16 v[28:31], v[128:131], v[206:209], 0
	v_mfma_f32_16x16x32_bf16 v[24:27], v[136:139], v[206:209], 0
	v_mfma_f32_16x16x32_bf16 v[12:15], v[128:131], v[214:217], 0
	v_mfma_f32_16x16x32_bf16 v[8:11], v[136:139], v[214:217], 0
	v_mfma_f32_16x16x32_bf16 v[60:63], v[132:135], v[194:197], v[60:63]
	v_mfma_f32_16x16x32_bf16 v[56:59], v[140:143], v[194:197], v[56:59]
	v_mfma_f32_16x16x32_bf16 v[44:47], v[132:135], v[202:205], v[44:47]
	v_mfma_f32_16x16x32_bf16 v[40:43], v[140:143], v[202:205], v[40:43]
	v_mfma_f32_16x16x32_bf16 v[28:31], v[132:135], v[210:213], v[28:31]
	v_mfma_f32_16x16x32_bf16 v[24:27], v[140:143], v[210:213], v[24:27]
	v_mfma_f32_16x16x32_bf16 v[12:15], v[132:135], v[218:221], v[12:15]
	v_mfma_f32_16x16x32_bf16 v[8:11], v[140:143], v[218:221], v[8:11]
	s_setprio 0
	s_setprio 1
	v_mfma_f32_16x16x32_bf16 v[52:55], v[144:147], v[180:183], 0
	v_mfma_f32_16x16x32_bf16 v[48:51], v[172:175], v[180:183], 0
	v_mfma_f32_16x16x32_bf16 v[36:39], v[144:147], v[198:201], 0
	v_mfma_f32_16x16x32_bf16 v[32:35], v[172:175], v[198:201], 0
	v_mfma_f32_16x16x32_bf16 v[20:23], v[144:147], v[206:209], 0
	v_mfma_f32_16x16x32_bf16 v[16:19], v[172:175], v[206:209], 0
	v_mfma_f32_16x16x32_bf16 v[4:7], v[144:147], v[214:217], 0
	v_mfma_f32_16x16x32_bf16 v[0:3], v[172:175], v[214:217], 0
	v_mfma_f32_16x16x32_bf16 v[52:55], v[148:151], v[194:197], v[52:55]
	v_mfma_f32_16x16x32_bf16 v[48:51], v[176:179], v[194:197], v[48:51]
	v_mfma_f32_16x16x32_bf16 v[36:39], v[148:151], v[202:205], v[36:39]
	v_mfma_f32_16x16x32_bf16 v[32:35], v[176:179], v[202:205], v[32:35]
	v_mfma_f32_16x16x32_bf16 v[20:23], v[148:151], v[210:213], v[20:23]
	v_mfma_f32_16x16x32_bf16 v[16:19], v[176:179], v[210:213], v[16:19]
	v_mfma_f32_16x16x32_bf16 v[4:7], v[148:151], v[218:221], v[4:7]
	v_mfma_f32_16x16x32_bf16 v[0:3], v[176:179], v[218:221], v[0:3]
	s_setprio 0
	s_barrier
	s_add_i32 s82, 0, 0x18000
	s_add_i32 s83, 0, 0x1c000
	v_add_u32_e32 v140, s82, v186
	v_add_u32_e32 v176, s83, v186
	ds_read_b128 v[128:131], v140
	v_xor_b32_e32 v253, 64, v140
	ds_read_b128 v[132:135], v253
	ds_read_b128 v[136:139], v140 offset:2048
	ds_read_b128 v[140:143], v253 offset:2048
	ds_read_b128 v[144:147], v176
	v_xor_b32_e32 v253, 64, v176
	ds_read_b128 v[148:151], v253
	ds_read_b128 v[172:175], v176 offset:2048
	ds_read_b128 v[176:179], v253 offset:2048
	s_add_u32 s54, s60, 0xb0000
	s_addc_u32 s55, s61, 0
	s_mov_b32 m0, s68
	v_lshl_add_u64 v[230:231], s[54:55], 0, v[152:153]
	ds_read_b128 v[180:183], v191 offset:32768
	v_xor_b32_e32 v253, 64, v191
	ds_read_b128 v[194:197], v253 offset:32768
	ds_read_b128 v[198:201], v191 offset:34816
	ds_read_b128 v[202:205], v253 offset:34816
	ds_read_b128 v[206:209], v191 offset:36864
	ds_read_b128 v[210:213], v253 offset:36864
	ds_read_b128 v[214:217], v191 offset:38912
	ds_read_b128 v[218:221], v253 offset:38912
	global_load_lds_dwordx4 v[230:231], off
	v_lshl_add_u64 v[230:231], s[54:55], 0, v[160:161]
	s_mov_b32 m0, s69
	s_nop 0
	global_load_lds_dwordx4 v[230:231], off
	s_waitcnt vmcnt(8)
	s_waitcnt lgkmcnt(0)
	s_barrier
	s_setprio 1
	s_waitcnt lgkmcnt(0)
	v_mfma_f32_16x16x32_bf16 v[124:127], v[128:131], v[180:183], v[124:127]
	v_mfma_f32_16x16x32_bf16 v[124:127], v[132:135], v[194:197], v[124:127]
	v_mfma_f32_16x16x32_bf16 v[108:111], v[132:135], v[202:205], v[108:111]
	v_mfma_f32_16x16x32_bf16 v[108:111], v[128:131], v[198:201], v[108:111]
	v_mfma_f32_16x16x32_bf16 v[92:95], v[128:131], v[206:209], v[92:95]
	v_mfma_f32_16x16x32_bf16 v[92:95], v[132:135], v[210:213], v[92:95]
	v_mfma_f32_16x16x32_bf16 v[76:79], v[132:135], v[218:221], v[76:79]
	v_mfma_f32_16x16x32_bf16 v[76:79], v[128:131], v[214:217], v[76:79]
	v_mfma_f32_16x16x32_bf16 v[72:75], v[136:139], v[214:217], v[72:75]
	v_mfma_f32_16x16x32_bf16 v[72:75], v[140:143], v[218:221], v[72:75]
	v_mfma_f32_16x16x32_bf16 v[88:91], v[140:143], v[210:213], v[88:91]
	v_mfma_f32_16x16x32_bf16 v[88:91], v[136:139], v[206:209], v[88:91]
	v_mfma_f32_16x16x32_bf16 v[104:107], v[136:139], v[198:201], v[104:107]
	v_mfma_f32_16x16x32_bf16 v[104:107], v[140:143], v[202:205], v[104:107]
	v_mfma_f32_16x16x32_bf16 v[120:123], v[140:143], v[194:197], v[120:123]
	v_mfma_f32_16x16x32_bf16 v[120:123], v[136:139], v[180:183], v[120:123]
	s_setprio 0
	s_setprio 1
	v_mfma_f32_16x16x32_bf16 v[116:119], v[144:147], v[180:183], v[116:119]
	v_mfma_f32_16x16x32_bf16 v[116:119], v[148:151], v[194:197], v[116:119]
	v_mfma_f32_16x16x32_bf16 v[100:103], v[148:151], v[202:205], v[100:103]
	v_mfma_f32_16x16x32_bf16 v[100:103], v[144:147], v[198:201], v[100:103]
	v_mfma_f32_16x16x32_bf16 v[84:87], v[144:147], v[206:209], v[84:87]
	v_mfma_f32_16x16x32_bf16 v[84:87], v[148:151], v[210:213], v[84:87]
	v_mfma_f32_16x16x32_bf16 v[68:71], v[148:151], v[218:221], v[68:71]
	v_mfma_f32_16x16x32_bf16 v[68:71], v[144:147], v[214:217], v[68:71]
	v_mfma_f32_16x16x32_bf16 v[64:67], v[172:175], v[214:217], v[64:67]
	v_mfma_f32_16x16x32_bf16 v[64:67], v[176:179], v[218:221], v[64:67]
	v_mfma_f32_16x16x32_bf16 v[80:83], v[176:179], v[210:213], v[80:83]
	v_mfma_f32_16x16x32_bf16 v[80:83], v[172:175], v[206:209], v[80:83]
	v_mfma_f32_16x16x32_bf16 v[96:99], v[172:175], v[198:201], v[96:99]
	v_mfma_f32_16x16x32_bf16 v[96:99], v[176:179], v[202:205], v[96:99]
	v_mfma_f32_16x16x32_bf16 v[112:115], v[176:179], v[194:197], v[112:115]
	v_mfma_f32_16x16x32_bf16 v[112:115], v[172:175], v[180:183], v[112:115]
	s_setprio 0
	s_barrier
	s_add_i32 s54, s82, s65
	v_lshl_add_u64 v[222:223], v[222:223], 0, s[28:29]
	s_mov_b32 m0, s54
	ds_read_b128 v[180:183], v191 offset:49152
	v_xor_b32_e32 v253, 64, v191
	ds_read_b128 v[194:197], v253 offset:49152
	ds_read_b128 v[198:201], v191 offset:51200
	ds_read_b128 v[202:205], v253 offset:51200
	ds_read_b128 v[206:209], v191 offset:53248
	ds_read_b128 v[210:213], v253 offset:53248
	ds_read_b128 v[214:217], v191 offset:55296
	ds_read_b128 v[218:221], v253 offset:55296
	global_load_lds_dwordx4 v[222:223], off
	s_add_i32 m0, s54, 0x2000
	s_add_u32 s54, s58, 0xb0080
	v_lshl_add_u64 v[222:223], v[224:225], 0, s[28:29]
	s_addc_u32 s55, s59, 0
	s_add_i32 s58, s83, s65
	global_load_lds_dwordx4 v[222:223], off
	v_lshl_add_u64 v[222:223], s[54:55], 0, v[154:155]
	s_mov_b32 m0, s58
	s_nop 0
	global_load_lds_dwordx4 v[222:223], off
	v_lshl_add_u64 v[222:223], s[54:55], 0, v[162:163]
	s_add_i32 m0, s58, 0x2000
	s_nop 0
	global_load_lds_dwordx4 v[222:223], off
	v_lshl_add_u64 v[222:223], v[226:227], 0, s[28:29]
	s_mov_b32 m0, s3
	s_nop 0
	global_load_lds_dwordx4 v[222:223], off
	v_lshl_add_u64 v[222:223], v[228:229], 0, s[28:29]
	s_mov_b32 m0, s71
	s_nop 0
	global_load_lds_dwordx4 v[222:223], off
	s_waitcnt vmcnt(8)
	s_waitcnt lgkmcnt(0)
	s_barrier
	s_setprio 1
	s_waitcnt lgkmcnt(0)
	v_mfma_f32_16x16x32_bf16 v[60:63], v[128:131], v[180:183], v[60:63]
	v_mfma_f32_16x16x32_bf16 v[60:63], v[132:135], v[194:197], v[60:63]
	v_mfma_f32_16x16x32_bf16 v[44:47], v[132:135], v[202:205], v[44:47]
	v_mfma_f32_16x16x32_bf16 v[44:47], v[128:131], v[198:201], v[44:47]
	v_mfma_f32_16x16x32_bf16 v[28:31], v[128:131], v[206:209], v[28:31]
	v_mfma_f32_16x16x32_bf16 v[28:31], v[132:135], v[210:213], v[28:31]
	v_mfma_f32_16x16x32_bf16 v[12:15], v[132:135], v[218:221], v[12:15]
	v_mfma_f32_16x16x32_bf16 v[12:15], v[128:131], v[214:217], v[12:15]
	v_mfma_f32_16x16x32_bf16 v[8:11], v[136:139], v[214:217], v[8:11]
	v_mfma_f32_16x16x32_bf16 v[8:11], v[140:143], v[218:221], v[8:11]
	v_mfma_f32_16x16x32_bf16 v[24:27], v[140:143], v[210:213], v[24:27]
	v_mfma_f32_16x16x32_bf16 v[24:27], v[136:139], v[206:209], v[24:27]
	v_mfma_f32_16x16x32_bf16 v[40:43], v[136:139], v[198:201], v[40:43]
	v_mfma_f32_16x16x32_bf16 v[40:43], v[140:143], v[202:205], v[40:43]
	v_mfma_f32_16x16x32_bf16 v[56:59], v[140:143], v[194:197], v[56:59]
	v_mfma_f32_16x16x32_bf16 v[56:59], v[136:139], v[180:183], v[56:59]
	s_setprio 0
	s_setprio 1
	v_mfma_f32_16x16x32_bf16 v[52:55], v[144:147], v[180:183], v[52:55]
	v_mfma_f32_16x16x32_bf16 v[52:55], v[148:151], v[194:197], v[52:55]
	v_mfma_f32_16x16x32_bf16 v[36:39], v[148:151], v[202:205], v[36:39]
	v_mfma_f32_16x16x32_bf16 v[36:39], v[144:147], v[198:201], v[36:39]
	v_mfma_f32_16x16x32_bf16 v[20:23], v[144:147], v[206:209], v[20:23]
	v_mfma_f32_16x16x32_bf16 v[20:23], v[148:151], v[210:213], v[20:23]
	v_mfma_f32_16x16x32_bf16 v[4:7], v[148:151], v[218:221], v[4:7]
	v_mfma_f32_16x16x32_bf16 v[4:7], v[144:147], v[214:217], v[4:7]
	v_mfma_f32_16x16x32_bf16 v[0:3], v[172:175], v[214:217], v[0:3]
	v_mfma_f32_16x16x32_bf16 v[0:3], v[176:179], v[218:221], v[0:3]
	v_mfma_f32_16x16x32_bf16 v[16:19], v[176:179], v[210:213], v[16:19]
	v_mfma_f32_16x16x32_bf16 v[16:19], v[172:175], v[206:209], v[16:19]
	v_mfma_f32_16x16x32_bf16 v[32:35], v[172:175], v[198:201], v[32:35]
	v_mfma_f32_16x16x32_bf16 v[32:35], v[176:179], v[202:205], v[32:35]
	v_mfma_f32_16x16x32_bf16 v[48:51], v[176:179], v[194:197], v[48:51]
	v_mfma_f32_16x16x32_bf16 v[48:51], v[172:175], v[180:183], v[48:51]
	s_setprio 0
	s_barrier
	s_add_i32 s81, s81, 2
	s_add_u32 s79, s79, 0x100
	s_addc_u32 s80, s80, 0
	s_cmp_gt_u32 s81, 41
	s_mov_b64 s[54:55], s[56:57]
	s_branch .LBB0_610
.Lfa_5:
	ds_read_b128 v[128:131], v189
	v_xor_b32_e32 v253, 64, v189
	ds_read_b128 v[132:135], v253
	ds_read_b128 v[136:139], v189 offset:2048
	ds_read_b128 v[140:143], v253 offset:2048
	ds_read_b128 v[144:147], v190
	v_xor_b32_e32 v253, 64, v190
	ds_read_b128 v[148:151], v253
	ds_read_b128 v[172:175], v190 offset:2048
	ds_read_b128 v[176:179], v253 offset:2048
	s_add_u32 s56, s54, 0x100
	s_addc_u32 s57, s55, 0
	s_cmp_eq_u32 s81, 40
	s_cselect_b32 s61, s17, s57
	s_cselect_b32 s60, s16, s56
	s_cselect_b32 s59, s53, s80
	s_cselect_b32 s58, s52, s79
	v_lshl_add_u64 v[222:223], s[54:55], 0, v[166:167]
	s_add_i32 m0, s66, 0xc000
	ds_read_b128 v[180:183], v191
	v_xor_b32_e32 v253, 64, v191
	ds_read_b128 v[194:197], v253
	ds_read_b128 v[198:201], v191 offset:2048
	ds_read_b128 v[202:205], v253 offset:2048
	ds_read_b128 v[206:209], v191 offset:4096
	ds_read_b128 v[210:213], v253 offset:4096
	ds_read_b128 v[214:217], v191 offset:6144
	ds_read_b128 v[218:221], v253 offset:6144
	global_load_lds_dwordx4 v[222:223], off
	v_lshl_add_u64 v[222:223], s[54:55], 0, v[164:165]
	s_add_i32 m0, s66, 0xe000
	s_nop 0
	global_load_lds_dwordx4 v[222:223], off
	s_waitcnt vmcnt(8)
	s_waitcnt lgkmcnt(0)
	s_barrier
	s_setprio 1
	s_waitcnt lgkmcnt(0)
	v_mfma_f32_16x16x32_bf16 v[124:127], v[128:131], v[180:183], 0
	v_mfma_f32_16x16x32_bf16 v[120:123], v[136:139], v[180:183], 0
	v_mfma_f32_16x16x32_bf16 v[108:111], v[128:131], v[198:201], 0
	v_mfma_f32_16x16x32_bf16 v[104:107], v[136:139], v[198:201], 0
	v_mfma_f32_16x16x32_bf16 v[92:95], v[128:131], v[206:209], 0
	v_mfma_f32_16x16x32_bf16 v[88:91], v[136:139], v[206:209], 0
	v_mfma_f32_16x16x32_bf16 v[76:79], v[128:131], v[214:217], 0
	v_mfma_f32_16x16x32_bf16 v[72:75], v[136:139], v[214:217], 0
	v_mfma_f32_16x16x32_bf16 v[124:127], v[132:135], v[194:197], v[124:127]
	v_mfma_f32_16x16x32_bf16 v[120:123], v[140:143], v[194:197], v[120:123]
	v_mfma_f32_16x16x32_bf16 v[108:111], v[132:135], v[202:205], v[108:111]
	v_mfma_f32_16x16x32_bf16 v[104:107], v[140:143], v[202:205], v[104:107]
	v_mfma_f32_16x16x32_bf16 v[92:95], v[132:135], v[210:213], v[92:95]
	v_mfma_f32_16x16x32_bf16 v[88:91], v[140:143], v[210:213], v[88:91]
	v_mfma_f32_16x16x32_bf16 v[76:79], v[132:135], v[218:221], v[76:79]
	v_mfma_f32_16x16x32_bf16 v[72:75], v[140:143], v[218:221], v[72:75]
	s_setprio 0
	s_setprio 1
	v_mfma_f32_16x16x32_bf16 v[116:119], v[144:147], v[180:183], 0
	v_mfma_f32_16x16x32_bf16 v[112:115], v[172:175], v[180:183], 0
	v_mfma_f32_16x16x32_bf16 v[100:103], v[144:147], v[198:201], 0
	v_mfma_f32_16x16x32_bf16 v[96:99], v[172:175], v[198:201], 0
	v_mfma_f32_16x16x32_bf16 v[84:87], v[144:147], v[206:209], 0
	v_mfma_f32_16x16x32_bf16 v[80:83], v[172:175], v[206:209], 0
	v_mfma_f32_16x16x32_bf16 v[68:71], v[144:147], v[214:217], 0
	v_mfma_f32_16x16x32_bf16 v[64:67], v[172:175], v[214:217], 0
	v_mfma_f32_16x16x32_bf16 v[116:119], v[148:151], v[194:197], v[116:119]
	v_mfma_f32_16x16x32_bf16 v[112:115], v[176:179], v[194:197], v[112:115]
	v_mfma_f32_16x16x32_bf16 v[100:103], v[148:151], v[202:205], v[100:103]
	v_mfma_f32_16x16x32_bf16 v[96:99], v[176:179], v[202:205], v[96:99]
	v_mfma_f32_16x16x32_bf16 v[84:87], v[148:151], v[210:213], v[84:87]
	v_mfma_f32_16x16x32_bf16 v[80:83], v[176:179], v[210:213], v[80:83]
	v_mfma_f32_16x16x32_bf16 v[68:71], v[148:151], v[218:221], v[68:71]
	v_mfma_f32_16x16x32_bf16 v[64:67], v[176:179], v[218:221], v[64:67]
	s_setprio 0
	s_barrier
	s_add_i32 s54, s75, s65
	v_lshl_add_u64 v[222:223], s[58:59], 0, v[154:155]
	s_mov_b32 m0, s54
	ds_read_b128 v[180:183], v191 offset:16384
	v_xor_b32_e32 v253, 64, v191
	ds_read_b128 v[194:197], v253 offset:16384
	ds_read_b128 v[198:201], v191 offset:18432
	ds_read_b128 v[202:205], v253 offset:18432
	ds_read_b128 v[206:209], v191 offset:20480
	ds_read_b128 v[210:213], v253 offset:20480
	ds_read_b128 v[214:217], v191 offset:22528
	ds_read_b128 v[218:221], v253 offset:22528
	global_load_lds_dwordx4 v[222:223], off
	s_add_i32 m0, s54, 0x2000
	s_add_u32 s54, s58, 0xb0000
	v_lshl_add_u64 v[224:225], s[58:59], 0, v[162:163]
	s_addc_u32 s55, s59, 0
	s_add_i32 s82, s76, s65
	global_load_lds_dwordx4 v[224:225], off
	v_lshl_add_u64 v[226:227], s[54:55], 0, v[154:155]
	s_mov_b32 m0, s82
	v_lshl_add_u64 v[228:229], s[60:61], 0, v[160:161]
	global_load_lds_dwordx4 v[226:227], off
	v_lshl_add_u64 v[226:227], s[54:55], 0, v[162:163]
	s_add_i32 m0, s82, 0x2000
	s_nop 0
	global_load_lds_dwordx4 v[226:227], off
	v_lshl_add_u64 v[226:227], s[60:61], 0, v[152:153]
	s_mov_b32 m0, s66
	s_nop 0
	global_load_lds_dwordx4 v[226:227], off
	s_mov_b32 m0, s67
	s_nop 0
	global_load_lds_dwordx4 v[228:229], off
	s_waitcnt vmcnt(8)
	s_waitcnt lgkmcnt(0)
	s_barrier
	s_setprio 1
	s_waitcnt lgkmcnt(0)
	v_mfma_f32_16x16x32_bf16 v[60:63], v[128:131], v[180:183], 0
	v_mfma_f32_16x16x32_bf16 v[56:59], v[136:139], v[180:183], 0
	v_mfma_f32_16x16x32_bf16 v[44:47], v[128:131], v[198:201], 0
	v_mfma_f32_16x16x32_bf16 v[40:43], v[136:139], v[198:201], 0
	v_mfma_f32_16x16x32_bf16 v[28:31], v[128:131], v[206:209], 0
	v_mfma_f32_16x16x32_bf16 v[24:27], v[136:139], v[206:209], 0
	v_mfma_f32_16x16x32_bf16 v[12:15], v[128:131], v[214:217], 0
	v_mfma_f32_16x16x32_bf16 v[8:11], v[136:139], v[214:217], 0
	v_mfma_f32_16x16x32_bf16 v[60:63], v[132:135], v[194:197], v[60:63]
	v_mfma_f32_16x16x32_bf16 v[56:59], v[140:143], v[194:197], v[56:59]
	v_mfma_f32_16x16x32_bf16 v[44:47], v[132:135], v[202:205], v[44:47]
	v_mfma_f32_16x16x32_bf16 v[40:43], v[140:143], v[202:205], v[40:43]
	v_mfma_f32_16x16x32_bf16 v[28:31], v[132:135], v[210:213], v[28:31]
	v_mfma_f32_16x16x32_bf16 v[24:27], v[140:143], v[210:213], v[24:27]
	v_mfma_f32_16x16x32_bf16 v[12:15], v[132:135], v[218:221], v[12:15]
	v_mfma_f32_16x16x32_bf16 v[8:11], v[140:143], v[218:221], v[8:11]
	s_setprio 0
	s_setprio 1
	v_mfma_f32_16x16x32_bf16 v[52:55], v[144:147], v[180:183], 0
	v_mfma_f32_16x16x32_bf16 v[48:51], v[172:175], v[180:183], 0
	v_mfma_f32_16x16x32_bf16 v[36:39], v[144:147], v[198:201], 0
	v_mfma_f32_16x16x32_bf16 v[32:35], v[172:175], v[198:201], 0
	v_mfma_f32_16x16x32_bf16 v[20:23], v[144:147], v[206:209], 0
	v_mfma_f32_16x16x32_bf16 v[16:19], v[172:175], v[206:209], 0
	v_mfma_f32_16x16x32_bf16 v[4:7], v[144:147], v[214:217], 0
	v_mfma_f32_16x16x32_bf16 v[0:3], v[172:175], v[214:217], 0
	v_mfma_f32_16x16x32_bf16 v[52:55], v[148:151], v[194:197], v[52:55]
	v_mfma_f32_16x16x32_bf16 v[48:51], v[176:179], v[194:197], v[48:51]
	v_mfma_f32_16x16x32_bf16 v[36:39], v[148:151], v[202:205], v[36:39]
	v_mfma_f32_16x16x32_bf16 v[32:35], v[176:179], v[202:205], v[32:35]
	v_mfma_f32_16x16x32_bf16 v[20:23], v[148:151], v[210:213], v[20:23]
	v_mfma_f32_16x16x32_bf16 v[16:19], v[176:179], v[210:213], v[16:19]
	v_mfma_f32_16x16x32_bf16 v[4:7], v[148:151], v[218:221], v[4:7]
	v_mfma_f32_16x16x32_bf16 v[0:3], v[176:179], v[218:221], v[0:3]
	s_setprio 0
	s_barrier
	s_add_i32 s82, 0, 0x18000
	s_add_i32 s83, 0, 0x1c000
	v_add_u32_e32 v140, s82, v186
	v_add_u32_e32 v176, s83, v186
	ds_read_b128 v[128:131], v140
	v_xor_b32_e32 v253, 64, v140
	ds_read_b128 v[132:135], v253
	ds_read_b128 v[136:139], v140 offset:2048
	ds_read_b128 v[140:143], v253 offset:2048
	ds_read_b128 v[144:147], v176
	v_xor_b32_e32 v253, 64, v176
	ds_read_b128 v[148:151], v253
	ds_read_b128 v[172:175], v176 offset:2048
	ds_read_b128 v[176:179], v253 offset:2048
	s_add_u32 s54, s60, 0xb0000
	s_addc_u32 s55, s61, 0
	s_mov_b32 m0, s68
	v_lshl_add_u64 v[230:231], s[54:55], 0, v[152:153]
	ds_read_b128 v[180:183], v191 offset:32768
	v_xor_b32_e32 v253, 64, v191
	ds_read_b128 v[194:197], v253 offset:32768
	ds_read_b128 v[198:201], v191 offset:34816
	ds_read_b128 v[202:205], v253 offset:34816
	ds_read_b128 v[206:209], v191 offset:36864
	ds_read_b128 v[210:213], v253 offset:36864
	ds_read_b128 v[214:217], v191 offset:38912
	ds_read_b128 v[218:221], v253 offset:38912
	global_load_lds_dwordx4 v[230:231], off
	v_lshl_add_u64 v[230:231], s[54:55], 0, v[160:161]
	s_mov_b32 m0, s69
	s_nop 0
	global_load_lds_dwordx4 v[230:231], off
	s_waitcnt vmcnt(8)
	s_waitcnt lgkmcnt(0)
	s_barrier
	s_setprio 1
	s_waitcnt lgkmcnt(0)
	v_mfma_f32_16x16x32_bf16 v[124:127], v[128:131], v[180:183], v[124:127]
	v_mfma_f32_16x16x32_bf16 v[124:127], v[132:135], v[194:197], v[124:127]
	v_mfma_f32_16x16x32_bf16 v[108:111], v[132:135], v[202:205], v[108:111]
	v_mfma_f32_16x16x32_bf16 v[108:111], v[128:131], v[198:201], v[108:111]
	v_mfma_f32_16x16x32_bf16 v[92:95], v[128:131], v[206:209], v[92:95]
	v_mfma_f32_16x16x32_bf16 v[92:95], v[132:135], v[210:213], v[92:95]
	v_mfma_f32_16x16x32_bf16 v[76:79], v[132:135], v[218:221], v[76:79]
	v_mfma_f32_16x16x32_bf16 v[76:79], v[128:131], v[214:217], v[76:79]
	v_mfma_f32_16x16x32_bf16 v[72:75], v[136:139], v[214:217], v[72:75]
	v_mfma_f32_16x16x32_bf16 v[72:75], v[140:143], v[218:221], v[72:75]
	v_mfma_f32_16x16x32_bf16 v[88:91], v[140:143], v[210:213], v[88:91]
	v_mfma_f32_16x16x32_bf16 v[88:91], v[136:139], v[206:209], v[88:91]
	v_mfma_f32_16x16x32_bf16 v[104:107], v[136:139], v[198:201], v[104:107]
	v_mfma_f32_16x16x32_bf16 v[104:107], v[140:143], v[202:205], v[104:107]
	v_mfma_f32_16x16x32_bf16 v[120:123], v[140:143], v[194:197], v[120:123]
	v_mfma_f32_16x16x32_bf16 v[120:123], v[136:139], v[180:183], v[120:123]
	s_setprio 0
	s_setprio 1
	v_mfma_f32_16x16x32_bf16 v[116:119], v[144:147], v[180:183], v[116:119]
	v_mfma_f32_16x16x32_bf16 v[116:119], v[148:151], v[194:197], v[116:119]
	v_mfma_f32_16x16x32_bf16 v[100:103], v[148:151], v[202:205], v[100:103]
	v_mfma_f32_16x16x32_bf16 v[100:103], v[144:147], v[198:201], v[100:103]
	v_mfma_f32_16x16x32_bf16 v[84:87], v[144:147], v[206:209], v[84:87]
	v_mfma_f32_16x16x32_bf16 v[84:87], v[148:151], v[210:213], v[84:87]
	v_mfma_f32_16x16x32_bf16 v[68:71], v[148:151], v[218:221], v[68:71]
	v_mfma_f32_16x16x32_bf16 v[68:71], v[144:147], v[214:217], v[68:71]
	v_mfma_f32_16x16x32_bf16 v[64:67], v[172:175], v[214:217], v[64:67]
	v_mfma_f32_16x16x32_bf16 v[64:67], v[176:179], v[218:221], v[64:67]
	v_mfma_f32_16x16x32_bf16 v[80:83], v[176:179], v[210:213], v[80:83]
	v_mfma_f32_16x16x32_bf16 v[80:83], v[172:175], v[206:209], v[80:83]
	v_mfma_f32_16x16x32_bf16 v[96:99], v[172:175], v[198:201], v[96:99]
	v_mfma_f32_16x16x32_bf16 v[96:99], v[176:179], v[202:205], v[96:99]
	v_mfma_f32_16x16x32_bf16 v[112:115], v[176:179], v[194:197], v[112:115]
	v_mfma_f32_16x16x32_bf16 v[112:115], v[172:175], v[180:183], v[112:115]
	s_setprio 0
	s_barrier
	s_add_i32 s54, s82, s65
	v_lshl_add_u64 v[222:223], v[222:223], 0, s[28:29]
	s_mov_b32 m0, s54
	ds_read_b128 v[180:183], v191 offset:49152
	v_xor_b32_e32 v253, 64, v191
	ds_read_b128 v[194:197], v253 offset:49152
	ds_read_b128 v[198:201], v191 offset:51200
	ds_read_b128 v[202:205], v253 offset:51200
	ds_read_b128 v[206:209], v191 offset:53248
	ds_read_b128 v[210:213], v253 offset:53248
	ds_read_b128 v[214:217], v191 offset:55296
	ds_read_b128 v[218:221], v253 offset:55296
	global_load_lds_dwordx4 v[222:223], off
	s_add_i32 m0, s54, 0x2000
	s_add_u32 s54, s58, 0xb0080
	v_lshl_add_u64 v[222:223], v[224:225], 0, s[28:29]
	s_addc_u32 s55, s59, 0
	s_add_i32 s58, s83, s65
	global_load_lds_dwordx4 v[222:223], off
	v_lshl_add_u64 v[222:223], s[54:55], 0, v[154:155]
	s_mov_b32 m0, s58
	s_nop 0
	global_load_lds_dwordx4 v[222:223], off
	v_lshl_add_u64 v[222:223], s[54:55], 0, v[162:163]
	s_add_i32 m0, s58, 0x2000
	s_nop 0
	global_load_lds_dwordx4 v[222:223], off
	v_lshl_add_u64 v[222:223], v[226:227], 0, s[28:29]
	s_mov_b32 m0, s3
	s_nop 0
	global_load_lds_dwordx4 v[222:223], off
	v_lshl_add_u64 v[222:223], v[228:229], 0, s[28:29]
	s_mov_b32 m0, s71
	s_nop 0
	global_load_lds_dwordx4 v[222:223], off
	s_waitcnt vmcnt(8)
	s_waitcnt lgkmcnt(0)
	s_barrier
	s_setprio 1
	s_waitcnt lgkmcnt(0)
	v_mfma_f32_16x16x32_bf16 v[60:63], v[128:131], v[180:183], v[60:63]
	v_mfma_f32_16x16x32_bf16 v[60:63], v[132:135], v[194:197], v[60:63]
	v_mfma_f32_16x16x32_bf16 v[44:47], v[132:135], v[202:205], v[44:47]
	v_mfma_f32_16x16x32_bf16 v[44:47], v[128:131], v[198:201], v[44:47]
	v_mfma_f32_16x16x32_bf16 v[28:31], v[128:131], v[206:209], v[28:31]
	v_mfma_f32_16x16x32_bf16 v[28:31], v[132:135], v[210:213], v[28:31]
	v_mfma_f32_16x16x32_bf16 v[12:15], v[132:135], v[218:221], v[12:15]
	v_mfma_f32_16x16x32_bf16 v[12:15], v[128:131], v[214:217], v[12:15]
	v_mfma_f32_16x16x32_bf16 v[8:11], v[136:139], v[214:217], v[8:11]
	v_mfma_f32_16x16x32_bf16 v[8:11], v[140:143], v[218:221], v[8:11]
	v_mfma_f32_16x16x32_bf16 v[24:27], v[140:143], v[210:213], v[24:27]
	v_mfma_f32_16x16x32_bf16 v[24:27], v[136:139], v[206:209], v[24:27]
	v_mfma_f32_16x16x32_bf16 v[40:43], v[136:139], v[198:201], v[40:43]
	v_mfma_f32_16x16x32_bf16 v[40:43], v[140:143], v[202:205], v[40:43]
	v_mfma_f32_16x16x32_bf16 v[56:59], v[140:143], v[194:197], v[56:59]
	v_mfma_f32_16x16x32_bf16 v[56:59], v[136:139], v[180:183], v[56:59]
	s_setprio 0
	s_setprio 1
	v_mfma_f32_16x16x32_bf16 v[52:55], v[144:147], v[180:183], v[52:55]
	v_mfma_f32_16x16x32_bf16 v[52:55], v[148:151], v[194:197], v[52:55]
	v_mfma_f32_16x16x32_bf16 v[36:39], v[148:151], v[202:205], v[36:39]
	v_mfma_f32_16x16x32_bf16 v[36:39], v[144:147], v[198:201], v[36:39]
	v_mfma_f32_16x16x32_bf16 v[20:23], v[144:147], v[206:209], v[20:23]
	v_mfma_f32_16x16x32_bf16 v[20:23], v[148:151], v[210:213], v[20:23]
	v_mfma_f32_16x16x32_bf16 v[4:7], v[148:151], v[218:221], v[4:7]
	v_mfma_f32_16x16x32_bf16 v[4:7], v[144:147], v[214:217], v[4:7]
	v_mfma_f32_16x16x32_bf16 v[0:3], v[172:175], v[214:217], v[0:3]
	v_mfma_f32_16x16x32_bf16 v[0:3], v[176:179], v[218:221], v[0:3]
	v_mfma_f32_16x16x32_bf16 v[16:19], v[176:179], v[210:213], v[16:19]
	v_mfma_f32_16x16x32_bf16 v[16:19], v[172:175], v[206:209], v[16:19]
	v_mfma_f32_16x16x32_bf16 v[32:35], v[172:175], v[198:201], v[32:35]
	v_mfma_f32_16x16x32_bf16 v[32:35], v[176:179], v[202:205], v[32:35]
	v_mfma_f32_16x16x32_bf16 v[48:51], v[176:179], v[194:197], v[48:51]
	v_mfma_f32_16x16x32_bf16 v[48:51], v[172:175], v[180:183], v[48:51]
	s_setprio 0
	s_barrier
	s_add_i32 s81, s81, 2
	s_add_u32 s79, s79, 0x100
	s_addc_u32 s80, s80, 0
	s_cmp_gt_u32 s81, 41
	s_mov_b64 s[54:55], s[56:57]
.LBB0_610:
	ds_read_b128 v[128:131], v189
	v_xor_b32_e32 v253, 64, v189
	ds_read_b128 v[132:135], v253
	ds_read_b128 v[136:139], v189 offset:2048
	ds_read_b128 v[140:143], v253 offset:2048
	ds_read_b128 v[144:147], v190
	v_xor_b32_e32 v253, 64, v190
	ds_read_b128 v[148:151], v253
	ds_read_b128 v[172:175], v190 offset:2048
	ds_read_b128 v[176:179], v253 offset:2048
	s_add_u32 s56, s54, 0x100
	s_addc_u32 s57, s55, 0
	s_cmp_eq_u32 s81, 40
	s_cselect_b32 s61, s17, s57
	s_cselect_b32 s60, s16, s56
	s_cselect_b32 s59, s53, s80
	s_cselect_b32 s58, s52, s79
	v_lshl_add_u64 v[222:223], s[54:55], 0, v[166:167]
	s_add_i32 m0, s66, 0xc000
	ds_read_b128 v[180:183], v191
	v_xor_b32_e32 v253, 64, v191
	ds_read_b128 v[194:197], v253
	ds_read_b128 v[198:201], v191 offset:2048
	ds_read_b128 v[202:205], v253 offset:2048
	ds_read_b128 v[206:209], v191 offset:4096
	ds_read_b128 v[210:213], v253 offset:4096
	ds_read_b128 v[214:217], v191 offset:6144
	ds_read_b128 v[218:221], v253 offset:6144
	global_load_lds_dwordx4 v[222:223], off
	v_lshl_add_u64 v[222:223], s[54:55], 0, v[164:165]
	s_add_i32 m0, s66, 0xe000
	s_nop 0
	global_load_lds_dwordx4 v[222:223], off
	s_waitcnt vmcnt(8)
	s_waitcnt lgkmcnt(0)
	s_barrier
	s_setprio 1
	s_waitcnt lgkmcnt(0)
	v_mfma_f32_16x16x32_bf16 v[124:127], v[128:131], v[180:183], v[124:127]
	v_mfma_f32_16x16x32_bf16 v[124:127], v[132:135], v[194:197], v[124:127]
	v_mfma_f32_16x16x32_bf16 v[108:111], v[132:135], v[202:205], v[108:111]
	v_mfma_f32_16x16x32_bf16 v[108:111], v[128:131], v[198:201], v[108:111]
	v_mfma_f32_16x16x32_bf16 v[92:95], v[128:131], v[206:209], v[92:95]
	v_mfma_f32_16x16x32_bf16 v[92:95], v[132:135], v[210:213], v[92:95]
	v_mfma_f32_16x16x32_bf16 v[76:79], v[132:135], v[218:221], v[76:79]
	v_mfma_f32_16x16x32_bf16 v[76:79], v[128:131], v[214:217], v[76:79]
	v_mfma_f32_16x16x32_bf16 v[72:75], v[136:139], v[214:217], v[72:75]
	v_mfma_f32_16x16x32_bf16 v[72:75], v[140:143], v[218:221], v[72:75]
	v_mfma_f32_16x16x32_bf16 v[88:91], v[140:143], v[210:213], v[88:91]
	v_mfma_f32_16x16x32_bf16 v[88:91], v[136:139], v[206:209], v[88:91]
	v_mfma_f32_16x16x32_bf16 v[104:107], v[136:139], v[198:201], v[104:107]
	v_mfma_f32_16x16x32_bf16 v[104:107], v[140:143], v[202:205], v[104:107]
	v_mfma_f32_16x16x32_bf16 v[120:123], v[140:143], v[194:197], v[120:123]
	v_mfma_f32_16x16x32_bf16 v[120:123], v[136:139], v[180:183], v[120:123]
	s_setprio 0
	s_setprio 1
	v_mfma_f32_16x16x32_bf16 v[116:119], v[144:147], v[180:183], v[116:119]
	v_mfma_f32_16x16x32_bf16 v[116:119], v[148:151], v[194:197], v[116:119]
	v_mfma_f32_16x16x32_bf16 v[100:103], v[148:151], v[202:205], v[100:103]
	v_mfma_f32_16x16x32_bf16 v[100:103], v[144:147], v[198:201], v[100:103]
	v_mfma_f32_16x16x32_bf16 v[84:87], v[144:147], v[206:209], v[84:87]
	v_mfma_f32_16x16x32_bf16 v[84:87], v[148:151], v[210:213], v[84:87]
	v_mfma_f32_16x16x32_bf16 v[68:71], v[148:151], v[218:221], v[68:71]
	v_mfma_f32_16x16x32_bf16 v[68:71], v[144:147], v[214:217], v[68:71]
	v_mfma_f32_16x16x32_bf16 v[64:67], v[172:175], v[214:217], v[64:67]
	v_mfma_f32_16x16x32_bf16 v[64:67], v[176:179], v[218:221], v[64:67]
	v_mfma_f32_16x16x32_bf16 v[80:83], v[176:179], v[210:213], v[80:83]
	v_mfma_f32_16x16x32_bf16 v[80:83], v[172:175], v[206:209], v[80:83]
	v_mfma_f32_16x16x32_bf16 v[96:99], v[172:175], v[198:201], v[96:99]
	v_mfma_f32_16x16x32_bf16 v[96:99], v[176:179], v[202:205], v[96:99]
	v_mfma_f32_16x16x32_bf16 v[112:115], v[176:179], v[194:197], v[112:115]
	v_mfma_f32_16x16x32_bf16 v[112:115], v[172:175], v[180:183], v[112:115]
	s_setprio 0
	s_barrier
	s_add_i32 s54, s75, s65
	v_lshl_add_u64 v[222:223], s[58:59], 0, v[154:155]
	s_mov_b32 m0, s54
	ds_read_b128 v[180:183], v191 offset:16384
	v_xor_b32_e32 v253, 64, v191
	ds_read_b128 v[194:197], v253 offset:16384
	ds_read_b128 v[198:201], v191 offset:18432
	ds_read_b128 v[202:205], v253 offset:18432
	ds_read_b128 v[206:209], v191 offset:20480
	ds_read_b128 v[210:213], v253 offset:20480
	ds_read_b128 v[214:217], v191 offset:22528
	ds_read_b128 v[218:221], v253 offset:22528
	global_load_lds_dwordx4 v[222:223], off
	s_add_i32 m0, s54, 0x2000
	s_add_u32 s54, s58, 0xb0000
	v_lshl_add_u64 v[224:225], s[58:59], 0, v[162:163]
	s_addc_u32 s55, s59, 0
	s_add_i32 s82, s76, s65
	global_load_lds_dwordx4 v[224:225], off
	v_lshl_add_u64 v[226:227], s[54:55], 0, v[154:155]
	s_mov_b32 m0, s82
	v_lshl_add_u64 v[228:229], s[60:61], 0, v[160:161]
	global_load_lds_dwordx4 v[226:227], off
	v_lshl_add_u64 v[226:227], s[54:55], 0, v[162:163]
	s_add_i32 m0, s82, 0x2000
	s_nop 0
	global_load_lds_dwordx4 v[226:227], off
	v_lshl_add_u64 v[226:227], s[60:61], 0, v[152:153]
	s_mov_b32 m0, s66
	s_nop 0
	global_load_lds_dwordx4 v[226:227], off
	s_mov_b32 m0, s67
	s_nop 0
	global_load_lds_dwordx4 v[228:229], off
	s_waitcnt vmcnt(8)
	s_waitcnt lgkmcnt(0)
	s_barrier
	s_setprio 1
	s_waitcnt lgkmcnt(0)
	v_mfma_f32_16x16x32_bf16 v[60:63], v[128:131], v[180:183], v[60:63]
	v_mfma_f32_16x16x32_bf16 v[60:63], v[132:135], v[194:197], v[60:63]
	v_mfma_f32_16x16x32_bf16 v[44:47], v[132:135], v[202:205], v[44:47]
	v_mfma_f32_16x16x32_bf16 v[44:47], v[128:131], v[198:201], v[44:47]
	v_mfma_f32_16x16x32_bf16 v[28:31], v[128:131], v[206:209], v[28:31]
	v_mfma_f32_16x16x32_bf16 v[28:31], v[132:135], v[210:213], v[28:31]
	v_mfma_f32_16x16x32_bf16 v[12:15], v[132:135], v[218:221], v[12:15]
	v_mfma_f32_16x16x32_bf16 v[12:15], v[128:131], v[214:217], v[12:15]
	v_mfma_f32_16x16x32_bf16 v[8:11], v[136:139], v[214:217], v[8:11]
	v_mfma_f32_16x16x32_bf16 v[8:11], v[140:143], v[218:221], v[8:11]
	v_mfma_f32_16x16x32_bf16 v[24:27], v[140:143], v[210:213], v[24:27]
	v_mfma_f32_16x16x32_bf16 v[24:27], v[136:139], v[206:209], v[24:27]
	v_mfma_f32_16x16x32_bf16 v[40:43], v[136:139], v[198:201], v[40:43]
	v_mfma_f32_16x16x32_bf16 v[40:43], v[140:143], v[202:205], v[40:43]
	v_mfma_f32_16x16x32_bf16 v[56:59], v[140:143], v[194:197], v[56:59]
	v_mfma_f32_16x16x32_bf16 v[56:59], v[136:139], v[180:183], v[56:59]
	s_setprio 0
	s_setprio 1
	v_mfma_f32_16x16x32_bf16 v[52:55], v[144:147], v[180:183], v[52:55]
	v_mfma_f32_16x16x32_bf16 v[52:55], v[148:151], v[194:197], v[52:55]
	v_mfma_f32_16x16x32_bf16 v[36:39], v[148:151], v[202:205], v[36:39]
	v_mfma_f32_16x16x32_bf16 v[36:39], v[144:147], v[198:201], v[36:39]
	v_mfma_f32_16x16x32_bf16 v[20:23], v[144:147], v[206:209], v[20:23]
	v_mfma_f32_16x16x32_bf16 v[20:23], v[148:151], v[210:213], v[20:23]
	v_mfma_f32_16x16x32_bf16 v[4:7], v[148:151], v[218:221], v[4:7]
	v_mfma_f32_16x16x32_bf16 v[4:7], v[144:147], v[214:217], v[4:7]
	v_mfma_f32_16x16x32_bf16 v[0:3], v[172:175], v[214:217], v[0:3]
	v_mfma_f32_16x16x32_bf16 v[0:3], v[176:179], v[218:221], v[0:3]
	v_mfma_f32_16x16x32_bf16 v[16:19], v[176:179], v[210:213], v[16:19]
	v_mfma_f32_16x16x32_bf16 v[16:19], v[172:175], v[206:209], v[16:19]
	v_mfma_f32_16x16x32_bf16 v[32:35], v[172:175], v[198:201], v[32:35]
	v_mfma_f32_16x16x32_bf16 v[32:35], v[176:179], v[202:205], v[32:35]
	v_mfma_f32_16x16x32_bf16 v[48:51], v[176:179], v[194:197], v[48:51]
	v_mfma_f32_16x16x32_bf16 v[48:51], v[172:175], v[180:183], v[48:51]
	s_setprio 0
	s_barrier
	s_add_i32 s82, 0, 0x18000
	s_add_i32 s83, 0, 0x1c000
	v_add_u32_e32 v140, s82, v186
	v_add_u32_e32 v176, s83, v186
	ds_read_b128 v[128:131], v140
	v_xor_b32_e32 v253, 64, v140
	ds_read_b128 v[132:135], v253
	ds_read_b128 v[136:139], v140 offset:2048
	ds_read_b128 v[140:143], v253 offset:2048
	ds_read_b128 v[144:147], v176
	v_xor_b32_e32 v253, 64, v176
	ds_read_b128 v[148:151], v253
	ds_read_b128 v[172:175], v176 offset:2048
	ds_read_b128 v[176:179], v253 offset:2048
	s_add_u32 s54, s60, 0xb0000
	s_addc_u32 s55, s61, 0
	s_mov_b32 m0, s68
	v_lshl_add_u64 v[230:231], s[54:55], 0, v[152:153]
	ds_read_b128 v[180:183], v191 offset:32768
	v_xor_b32_e32 v253, 64, v191
	ds_read_b128 v[194:197], v253 offset:32768
	ds_read_b128 v[198:201], v191 offset:34816
	ds_read_b128 v[202:205], v253 offset:34816
	ds_read_b128 v[206:209], v191 offset:36864
	ds_read_b128 v[210:213], v253 offset:36864
	ds_read_b128 v[214:217], v191 offset:38912
	ds_read_b128 v[218:221], v253 offset:38912
	global_load_lds_dwordx4 v[230:231], off
	v_lshl_add_u64 v[230:231], s[54:55], 0, v[160:161]
	s_mov_b32 m0, s69
	s_nop 0
	global_load_lds_dwordx4 v[230:231], off
	s_waitcnt vmcnt(8)
	s_waitcnt lgkmcnt(0)
	s_barrier
	s_setprio 1
	s_waitcnt lgkmcnt(0)
	v_mfma_f32_16x16x32_bf16 v[124:127], v[128:131], v[180:183], v[124:127]
	v_mfma_f32_16x16x32_bf16 v[124:127], v[132:135], v[194:197], v[124:127]
	v_mfma_f32_16x16x32_bf16 v[108:111], v[132:135], v[202:205], v[108:111]
	v_mfma_f32_16x16x32_bf16 v[108:111], v[128:131], v[198:201], v[108:111]
	v_mfma_f32_16x16x32_bf16 v[92:95], v[128:131], v[206:209], v[92:95]
	v_mfma_f32_16x16x32_bf16 v[92:95], v[132:135], v[210:213], v[92:95]
	v_mfma_f32_16x16x32_bf16 v[76:79], v[132:135], v[218:221], v[76:79]
	v_mfma_f32_16x16x32_bf16 v[76:79], v[128:131], v[214:217], v[76:79]
	v_mfma_f32_16x16x32_bf16 v[72:75], v[136:139], v[214:217], v[72:75]
	v_mfma_f32_16x16x32_bf16 v[72:75], v[140:143], v[218:221], v[72:75]
	v_mfma_f32_16x16x32_bf16 v[88:91], v[140:143], v[210:213], v[88:91]
	v_mfma_f32_16x16x32_bf16 v[88:91], v[136:139], v[206:209], v[88:91]
	v_mfma_f32_16x16x32_bf16 v[104:107], v[136:139], v[198:201], v[104:107]
	v_mfma_f32_16x16x32_bf16 v[104:107], v[140:143], v[202:205], v[104:107]
	v_mfma_f32_16x16x32_bf16 v[120:123], v[140:143], v[194:197], v[120:123]
	v_mfma_f32_16x16x32_bf16 v[120:123], v[136:139], v[180:183], v[120:123]
	s_setprio 0
	s_setprio 1
	v_mfma_f32_16x16x32_bf16 v[116:119], v[144:147], v[180:183], v[116:119]
	v_mfma_f32_16x16x32_bf16 v[116:119], v[148:151], v[194:197], v[116:119]
	v_mfma_f32_16x16x32_bf16 v[100:103], v[148:151], v[202:205], v[100:103]
	v_mfma_f32_16x16x32_bf16 v[100:103], v[144:147], v[198:201], v[100:103]
	v_mfma_f32_16x16x32_bf16 v[84:87], v[144:147], v[206:209], v[84:87]
	v_mfma_f32_16x16x32_bf16 v[84:87], v[148:151], v[210:213], v[84:87]
	v_mfma_f32_16x16x32_bf16 v[68:71], v[148:151], v[218:221], v[68:71]
	v_mfma_f32_16x16x32_bf16 v[68:71], v[144:147], v[214:217], v[68:71]
	v_mfma_f32_16x16x32_bf16 v[64:67], v[172:175], v[214:217], v[64:67]
	v_mfma_f32_16x16x32_bf16 v[64:67], v[176:179], v[218:221], v[64:67]
	v_mfma_f32_16x16x32_bf16 v[80:83], v[176:179], v[210:213], v[80:83]
	v_mfma_f32_16x16x32_bf16 v[80:83], v[172:175], v[206:209], v[80:83]
	v_mfma_f32_16x16x32_bf16 v[96:99], v[172:175], v[198:201], v[96:99]
	v_mfma_f32_16x16x32_bf16 v[96:99], v[176:179], v[202:205], v[96:99]
	v_mfma_f32_16x16x32_bf16 v[112:115], v[176:179], v[194:197], v[112:115]
	v_mfma_f32_16x16x32_bf16 v[112:115], v[172:175], v[180:183], v[112:115]
	s_setprio 0
	s_barrier
	s_add_i32 s54, s82, s65
	v_lshl_add_u64 v[222:223], v[222:223], 0, s[28:29]
	s_mov_b32 m0, s54
	ds_read_b128 v[180:183], v191 offset:49152
	v_xor_b32_e32 v253, 64, v191
	ds_read_b128 v[194:197], v253 offset:49152
	ds_read_b128 v[198:201], v191 offset:51200
	ds_read_b128 v[202:205], v253 offset:51200
	ds_read_b128 v[206:209], v191 offset:53248
	ds_read_b128 v[210:213], v253 offset:53248
	ds_read_b128 v[214:217], v191 offset:55296
	ds_read_b128 v[218:221], v253 offset:55296
	global_load_lds_dwordx4 v[222:223], off
	s_add_i32 m0, s54, 0x2000
	s_add_u32 s54, s58, 0xb0080
	v_lshl_add_u64 v[222:223], v[224:225], 0, s[28:29]
	s_addc_u32 s55, s59, 0
	s_add_i32 s58, s83, s65
	global_load_lds_dwordx4 v[222:223], off
	v_lshl_add_u64 v[222:223], s[54:55], 0, v[154:155]
	s_mov_b32 m0, s58
	s_nop 0
	global_load_lds_dwordx4 v[222:223], off
	v_lshl_add_u64 v[222:223], s[54:55], 0, v[162:163]
	s_add_i32 m0, s58, 0x2000
	s_nop 0
	global_load_lds_dwordx4 v[222:223], off
	v_lshl_add_u64 v[222:223], v[226:227], 0, s[28:29]
	s_mov_b32 m0, s3
	s_nop 0
	global_load_lds_dwordx4 v[222:223], off
	v_lshl_add_u64 v[222:223], v[228:229], 0, s[28:29]
	s_mov_b32 m0, s71
	s_nop 0
	global_load_lds_dwordx4 v[222:223], off
	s_waitcnt vmcnt(8)
	s_waitcnt lgkmcnt(0)
	s_barrier
	s_setprio 1
	s_waitcnt lgkmcnt(0)
	v_mfma_f32_16x16x32_bf16 v[60:63], v[128:131], v[180:183], v[60:63]
	v_mfma_f32_16x16x32_bf16 v[60:63], v[132:135], v[194:197], v[60:63]
	v_mfma_f32_16x16x32_bf16 v[44:47], v[132:135], v[202:205], v[44:47]
	v_mfma_f32_16x16x32_bf16 v[44:47], v[128:131], v[198:201], v[44:47]
	v_mfma_f32_16x16x32_bf16 v[28:31], v[128:131], v[206:209], v[28:31]
	v_mfma_f32_16x16x32_bf16 v[28:31], v[132:135], v[210:213], v[28:31]
	v_mfma_f32_16x16x32_bf16 v[12:15], v[132:135], v[218:221], v[12:15]
	v_mfma_f32_16x16x32_bf16 v[12:15], v[128:131], v[214:217], v[12:15]
	v_mfma_f32_16x16x32_bf16 v[8:11], v[136:139], v[214:217], v[8:11]
	v_mfma_f32_16x16x32_bf16 v[8:11], v[140:143], v[218:221], v[8:11]
	v_mfma_f32_16x16x32_bf16 v[24:27], v[140:143], v[210:213], v[24:27]
	v_mfma_f32_16x16x32_bf16 v[24:27], v[136:139], v[206:209], v[24:27]
	v_mfma_f32_16x16x32_bf16 v[40:43], v[136:139], v[198:201], v[40:43]
	v_mfma_f32_16x16x32_bf16 v[40:43], v[140:143], v[202:205], v[40:43]
	v_mfma_f32_16x16x32_bf16 v[56:59], v[140:143], v[194:197], v[56:59]
	v_mfma_f32_16x16x32_bf16 v[56:59], v[136:139], v[180:183], v[56:59]
	s_setprio 0
	s_setprio 1
	v_mfma_f32_16x16x32_bf16 v[52:55], v[144:147], v[180:183], v[52:55]
	v_mfma_f32_16x16x32_bf16 v[52:55], v[148:151], v[194:197], v[52:55]
	v_mfma_f32_16x16x32_bf16 v[36:39], v[148:151], v[202:205], v[36:39]
	v_mfma_f32_16x16x32_bf16 v[36:39], v[144:147], v[198:201], v[36:39]
	v_mfma_f32_16x16x32_bf16 v[20:23], v[144:147], v[206:209], v[20:23]
	v_mfma_f32_16x16x32_bf16 v[20:23], v[148:151], v[210:213], v[20:23]
	v_mfma_f32_16x16x32_bf16 v[4:7], v[148:151], v[218:221], v[4:7]
	v_mfma_f32_16x16x32_bf16 v[4:7], v[144:147], v[214:217], v[4:7]
	v_mfma_f32_16x16x32_bf16 v[0:3], v[172:175], v[214:217], v[0:3]
	v_mfma_f32_16x16x32_bf16 v[0:3], v[176:179], v[218:221], v[0:3]
	v_mfma_f32_16x16x32_bf16 v[16:19], v[176:179], v[210:213], v[16:19]
	v_mfma_f32_16x16x32_bf16 v[16:19], v[172:175], v[206:209], v[16:19]
	v_mfma_f32_16x16x32_bf16 v[32:35], v[172:175], v[198:201], v[32:35]
	v_mfma_f32_16x16x32_bf16 v[32:35], v[176:179], v[202:205], v[32:35]
	v_mfma_f32_16x16x32_bf16 v[48:51], v[176:179], v[194:197], v[48:51]
	v_mfma_f32_16x16x32_bf16 v[48:51], v[172:175], v[180:183], v[48:51]
	s_setprio 0
	s_barrier
	s_add_i32 s81, s81, 2
	s_add_u32 s79, s79, 0x100
	s_addc_u32 s80, s80, 0
	s_cmp_gt_u32 s81, 41
	s_mov_b64 s[54:55], s[56:57]
	s_cbranch_scc0 .LBB0_610
	s_and_b64 vcc, exec, s[30:31]
	s_cbranch_vccz .LBB0_613
	s_barrier

.LBB0_873:
	s_ashr_i32 s49, s48, 31
	s_lshl_b64 s[50:51], s[48:49], 19
	s_add_u32 s50, s35, s50
	s_addc_u32 s51, s60, s51
	s_and_b64 s[52:53], s[10:11], exec
	s_cselect_b32 s49, s51, s59
	s_cselect_b32 s80, s50, s58
	s_ashr_i32 s47, s46, 31
	s_lshl_b64 s[52:53], s[46:47], 19
	s_add_u32 s52, s61, s52
	s_addc_u32 s53, s62, s53
	s_and_b64 s[82:83], s[10:11], exec
	s_cselect_b32 s81, s53, s57
	s_cselect_b32 s82, s52, s56
	s_lshl_b32 s47, s54, 8
	v_add_u32_e32 v0, s47, v151
	s_add_u32 s83, s56, 0x100
	v_ashrrev_i32_e32 v1, 31, v0
	s_addc_u32 s84, s57, 0
	v_lshl_add_u64 v[144:145], v[0:1], 4, s[20:21]
	s_add_u32 s54, s58, 0x40080
	s_addc_u32 s55, s59, 0
	s_mov_b32 s85, -2
	s_mov_b64 s[56:57], 0
	s_cmp_eq_u32 s68, 1
	s_cbranch_scc1 .Lfa_8
	v_add_u32_e32 v146, s73, v149
	ds_read_b128 v[162:165], v146
	v_xor_b32_e32 v253, 64, v146
	ds_read_b128 v[166:169], v253
	ds_read_b128 v[170:173], v146 offset:2048
	ds_read_b128 v[174:177], v253 offset:2048
	v_add_u32_e32 v146, s74, v149
	ds_read_b128 v[178:181], v146
	v_xor_b32_e32 v253, 64, v146
	ds_read_b128 v[186:189], v253
	ds_read_b128 v[190:193], v146 offset:2048
	ds_read_b128 v[194:197], v253 offset:2048
	s_add_u32 s58, s54, 0xfffc0080
	s_addc_u32 s59, s55, -1
	s_and_b64 s[56:57], s[56:57], exec
	s_cselect_b32 s59, s49, s59
	s_cselect_b32 s58, s80, s58
	s_cselect_b32 s57, s81, s84
	s_cselect_b32 s56, s82, s83
	v_lshl_add_u64 v[182:183], s[54:55], 0, v[138:139]
	s_add_i32 m0, s64, 0xc000
	ds_read_b128 v[198:201], v154
	v_xor_b32_e32 v253, 64, v154
	ds_read_b128 v[202:205], v253
	ds_read_b128 v[206:209], v154 offset:2048
	ds_read_b128 v[210:213], v253 offset:2048
	ds_read_b128 v[214:217], v154 offset:4096
	ds_read_b128 v[218:221], v253 offset:4096
	ds_read_b128 v[222:225], v154 offset:6144
	ds_read_b128 v[226:229], v253 offset:6144
	global_load_lds_dwordx4 v[182:183], off
	v_lshl_add_u64 v[182:183], s[54:55], 0, v[136:137]
	s_add_i32 m0, s64, 0xe000
	s_nop 0
	global_load_lds_dwordx4 v[182:183], off
	s_waitcnt vmcnt(24)
	s_waitcnt lgkmcnt(0)
	s_barrier
	s_setprio 1
	s_waitcnt lgkmcnt(0)
	v_mfma_f32_16x16x32_bf16 v[124:127], v[162:165], v[198:201], 0
	v_mfma_f32_16x16x32_bf16 v[120:123], v[170:173], v[198:201], 0
	v_mfma_f32_16x16x32_bf16 v[112:115], v[162:165], v[206:209], 0
	v_mfma_f32_16x16x32_bf16 v[104:107], v[170:173], v[206:209], 0
	v_mfma_f32_16x16x32_bf16 v[96:99], v[162:165], v[214:217], 0
	v_mfma_f32_16x16x32_bf16 v[88:91], v[170:173], v[214:217], 0
	v_mfma_f32_16x16x32_bf16 v[80:83], v[162:165], v[222:225], 0
	v_mfma_f32_16x16x32_bf16 v[72:75], v[170:173], v[222:225], 0
	v_mfma_f32_16x16x32_bf16 v[124:127], v[166:169], v[202:205], v[124:127]
	v_mfma_f32_16x16x32_bf16 v[120:123], v[174:177], v[202:205], v[120:123]
	v_mfma_f32_16x16x32_bf16 v[112:115], v[166:169], v[210:213], v[112:115]
	v_mfma_f32_16x16x32_bf16 v[104:107], v[174:177], v[210:213], v[104:107]
	v_mfma_f32_16x16x32_bf16 v[96:99], v[166:169], v[218:221], v[96:99]
	v_mfma_f32_16x16x32_bf16 v[88:91], v[174:177], v[218:221], v[88:91]
	v_mfma_f32_16x16x32_bf16 v[80:83], v[166:169], v[226:229], v[80:83]
	v_mfma_f32_16x16x32_bf16 v[72:75], v[174:177], v[226:229], v[72:75]
	s_setprio 0
	s_setprio 1
	v_mfma_f32_16x16x32_bf16 v[116:119], v[178:181], v[198:201], 0
	v_mfma_f32_16x16x32_bf16 v[108:111], v[190:193], v[198:201], 0
	v_mfma_f32_16x16x32_bf16 v[100:103], v[178:181], v[206:209], 0
	v_mfma_f32_16x16x32_bf16 v[92:95], v[190:193], v[206:209], 0
	v_mfma_f32_16x16x32_bf16 v[84:87], v[178:181], v[214:217], 0
	v_mfma_f32_16x16x32_bf16 v[76:79], v[190:193], v[214:217], 0
	v_mfma_f32_16x16x32_bf16 v[68:71], v[178:181], v[222:225], 0
	v_mfma_f32_16x16x32_bf16 v[64:67], v[190:193], v[222:225], 0
	v_mfma_f32_16x16x32_bf16 v[116:119], v[186:189], v[202:205], v[116:119]
	v_mfma_f32_16x16x32_bf16 v[108:111], v[194:197], v[202:205], v[108:111]
	v_mfma_f32_16x16x32_bf16 v[100:103], v[186:189], v[210:213], v[100:103]
	v_mfma_f32_16x16x32_bf16 v[92:95], v[194:197], v[210:213], v[92:95]
	v_mfma_f32_16x16x32_bf16 v[84:87], v[186:189], v[218:221], v[84:87]
	v_mfma_f32_16x16x32_bf16 v[76:79], v[194:197], v[218:221], v[76:79]
	v_mfma_f32_16x16x32_bf16 v[68:71], v[186:189], v[226:229], v[68:71]
	v_mfma_f32_16x16x32_bf16 v[64:67], v[194:197], v[226:229], v[64:67]
	s_setprio 0
	s_barrier
	s_add_i32 s86, s73, s63
	v_lshl_add_u64 v[182:183], s[56:57], 0, v[130:131]
	s_mov_b32 m0, s86
	ds_read_b128 v[198:201], v154 offset:16384
	v_xor_b32_e32 v253, 64, v154
	ds_read_b128 v[202:205], v253 offset:16384
	ds_read_b128 v[206:209], v154 offset:18432
	ds_read_b128 v[210:213], v253 offset:18432
	ds_read_b128 v[214:217], v154 offset:20480
	ds_read_b128 v[218:221], v253 offset:20480
	ds_read_b128 v[222:225], v154 offset:22528
	ds_read_b128 v[226:229], v253 offset:22528
	global_load_lds_dwordx4 v[182:183], off
	s_add_i32 m0, s86, 0x2000
	s_add_u32 s86, s56, 0x40000
	v_lshl_add_u64 v[230:231], s[56:57], 0, v[134:135]
	s_addc_u32 s87, s57, 0
	s_add_i32 s88, s74, s63
	global_load_lds_dwordx4 v[230:231], off
	v_lshl_add_u64 v[232:233], s[86:87], 0, v[130:131]
	s_mov_b32 m0, s88
	v_lshl_add_u64 v[234:235], s[58:59], 0, v[132:133]
	global_load_lds_dwordx4 v[232:233], off
	v_lshl_add_u64 v[232:233], s[86:87], 0, v[134:135]
	s_add_i32 m0, s88, 0x2000
	s_nop 0
	global_load_lds_dwordx4 v[232:233], off
	v_lshl_add_u64 v[232:233], s[58:59], 0, v[128:129]
	s_mov_b32 m0, s64
	s_nop 0
	global_load_lds_dwordx4 v[232:233], off
	s_mov_b32 m0, s65
	s_nop 0
	global_load_lds_dwordx4 v[234:235], off
	s_waitcnt vmcnt(24)
	s_waitcnt lgkmcnt(0)
	s_barrier
	s_setprio 1
	s_waitcnt lgkmcnt(0)
	v_mfma_f32_16x16x32_bf16 v[60:63], v[162:165], v[198:201], 0
	v_mfma_f32_16x16x32_bf16 v[56:59], v[170:173], v[198:201], 0
	v_mfma_f32_16x16x32_bf16 v[48:51], v[162:165], v[206:209], 0
	v_mfma_f32_16x16x32_bf16 v[40:43], v[170:173], v[206:209], 0
	v_mfma_f32_16x16x32_bf16 v[32:35], v[162:165], v[214:217], 0
	v_mfma_f32_16x16x32_bf16 v[24:27], v[170:173], v[214:217], 0
	v_mfma_f32_16x16x32_bf16 v[16:19], v[162:165], v[222:225], 0
	v_mfma_f32_16x16x32_bf16 v[8:11], v[170:173], v[222:225], 0
	v_mfma_f32_16x16x32_bf16 v[60:63], v[166:169], v[202:205], v[60:63]
	v_mfma_f32_16x16x32_bf16 v[56:59], v[174:177], v[202:205], v[56:59]
	v_mfma_f32_16x16x32_bf16 v[48:51], v[166:169], v[210:213], v[48:51]
	v_mfma_f32_16x16x32_bf16 v[40:43], v[174:177], v[210:213], v[40:43]
	v_mfma_f32_16x16x32_bf16 v[32:35], v[166:169], v[218:221], v[32:35]
	v_mfma_f32_16x16x32_bf16 v[24:27], v[174:177], v[218:221], v[24:27]
	v_mfma_f32_16x16x32_bf16 v[16:19], v[166:169], v[226:229], v[16:19]
	v_mfma_f32_16x16x32_bf16 v[8:11], v[174:177], v[226:229], v[8:11]
	s_setprio 0
	s_setprio 1
	v_mfma_f32_16x16x32_bf16 v[52:55], v[178:181], v[198:201], 0
	v_mfma_f32_16x16x32_bf16 v[44:47], v[190:193], v[198:201], 0
	v_mfma_f32_16x16x32_bf16 v[36:39], v[178:181], v[206:209], 0
	v_mfma_f32_16x16x32_bf16 v[28:31], v[190:193], v[206:209], 0
	v_mfma_f32_16x16x32_bf16 v[20:23], v[178:181], v[214:217], 0
	v_mfma_f32_16x16x32_bf16 v[12:15], v[190:193], v[214:217], 0
	v_mfma_f32_16x16x32_bf16 v[4:7], v[178:181], v[222:225], 0
	v_mfma_f32_16x16x32_bf16 v[0:3], v[190:193], v[222:225], 0
	v_mfma_f32_16x16x32_bf16 v[52:55], v[186:189], v[202:205], v[52:55]
	v_mfma_f32_16x16x32_bf16 v[44:47], v[194:197], v[202:205], v[44:47]
	v_mfma_f32_16x16x32_bf16 v[36:39], v[186:189], v[210:213], v[36:39]
	v_mfma_f32_16x16x32_bf16 v[28:31], v[194:197], v[210:213], v[28:31]
	v_mfma_f32_16x16x32_bf16 v[20:23], v[186:189], v[218:221], v[20:23]
	v_mfma_f32_16x16x32_bf16 v[12:15], v[194:197], v[218:221], v[12:15]
	v_mfma_f32_16x16x32_bf16 v[4:7], v[186:189], v[226:229], v[4:7]
	v_mfma_f32_16x16x32_bf16 v[0:3], v[194:197], v[226:229], v[0:3]
	s_setprio 0
	s_barrier
	s_add_i32 s86, 0, 0x18000
	v_add_u32_e32 v146, s86, v149
	s_add_i32 s87, 0, 0x1c000
	ds_read_b128 v[162:165], v146
	v_xor_b32_e32 v253, 64, v146
	ds_read_b128 v[166:169], v253
	ds_read_b128 v[170:173], v146 offset:2048
	ds_read_b128 v[174:177], v253 offset:2048
	v_add_u32_e32 v146, s87, v149
	ds_read_b128 v[178:181], v146
	v_xor_b32_e32 v253, 64, v146
	ds_read_b128 v[186:189], v253
	ds_read_b128 v[190:193], v146 offset:2048
	ds_read_b128 v[194:197], v253 offset:2048
	s_add_u32 s58, s58, 0x40000
	s_addc_u32 s59, s59, 0
	s_mov_b32 m0, s66
	v_lshl_add_u64 v[236:237], s[58:59], 0, v[128:129]
	ds_read_b128 v[198:201], v154 offset:32768
	v_xor_b32_e32 v253, 64, v154
	ds_read_b128 v[202:205], v253 offset:32768
	ds_read_b128 v[206:209], v154 offset:34816
	ds_read_b128 v[210:213], v253 offset:34816
	ds_read_b128 v[214:217], v154 offset:36864
	ds_read_b128 v[218:221], v253 offset:36864
	ds_read_b128 v[222:225], v154 offset:38912
	ds_read_b128 v[226:229], v253 offset:38912
	global_load_lds_dwordx4 v[236:237], off
	v_lshl_add_u64 v[236:237], s[58:59], 0, v[132:133]
	s_mov_b32 m0, s67
	s_nop 0
	global_load_lds_dwordx4 v[236:237], off
	s_waitcnt vmcnt(8)
	s_waitcnt lgkmcnt(0)
	s_barrier
	s_setprio 1
	s_waitcnt lgkmcnt(0)
	v_mfma_f32_16x16x32_bf16 v[124:127], v[162:165], v[198:201], v[124:127]
	v_mfma_f32_16x16x32_bf16 v[124:127], v[166:169], v[202:205], v[124:127]
	v_mfma_f32_16x16x32_bf16 v[112:115], v[166:169], v[210:213], v[112:115]
	v_mfma_f32_16x16x32_bf16 v[112:115], v[162:165], v[206:209], v[112:115]
	v_mfma_f32_16x16x32_bf16 v[96:99], v[162:165], v[214:217], v[96:99]
	v_mfma_f32_16x16x32_bf16 v[96:99], v[166:169], v[218:221], v[96:99]
	v_mfma_f32_16x16x32_bf16 v[80:83], v[166:169], v[226:229], v[80:83]
	v_mfma_f32_16x16x32_bf16 v[80:83], v[162:165], v[222:225], v[80:83]
	v_mfma_f32_16x16x32_bf16 v[72:75], v[170:173], v[222:225], v[72:75]
	v_mfma_f32_16x16x32_bf16 v[72:75], v[174:177], v[226:229], v[72:75]
	v_mfma_f32_16x16x32_bf16 v[88:91], v[174:177], v[218:221], v[88:91]
	v_mfma_f32_16x16x32_bf16 v[88:91], v[170:173], v[214:217], v[88:91]
	v_mfma_f32_16x16x32_bf16 v[104:107], v[170:173], v[206:209], v[104:107]
	v_mfma_f32_16x16x32_bf16 v[104:107], v[174:177], v[210:213], v[104:107]
	v_mfma_f32_16x16x32_bf16 v[120:123], v[174:177], v[202:205], v[120:123]
	v_mfma_f32_16x16x32_bf16 v[120:123], v[170:173], v[198:201], v[120:123]
	s_setprio 0
	s_setprio 1
	v_mfma_f32_16x16x32_bf16 v[116:119], v[178:181], v[198:201], v[116:119]
	v_mfma_f32_16x16x32_bf16 v[116:119], v[186:189], v[202:205], v[116:119]
	v_mfma_f32_16x16x32_bf16 v[100:103], v[186:189], v[210:213], v[100:103]
	v_mfma_f32_16x16x32_bf16 v[100:103], v[178:181], v[206:209], v[100:103]
	v_mfma_f32_16x16x32_bf16 v[84:87], v[178:181], v[214:217], v[84:87]
	v_mfma_f32_16x16x32_bf16 v[84:87], v[186:189], v[218:221], v[84:87]
	v_mfma_f32_16x16x32_bf16 v[68:71], v[186:189], v[226:229], v[68:71]
	v_mfma_f32_16x16x32_bf16 v[68:71], v[178:181], v[222:225], v[68:71]
	v_mfma_f32_16x16x32_bf16 v[64:67], v[190:193], v[222:225], v[64:67]
	v_mfma_f32_16x16x32_bf16 v[64:67], v[194:197], v[226:229], v[64:67]
	v_mfma_f32_16x16x32_bf16 v[76:79], v[194:197], v[218:221], v[76:79]
	v_mfma_f32_16x16x32_bf16 v[76:79], v[190:193], v[214:217], v[76:79]
	v_mfma_f32_16x16x32_bf16 v[92:95], v[190:193], v[206:209], v[92:95]
	v_mfma_f32_16x16x32_bf16 v[92:95], v[194:197], v[210:213], v[92:95]
	v_mfma_f32_16x16x32_bf16 v[108:111], v[194:197], v[202:205], v[108:111]
	v_mfma_f32_16x16x32_bf16 v[108:111], v[190:193], v[198:201], v[108:111]
	s_setprio 0
	s_barrier
	s_add_i32 s58, s86, s63
	v_lshl_add_u64 v[182:183], v[182:183], 0, s[22:23]
	s_mov_b32 m0, s58
	ds_read_b128 v[198:201], v154 offset:49152
	v_xor_b32_e32 v253, 64, v154
	ds_read_b128 v[202:205], v253 offset:49152
	ds_read_b128 v[206:209], v154 offset:51200
	ds_read_b128 v[210:213], v253 offset:51200
	ds_read_b128 v[214:217], v154 offset:53248
	ds_read_b128 v[218:221], v253 offset:53248
	ds_read_b128 v[222:225], v154 offset:55296
	ds_read_b128 v[226:229], v253 offset:55296
	global_load_lds_dwordx4 v[182:183], off
	s_add_i32 m0, s58, 0x2000
	s_add_u32 s56, s56, 0x40080
	v_lshl_add_u64 v[182:183], v[230:231], 0, s[22:23]
	s_addc_u32 s57, s57, 0
	s_add_i32 s58, s87, s63
	global_load_lds_dwordx4 v[182:183], off
	v_lshl_add_u64 v[182:183], s[56:57], 0, v[130:131]
	s_mov_b32 m0, s58
	s_nop 0
	global_load_lds_dwordx4 v[182:183], off
	v_lshl_add_u64 v[182:183], s[56:57], 0, v[134:135]
	s_add_i32 m0, s58, 0x2000
	s_nop 0
	global_load_lds_dwordx4 v[182:183], off
	v_lshl_add_u64 v[182:183], v[232:233], 0, s[22:23]
	s_mov_b32 m0, s69
	s_nop 0
	global_load_lds_dwordx4 v[182:183], off
	v_lshl_add_u64 v[182:183], v[234:235], 0, s[22:23]
	s_mov_b32 m0, s70
	s_nop 0
	global_load_lds_dwordx4 v[182:183], off
	s_waitcnt vmcnt(8)
	s_waitcnt lgkmcnt(0)
	s_barrier
	s_setprio 1
	s_waitcnt lgkmcnt(0)
	v_mfma_f32_16x16x32_bf16 v[60:63], v[162:165], v[198:201], v[60:63]
	v_mfma_f32_16x16x32_bf16 v[60:63], v[166:169], v[202:205], v[60:63]
	v_mfma_f32_16x16x32_bf16 v[48:51], v[166:169], v[210:213], v[48:51]
	v_mfma_f32_16x16x32_bf16 v[48:51], v[162:165], v[206:209], v[48:51]
	v_mfma_f32_16x16x32_bf16 v[32:35], v[162:165], v[214:217], v[32:35]
	v_mfma_f32_16x16x32_bf16 v[32:35], v[166:169], v[218:221], v[32:35]
	v_mfma_f32_16x16x32_bf16 v[16:19], v[166:169], v[226:229], v[16:19]
	v_mfma_f32_16x16x32_bf16 v[16:19], v[162:165], v[222:225], v[16:19]
	v_mfma_f32_16x16x32_bf16 v[8:11], v[170:173], v[222:225], v[8:11]
	v_mfma_f32_16x16x32_bf16 v[8:11], v[174:177], v[226:229], v[8:11]
	v_mfma_f32_16x16x32_bf16 v[24:27], v[174:177], v[218:221], v[24:27]
	v_mfma_f32_16x16x32_bf16 v[24:27], v[170:173], v[214:217], v[24:27]
	v_mfma_f32_16x16x32_bf16 v[40:43], v[170:173], v[206:209], v[40:43]
	v_mfma_f32_16x16x32_bf16 v[40:43], v[174:177], v[210:213], v[40:43]
	v_mfma_f32_16x16x32_bf16 v[56:59], v[174:177], v[202:205], v[56:59]
	v_mfma_f32_16x16x32_bf16 v[56:59], v[170:173], v[198:201], v[56:59]
	s_setprio 0
	s_setprio 1
	v_mfma_f32_16x16x32_bf16 v[52:55], v[178:181], v[198:201], v[52:55]
	v_mfma_f32_16x16x32_bf16 v[52:55], v[186:189], v[202:205], v[52:55]
	v_mfma_f32_16x16x32_bf16 v[36:39], v[186:189], v[210:213], v[36:39]
	v_mfma_f32_16x16x32_bf16 v[36:39], v[178:181], v[206:209], v[36:39]
	v_mfma_f32_16x16x32_bf16 v[20:23], v[178:181], v[214:217], v[20:23]
	v_mfma_f32_16x16x32_bf16 v[20:23], v[186:189], v[218:221], v[20:23]
	v_mfma_f32_16x16x32_bf16 v[4:7], v[186:189], v[226:229], v[4:7]
	v_mfma_f32_16x16x32_bf16 v[4:7], v[178:181], v[222:225], v[4:7]
	v_mfma_f32_16x16x32_bf16 v[0:3], v[190:193], v[222:225], v[0:3]
	v_mfma_f32_16x16x32_bf16 v[0:3], v[194:197], v[226:229], v[0:3]
	v_mfma_f32_16x16x32_bf16 v[12:15], v[194:197], v[218:221], v[12:15]
	v_mfma_f32_16x16x32_bf16 v[12:15], v[190:193], v[214:217], v[12:15]
	v_mfma_f32_16x16x32_bf16 v[28:31], v[190:193], v[206:209], v[28:31]
	v_mfma_f32_16x16x32_bf16 v[28:31], v[194:197], v[210:213], v[28:31]
	v_mfma_f32_16x16x32_bf16 v[44:47], v[194:197], v[202:205], v[44:47]
	v_mfma_f32_16x16x32_bf16 v[44:47], v[190:193], v[198:201], v[44:47]
	s_setprio 0
	s_barrier
	s_add_i32 s85, s85, 2
	s_add_u32 s83, s83, 0x100
	s_addc_u32 s84, s84, 0
	s_add_u32 s54, s54, 0x100
	s_addc_u32 s55, s55, 0
	s_branch .LBB0_875
.Lfa_8:
	v_add_u32_e32 v146, s73, v149
	ds_read_b128 v[162:165], v146
	v_xor_b32_e32 v253, 64, v146
	ds_read_b128 v[166:169], v253
	ds_read_b128 v[170:173], v146 offset:2048
	ds_read_b128 v[174:177], v253 offset:2048
	v_add_u32_e32 v146, s74, v149
	ds_read_b128 v[178:181], v146
	v_xor_b32_e32 v253, 64, v146
	ds_read_b128 v[186:189], v253
	ds_read_b128 v[190:193], v146 offset:2048
	ds_read_b128 v[194:197], v253 offset:2048
	s_add_u32 s58, s54, 0xfffc0080
	s_addc_u32 s59, s55, -1
	s_and_b64 s[56:57], s[56:57], exec
	s_cselect_b32 s59, s49, s59
	s_cselect_b32 s58, s80, s58
	s_cselect_b32 s57, s81, s84
	s_cselect_b32 s56, s82, s83
	v_lshl_add_u64 v[182:183], s[54:55], 0, v[138:139]
	s_add_i32 m0, s64, 0xc000
	ds_read_b128 v[198:201], v154
	v_xor_b32_e32 v253, 64, v154
	ds_read_b128 v[202:205], v253
	ds_read_b128 v[206:209], v154 offset:2048
	ds_read_b128 v[210:213], v253 offset:2048
	ds_read_b128 v[214:217], v154 offset:4096
	ds_read_b128 v[218:221], v253 offset:4096
	ds_read_b128 v[222:225], v154 offset:6144
	ds_read_b128 v[226:229], v253 offset:6144
	global_load_lds_dwordx4 v[182:183], off
	v_lshl_add_u64 v[182:183], s[54:55], 0, v[136:137]
	s_add_i32 m0, s64, 0xe000
	s_nop 0
	global_load_lds_dwordx4 v[182:183], off
	s_waitcnt vmcnt(8)
	s_waitcnt lgkmcnt(0)
	s_barrier
	s_setprio 1
	s_waitcnt lgkmcnt(0)
	v_mfma_f32_16x16x32_bf16 v[124:127], v[162:165], v[198:201], 0
	v_mfma_f32_16x16x32_bf16 v[120:123], v[170:173], v[198:201], 0
	v_mfma_f32_16x16x32_bf16 v[112:115], v[162:165], v[206:209], 0
	v_mfma_f32_16x16x32_bf16 v[104:107], v[170:173], v[206:209], 0
	v_mfma_f32_16x16x32_bf16 v[96:99], v[162:165], v[214:217], 0
	v_mfma_f32_16x16x32_bf16 v[88:91], v[170:173], v[214:217], 0
	v_mfma_f32_16x16x32_bf16 v[80:83], v[162:165], v[222:225], 0
	v_mfma_f32_16x16x32_bf16 v[72:75], v[170:173], v[222:225], 0
	v_mfma_f32_16x16x32_bf16 v[124:127], v[166:169], v[202:205], v[124:127]
	v_mfma_f32_16x16x32_bf16 v[120:123], v[174:177], v[202:205], v[120:123]
	v_mfma_f32_16x16x32_bf16 v[112:115], v[166:169], v[210:213], v[112:115]
	v_mfma_f32_16x16x32_bf16 v[104:107], v[174:177], v[210:213], v[104:107]
	v_mfma_f32_16x16x32_bf16 v[96:99], v[166:169], v[218:221], v[96:99]
	v_mfma_f32_16x16x32_bf16 v[88:91], v[174:177], v[218:221], v[88:91]
	v_mfma_f32_16x16x32_bf16 v[80:83], v[166:169], v[226:229], v[80:83]
	v_mfma_f32_16x16x32_bf16 v[72:75], v[174:177], v[226:229], v[72:75]
	s_setprio 0
	s_setprio 1
	v_mfma_f32_16x16x32_bf16 v[116:119], v[178:181], v[198:201], 0
	v_mfma_f32_16x16x32_bf16 v[108:111], v[190:193], v[198:201], 0
	v_mfma_f32_16x16x32_bf16 v[100:103], v[178:181], v[206:209], 0
	v_mfma_f32_16x16x32_bf16 v[92:95], v[190:193], v[206:209], 0
	v_mfma_f32_16x16x32_bf16 v[84:87], v[178:181], v[214:217], 0
	v_mfma_f32_16x16x32_bf16 v[76:79], v[190:193], v[214:217], 0
	v_mfma_f32_16x16x32_bf16 v[68:71], v[178:181], v[222:225], 0
	v_mfma_f32_16x16x32_bf16 v[64:67], v[190:193], v[222:225], 0
	v_mfma_f32_16x16x32_bf16 v[116:119], v[186:189], v[202:205], v[116:119]
	v_mfma_f32_16x16x32_bf16 v[108:111], v[194:197], v[202:205], v[108:111]
	v_mfma_f32_16x16x32_bf16 v[100:103], v[186:189], v[210:213], v[100:103]
	v_mfma_f32_16x16x32_bf16 v[92:95], v[194:197], v[210:213], v[92:95]
	v_mfma_f32_16x16x32_bf16 v[84:87], v[186:189], v[218:221], v[84:87]
	v_mfma_f32_16x16x32_bf16 v[76:79], v[194:197], v[218:221], v[76:79]
	v_mfma_f32_16x16x32_bf16 v[68:71], v[186:189], v[226:229], v[68:71]
	v_mfma_f32_16x16x32_bf16 v[64:67], v[194:197], v[226:229], v[64:67]
	s_setprio 0
	s_barrier
	s_add_i32 s86, s73, s63
	v_lshl_add_u64 v[182:183], s[56:57], 0, v[130:131]
	s_mov_b32 m0, s86
	ds_read_b128 v[198:201], v154 offset:16384
	v_xor_b32_e32 v253, 64, v154
	ds_read_b128 v[202:205], v253 offset:16384
	ds_read_b128 v[206:209], v154 offset:18432
	ds_read_b128 v[210:213], v253 offset:18432
	ds_read_b128 v[214:217], v154 offset:20480
	ds_read_b128 v[218:221], v253 offset:20480
	ds_read_b128 v[222:225], v154 offset:22528
	ds_read_b128 v[226:229], v253 offset:22528
	global_load_lds_dwordx4 v[182:183], off
	s_add_i32 m0, s86, 0x2000
	s_add_u32 s86, s56, 0x40000
	v_lshl_add_u64 v[230:231], s[56:57], 0, v[134:135]
	s_addc_u32 s87, s57, 0
	s_add_i32 s88, s74, s63
	global_load_lds_dwordx4 v[230:231], off
	v_lshl_add_u64 v[232:233], s[86:87], 0, v[130:131]
	s_mov_b32 m0, s88
	v_lshl_add_u64 v[234:235], s[58:59], 0, v[132:133]
	global_load_lds_dwordx4 v[232:233], off
	v_lshl_add_u64 v[232:233], s[86:87], 0, v[134:135]
	s_add_i32 m0, s88, 0x2000
	s_nop 0
	global_load_lds_dwordx4 v[232:233], off
	v_lshl_add_u64 v[232:233], s[58:59], 0, v[128:129]
	s_mov_b32 m0, s64
	s_nop 0
	global_load_lds_dwordx4 v[232:233], off
	s_mov_b32 m0, s65
	s_nop 0
	global_load_lds_dwordx4 v[234:235], off
	s_waitcnt vmcnt(8)
	s_waitcnt lgkmcnt(0)
	s_barrier
	s_setprio 1
	s_waitcnt lgkmcnt(0)
	v_mfma_f32_16x16x32_bf16 v[60:63], v[162:165], v[198:201], 0
	v_mfma_f32_16x16x32_bf16 v[56:59], v[170:173], v[198:201], 0
	v_mfma_f32_16x16x32_bf16 v[48:51], v[162:165], v[206:209], 0
	v_mfma_f32_16x16x32_bf16 v[40:43], v[170:173], v[206:209], 0
	v_mfma_f32_16x16x32_bf16 v[32:35], v[162:165], v[214:217], 0
	v_mfma_f32_16x16x32_bf16 v[24:27], v[170:173], v[214:217], 0
	v_mfma_f32_16x16x32_bf16 v[16:19], v[162:165], v[222:225], 0
	v_mfma_f32_16x16x32_bf16 v[8:11], v[170:173], v[222:225], 0
	v_mfma_f32_16x16x32_bf16 v[60:63], v[166:169], v[202:205], v[60:63]
	v_mfma_f32_16x16x32_bf16 v[56:59], v[174:177], v[202:205], v[56:59]
	v_mfma_f32_16x16x32_bf16 v[48:51], v[166:169], v[210:213], v[48:51]
	v_mfma_f32_16x16x32_bf16 v[40:43], v[174:177], v[210:213], v[40:43]
	v_mfma_f32_16x16x32_bf16 v[32:35], v[166:169], v[218:221], v[32:35]
	v_mfma_f32_16x16x32_bf16 v[24:27], v[174:177], v[218:221], v[24:27]
	v_mfma_f32_16x16x32_bf16 v[16:19], v[166:169], v[226:229], v[16:19]
	v_mfma_f32_16x16x32_bf16 v[8:11], v[174:177], v[226:229], v[8:11]
	s_setprio 0
	s_setprio 1
	v_mfma_f32_16x16x32_bf16 v[52:55], v[178:181], v[198:201], 0
	v_mfma_f32_16x16x32_bf16 v[44:47], v[190:193], v[198:201], 0
	v_mfma_f32_16x16x32_bf16 v[36:39], v[178:181], v[206:209], 0
	v_mfma_f32_16x16x32_bf16 v[28:31], v[190:193], v[206:209], 0
	v_mfma_f32_16x16x32_bf16 v[20:23], v[178:181], v[214:217], 0
	v_mfma_f32_16x16x32_bf16 v[12:15], v[190:193], v[214:217], 0
	v_mfma_f32_16x16x32_bf16 v[4:7], v[178:181], v[222:225], 0
	v_mfma_f32_16x16x32_bf16 v[0:3], v[190:193], v[222:225], 0
	v_mfma_f32_16x16x32_bf16 v[52:55], v[186:189], v[202:205], v[52:55]
	v_mfma_f32_16x16x32_bf16 v[44:47], v[194:197], v[202:205], v[44:47]
	v_mfma_f32_16x16x32_bf16 v[36:39], v[186:189], v[210:213], v[36:39]
	v_mfma_f32_16x16x32_bf16 v[28:31], v[194:197], v[210:213], v[28:31]
	v_mfma_f32_16x16x32_bf16 v[20:23], v[186:189], v[218:221], v[20:23]
	v_mfma_f32_16x16x32_bf16 v[12:15], v[194:197], v[218:221], v[12:15]
	v_mfma_f32_16x16x32_bf16 v[4:7], v[186:189], v[226:229], v[4:7]
	v_mfma_f32_16x16x32_bf16 v[0:3], v[194:197], v[226:229], v[0:3]
	s_setprio 0
	s_barrier
	s_add_i32 s86, 0, 0x18000
	v_add_u32_e32 v146, s86, v149
	s_add_i32 s87, 0, 0x1c000
	ds_read_b128 v[162:165], v146
	v_xor_b32_e32 v253, 64, v146
	ds_read_b128 v[166:169], v253
	ds_read_b128 v[170:173], v146 offset:2048
	ds_read_b128 v[174:177], v253 offset:2048
	v_add_u32_e32 v146, s87, v149
	ds_read_b128 v[178:181], v146
	v_xor_b32_e32 v253, 64, v146
	ds_read_b128 v[186:189], v253
	ds_read_b128 v[190:193], v146 offset:2048
	ds_read_b128 v[194:197], v253 offset:2048
	s_add_u32 s58, s58, 0x40000
	s_addc_u32 s59, s59, 0
	s_mov_b32 m0, s66
	v_lshl_add_u64 v[236:237], s[58:59], 0, v[128:129]
	ds_read_b128 v[198:201], v154 offset:32768
	v_xor_b32_e32 v253, 64, v154
	ds_read_b128 v[202:205], v253 offset:32768
	ds_read_b128 v[206:209], v154 offset:34816
	ds_read_b128 v[210:213], v253 offset:34816
	ds_read_b128 v[214:217], v154 offset:36864
	ds_read_b128 v[218:221], v253 offset:36864
	ds_read_b128 v[222:225], v154 offset:38912
	ds_read_b128 v[226:229], v253 offset:38912
	global_load_lds_dwordx4 v[236:237], off
	v_lshl_add_u64 v[236:237], s[58:59], 0, v[132:133]
	s_mov_b32 m0, s67
	s_nop 0
	global_load_lds_dwordx4 v[236:237], off
	s_waitcnt vmcnt(8)
	s_waitcnt lgkmcnt(0)
	s_barrier
	s_setprio 1
	s_waitcnt lgkmcnt(0)
	v_mfma_f32_16x16x32_bf16 v[124:127], v[162:165], v[198:201], v[124:127]
	v_mfma_f32_16x16x32_bf16 v[124:127], v[166:169], v[202:205], v[124:127]
	v_mfma_f32_16x16x32_bf16 v[112:115], v[166:169], v[210:213], v[112:115]
	v_mfma_f32_16x16x32_bf16 v[112:115], v[162:165], v[206:209], v[112:115]
	v_mfma_f32_16x16x32_bf16 v[96:99], v[162:165], v[214:217], v[96:99]
	v_mfma_f32_16x16x32_bf16 v[96:99], v[166:169], v[218:221], v[96:99]
	v_mfma_f32_16x16x32_bf16 v[80:83], v[166:169], v[226:229], v[80:83]
	v_mfma_f32_16x16x32_bf16 v[80:83], v[162:165], v[222:225], v[80:83]
	v_mfma_f32_16x16x32_bf16 v[72:75], v[170:173], v[222:225], v[72:75]
	v_mfma_f32_16x16x32_bf16 v[72:75], v[174:177], v[226:229], v[72:75]
	v_mfma_f32_16x16x32_bf16 v[88:91], v[174:177], v[218:221], v[88:91]
	v_mfma_f32_16x16x32_bf16 v[88:91], v[170:173], v[214:217], v[88:91]
	v_mfma_f32_16x16x32_bf16 v[104:107], v[170:173], v[206:209], v[104:107]
	v_mfma_f32_16x16x32_bf16 v[104:107], v[174:177], v[210:213], v[104:107]
	v_mfma_f32_16x16x32_bf16 v[120:123], v[174:177], v[202:205], v[120:123]
	v_mfma_f32_16x16x32_bf16 v[120:123], v[170:173], v[198:201], v[120:123]
	s_setprio 0
	s_setprio 1
	v_mfma_f32_16x16x32_bf16 v[116:119], v[178:181], v[198:201], v[116:119]
	v_mfma_f32_16x16x32_bf16 v[116:119], v[186:189], v[202:205], v[116:119]
	v_mfma_f32_16x16x32_bf16 v[100:103], v[186:189], v[210:213], v[100:103]
	v_mfma_f32_16x16x32_bf16 v[100:103], v[178:181], v[206:209], v[100:103]
	v_mfma_f32_16x16x32_bf16 v[84:87], v[178:181], v[214:217], v[84:87]
	v_mfma_f32_16x16x32_bf16 v[84:87], v[186:189], v[218:221], v[84:87]
	v_mfma_f32_16x16x32_bf16 v[68:71], v[186:189], v[226:229], v[68:71]
	v_mfma_f32_16x16x32_bf16 v[68:71], v[178:181], v[222:225], v[68:71]
	v_mfma_f32_16x16x32_bf16 v[64:67], v[190:193], v[222:225], v[64:67]
	v_mfma_f32_16x16x32_bf16 v[64:67], v[194:197], v[226:229], v[64:67]
	v_mfma_f32_16x16x32_bf16 v[76:79], v[194:197], v[218:221], v[76:79]
	v_mfma_f32_16x16x32_bf16 v[76:79], v[190:193], v[214:217], v[76:79]
	v_mfma_f32_16x16x32_bf16 v[92:95], v[190:193], v[206:209], v[92:95]
	v_mfma_f32_16x16x32_bf16 v[92:95], v[194:197], v[210:213], v[92:95]
	v_mfma_f32_16x16x32_bf16 v[108:111], v[194:197], v[202:205], v[108:111]
	v_mfma_f32_16x16x32_bf16 v[108:111], v[190:193], v[198:201], v[108:111]
	s_setprio 0
	s_barrier
	s_add_i32 s58, s86, s63
	v_lshl_add_u64 v[182:183], v[182:183], 0, s[22:23]
	s_mov_b32 m0, s58
	ds_read_b128 v[198:201], v154 offset:49152
	v_xor_b32_e32 v253, 64, v154
	ds_read_b128 v[202:205], v253 offset:49152
	ds_read_b128 v[206:209], v154 offset:51200
	ds_read_b128 v[210:213], v253 offset:51200
	ds_read_b128 v[214:217], v154 offset:53248
	ds_read_b128 v[218:221], v253 offset:53248
	ds_read_b128 v[222:225], v154 offset:55296
	ds_read_b128 v[226:229], v253 offset:55296
	global_load_lds_dwordx4 v[182:183], off
	s_add_i32 m0, s58, 0x2000
	s_add_u32 s56, s56, 0x40080
	v_lshl_add_u64 v[182:183], v[230:231], 0, s[22:23]
	s_addc_u32 s57, s57, 0
	s_add_i32 s58, s87, s63
	global_load_lds_dwordx4 v[182:183], off
	v_lshl_add_u64 v[182:183], s[56:57], 0, v[130:131]
	s_mov_b32 m0, s58
	s_nop 0
	global_load_lds_dwordx4 v[182:183], off
	v_lshl_add_u64 v[182:183], s[56:57], 0, v[134:135]
	s_add_i32 m0, s58, 0x2000
	s_nop 0
	global_load_lds_dwordx4 v[182:183], off
	v_lshl_add_u64 v[182:183], v[232:233], 0, s[22:23]
	s_mov_b32 m0, s69
	s_nop 0
	global_load_lds_dwordx4 v[182:183], off
	v_lshl_add_u64 v[182:183], v[234:235], 0, s[22:23]
	s_mov_b32 m0, s70
	s_nop 0
	global_load_lds_dwordx4 v[182:183], off
	s_waitcnt vmcnt(8)
	s_waitcnt lgkmcnt(0)
	s_barrier
	s_setprio 1
	s_waitcnt lgkmcnt(0)
	v_mfma_f32_16x16x32_bf16 v[60:63], v[162:165], v[198:201], v[60:63]
	v_mfma_f32_16x16x32_bf16 v[60:63], v[166:169], v[202:205], v[60:63]
	v_mfma_f32_16x16x32_bf16 v[48:51], v[166:169], v[210:213], v[48:51]
	v_mfma_f32_16x16x32_bf16 v[48:51], v[162:165], v[206:209], v[48:51]
	v_mfma_f32_16x16x32_bf16 v[32:35], v[162:165], v[214:217], v[32:35]
	v_mfma_f32_16x16x32_bf16 v[32:35], v[166:169], v[218:221], v[32:35]
	v_mfma_f32_16x16x32_bf16 v[16:19], v[166:169], v[226:229], v[16:19]
	v_mfma_f32_16x16x32_bf16 v[16:19], v[162:165], v[222:225], v[16:19]
	v_mfma_f32_16x16x32_bf16 v[8:11], v[170:173], v[222:225], v[8:11]
	v_mfma_f32_16x16x32_bf16 v[8:11], v[174:177], v[226:229], v[8:11]
	v_mfma_f32_16x16x32_bf16 v[24:27], v[174:177], v[218:221], v[24:27]
	v_mfma_f32_16x16x32_bf16 v[24:27], v[170:173], v[214:217], v[24:27]
	v_mfma_f32_16x16x32_bf16 v[40:43], v[170:173], v[206:209], v[40:43]
	v_mfma_f32_16x16x32_bf16 v[40:43], v[174:177], v[210:213], v[40:43]
	v_mfma_f32_16x16x32_bf16 v[56:59], v[174:177], v[202:205], v[56:59]
	v_mfma_f32_16x16x32_bf16 v[56:59], v[170:173], v[198:201], v[56:59]
	s_setprio 0
	s_setprio 1
	v_mfma_f32_16x16x32_bf16 v[52:55], v[178:181], v[198:201], v[52:55]
	v_mfma_f32_16x16x32_bf16 v[52:55], v[186:189], v[202:205], v[52:55]
	v_mfma_f32_16x16x32_bf16 v[36:39], v[186:189], v[210:213], v[36:39]
	v_mfma_f32_16x16x32_bf16 v[36:39], v[178:181], v[206:209], v[36:39]
	v_mfma_f32_16x16x32_bf16 v[20:23], v[178:181], v[214:217], v[20:23]
	v_mfma_f32_16x16x32_bf16 v[20:23], v[186:189], v[218:221], v[20:23]
	v_mfma_f32_16x16x32_bf16 v[4:7], v[186:189], v[226:229], v[4:7]
	v_mfma_f32_16x16x32_bf16 v[4:7], v[178:181], v[222:225], v[4:7]
	v_mfma_f32_16x16x32_bf16 v[0:3], v[190:193], v[222:225], v[0:3]
	v_mfma_f32_16x16x32_bf16 v[0:3], v[194:197], v[226:229], v[0:3]
	v_mfma_f32_16x16x32_bf16 v[12:15], v[194:197], v[218:221], v[12:15]
	v_mfma_f32_16x16x32_bf16 v[12:15], v[190:193], v[214:217], v[12:15]
	v_mfma_f32_16x16x32_bf16 v[28:31], v[190:193], v[206:209], v[28:31]
	v_mfma_f32_16x16x32_bf16 v[28:31], v[194:197], v[210:213], v[28:31]
	v_mfma_f32_16x16x32_bf16 v[44:47], v[194:197], v[202:205], v[44:47]
	v_mfma_f32_16x16x32_bf16 v[44:47], v[190:193], v[198:201], v[44:47]
	s_setprio 0
	s_barrier
	s_add_i32 s85, s85, 2
	s_add_u32 s83, s83, 0x100
	s_addc_u32 s84, s84, 0
	s_add_u32 s54, s54, 0x100
	s_addc_u32 s55, s55, 0
	s_branch .LBB0_875
.LBB0_874:
	v_add_u32_e32 v146, s73, v149
	ds_read_b128 v[162:165], v146
	v_xor_b32_e32 v253, 64, v146
	ds_read_b128 v[166:169], v253
	ds_read_b128 v[170:173], v146 offset:2048
	ds_read_b128 v[174:177], v253 offset:2048
	v_add_u32_e32 v146, s74, v149
	ds_read_b128 v[178:181], v146
	v_xor_b32_e32 v253, 64, v146
	ds_read_b128 v[186:189], v253
	ds_read_b128 v[190:193], v146 offset:2048
	ds_read_b128 v[194:197], v253 offset:2048
	s_add_u32 s58, s54, 0xfffc0080
	s_addc_u32 s59, s55, -1
	s_and_b64 s[56:57], s[56:57], exec
	s_cselect_b32 s59, s49, s59
	s_cselect_b32 s58, s80, s58
	s_cselect_b32 s57, s81, s84
	s_cselect_b32 s56, s82, s83
	v_lshl_add_u64 v[182:183], s[54:55], 0, v[138:139]
	s_add_i32 m0, s64, 0xc000
	ds_read_b128 v[198:201], v154
	v_xor_b32_e32 v253, 64, v154
	ds_read_b128 v[202:205], v253
	ds_read_b128 v[206:209], v154 offset:2048
	ds_read_b128 v[210:213], v253 offset:2048
	ds_read_b128 v[214:217], v154 offset:4096
	ds_read_b128 v[218:221], v253 offset:4096
	ds_read_b128 v[222:225], v154 offset:6144
	ds_read_b128 v[226:229], v253 offset:6144
	global_load_lds_dwordx4 v[182:183], off
	v_lshl_add_u64 v[182:183], s[54:55], 0, v[136:137]
	s_add_i32 m0, s64, 0xe000
	s_nop 0
	global_load_lds_dwordx4 v[182:183], off
	s_waitcnt vmcnt(8)
	s_waitcnt lgkmcnt(0)
	s_barrier
	s_setprio 1
	s_waitcnt lgkmcnt(0)
	v_mfma_f32_16x16x32_bf16 v[124:127], v[162:165], v[198:201], v[124:127]
	v_mfma_f32_16x16x32_bf16 v[124:127], v[166:169], v[202:205], v[124:127]
	v_mfma_f32_16x16x32_bf16 v[112:115], v[166:169], v[210:213], v[112:115]
	v_mfma_f32_16x16x32_bf16 v[112:115], v[162:165], v[206:209], v[112:115]
	v_mfma_f32_16x16x32_bf16 v[96:99], v[162:165], v[214:217], v[96:99]
	v_mfma_f32_16x16x32_bf16 v[96:99], v[166:169], v[218:221], v[96:99]
	v_mfma_f32_16x16x32_bf16 v[80:83], v[166:169], v[226:229], v[80:83]
	v_mfma_f32_16x16x32_bf16 v[80:83], v[162:165], v[222:225], v[80:83]
	v_mfma_f32_16x16x32_bf16 v[72:75], v[170:173], v[222:225], v[72:75]
	v_mfma_f32_16x16x32_bf16 v[72:75], v[174:177], v[226:229], v[72:75]
	v_mfma_f32_16x16x32_bf16 v[88:91], v[174:177], v[218:221], v[88:91]
	v_mfma_f32_16x16x32_bf16 v[88:91], v[170:173], v[214:217], v[88:91]
	v_mfma_f32_16x16x32_bf16 v[104:107], v[170:173], v[206:209], v[104:107]
	v_mfma_f32_16x16x32_bf16 v[104:107], v[174:177], v[210:213], v[104:107]
	v_mfma_f32_16x16x32_bf16 v[120:123], v[174:177], v[202:205], v[120:123]
	v_mfma_f32_16x16x32_bf16 v[120:123], v[170:173], v[198:201], v[120:123]
	s_setprio 0
	s_setprio 1
	v_mfma_f32_16x16x32_bf16 v[116:119], v[178:181], v[198:201], v[116:119]
	v_mfma_f32_16x16x32_bf16 v[116:119], v[186:189], v[202:205], v[116:119]
	v_mfma_f32_16x16x32_bf16 v[100:103], v[186:189], v[210:213], v[100:103]
	v_mfma_f32_16x16x32_bf16 v[100:103], v[178:181], v[206:209], v[100:103]
	v_mfma_f32_16x16x32_bf16 v[84:87], v[178:181], v[214:217], v[84:87]
	v_mfma_f32_16x16x32_bf16 v[84:87], v[186:189], v[218:221], v[84:87]
	v_mfma_f32_16x16x32_bf16 v[68:71], v[186:189], v[226:229], v[68:71]
	v_mfma_f32_16x16x32_bf16 v[68:71], v[178:181], v[222:225], v[68:71]
	v_mfma_f32_16x16x32_bf16 v[64:67], v[190:193], v[222:225], v[64:67]
	v_mfma_f32_16x16x32_bf16 v[64:67], v[194:197], v[226:229], v[64:67]
	v_mfma_f32_16x16x32_bf16 v[76:79], v[194:197], v[218:221], v[76:79]
	v_mfma_f32_16x16x32_bf16 v[76:79], v[190:193], v[214:217], v[76:79]
	v_mfma_f32_16x16x32_bf16 v[92:95], v[190:193], v[206:209], v[92:95]
	v_mfma_f32_16x16x32_bf16 v[92:95], v[194:197], v[210:213], v[92:95]
	v_mfma_f32_16x16x32_bf16 v[108:111], v[194:197], v[202:205], v[108:111]
	v_mfma_f32_16x16x32_bf16 v[108:111], v[190:193], v[198:201], v[108:111]
	s_setprio 0
	s_barrier
	s_add_i32 s86, s73, s63
	v_lshl_add_u64 v[182:183], s[56:57], 0, v[130:131]
	s_mov_b32 m0, s86
	ds_read_b128 v[198:201], v154 offset:16384
	v_xor_b32_e32 v253, 64, v154
	ds_read_b128 v[202:205], v253 offset:16384
	ds_read_b128 v[206:209], v154 offset:18432
	ds_read_b128 v[210:213], v253 offset:18432
	ds_read_b128 v[214:217], v154 offset:20480
	ds_read_b128 v[218:221], v253 offset:20480
	ds_read_b128 v[222:225], v154 offset:22528
	ds_read_b128 v[226:229], v253 offset:22528
	global_load_lds_dwordx4 v[182:183], off
	s_add_i32 m0, s86, 0x2000
	s_add_u32 s86, s56, 0x40000
	v_lshl_add_u64 v[230:231], s[56:57], 0, v[134:135]
	s_addc_u32 s87, s57, 0
	s_add_i32 s88, s74, s63
	global_load_lds_dwordx4 v[230:231], off
	v_lshl_add_u64 v[232:233], s[86:87], 0, v[130:131]
	s_mov_b32 m0, s88
	v_lshl_add_u64 v[234:235], s[58:59], 0, v[132:133]
	global_load_lds_dwordx4 v[232:233], off
	v_lshl_add_u64 v[232:233], s[86:87], 0, v[134:135]
	s_add_i32 m0, s88, 0x2000
	s_nop 0
	global_load_lds_dwordx4 v[232:233], off
	v_lshl_add_u64 v[232:233], s[58:59], 0, v[128:129]
	s_mov_b32 m0, s64
	s_nop 0
	global_load_lds_dwordx4 v[232:233], off
	s_mov_b32 m0, s65
	s_nop 0
	global_load_lds_dwordx4 v[234:235], off
	s_waitcnt vmcnt(8)
	s_waitcnt lgkmcnt(0)
	s_barrier
	s_setprio 1
	s_waitcnt lgkmcnt(0)
	v_mfma_f32_16x16x32_bf16 v[60:63], v[162:165], v[198:201], v[60:63]
	v_mfma_f32_16x16x32_bf16 v[60:63], v[166:169], v[202:205], v[60:63]
	v_mfma_f32_16x16x32_bf16 v[48:51], v[166:169], v[210:213], v[48:51]
	v_mfma_f32_16x16x32_bf16 v[48:51], v[162:165], v[206:209], v[48:51]
	v_mfma_f32_16x16x32_bf16 v[32:35], v[162:165], v[214:217], v[32:35]
	v_mfma_f32_16x16x32_bf16 v[32:35], v[166:169], v[218:221], v[32:35]
	v_mfma_f32_16x16x32_bf16 v[16:19], v[166:169], v[226:229], v[16:19]
	v_mfma_f32_16x16x32_bf16 v[16:19], v[162:165], v[222:225], v[16:19]
	v_mfma_f32_16x16x32_bf16 v[8:11], v[170:173], v[222:225], v[8:11]
	v_mfma_f32_16x16x32_bf16 v[8:11], v[174:177], v[226:229], v[8:11]
	v_mfma_f32_16x16x32_bf16 v[24:27], v[174:177], v[218:221], v[24:27]
	v_mfma_f32_16x16x32_bf16 v[24:27], v[170:173], v[214:217], v[24:27]
	v_mfma_f32_16x16x32_bf16 v[40:43], v[170:173], v[206:209], v[40:43]
	v_mfma_f32_16x16x32_bf16 v[40:43], v[174:177], v[210:213], v[40:43]
	v_mfma_f32_16x16x32_bf16 v[56:59], v[174:177], v[202:205], v[56:59]
	v_mfma_f32_16x16x32_bf16 v[56:59], v[170:173], v[198:201], v[56:59]
	s_setprio 0
	s_setprio 1
	v_mfma_f32_16x16x32_bf16 v[52:55], v[178:181], v[198:201], v[52:55]
	v_mfma_f32_16x16x32_bf16 v[52:55], v[186:189], v[202:205], v[52:55]
	v_mfma_f32_16x16x32_bf16 v[36:39], v[186:189], v[210:213], v[36:39]
	v_mfma_f32_16x16x32_bf16 v[36:39], v[178:181], v[206:209], v[36:39]
	v_mfma_f32_16x16x32_bf16 v[20:23], v[178:181], v[214:217], v[20:23]
	v_mfma_f32_16x16x32_bf16 v[20:23], v[186:189], v[218:221], v[20:23]
	v_mfma_f32_16x16x32_bf16 v[4:7], v[186:189], v[226:229], v[4:7]
	v_mfma_f32_16x16x32_bf16 v[4:7], v[178:181], v[222:225], v[4:7]
	v_mfma_f32_16x16x32_bf16 v[0:3], v[190:193], v[222:225], v[0:3]
	v_mfma_f32_16x16x32_bf16 v[0:3], v[194:197], v[226:229], v[0:3]
	v_mfma_f32_16x16x32_bf16 v[12:15], v[194:197], v[218:221], v[12:15]
	v_mfma_f32_16x16x32_bf16 v[12:15], v[190:193], v[214:217], v[12:15]
	v_mfma_f32_16x16x32_bf16 v[28:31], v[190:193], v[206:209], v[28:31]
	v_mfma_f32_16x16x32_bf16 v[28:31], v[194:197], v[210:213], v[28:31]
	v_mfma_f32_16x16x32_bf16 v[44:47], v[194:197], v[202:205], v[44:47]
	v_mfma_f32_16x16x32_bf16 v[44:47], v[190:193], v[198:201], v[44:47]
	s_setprio 0
	s_barrier
	s_add_i32 s86, 0, 0x18000
	v_add_u32_e32 v146, s86, v149
	s_add_i32 s87, 0, 0x1c000
	ds_read_b128 v[162:165], v146
	v_xor_b32_e32 v253, 64, v146
	ds_read_b128 v[166:169], v253
	ds_read_b128 v[170:173], v146 offset:2048
	ds_read_b128 v[174:177], v253 offset:2048
	v_add_u32_e32 v146, s87, v149
	ds_read_b128 v[178:181], v146
	v_xor_b32_e32 v253, 64, v146
	ds_read_b128 v[186:189], v253
	ds_read_b128 v[190:193], v146 offset:2048
	ds_read_b128 v[194:197], v253 offset:2048
	s_add_u32 s58, s58, 0x40000
	s_addc_u32 s59, s59, 0
	s_mov_b32 m0, s66
	v_lshl_add_u64 v[236:237], s[58:59], 0, v[128:129]
	ds_read_b128 v[198:201], v154 offset:32768
	v_xor_b32_e32 v253, 64, v154
	ds_read_b128 v[202:205], v253 offset:32768
	ds_read_b128 v[206:209], v154 offset:34816
	ds_read_b128 v[210:213], v253 offset:34816
	ds_read_b128 v[214:217], v154 offset:36864
	ds_read_b128 v[218:221], v253 offset:36864
	ds_read_b128 v[222:225], v154 offset:38912
	ds_read_b128 v[226:229], v253 offset:38912
	global_load_lds_dwordx4 v[236:237], off
	v_lshl_add_u64 v[236:237], s[58:59], 0, v[132:133]
	s_mov_b32 m0, s67
	s_nop 0
	global_load_lds_dwordx4 v[236:237], off
	s_waitcnt vmcnt(8)
	s_waitcnt lgkmcnt(0)
	s_barrier
	s_setprio 1
	s_waitcnt lgkmcnt(0)
	v_mfma_f32_16x16x32_bf16 v[124:127], v[162:165], v[198:201], v[124:127]
	v_mfma_f32_16x16x32_bf16 v[124:127], v[166:169], v[202:205], v[124:127]
	v_mfma_f32_16x16x32_bf16 v[112:115], v[166:169], v[210:213], v[112:115]
	v_mfma_f32_16x16x32_bf16 v[112:115], v[162:165], v[206:209], v[112:115]
	v_mfma_f32_16x16x32_bf16 v[96:99], v[162:165], v[214:217], v[96:99]
	v_mfma_f32_16x16x32_bf16 v[96:99], v[166:169], v[218:221], v[96:99]
	v_mfma_f32_16x16x32_bf16 v[80:83], v[166:169], v[226:229], v[80:83]
	v_mfma_f32_16x16x32_bf16 v[80:83], v[162:165], v[222:225], v[80:83]
	v_mfma_f32_16x16x32_bf16 v[72:75], v[170:173], v[222:225], v[72:75]
	v_mfma_f32_16x16x32_bf16 v[72:75], v[174:177], v[226:229], v[72:75]
	v_mfma_f32_16x16x32_bf16 v[88:91], v[174:177], v[218:221], v[88:91]
	v_mfma_f32_16x16x32_bf16 v[88:91], v[170:173], v[214:217], v[88:91]
	v_mfma_f32_16x16x32_bf16 v[104:107], v[170:173], v[206:209], v[104:107]
	v_mfma_f32_16x16x32_bf16 v[104:107], v[174:177], v[210:213], v[104:107]
	v_mfma_f32_16x16x32_bf16 v[120:123], v[174:177], v[202:205], v[120:123]
	v_mfma_f32_16x16x32_bf16 v[120:123], v[170:173], v[198:201], v[120:123]
	s_setprio 0
	s_setprio 1
	v_mfma_f32_16x16x32_bf16 v[116:119], v[178:181], v[198:201], v[116:119]
	v_mfma_f32_16x16x32_bf16 v[116:119], v[186:189], v[202:205], v[116:119]
	v_mfma_f32_16x16x32_bf16 v[100:103], v[186:189], v[210:213], v[100:103]
	v_mfma_f32_16x16x32_bf16 v[100:103], v[178:181], v[206:209], v[100:103]
	v_mfma_f32_16x16x32_bf16 v[84:87], v[178:181], v[214:217], v[84:87]
	v_mfma_f32_16x16x32_bf16 v[84:87], v[186:189], v[218:221], v[84:87]
	v_mfma_f32_16x16x32_bf16 v[68:71], v[186:189], v[226:229], v[68:71]
	v_mfma_f32_16x16x32_bf16 v[68:71], v[178:181], v[222:225], v[68:71]
	v_mfma_f32_16x16x32_bf16 v[64:67], v[190:193], v[222:225], v[64:67]
	v_mfma_f32_16x16x32_bf16 v[64:67], v[194:197], v[226:229], v[64:67]
	v_mfma_f32_16x16x32_bf16 v[76:79], v[194:197], v[218:221], v[76:79]
	v_mfma_f32_16x16x32_bf16 v[76:79], v[190:193], v[214:217], v[76:79]
	v_mfma_f32_16x16x32_bf16 v[92:95], v[190:193], v[206:209], v[92:95]
	v_mfma_f32_16x16x32_bf16 v[92:95], v[194:197], v[210:213], v[92:95]
	v_mfma_f32_16x16x32_bf16 v[108:111], v[194:197], v[202:205], v[108:111]
	v_mfma_f32_16x16x32_bf16 v[108:111], v[190:193], v[198:201], v[108:111]
	s_setprio 0
	s_barrier
	s_add_i32 s58, s86, s63
	v_lshl_add_u64 v[182:183], v[182:183], 0, s[22:23]
	s_mov_b32 m0, s58
	ds_read_b128 v[198:201], v154 offset:49152
	v_xor_b32_e32 v253, 64, v154
	ds_read_b128 v[202:205], v253 offset:49152
	ds_read_b128 v[206:209], v154 offset:51200
	ds_read_b128 v[210:213], v253 offset:51200
	ds_read_b128 v[214:217], v154 offset:53248
	ds_read_b128 v[218:221], v253 offset:53248
	ds_read_b128 v[222:225], v154 offset:55296
	ds_read_b128 v[226:229], v253 offset:55296
	global_load_lds_dwordx4 v[182:183], off
	s_add_i32 m0, s58, 0x2000
	s_add_u32 s56, s56, 0x40080
	v_lshl_add_u64 v[182:183], v[230:231], 0, s[22:23]
	s_addc_u32 s57, s57, 0
	s_add_i32 s58, s87, s63
	global_load_lds_dwordx4 v[182:183], off
	v_lshl_add_u64 v[182:183], s[56:57], 0, v[130:131]
	s_mov_b32 m0, s58
	s_nop 0
	global_load_lds_dwordx4 v[182:183], off
	v_lshl_add_u64 v[182:183], s[56:57], 0, v[134:135]
	s_add_i32 m0, s58, 0x2000
	s_nop 0
	global_load_lds_dwordx4 v[182:183], off
	v_lshl_add_u64 v[182:183], v[232:233], 0, s[22:23]
	s_mov_b32 m0, s69
	s_nop 0
	global_load_lds_dwordx4 v[182:183], off
	v_lshl_add_u64 v[182:183], v[234:235], 0, s[22:23]
	s_mov_b32 m0, s70
	s_nop 0
	global_load_lds_dwordx4 v[182:183], off
	s_waitcnt vmcnt(8)
	s_waitcnt lgkmcnt(0)
	s_barrier
	s_setprio 1
	s_waitcnt lgkmcnt(0)
	v_mfma_f32_16x16x32_bf16 v[60:63], v[162:165], v[198:201], v[60:63]
	v_mfma_f32_16x16x32_bf16 v[60:63], v[166:169], v[202:205], v[60:63]
	v_mfma_f32_16x16x32_bf16 v[48:51], v[166:169], v[210:213], v[48:51]
	v_mfma_f32_16x16x32_bf16 v[48:51], v[162:165], v[206:209], v[48:51]
	v_mfma_f32_16x16x32_bf16 v[32:35], v[162:165], v[214:217], v[32:35]
	v_mfma_f32_16x16x32_bf16 v[32:35], v[166:169], v[218:221], v[32:35]
	v_mfma_f32_16x16x32_bf16 v[16:19], v[166:169], v[226:229], v[16:19]
	v_mfma_f32_16x16x32_bf16 v[16:19], v[162:165], v[222:225], v[16:19]
	v_mfma_f32_16x16x32_bf16 v[8:11], v[170:173], v[222:225], v[8:11]
	v_mfma_f32_16x16x32_bf16 v[8:11], v[174:177], v[226:229], v[8:11]
	v_mfma_f32_16x16x32_bf16 v[24:27], v[174:177], v[218:221], v[24:27]
	v_mfma_f32_16x16x32_bf16 v[24:27], v[170:173], v[214:217], v[24:27]
	v_mfma_f32_16x16x32_bf16 v[40:43], v[170:173], v[206:209], v[40:43]
	v_mfma_f32_16x16x32_bf16 v[40:43], v[174:177], v[210:213], v[40:43]
	v_mfma_f32_16x16x32_bf16 v[56:59], v[174:177], v[202:205], v[56:59]
	v_mfma_f32_16x16x32_bf16 v[56:59], v[170:173], v[198:201], v[56:59]
	s_setprio 0
	s_setprio 1
	v_mfma_f32_16x16x32_bf16 v[52:55], v[178:181], v[198:201], v[52:55]
	v_mfma_f32_16x16x32_bf16 v[52:55], v[186:189], v[202:205], v[52:55]
	v_mfma_f32_16x16x32_bf16 v[36:39], v[186:189], v[210:213], v[36:39]
	v_mfma_f32_16x16x32_bf16 v[36:39], v[178:181], v[206:209], v[36:39]
	v_mfma_f32_16x16x32_bf16 v[20:23], v[178:181], v[214:217], v[20:23]
	v_mfma_f32_16x16x32_bf16 v[20:23], v[186:189], v[218:221], v[20:23]
	v_mfma_f32_16x16x32_bf16 v[4:7], v[186:189], v[226:229], v[4:7]
	v_mfma_f32_16x16x32_bf16 v[4:7], v[178:181], v[222:225], v[4:7]
	v_mfma_f32_16x16x32_bf16 v[0:3], v[190:193], v[222:225], v[0:3]
	v_mfma_f32_16x16x32_bf16 v[0:3], v[194:197], v[226:229], v[0:3]
	v_mfma_f32_16x16x32_bf16 v[12:15], v[194:197], v[218:221], v[12:15]
	v_mfma_f32_16x16x32_bf16 v[12:15], v[190:193], v[214:217], v[12:15]
	v_mfma_f32_16x16x32_bf16 v[28:31], v[190:193], v[206:209], v[28:31]
	v_mfma_f32_16x16x32_bf16 v[28:31], v[194:197], v[210:213], v[28:31]
	v_mfma_f32_16x16x32_bf16 v[44:47], v[194:197], v[202:205], v[44:47]
	v_mfma_f32_16x16x32_bf16 v[44:47], v[190:193], v[198:201], v[44:47]
	s_setprio 0
	s_barrier
	s_add_i32 s85, s85, 2
	s_add_u32 s83, s83, 0x100
	s_addc_u32 s84, s84, 0
	s_add_u32 s54, s54, 0x100
	s_addc_u32 s55, s55, 0
	s_cmp_gt_u32 s85, 13
	s_cbranch_scc1 .LBB0_877

.LBB0_1010:
	s_ashr_i32 s51, s50, 31
	s_lshl_b64 s[52:53], s[50:51], 19
	s_add_u32 s52, s33, s52
	s_addc_u32 s53, s35, s53
	s_and_b64 s[54:55], s[12:13], exec
	s_cselect_b32 s15, s53, s61
	s_cselect_b32 s51, s52, s60
	s_ashr_i32 s49, s48, 31
	s_lshl_b64 s[54:55], s[48:49], 19
	s_add_u32 s54, s64, s54
	s_addc_u32 s55, s65, s55
	s_and_b64 s[62:63], s[12:13], exec
	s_cselect_b32 s49, s55, s59
	s_cselect_b32 s57, s54, s58
	s_add_u32 s78, s58, 0x100
	s_addc_u32 s79, s59, 0
	s_add_u32 s58, s60, 0x40080
	s_addc_u32 s59, s61, 0
	s_mov_b32 s80, -2
	s_waitcnt lgkmcnt(0)
	s_cmp_eq_u32 s71, 1
	s_cbranch_scc1 .Lfa_9
	ds_read_b128 v[128:131], v188
	v_xor_b32_e32 v253, 64, v188
	ds_read_b128 v[132:135], v253
	ds_read_b128 v[136:139], v188 offset:2048
	ds_read_b128 v[140:143], v253 offset:2048
	ds_read_b128 v[144:147], v189
	v_xor_b32_e32 v253, 64, v189
	ds_read_b128 v[148:151], v253
	ds_read_b128 v[172:175], v189 offset:2048
	ds_read_b128 v[176:179], v253 offset:2048
	s_add_u32 s60, s58, 0xfffc0080
	s_addc_u32 s61, s59, -1
	s_cmp_eq_u32 s80, 12
	s_cselect_b32 s63, s15, s61
	s_cselect_b32 s62, s51, s60
	s_cselect_b32 s61, s49, s79
	s_cselect_b32 s60, s57, s78
	v_lshl_add_u64 v[220:221], s[58:59], 0, v[166:167]
	s_add_i32 m0, s67, 0xc000
	ds_read_b128 v[180:183], v190
	v_xor_b32_e32 v253, 64, v190
	ds_read_b128 v[192:195], v253
	ds_read_b128 v[196:199], v190 offset:2048
	ds_read_b128 v[200:203], v253 offset:2048
	ds_read_b128 v[204:207], v190 offset:4096
	ds_read_b128 v[208:211], v253 offset:4096
	ds_read_b128 v[212:215], v190 offset:6144
	ds_read_b128 v[216:219], v253 offset:6144
	global_load_lds_dwordx4 v[220:221], off
	v_lshl_add_u64 v[220:221], s[58:59], 0, v[164:165]
	s_add_i32 m0, s67, 0xe000
	s_nop 0
	global_load_lds_dwordx4 v[220:221], off
	s_waitcnt vmcnt(24)
	s_waitcnt lgkmcnt(0)
	s_barrier
	s_setprio 1
	s_waitcnt lgkmcnt(0)
	v_mfma_f32_16x16x32_bf16 v[124:127], v[128:131], v[180:183], 0
	v_mfma_f32_16x16x32_bf16 v[120:123], v[136:139], v[180:183], 0
	v_mfma_f32_16x16x32_bf16 v[108:111], v[128:131], v[196:199], 0
	v_mfma_f32_16x16x32_bf16 v[104:107], v[136:139], v[196:199], 0
	v_mfma_f32_16x16x32_bf16 v[92:95], v[128:131], v[204:207], 0
	v_mfma_f32_16x16x32_bf16 v[88:91], v[136:139], v[204:207], 0
	v_mfma_f32_16x16x32_bf16 v[76:79], v[128:131], v[212:215], 0
	v_mfma_f32_16x16x32_bf16 v[72:75], v[136:139], v[212:215], 0
	v_mfma_f32_16x16x32_bf16 v[124:127], v[132:135], v[192:195], v[124:127]
	v_mfma_f32_16x16x32_bf16 v[120:123], v[140:143], v[192:195], v[120:123]
	v_mfma_f32_16x16x32_bf16 v[108:111], v[132:135], v[200:203], v[108:111]
	v_mfma_f32_16x16x32_bf16 v[104:107], v[140:143], v[200:203], v[104:107]
	v_mfma_f32_16x16x32_bf16 v[92:95], v[132:135], v[208:211], v[92:95]
	v_mfma_f32_16x16x32_bf16 v[88:91], v[140:143], v[208:211], v[88:91]
	v_mfma_f32_16x16x32_bf16 v[76:79], v[132:135], v[216:219], v[76:79]
	v_mfma_f32_16x16x32_bf16 v[72:75], v[140:143], v[216:219], v[72:75]
	s_setprio 0
	s_setprio 1
	v_mfma_f32_16x16x32_bf16 v[116:119], v[144:147], v[180:183], 0
	v_mfma_f32_16x16x32_bf16 v[112:115], v[172:175], v[180:183], 0
	v_mfma_f32_16x16x32_bf16 v[100:103], v[144:147], v[196:199], 0
	v_mfma_f32_16x16x32_bf16 v[96:99], v[172:175], v[196:199], 0
	v_mfma_f32_16x16x32_bf16 v[84:87], v[144:147], v[204:207], 0
	v_mfma_f32_16x16x32_bf16 v[80:83], v[172:175], v[204:207], 0
	v_mfma_f32_16x16x32_bf16 v[68:71], v[144:147], v[212:215], 0
	v_mfma_f32_16x16x32_bf16 v[64:67], v[172:175], v[212:215], 0
	v_mfma_f32_16x16x32_bf16 v[116:119], v[148:151], v[192:195], v[116:119]
	v_mfma_f32_16x16x32_bf16 v[112:115], v[176:179], v[192:195], v[112:115]
	v_mfma_f32_16x16x32_bf16 v[100:103], v[148:151], v[200:203], v[100:103]
	v_mfma_f32_16x16x32_bf16 v[96:99], v[176:179], v[200:203], v[96:99]
	v_mfma_f32_16x16x32_bf16 v[84:87], v[148:151], v[208:211], v[84:87]
	v_mfma_f32_16x16x32_bf16 v[80:83], v[176:179], v[208:211], v[80:83]
	v_mfma_f32_16x16x32_bf16 v[68:71], v[148:151], v[216:219], v[68:71]
	v_mfma_f32_16x16x32_bf16 v[64:67], v[176:179], v[216:219], v[64:67]
	s_setprio 0
	s_barrier
	s_add_i32 s81, s76, s66
	v_lshl_add_u64 v[220:221], s[60:61], 0, v[154:155]
	s_mov_b32 m0, s81
	ds_read_b128 v[180:183], v190 offset:16384
	v_xor_b32_e32 v253, 64, v190
	ds_read_b128 v[192:195], v253 offset:16384
	ds_read_b128 v[196:199], v190 offset:18432
	ds_read_b128 v[200:203], v253 offset:18432
	ds_read_b128 v[204:207], v190 offset:20480
	ds_read_b128 v[208:211], v253 offset:20480
	ds_read_b128 v[212:215], v190 offset:22528
	ds_read_b128 v[216:219], v253 offset:22528
	global_load_lds_dwordx4 v[220:221], off
	s_add_i32 m0, s81, 0x2000
	s_add_u32 s82, s60, 0x40000
	v_lshl_add_u64 v[222:223], s[60:61], 0, v[162:163]
	s_addc_u32 s83, s61, 0
	s_add_i32 s81, s77, s66
	global_load_lds_dwordx4 v[222:223], off
	v_lshl_add_u64 v[224:225], s[82:83], 0, v[154:155]
	s_mov_b32 m0, s81
	v_lshl_add_u64 v[226:227], s[62:63], 0, v[160:161]
	global_load_lds_dwordx4 v[224:225], off
	v_lshl_add_u64 v[224:225], s[82:83], 0, v[162:163]
	s_add_i32 m0, s81, 0x2000
	s_nop 0
	global_load_lds_dwordx4 v[224:225], off
	v_lshl_add_u64 v[224:225], s[62:63], 0, v[152:153]
	s_mov_b32 m0, s67
	s_nop 0
	global_load_lds_dwordx4 v[224:225], off
	s_mov_b32 m0, s68
	s_nop 0
	global_load_lds_dwordx4 v[226:227], off
	s_waitcnt vmcnt(24)
	s_waitcnt lgkmcnt(0)
	s_barrier
	s_setprio 1
	s_waitcnt lgkmcnt(0)
	v_mfma_f32_16x16x32_bf16 v[60:63], v[128:131], v[180:183], 0
	v_mfma_f32_16x16x32_bf16 v[56:59], v[136:139], v[180:183], 0
	v_mfma_f32_16x16x32_bf16 v[44:47], v[128:131], v[196:199], 0
	v_mfma_f32_16x16x32_bf16 v[40:43], v[136:139], v[196:199], 0
	v_mfma_f32_16x16x32_bf16 v[28:31], v[128:131], v[204:207], 0
	v_mfma_f32_16x16x32_bf16 v[24:27], v[136:139], v[204:207], 0
	v_mfma_f32_16x16x32_bf16 v[12:15], v[128:131], v[212:215], 0
	v_mfma_f32_16x16x32_bf16 v[8:11], v[136:139], v[212:215], 0
	v_mfma_f32_16x16x32_bf16 v[60:63], v[132:135], v[192:195], v[60:63]
	v_mfma_f32_16x16x32_bf16 v[56:59], v[140:143], v[192:195], v[56:59]
	v_mfma_f32_16x16x32_bf16 v[44:47], v[132:135], v[200:203], v[44:47]
	v_mfma_f32_16x16x32_bf16 v[40:43], v[140:143], v[200:203], v[40:43]
	v_mfma_f32_16x16x32_bf16 v[28:31], v[132:135], v[208:211], v[28:31]
	v_mfma_f32_16x16x32_bf16 v[24:27], v[140:143], v[208:211], v[24:27]
	v_mfma_f32_16x16x32_bf16 v[12:15], v[132:135], v[216:219], v[12:15]
	v_mfma_f32_16x16x32_bf16 v[8:11], v[140:143], v[216:219], v[8:11]
	s_setprio 0
	s_setprio 1
	v_mfma_f32_16x16x32_bf16 v[52:55], v[144:147], v[180:183], 0
	v_mfma_f32_16x16x32_bf16 v[48:51], v[172:175], v[180:183], 0
	v_mfma_f32_16x16x32_bf16 v[36:39], v[144:147], v[196:199], 0
	v_mfma_f32_16x16x32_bf16 v[32:35], v[172:175], v[196:199], 0
	v_mfma_f32_16x16x32_bf16 v[20:23], v[144:147], v[204:207], 0
	v_mfma_f32_16x16x32_bf16 v[16:19], v[172:175], v[204:207], 0
	v_mfma_f32_16x16x32_bf16 v[4:7], v[144:147], v[212:215], 0
	v_mfma_f32_16x16x32_bf16 v[0:3], v[172:175], v[212:215], 0
	v_mfma_f32_16x16x32_bf16 v[52:55], v[148:151], v[192:195], v[52:55]
	v_mfma_f32_16x16x32_bf16 v[48:51], v[176:179], v[192:195], v[48:51]
	v_mfma_f32_16x16x32_bf16 v[36:39], v[148:151], v[200:203], v[36:39]
	v_mfma_f32_16x16x32_bf16 v[32:35], v[176:179], v[200:203], v[32:35]
	v_mfma_f32_16x16x32_bf16 v[20:23], v[148:151], v[208:211], v[20:23]
	v_mfma_f32_16x16x32_bf16 v[16:19], v[176:179], v[208:211], v[16:19]
	v_mfma_f32_16x16x32_bf16 v[4:7], v[148:151], v[216:219], v[4:7]
	v_mfma_f32_16x16x32_bf16 v[0:3], v[176:179], v[216:219], v[0:3]
	s_setprio 0
	s_barrier
	s_add_i32 s81, 0, 0x18000
	s_add_i32 s82, 0, 0x1c000
	v_add_u32_e32 v140, s81, v185
	v_add_u32_e32 v176, s82, v185
	ds_read_b128 v[128:131], v140
	v_xor_b32_e32 v253, 64, v140
	ds_read_b128 v[132:135], v253
	ds_read_b128 v[136:139], v140 offset:2048
	ds_read_b128 v[140:143], v253 offset:2048
	ds_read_b128 v[144:147], v176
	v_xor_b32_e32 v253, 64, v176
	ds_read_b128 v[148:151], v253
	ds_read_b128 v[172:175], v176 offset:2048
	ds_read_b128 v[176:179], v253 offset:2048
	s_add_u32 s62, s62, 0x40000
	s_addc_u32 s63, s63, 0
	s_mov_b32 m0, s69
	v_lshl_add_u64 v[228:229], s[62:63], 0, v[152:153]
	ds_read_b128 v[180:183], v190 offset:32768
	v_xor_b32_e32 v253, 64, v190
	ds_read_b128 v[192:195], v253 offset:32768
	ds_read_b128 v[196:199], v190 offset:34816
	ds_read_b128 v[200:203], v253 offset:34816
	ds_read_b128 v[204:207], v190 offset:36864
	ds_read_b128 v[208:211], v253 offset:36864
	ds_read_b128 v[212:215], v190 offset:38912
	ds_read_b128 v[216:219], v253 offset:38912
	global_load_lds_dwordx4 v[228:229], off
	v_lshl_add_u64 v[228:229], s[62:63], 0, v[160:161]
	s_mov_b32 m0, s70
	s_nop 0
	global_load_lds_dwordx4 v[228:229], off
	s_waitcnt vmcnt(8)
	s_waitcnt lgkmcnt(0)
	s_barrier
	s_setprio 1
	s_waitcnt lgkmcnt(0)
	v_mfma_f32_16x16x32_bf16 v[124:127], v[128:131], v[180:183], v[124:127]
	v_mfma_f32_16x16x32_bf16 v[124:127], v[132:135], v[192:195], v[124:127]
	v_mfma_f32_16x16x32_bf16 v[108:111], v[132:135], v[200:203], v[108:111]
	v_mfma_f32_16x16x32_bf16 v[108:111], v[128:131], v[196:199], v[108:111]
	v_mfma_f32_16x16x32_bf16 v[92:95], v[128:131], v[204:207], v[92:95]
	v_mfma_f32_16x16x32_bf16 v[92:95], v[132:135], v[208:211], v[92:95]
	v_mfma_f32_16x16x32_bf16 v[76:79], v[132:135], v[216:219], v[76:79]
	v_mfma_f32_16x16x32_bf16 v[76:79], v[128:131], v[212:215], v[76:79]
	v_mfma_f32_16x16x32_bf16 v[72:75], v[136:139], v[212:215], v[72:75]
	v_mfma_f32_16x16x32_bf16 v[72:75], v[140:143], v[216:219], v[72:75]
	v_mfma_f32_16x16x32_bf16 v[88:91], v[140:143], v[208:211], v[88:91]
	v_mfma_f32_16x16x32_bf16 v[88:91], v[136:139], v[204:207], v[88:91]
	v_mfma_f32_16x16x32_bf16 v[104:107], v[136:139], v[196:199], v[104:107]
	v_mfma_f32_16x16x32_bf16 v[104:107], v[140:143], v[200:203], v[104:107]
	v_mfma_f32_16x16x32_bf16 v[120:123], v[140:143], v[192:195], v[120:123]
	v_mfma_f32_16x16x32_bf16 v[120:123], v[136:139], v[180:183], v[120:123]
	s_setprio 0
	s_setprio 1
	v_mfma_f32_16x16x32_bf16 v[116:119], v[144:147], v[180:183], v[116:119]
	v_mfma_f32_16x16x32_bf16 v[116:119], v[148:151], v[192:195], v[116:119]
	v_mfma_f32_16x16x32_bf16 v[100:103], v[148:151], v[200:203], v[100:103]
	v_mfma_f32_16x16x32_bf16 v[100:103], v[144:147], v[196:199], v[100:103]
	v_mfma_f32_16x16x32_bf16 v[84:87], v[144:147], v[204:207], v[84:87]
	v_mfma_f32_16x16x32_bf16 v[84:87], v[148:151], v[208:211], v[84:87]
	v_mfma_f32_16x16x32_bf16 v[68:71], v[148:151], v[216:219], v[68:71]
	v_mfma_f32_16x16x32_bf16 v[68:71], v[144:147], v[212:215], v[68:71]
	v_mfma_f32_16x16x32_bf16 v[64:67], v[172:175], v[212:215], v[64:67]
	v_mfma_f32_16x16x32_bf16 v[64:67], v[176:179], v[216:219], v[64:67]
	v_mfma_f32_16x16x32_bf16 v[80:83], v[176:179], v[208:211], v[80:83]
	v_mfma_f32_16x16x32_bf16 v[80:83], v[172:175], v[204:207], v[80:83]
	v_mfma_f32_16x16x32_bf16 v[96:99], v[172:175], v[196:199], v[96:99]
	v_mfma_f32_16x16x32_bf16 v[96:99], v[176:179], v[200:203], v[96:99]
	v_mfma_f32_16x16x32_bf16 v[112:115], v[176:179], v[192:195], v[112:115]
	v_mfma_f32_16x16x32_bf16 v[112:115], v[172:175], v[180:183], v[112:115]
	s_setprio 0
	s_barrier
	s_add_i32 s62, s81, s66
	v_lshl_add_u64 v[220:221], v[220:221], 0, s[26:27]
	s_mov_b32 m0, s62
	ds_read_b128 v[180:183], v190 offset:49152
	v_xor_b32_e32 v253, 64, v190
	ds_read_b128 v[192:195], v253 offset:49152
	ds_read_b128 v[196:199], v190 offset:51200
	ds_read_b128 v[200:203], v253 offset:51200
	ds_read_b128 v[204:207], v190 offset:53248
	ds_read_b128 v[208:211], v253 offset:53248
	ds_read_b128 v[212:215], v190 offset:55296
	ds_read_b128 v[216:219], v253 offset:55296
	global_load_lds_dwordx4 v[220:221], off
	s_add_i32 m0, s62, 0x2000
	s_add_u32 s60, s60, 0x40080
	v_lshl_add_u64 v[220:221], v[222:223], 0, s[26:27]
	s_addc_u32 s61, s61, 0
	s_add_i32 s62, s82, s66
	global_load_lds_dwordx4 v[220:221], off
	v_lshl_add_u64 v[220:221], s[60:61], 0, v[154:155]
	s_mov_b32 m0, s62
	s_nop 0
	global_load_lds_dwordx4 v[220:221], off
	v_lshl_add_u64 v[220:221], s[60:61], 0, v[162:163]
	s_add_i32 m0, s62, 0x2000
	s_nop 0
	global_load_lds_dwordx4 v[220:221], off
	v_lshl_add_u64 v[220:221], v[224:225], 0, s[26:27]
	s_mov_b32 m0, s3
	s_nop 0
	global_load_lds_dwordx4 v[220:221], off
	v_lshl_add_u64 v[220:221], v[226:227], 0, s[26:27]
	s_mov_b32 m0, s72
	s_nop 0
	global_load_lds_dwordx4 v[220:221], off
	s_waitcnt vmcnt(8)
	s_waitcnt lgkmcnt(0)
	s_barrier
	s_setprio 1
	s_waitcnt lgkmcnt(0)
	v_mfma_f32_16x16x32_bf16 v[60:63], v[128:131], v[180:183], v[60:63]
	v_mfma_f32_16x16x32_bf16 v[60:63], v[132:135], v[192:195], v[60:63]
	v_mfma_f32_16x16x32_bf16 v[44:47], v[132:135], v[200:203], v[44:47]
	v_mfma_f32_16x16x32_bf16 v[44:47], v[128:131], v[196:199], v[44:47]
	v_mfma_f32_16x16x32_bf16 v[28:31], v[128:131], v[204:207], v[28:31]
	v_mfma_f32_16x16x32_bf16 v[28:31], v[132:135], v[208:211], v[28:31]
	v_mfma_f32_16x16x32_bf16 v[12:15], v[132:135], v[216:219], v[12:15]
	v_mfma_f32_16x16x32_bf16 v[12:15], v[128:131], v[212:215], v[12:15]
	v_mfma_f32_16x16x32_bf16 v[8:11], v[136:139], v[212:215], v[8:11]
	v_mfma_f32_16x16x32_bf16 v[8:11], v[140:143], v[216:219], v[8:11]
	v_mfma_f32_16x16x32_bf16 v[24:27], v[140:143], v[208:211], v[24:27]
	v_mfma_f32_16x16x32_bf16 v[24:27], v[136:139], v[204:207], v[24:27]
	v_mfma_f32_16x16x32_bf16 v[40:43], v[136:139], v[196:199], v[40:43]
	v_mfma_f32_16x16x32_bf16 v[40:43], v[140:143], v[200:203], v[40:43]
	v_mfma_f32_16x16x32_bf16 v[56:59], v[140:143], v[192:195], v[56:59]
	v_mfma_f32_16x16x32_bf16 v[56:59], v[136:139], v[180:183], v[56:59]
	s_setprio 0
	s_setprio 1
	v_mfma_f32_16x16x32_bf16 v[52:55], v[144:147], v[180:183], v[52:55]
	v_mfma_f32_16x16x32_bf16 v[52:55], v[148:151], v[192:195], v[52:55]
	v_mfma_f32_16x16x32_bf16 v[36:39], v[148:151], v[200:203], v[36:39]
	v_mfma_f32_16x16x32_bf16 v[36:39], v[144:147], v[196:199], v[36:39]
	v_mfma_f32_16x16x32_bf16 v[20:23], v[144:147], v[204:207], v[20:23]
	v_mfma_f32_16x16x32_bf16 v[20:23], v[148:151], v[208:211], v[20:23]
	v_mfma_f32_16x16x32_bf16 v[4:7], v[148:151], v[216:219], v[4:7]
	v_mfma_f32_16x16x32_bf16 v[4:7], v[144:147], v[212:215], v[4:7]
	v_mfma_f32_16x16x32_bf16 v[0:3], v[172:175], v[212:215], v[0:3]
	v_mfma_f32_16x16x32_bf16 v[0:3], v[176:179], v[216:219], v[0:3]
	v_mfma_f32_16x16x32_bf16 v[16:19], v[176:179], v[208:211], v[16:19]
	v_mfma_f32_16x16x32_bf16 v[16:19], v[172:175], v[204:207], v[16:19]
	v_mfma_f32_16x16x32_bf16 v[32:35], v[172:175], v[196:199], v[32:35]
	v_mfma_f32_16x16x32_bf16 v[32:35], v[176:179], v[200:203], v[32:35]
	v_mfma_f32_16x16x32_bf16 v[48:51], v[176:179], v[192:195], v[48:51]
	v_mfma_f32_16x16x32_bf16 v[48:51], v[172:175], v[180:183], v[48:51]
	s_setprio 0
	s_barrier
	s_add_i32 s80, s80, 2
	s_add_u32 s78, s78, 0x100
	s_addc_u32 s79, s79, 0
	s_add_u32 s58, s58, 0x100
	s_addc_u32 s59, s59, 0
	s_cmp_gt_u32 s80, 13
	s_branch .LBB0_1011
.Lfa_9:
	ds_read_b128 v[128:131], v188
	v_xor_b32_e32 v253, 64, v188
	ds_read_b128 v[132:135], v253
	ds_read_b128 v[136:139], v188 offset:2048
	ds_read_b128 v[140:143], v253 offset:2048
	ds_read_b128 v[144:147], v189
	v_xor_b32_e32 v253, 64, v189
	ds_read_b128 v[148:151], v253
	ds_read_b128 v[172:175], v189 offset:2048
	ds_read_b128 v[176:179], v253 offset:2048
	s_add_u32 s60, s58, 0xfffc0080
	s_addc_u32 s61, s59, -1
	s_cmp_eq_u32 s80, 12
	s_cselect_b32 s63, s15, s61
	s_cselect_b32 s62, s51, s60
	s_cselect_b32 s61, s49, s79
	s_cselect_b32 s60, s57, s78
	v_lshl_add_u64 v[220:221], s[58:59], 0, v[166:167]
	s_add_i32 m0, s67, 0xc000
	ds_read_b128 v[180:183], v190
	v_xor_b32_e32 v253, 64, v190
	ds_read_b128 v[192:195], v253
	ds_read_b128 v[196:199], v190 offset:2048
	ds_read_b128 v[200:203], v253 offset:2048
	ds_read_b128 v[204:207], v190 offset:4096
	ds_read_b128 v[208:211], v253 offset:4096
	ds_read_b128 v[212:215], v190 offset:6144
	ds_read_b128 v[216:219], v253 offset:6144
	global_load_lds_dwordx4 v[220:221], off
	v_lshl_add_u64 v[220:221], s[58:59], 0, v[164:165]
	s_add_i32 m0, s67, 0xe000
	s_nop 0
	global_load_lds_dwordx4 v[220:221], off
	s_waitcnt vmcnt(8)
	s_waitcnt lgkmcnt(0)
	s_barrier
	s_setprio 1
	s_waitcnt lgkmcnt(0)
	v_mfma_f32_16x16x32_bf16 v[124:127], v[128:131], v[180:183], 0
	v_mfma_f32_16x16x32_bf16 v[120:123], v[136:139], v[180:183], 0
	v_mfma_f32_16x16x32_bf16 v[108:111], v[128:131], v[196:199], 0
	v_mfma_f32_16x16x32_bf16 v[104:107], v[136:139], v[196:199], 0
	v_mfma_f32_16x16x32_bf16 v[92:95], v[128:131], v[204:207], 0
	v_mfma_f32_16x16x32_bf16 v[88:91], v[136:139], v[204:207], 0
	v_mfma_f32_16x16x32_bf16 v[76:79], v[128:131], v[212:215], 0
	v_mfma_f32_16x16x32_bf16 v[72:75], v[136:139], v[212:215], 0
	v_mfma_f32_16x16x32_bf16 v[124:127], v[132:135], v[192:195], v[124:127]
	v_mfma_f32_16x16x32_bf16 v[120:123], v[140:143], v[192:195], v[120:123]
	v_mfma_f32_16x16x32_bf16 v[108:111], v[132:135], v[200:203], v[108:111]
	v_mfma_f32_16x16x32_bf16 v[104:107], v[140:143], v[200:203], v[104:107]
	v_mfma_f32_16x16x32_bf16 v[92:95], v[132:135], v[208:211], v[92:95]
	v_mfma_f32_16x16x32_bf16 v[88:91], v[140:143], v[208:211], v[88:91]
	v_mfma_f32_16x16x32_bf16 v[76:79], v[132:135], v[216:219], v[76:79]
	v_mfma_f32_16x16x32_bf16 v[72:75], v[140:143], v[216:219], v[72:75]
	s_setprio 0
	s_setprio 1
	v_mfma_f32_16x16x32_bf16 v[116:119], v[144:147], v[180:183], 0
	v_mfma_f32_16x16x32_bf16 v[112:115], v[172:175], v[180:183], 0
	v_mfma_f32_16x16x32_bf16 v[100:103], v[144:147], v[196:199], 0
	v_mfma_f32_16x16x32_bf16 v[96:99], v[172:175], v[196:199], 0
	v_mfma_f32_16x16x32_bf16 v[84:87], v[144:147], v[204:207], 0
	v_mfma_f32_16x16x32_bf16 v[80:83], v[172:175], v[204:207], 0
	v_mfma_f32_16x16x32_bf16 v[68:71], v[144:147], v[212:215], 0
	v_mfma_f32_16x16x32_bf16 v[64:67], v[172:175], v[212:215], 0
	v_mfma_f32_16x16x32_bf16 v[116:119], v[148:151], v[192:195], v[116:119]
	v_mfma_f32_16x16x32_bf16 v[112:115], v[176:179], v[192:195], v[112:115]
	v_mfma_f32_16x16x32_bf16 v[100:103], v[148:151], v[200:203], v[100:103]
	v_mfma_f32_16x16x32_bf16 v[96:99], v[176:179], v[200:203], v[96:99]
	v_mfma_f32_16x16x32_bf16 v[84:87], v[148:151], v[208:211], v[84:87]
	v_mfma_f32_16x16x32_bf16 v[80:83], v[176:179], v[208:211], v[80:83]
	v_mfma_f32_16x16x32_bf16 v[68:71], v[148:151], v[216:219], v[68:71]
	v_mfma_f32_16x16x32_bf16 v[64:67], v[176:179], v[216:219], v[64:67]
	s_setprio 0
	s_barrier
	s_add_i32 s81, s76, s66
	v_lshl_add_u64 v[220:221], s[60:61], 0, v[154:155]
	s_mov_b32 m0, s81
	ds_read_b128 v[180:183], v190 offset:16384
	v_xor_b32_e32 v253, 64, v190
	ds_read_b128 v[192:195], v253 offset:16384
	ds_read_b128 v[196:199], v190 offset:18432
	ds_read_b128 v[200:203], v253 offset:18432
	ds_read_b128 v[204:207], v190 offset:20480
	ds_read_b128 v[208:211], v253 offset:20480
	ds_read_b128 v[212:215], v190 offset:22528
	ds_read_b128 v[216:219], v253 offset:22528
	global_load_lds_dwordx4 v[220:221], off
	s_add_i32 m0, s81, 0x2000
	s_add_u32 s82, s60, 0x40000
	v_lshl_add_u64 v[222:223], s[60:61], 0, v[162:163]
	s_addc_u32 s83, s61, 0
	s_add_i32 s81, s77, s66
	global_load_lds_dwordx4 v[222:223], off
	v_lshl_add_u64 v[224:225], s[82:83], 0, v[154:155]
	s_mov_b32 m0, s81
	v_lshl_add_u64 v[226:227], s[62:63], 0, v[160:161]
	global_load_lds_dwordx4 v[224:225], off
	v_lshl_add_u64 v[224:225], s[82:83], 0, v[162:163]
	s_add_i32 m0, s81, 0x2000
	s_nop 0
	global_load_lds_dwordx4 v[224:225], off
	v_lshl_add_u64 v[224:225], s[62:63], 0, v[152:153]
	s_mov_b32 m0, s67
	s_nop 0
	global_load_lds_dwordx4 v[224:225], off
	s_mov_b32 m0, s68
	s_nop 0
	global_load_lds_dwordx4 v[226:227], off
	s_waitcnt vmcnt(8)
	s_waitcnt lgkmcnt(0)
	s_barrier
	s_setprio 1
	s_waitcnt lgkmcnt(0)
	v_mfma_f32_16x16x32_bf16 v[60:63], v[128:131], v[180:183], 0
	v_mfma_f32_16x16x32_bf16 v[56:59], v[136:139], v[180:183], 0
	v_mfma_f32_16x16x32_bf16 v[44:47], v[128:131], v[196:199], 0
	v_mfma_f32_16x16x32_bf16 v[40:43], v[136:139], v[196:199], 0
	v_mfma_f32_16x16x32_bf16 v[28:31], v[128:131], v[204:207], 0
	v_mfma_f32_16x16x32_bf16 v[24:27], v[136:139], v[204:207], 0
	v_mfma_f32_16x16x32_bf16 v[12:15], v[128:131], v[212:215], 0
	v_mfma_f32_16x16x32_bf16 v[8:11], v[136:139], v[212:215], 0
	v_mfma_f32_16x16x32_bf16 v[60:63], v[132:135], v[192:195], v[60:63]
	v_mfma_f32_16x16x32_bf16 v[56:59], v[140:143], v[192:195], v[56:59]
	v_mfma_f32_16x16x32_bf16 v[44:47], v[132:135], v[200:203], v[44:47]
	v_mfma_f32_16x16x32_bf16 v[40:43], v[140:143], v[200:203], v[40:43]
	v_mfma_f32_16x16x32_bf16 v[28:31], v[132:135], v[208:211], v[28:31]
	v_mfma_f32_16x16x32_bf16 v[24:27], v[140:143], v[208:211], v[24:27]
	v_mfma_f32_16x16x32_bf16 v[12:15], v[132:135], v[216:219], v[12:15]
	v_mfma_f32_16x16x32_bf16 v[8:11], v[140:143], v[216:219], v[8:11]
	s_setprio 0
	s_setprio 1
	v_mfma_f32_16x16x32_bf16 v[52:55], v[144:147], v[180:183], 0
	v_mfma_f32_16x16x32_bf16 v[48:51], v[172:175], v[180:183], 0
	v_mfma_f32_16x16x32_bf16 v[36:39], v[144:147], v[196:199], 0
	v_mfma_f32_16x16x32_bf16 v[32:35], v[172:175], v[196:199], 0
	v_mfma_f32_16x16x32_bf16 v[20:23], v[144:147], v[204:207], 0
	v_mfma_f32_16x16x32_bf16 v[16:19], v[172:175], v[204:207], 0
	v_mfma_f32_16x16x32_bf16 v[4:7], v[144:147], v[212:215], 0
	v_mfma_f32_16x16x32_bf16 v[0:3], v[172:175], v[212:215], 0
	v_mfma_f32_16x16x32_bf16 v[52:55], v[148:151], v[192:195], v[52:55]
	v_mfma_f32_16x16x32_bf16 v[48:51], v[176:179], v[192:195], v[48:51]
	v_mfma_f32_16x16x32_bf16 v[36:39], v[148:151], v[200:203], v[36:39]
	v_mfma_f32_16x16x32_bf16 v[32:35], v[176:179], v[200:203], v[32:35]
	v_mfma_f32_16x16x32_bf16 v[20:23], v[148:151], v[208:211], v[20:23]
	v_mfma_f32_16x16x32_bf16 v[16:19], v[176:179], v[208:211], v[16:19]
	v_mfma_f32_16x16x32_bf16 v[4:7], v[148:151], v[216:219], v[4:7]
	v_mfma_f32_16x16x32_bf16 v[0:3], v[176:179], v[216:219], v[0:3]
	s_setprio 0
	s_barrier
	s_add_i32 s81, 0, 0x18000
	s_add_i32 s82, 0, 0x1c000
	v_add_u32_e32 v140, s81, v185
	v_add_u32_e32 v176, s82, v185
	ds_read_b128 v[128:131], v140
	v_xor_b32_e32 v253, 64, v140
	ds_read_b128 v[132:135], v253
	ds_read_b128 v[136:139], v140 offset:2048
	ds_read_b128 v[140:143], v253 offset:2048
	ds_read_b128 v[144:147], v176
	v_xor_b32_e32 v253, 64, v176
	ds_read_b128 v[148:151], v253
	ds_read_b128 v[172:175], v176 offset:2048
	ds_read_b128 v[176:179], v253 offset:2048
	s_add_u32 s62, s62, 0x40000
	s_addc_u32 s63, s63, 0
	s_mov_b32 m0, s69
	v_lshl_add_u64 v[228:229], s[62:63], 0, v[152:153]
	ds_read_b128 v[180:183], v190 offset:32768
	v_xor_b32_e32 v253, 64, v190
	ds_read_b128 v[192:195], v253 offset:32768
	ds_read_b128 v[196:199], v190 offset:34816
	ds_read_b128 v[200:203], v253 offset:34816
	ds_read_b128 v[204:207], v190 offset:36864
	ds_read_b128 v[208:211], v253 offset:36864
	ds_read_b128 v[212:215], v190 offset:38912
	ds_read_b128 v[216:219], v253 offset:38912
	global_load_lds_dwordx4 v[228:229], off
	v_lshl_add_u64 v[228:229], s[62:63], 0, v[160:161]
	s_mov_b32 m0, s70
	s_nop 0
	global_load_lds_dwordx4 v[228:229], off
	s_waitcnt vmcnt(8)
	s_waitcnt lgkmcnt(0)
	s_barrier
	s_setprio 1
	s_waitcnt lgkmcnt(0)
	v_mfma_f32_16x16x32_bf16 v[124:127], v[128:131], v[180:183], v[124:127]
	v_mfma_f32_16x16x32_bf16 v[124:127], v[132:135], v[192:195], v[124:127]
	v_mfma_f32_16x16x32_bf16 v[108:111], v[132:135], v[200:203], v[108:111]
	v_mfma_f32_16x16x32_bf16 v[108:111], v[128:131], v[196:199], v[108:111]
	v_mfma_f32_16x16x32_bf16 v[92:95], v[128:131], v[204:207], v[92:95]
	v_mfma_f32_16x16x32_bf16 v[92:95], v[132:135], v[208:211], v[92:95]
	v_mfma_f32_16x16x32_bf16 v[76:79], v[132:135], v[216:219], v[76:79]
	v_mfma_f32_16x16x32_bf16 v[76:79], v[128:131], v[212:215], v[76:79]
	v_mfma_f32_16x16x32_bf16 v[72:75], v[136:139], v[212:215], v[72:75]
	v_mfma_f32_16x16x32_bf16 v[72:75], v[140:143], v[216:219], v[72:75]
	v_mfma_f32_16x16x32_bf16 v[88:91], v[140:143], v[208:211], v[88:91]
	v_mfma_f32_16x16x32_bf16 v[88:91], v[136:139], v[204:207], v[88:91]
	v_mfma_f32_16x16x32_bf16 v[104:107], v[136:139], v[196:199], v[104:107]
	v_mfma_f32_16x16x32_bf16 v[104:107], v[140:143], v[200:203], v[104:107]
	v_mfma_f32_16x16x32_bf16 v[120:123], v[140:143], v[192:195], v[120:123]
	v_mfma_f32_16x16x32_bf16 v[120:123], v[136:139], v[180:183], v[120:123]
	s_setprio 0
	s_setprio 1
	v_mfma_f32_16x16x32_bf16 v[116:119], v[144:147], v[180:183], v[116:119]
	v_mfma_f32_16x16x32_bf16 v[116:119], v[148:151], v[192:195], v[116:119]
	v_mfma_f32_16x16x32_bf16 v[100:103], v[148:151], v[200:203], v[100:103]
	v_mfma_f32_16x16x32_bf16 v[100:103], v[144:147], v[196:199], v[100:103]
	v_mfma_f32_16x16x32_bf16 v[84:87], v[144:147], v[204:207], v[84:87]
	v_mfma_f32_16x16x32_bf16 v[84:87], v[148:151], v[208:211], v[84:87]
	v_mfma_f32_16x16x32_bf16 v[68:71], v[148:151], v[216:219], v[68:71]
	v_mfma_f32_16x16x32_bf16 v[68:71], v[144:147], v[212:215], v[68:71]
	v_mfma_f32_16x16x32_bf16 v[64:67], v[172:175], v[212:215], v[64:67]
	v_mfma_f32_16x16x32_bf16 v[64:67], v[176:179], v[216:219], v[64:67]
	v_mfma_f32_16x16x32_bf16 v[80:83], v[176:179], v[208:211], v[80:83]
	v_mfma_f32_16x16x32_bf16 v[80:83], v[172:175], v[204:207], v[80:83]
	v_mfma_f32_16x16x32_bf16 v[96:99], v[172:175], v[196:199], v[96:99]
	v_mfma_f32_16x16x32_bf16 v[96:99], v[176:179], v[200:203], v[96:99]
	v_mfma_f32_16x16x32_bf16 v[112:115], v[176:179], v[192:195], v[112:115]
	v_mfma_f32_16x16x32_bf16 v[112:115], v[172:175], v[180:183], v[112:115]
	s_setprio 0
	s_barrier
	s_add_i32 s62, s81, s66
	v_lshl_add_u64 v[220:221], v[220:221], 0, s[26:27]
	s_mov_b32 m0, s62
	ds_read_b128 v[180:183], v190 offset:49152
	v_xor_b32_e32 v253, 64, v190
	ds_read_b128 v[192:195], v253 offset:49152
	ds_read_b128 v[196:199], v190 offset:51200
	ds_read_b128 v[200:203], v253 offset:51200
	ds_read_b128 v[204:207], v190 offset:53248
	ds_read_b128 v[208:211], v253 offset:53248
	ds_read_b128 v[212:215], v190 offset:55296
	ds_read_b128 v[216:219], v253 offset:55296
	global_load_lds_dwordx4 v[220:221], off
	s_add_i32 m0, s62, 0x2000
	s_add_u32 s60, s60, 0x40080
	v_lshl_add_u64 v[220:221], v[222:223], 0, s[26:27]
	s_addc_u32 s61, s61, 0
	s_add_i32 s62, s82, s66
	global_load_lds_dwordx4 v[220:221], off
	v_lshl_add_u64 v[220:221], s[60:61], 0, v[154:155]
	s_mov_b32 m0, s62
	s_nop 0
	global_load_lds_dwordx4 v[220:221], off
	v_lshl_add_u64 v[220:221], s[60:61], 0, v[162:163]
	s_add_i32 m0, s62, 0x2000
	s_nop 0
	global_load_lds_dwordx4 v[220:221], off
	v_lshl_add_u64 v[220:221], v[224:225], 0, s[26:27]
	s_mov_b32 m0, s3
	s_nop 0
	global_load_lds_dwordx4 v[220:221], off
	v_lshl_add_u64 v[220:221], v[226:227], 0, s[26:27]
	s_mov_b32 m0, s72
	s_nop 0
	global_load_lds_dwordx4 v[220:221], off
	s_waitcnt vmcnt(8)
	s_waitcnt lgkmcnt(0)
	s_barrier
	s_setprio 1
	s_waitcnt lgkmcnt(0)
	v_mfma_f32_16x16x32_bf16 v[60:63], v[128:131], v[180:183], v[60:63]
	v_mfma_f32_16x16x32_bf16 v[60:63], v[132:135], v[192:195], v[60:63]
	v_mfma_f32_16x16x32_bf16 v[44:47], v[132:135], v[200:203], v[44:47]
	v_mfma_f32_16x16x32_bf16 v[44:47], v[128:131], v[196:199], v[44:47]
	v_mfma_f32_16x16x32_bf16 v[28:31], v[128:131], v[204:207], v[28:31]
	v_mfma_f32_16x16x32_bf16 v[28:31], v[132:135], v[208:211], v[28:31]
	v_mfma_f32_16x16x32_bf16 v[12:15], v[132:135], v[216:219], v[12:15]
	v_mfma_f32_16x16x32_bf16 v[12:15], v[128:131], v[212:215], v[12:15]
	v_mfma_f32_16x16x32_bf16 v[8:11], v[136:139], v[212:215], v[8:11]
	v_mfma_f32_16x16x32_bf16 v[8:11], v[140:143], v[216:219], v[8:11]
	v_mfma_f32_16x16x32_bf16 v[24:27], v[140:143], v[208:211], v[24:27]
	v_mfma_f32_16x16x32_bf16 v[24:27], v[136:139], v[204:207], v[24:27]
	v_mfma_f32_16x16x32_bf16 v[40:43], v[136:139], v[196:199], v[40:43]
	v_mfma_f32_16x16x32_bf16 v[40:43], v[140:143], v[200:203], v[40:43]
	v_mfma_f32_16x16x32_bf16 v[56:59], v[140:143], v[192:195], v[56:59]
	v_mfma_f32_16x16x32_bf16 v[56:59], v[136:139], v[180:183], v[56:59]
	s_setprio 0
	s_setprio 1
	v_mfma_f32_16x16x32_bf16 v[52:55], v[144:147], v[180:183], v[52:55]
	v_mfma_f32_16x16x32_bf16 v[52:55], v[148:151], v[192:195], v[52:55]
	v_mfma_f32_16x16x32_bf16 v[36:39], v[148:151], v[200:203], v[36:39]
	v_mfma_f32_16x16x32_bf16 v[36:39], v[144:147], v[196:199], v[36:39]
	v_mfma_f32_16x16x32_bf16 v[20:23], v[144:147], v[204:207], v[20:23]
	v_mfma_f32_16x16x32_bf16 v[20:23], v[148:151], v[208:211], v[20:23]
	v_mfma_f32_16x16x32_bf16 v[4:7], v[148:151], v[216:219], v[4:7]
	v_mfma_f32_16x16x32_bf16 v[4:7], v[144:147], v[212:215], v[4:7]
	v_mfma_f32_16x16x32_bf16 v[0:3], v[172:175], v[212:215], v[0:3]
	v_mfma_f32_16x16x32_bf16 v[0:3], v[176:179], v[216:219], v[0:3]
	v_mfma_f32_16x16x32_bf16 v[16:19], v[176:179], v[208:211], v[16:19]
	v_mfma_f32_16x16x32_bf16 v[16:19], v[172:175], v[204:207], v[16:19]
	v_mfma_f32_16x16x32_bf16 v[32:35], v[172:175], v[196:199], v[32:35]
	v_mfma_f32_16x16x32_bf16 v[32:35], v[176:179], v[200:203], v[32:35]
	v_mfma_f32_16x16x32_bf16 v[48:51], v[176:179], v[192:195], v[48:51]
	v_mfma_f32_16x16x32_bf16 v[48:51], v[172:175], v[180:183], v[48:51]
	s_setprio 0
	s_barrier
	s_add_i32 s80, s80, 2
	s_add_u32 s78, s78, 0x100
	s_addc_u32 s79, s79, 0
	s_add_u32 s58, s58, 0x100
	s_addc_u32 s59, s59, 0
	s_cmp_gt_u32 s80, 13
.LBB0_1011:
	ds_read_b128 v[128:131], v188
	v_xor_b32_e32 v253, 64, v188
	ds_read_b128 v[132:135], v253
	ds_read_b128 v[136:139], v188 offset:2048
	ds_read_b128 v[140:143], v253 offset:2048
	ds_read_b128 v[144:147], v189
	v_xor_b32_e32 v253, 64, v189
	ds_read_b128 v[148:151], v253
	ds_read_b128 v[172:175], v189 offset:2048
	ds_read_b128 v[176:179], v253 offset:2048
	s_add_u32 s60, s58, 0xfffc0080
	s_addc_u32 s61, s59, -1
	s_cmp_eq_u32 s80, 12
	s_cselect_b32 s63, s15, s61
	s_cselect_b32 s62, s51, s60
	s_cselect_b32 s61, s49, s79
	s_cselect_b32 s60, s57, s78
	v_lshl_add_u64 v[220:221], s[58:59], 0, v[166:167]
	s_add_i32 m0, s67, 0xc000
	ds_read_b128 v[180:183], v190
	v_xor_b32_e32 v253, 64, v190
	ds_read_b128 v[192:195], v253
	ds_read_b128 v[196:199], v190 offset:2048
	ds_read_b128 v[200:203], v253 offset:2048
	ds_read_b128 v[204:207], v190 offset:4096
	ds_read_b128 v[208:211], v253 offset:4096
	ds_read_b128 v[212:215], v190 offset:6144
	ds_read_b128 v[216:219], v253 offset:6144
	global_load_lds_dwordx4 v[220:221], off
	v_lshl_add_u64 v[220:221], s[58:59], 0, v[164:165]
	s_add_i32 m0, s67, 0xe000
	s_nop 0
	global_load_lds_dwordx4 v[220:221], off
	s_waitcnt vmcnt(8)
	s_waitcnt lgkmcnt(0)
	s_barrier
	s_setprio 1
	s_waitcnt lgkmcnt(0)
	v_mfma_f32_16x16x32_bf16 v[124:127], v[128:131], v[180:183], v[124:127]
	v_mfma_f32_16x16x32_bf16 v[124:127], v[132:135], v[192:195], v[124:127]
	v_mfma_f32_16x16x32_bf16 v[108:111], v[132:135], v[200:203], v[108:111]
	v_mfma_f32_16x16x32_bf16 v[108:111], v[128:131], v[196:199], v[108:111]
	v_mfma_f32_16x16x32_bf16 v[92:95], v[128:131], v[204:207], v[92:95]
	v_mfma_f32_16x16x32_bf16 v[92:95], v[132:135], v[208:211], v[92:95]
	v_mfma_f32_16x16x32_bf16 v[76:79], v[132:135], v[216:219], v[76:79]
	v_mfma_f32_16x16x32_bf16 v[76:79], v[128:131], v[212:215], v[76:79]
	v_mfma_f32_16x16x32_bf16 v[72:75], v[136:139], v[212:215], v[72:75]
	v_mfma_f32_16x16x32_bf16 v[72:75], v[140:143], v[216:219], v[72:75]
	v_mfma_f32_16x16x32_bf16 v[88:91], v[140:143], v[208:211], v[88:91]
	v_mfma_f32_16x16x32_bf16 v[88:91], v[136:139], v[204:207], v[88:91]
	v_mfma_f32_16x16x32_bf16 v[104:107], v[136:139], v[196:199], v[104:107]
	v_mfma_f32_16x16x32_bf16 v[104:107], v[140:143], v[200:203], v[104:107]
	v_mfma_f32_16x16x32_bf16 v[120:123], v[140:143], v[192:195], v[120:123]
	v_mfma_f32_16x16x32_bf16 v[120:123], v[136:139], v[180:183], v[120:123]
	s_setprio 0
	s_setprio 1
	v_mfma_f32_16x16x32_bf16 v[116:119], v[144:147], v[180:183], v[116:119]
	v_mfma_f32_16x16x32_bf16 v[116:119], v[148:151], v[192:195], v[116:119]
	v_mfma_f32_16x16x32_bf16 v[100:103], v[148:151], v[200:203], v[100:103]
	v_mfma_f32_16x16x32_bf16 v[100:103], v[144:147], v[196:199], v[100:103]
	v_mfma_f32_16x16x32_bf16 v[84:87], v[144:147], v[204:207], v[84:87]
	v_mfma_f32_16x16x32_bf16 v[84:87], v[148:151], v[208:211], v[84:87]
	v_mfma_f32_16x16x32_bf16 v[68:71], v[148:151], v[216:219], v[68:71]
	v_mfma_f32_16x16x32_bf16 v[68:71], v[144:147], v[212:215], v[68:71]
	v_mfma_f32_16x16x32_bf16 v[64:67], v[172:175], v[212:215], v[64:67]
	v_mfma_f32_16x16x32_bf16 v[64:67], v[176:179], v[216:219], v[64:67]
	v_mfma_f32_16x16x32_bf16 v[80:83], v[176:179], v[208:211], v[80:83]
	v_mfma_f32_16x16x32_bf16 v[80:83], v[172:175], v[204:207], v[80:83]
	v_mfma_f32_16x16x32_bf16 v[96:99], v[172:175], v[196:199], v[96:99]
	v_mfma_f32_16x16x32_bf16 v[96:99], v[176:179], v[200:203], v[96:99]
	v_mfma_f32_16x16x32_bf16 v[112:115], v[176:179], v[192:195], v[112:115]
	v_mfma_f32_16x16x32_bf16 v[112:115], v[172:175], v[180:183], v[112:115]
	s_setprio 0
	s_barrier
	s_add_i32 s81, s76, s66
	v_lshl_add_u64 v[220:221], s[60:61], 0, v[154:155]
	s_mov_b32 m0, s81
	ds_read_b128 v[180:183], v190 offset:16384
	v_xor_b32_e32 v253, 64, v190
	ds_read_b128 v[192:195], v253 offset:16384
	ds_read_b128 v[196:199], v190 offset:18432
	ds_read_b128 v[200:203], v253 offset:18432
	ds_read_b128 v[204:207], v190 offset:20480
	ds_read_b128 v[208:211], v253 offset:20480
	ds_read_b128 v[212:215], v190 offset:22528
	ds_read_b128 v[216:219], v253 offset:22528
	global_load_lds_dwordx4 v[220:221], off
	s_add_i32 m0, s81, 0x2000
	s_add_u32 s82, s60, 0x40000
	v_lshl_add_u64 v[222:223], s[60:61], 0, v[162:163]
	s_addc_u32 s83, s61, 0
	s_add_i32 s81, s77, s66
	global_load_lds_dwordx4 v[222:223], off
	v_lshl_add_u64 v[224:225], s[82:83], 0, v[154:155]
	s_mov_b32 m0, s81
	v_lshl_add_u64 v[226:227], s[62:63], 0, v[160:161]
	global_load_lds_dwordx4 v[224:225], off
	v_lshl_add_u64 v[224:225], s[82:83], 0, v[162:163]
	s_add_i32 m0, s81, 0x2000
	s_nop 0
	global_load_lds_dwordx4 v[224:225], off
	v_lshl_add_u64 v[224:225], s[62:63], 0, v[152:153]
	s_mov_b32 m0, s67
	s_nop 0
	global_load_lds_dwordx4 v[224:225], off
	s_mov_b32 m0, s68
	s_nop 0
	global_load_lds_dwordx4 v[226:227], off
	s_waitcnt vmcnt(8)
	s_waitcnt lgkmcnt(0)
	s_barrier
	s_setprio 1
	s_waitcnt lgkmcnt(0)
	v_mfma_f32_16x16x32_bf16 v[60:63], v[128:131], v[180:183], v[60:63]
	v_mfma_f32_16x16x32_bf16 v[60:63], v[132:135], v[192:195], v[60:63]
	v_mfma_f32_16x16x32_bf16 v[44:47], v[132:135], v[200:203], v[44:47]
	v_mfma_f32_16x16x32_bf16 v[44:47], v[128:131], v[196:199], v[44:47]
	v_mfma_f32_16x16x32_bf16 v[28:31], v[128:131], v[204:207], v[28:31]
	v_mfma_f32_16x16x32_bf16 v[28:31], v[132:135], v[208:211], v[28:31]
	v_mfma_f32_16x16x32_bf16 v[12:15], v[132:135], v[216:219], v[12:15]
	v_mfma_f32_16x16x32_bf16 v[12:15], v[128:131], v[212:215], v[12:15]
	v_mfma_f32_16x16x32_bf16 v[8:11], v[136:139], v[212:215], v[8:11]
	v_mfma_f32_16x16x32_bf16 v[8:11], v[140:143], v[216:219], v[8:11]
	v_mfma_f32_16x16x32_bf16 v[24:27], v[140:143], v[208:211], v[24:27]
	v_mfma_f32_16x16x32_bf16 v[24:27], v[136:139], v[204:207], v[24:27]
	v_mfma_f32_16x16x32_bf16 v[40:43], v[136:139], v[196:199], v[40:43]
	v_mfma_f32_16x16x32_bf16 v[40:43], v[140:143], v[200:203], v[40:43]
	v_mfma_f32_16x16x32_bf16 v[56:59], v[140:143], v[192:195], v[56:59]
	v_mfma_f32_16x16x32_bf16 v[56:59], v[136:139], v[180:183], v[56:59]
	s_setprio 0
	s_setprio 1
	v_mfma_f32_16x16x32_bf16 v[52:55], v[144:147], v[180:183], v[52:55]
	v_mfma_f32_16x16x32_bf16 v[52:55], v[148:151], v[192:195], v[52:55]
	v_mfma_f32_16x16x32_bf16 v[36:39], v[148:151], v[200:203], v[36:39]
	v_mfma_f32_16x16x32_bf16 v[36:39], v[144:147], v[196:199], v[36:39]
	v_mfma_f32_16x16x32_bf16 v[20:23], v[144:147], v[204:207], v[20:23]
	v_mfma_f32_16x16x32_bf16 v[20:23], v[148:151], v[208:211], v[20:23]
	v_mfma_f32_16x16x32_bf16 v[4:7], v[148:151], v[216:219], v[4:7]
	v_mfma_f32_16x16x32_bf16 v[4:7], v[144:147], v[212:215], v[4:7]
	v_mfma_f32_16x16x32_bf16 v[0:3], v[172:175], v[212:215], v[0:3]
	v_mfma_f32_16x16x32_bf16 v[0:3], v[176:179], v[216:219], v[0:3]
	v_mfma_f32_16x16x32_bf16 v[16:19], v[176:179], v[208:211], v[16:19]
	v_mfma_f32_16x16x32_bf16 v[16:19], v[172:175], v[204:207], v[16:19]
	v_mfma_f32_16x16x32_bf16 v[32:35], v[172:175], v[196:199], v[32:35]
	v_mfma_f32_16x16x32_bf16 v[32:35], v[176:179], v[200:203], v[32:35]
	v_mfma_f32_16x16x32_bf16 v[48:51], v[176:179], v[192:195], v[48:51]
	v_mfma_f32_16x16x32_bf16 v[48:51], v[172:175], v[180:183], v[48:51]
	s_setprio 0
	s_barrier
	s_add_i32 s81, 0, 0x18000
	s_add_i32 s82, 0, 0x1c000
	v_add_u32_e32 v140, s81, v185
	v_add_u32_e32 v176, s82, v185
	ds_read_b128 v[128:131], v140
	v_xor_b32_e32 v253, 64, v140
	ds_read_b128 v[132:135], v253
	ds_read_b128 v[136:139], v140 offset:2048
	ds_read_b128 v[140:143], v253 offset:2048
	ds_read_b128 v[144:147], v176
	v_xor_b32_e32 v253, 64, v176
	ds_read_b128 v[148:151], v253
	ds_read_b128 v[172:175], v176 offset:2048
	ds_read_b128 v[176:179], v253 offset:2048
	s_add_u32 s62, s62, 0x40000
	s_addc_u32 s63, s63, 0
	s_mov_b32 m0, s69
	v_lshl_add_u64 v[228:229], s[62:63], 0, v[152:153]
	ds_read_b128 v[180:183], v190 offset:32768
	v_xor_b32_e32 v253, 64, v190
	ds_read_b128 v[192:195], v253 offset:32768
	ds_read_b128 v[196:199], v190 offset:34816
	ds_read_b128 v[200:203], v253 offset:34816
	ds_read_b128 v[204:207], v190 offset:36864
	ds_read_b128 v[208:211], v253 offset:36864
	ds_read_b128 v[212:215], v190 offset:38912
	ds_read_b128 v[216:219], v253 offset:38912
	global_load_lds_dwordx4 v[228:229], off
	v_lshl_add_u64 v[228:229], s[62:63], 0, v[160:161]
	s_mov_b32 m0, s70
	s_nop 0
	global_load_lds_dwordx4 v[228:229], off
	s_waitcnt vmcnt(8)
	s_waitcnt lgkmcnt(0)
	s_barrier
	s_setprio 1
	s_waitcnt lgkmcnt(0)
	v_mfma_f32_16x16x32_bf16 v[124:127], v[128:131], v[180:183], v[124:127]
	v_mfma_f32_16x16x32_bf16 v[124:127], v[132:135], v[192:195], v[124:127]
	v_mfma_f32_16x16x32_bf16 v[108:111], v[132:135], v[200:203], v[108:111]
	v_mfma_f32_16x16x32_bf16 v[108:111], v[128:131], v[196:199], v[108:111]
	v_mfma_f32_16x16x32_bf16 v[92:95], v[128:131], v[204:207], v[92:95]
	v_mfma_f32_16x16x32_bf16 v[92:95], v[132:135], v[208:211], v[92:95]
	v_mfma_f32_16x16x32_bf16 v[76:79], v[132:135], v[216:219], v[76:79]
	v_mfma_f32_16x16x32_bf16 v[76:79], v[128:131], v[212:215], v[76:79]
	v_mfma_f32_16x16x32_bf16 v[72:75], v[136:139], v[212:215], v[72:75]
	v_mfma_f32_16x16x32_bf16 v[72:75], v[140:143], v[216:219], v[72:75]
	v_mfma_f32_16x16x32_bf16 v[88:91], v[140:143], v[208:211], v[88:91]
	v_mfma_f32_16x16x32_bf16 v[88:91], v[136:139], v[204:207], v[88:91]
	v_mfma_f32_16x16x32_bf16 v[104:107], v[136:139], v[196:199], v[104:107]
	v_mfma_f32_16x16x32_bf16 v[104:107], v[140:143], v[200:203], v[104:107]
	v_mfma_f32_16x16x32_bf16 v[120:123], v[140:143], v[192:195], v[120:123]
	v_mfma_f32_16x16x32_bf16 v[120:123], v[136:139], v[180:183], v[120:123]
	s_setprio 0
	s_setprio 1
	v_mfma_f32_16x16x32_bf16 v[116:119], v[144:147], v[180:183], v[116:119]
	v_mfma_f32_16x16x32_bf16 v[116:119], v[148:151], v[192:195], v[116:119]
	v_mfma_f32_16x16x32_bf16 v[100:103], v[148:151], v[200:203], v[100:103]
	v_mfma_f32_16x16x32_bf16 v[100:103], v[144:147], v[196:199], v[100:103]
	v_mfma_f32_16x16x32_bf16 v[84:87], v[144:147], v[204:207], v[84:87]
	v_mfma_f32_16x16x32_bf16 v[84:87], v[148:151], v[208:211], v[84:87]
	v_mfma_f32_16x16x32_bf16 v[68:71], v[148:151], v[216:219], v[68:71]
	v_mfma_f32_16x16x32_bf16 v[68:71], v[144:147], v[212:215], v[68:71]
	v_mfma_f32_16x16x32_bf16 v[64:67], v[172:175], v[212:215], v[64:67]
	v_mfma_f32_16x16x32_bf16 v[64:67], v[176:179], v[216:219], v[64:67]
	v_mfma_f32_16x16x32_bf16 v[80:83], v[176:179], v[208:211], v[80:83]
	v_mfma_f32_16x16x32_bf16 v[80:83], v[172:175], v[204:207], v[80:83]
	v_mfma_f32_16x16x32_bf16 v[96:99], v[172:175], v[196:199], v[96:99]
	v_mfma_f32_16x16x32_bf16 v[96:99], v[176:179], v[200:203], v[96:99]
	v_mfma_f32_16x16x32_bf16 v[112:115], v[176:179], v[192:195], v[112:115]
	v_mfma_f32_16x16x32_bf16 v[112:115], v[172:175], v[180:183], v[112:115]
	s_setprio 0
	s_barrier
	s_add_i32 s62, s81, s66
	v_lshl_add_u64 v[220:221], v[220:221], 0, s[26:27]
	s_mov_b32 m0, s62
	ds_read_b128 v[180:183], v190 offset:49152
	v_xor_b32_e32 v253, 64, v190
	ds_read_b128 v[192:195], v253 offset:49152
	ds_read_b128 v[196:199], v190 offset:51200
	ds_read_b128 v[200:203], v253 offset:51200
	ds_read_b128 v[204:207], v190 offset:53248
	ds_read_b128 v[208:211], v253 offset:53248
	ds_read_b128 v[212:215], v190 offset:55296
	ds_read_b128 v[216:219], v253 offset:55296
	global_load_lds_dwordx4 v[220:221], off
	s_add_i32 m0, s62, 0x2000
	s_add_u32 s60, s60, 0x40080
	v_lshl_add_u64 v[220:221], v[222:223], 0, s[26:27]
	s_addc_u32 s61, s61, 0
	s_add_i32 s62, s82, s66
	global_load_lds_dwordx4 v[220:221], off
	v_lshl_add_u64 v[220:221], s[60:61], 0, v[154:155]
	s_mov_b32 m0, s62
	s_nop 0
	global_load_lds_dwordx4 v[220:221], off
	v_lshl_add_u64 v[220:221], s[60:61], 0, v[162:163]
	s_add_i32 m0, s62, 0x2000
	s_nop 0
	global_load_lds_dwordx4 v[220:221], off
	v_lshl_add_u64 v[220:221], v[224:225], 0, s[26:27]
	s_mov_b32 m0, s3
	s_nop 0
	global_load_lds_dwordx4 v[220:221], off
	v_lshl_add_u64 v[220:221], v[226:227], 0, s[26:27]
	s_mov_b32 m0, s72
	s_nop 0
	global_load_lds_dwordx4 v[220:221], off
	s_waitcnt vmcnt(8)
	s_waitcnt lgkmcnt(0)
	s_barrier
	s_setprio 1
	s_waitcnt lgkmcnt(0)
	v_mfma_f32_16x16x32_bf16 v[60:63], v[128:131], v[180:183], v[60:63]
	v_mfma_f32_16x16x32_bf16 v[60:63], v[132:135], v[192:195], v[60:63]
	v_mfma_f32_16x16x32_bf16 v[44:47], v[132:135], v[200:203], v[44:47]
	v_mfma_f32_16x16x32_bf16 v[44:47], v[128:131], v[196:199], v[44:47]
	v_mfma_f32_16x16x32_bf16 v[28:31], v[128:131], v[204:207], v[28:31]
	v_mfma_f32_16x16x32_bf16 v[28:31], v[132:135], v[208:211], v[28:31]
	v_mfma_f32_16x16x32_bf16 v[12:15], v[132:135], v[216:219], v[12:15]
	v_mfma_f32_16x16x32_bf16 v[12:15], v[128:131], v[212:215], v[12:15]
	v_mfma_f32_16x16x32_bf16 v[8:11], v[136:139], v[212:215], v[8:11]
	v_mfma_f32_16x16x32_bf16 v[8:11], v[140:143], v[216:219], v[8:11]
	v_mfma_f32_16x16x32_bf16 v[24:27], v[140:143], v[208:211], v[24:27]
	v_mfma_f32_16x16x32_bf16 v[24:27], v[136:139], v[204:207], v[24:27]
	v_mfma_f32_16x16x32_bf16 v[40:43], v[136:139], v[196:199], v[40:43]
	v_mfma_f32_16x16x32_bf16 v[40:43], v[140:143], v[200:203], v[40:43]
	v_mfma_f32_16x16x32_bf16 v[56:59], v[140:143], v[192:195], v[56:59]
	v_mfma_f32_16x16x32_bf16 v[56:59], v[136:139], v[180:183], v[56:59]
	s_setprio 0
	s_setprio 1
	v_mfma_f32_16x16x32_bf16 v[52:55], v[144:147], v[180:183], v[52:55]
	v_mfma_f32_16x16x32_bf16 v[52:55], v[148:151], v[192:195], v[52:55]
	v_mfma_f32_16x16x32_bf16 v[36:39], v[148:151], v[200:203], v[36:39]
	v_mfma_f32_16x16x32_bf16 v[36:39], v[144:147], v[196:199], v[36:39]
	v_mfma_f32_16x16x32_bf16 v[20:23], v[144:147], v[204:207], v[20:23]
	v_mfma_f32_16x16x32_bf16 v[20:23], v[148:151], v[208:211], v[20:23]
	v_mfma_f32_16x16x32_bf16 v[4:7], v[148:151], v[216:219], v[4:7]
	v_mfma_f32_16x16x32_bf16 v[4:7], v[144:147], v[212:215], v[4:7]
	v_mfma_f32_16x16x32_bf16 v[0:3], v[172:175], v[212:215], v[0:3]
	v_mfma_f32_16x16x32_bf16 v[0:3], v[176:179], v[216:219], v[0:3]
	v_mfma_f32_16x16x32_bf16 v[16:19], v[176:179], v[208:211], v[16:19]
	v_mfma_f32_16x16x32_bf16 v[16:19], v[172:175], v[204:207], v[16:19]
	v_mfma_f32_16x16x32_bf16 v[32:35], v[172:175], v[196:199], v[32:35]
	v_mfma_f32_16x16x32_bf16 v[32:35], v[176:179], v[200:203], v[32:35]
	v_mfma_f32_16x16x32_bf16 v[48:51], v[176:179], v[192:195], v[48:51]
	v_mfma_f32_16x16x32_bf16 v[48:51], v[172:175], v[180:183], v[48:51]
	s_setprio 0
	s_barrier
	s_add_i32 s80, s80, 2
	s_add_u32 s78, s78, 0x100
	s_addc_u32 s79, s79, 0
	s_add_u32 s58, s58, 0x100
	s_addc_u32 s59, s59, 0
	s_cmp_gt_u32 s80, 13
	s_cbranch_scc0 .LBB0_1011
	s_and_b64 vcc, exec, s[28:29]
	s_cbranch_vccz .LBB0_1014
	s_barrier

.LBB0_1096:
	s_ashr_i32 s25, s24, 31
	s_lshl_b64 s[26:27], s[24:25], 19
	s_add_u32 s26, s3, s26
	s_addc_u32 s27, s33, s27
	s_and_b64 s[28:29], s[6:7], exec
	s_cselect_b32 s25, s27, s47
	s_cselect_b32 s65, s26, s46
	s_ashr_i32 s23, s22, 31
	s_lshl_b64 s[28:29], s[22:23], 19
	s_add_u32 s28, s35, s28
	s_addc_u32 s29, s48, s29
	s_and_b64 s[66:67], s[6:7], exec
	s_cselect_b32 s66, s29, s45
	s_cselect_b32 s67, s28, s44
	s_lshl_b32 s23, s30, 8
	v_add_u32_e32 v0, s23, v148
	s_add_u32 s68, s44, 0x100
	v_ashrrev_i32_e32 v1, 31, v0
	s_addc_u32 s69, s45, 0
	v_lshl_add_u64 v[144:145], v[0:1], 4, s[12:13]
	s_add_u32 s30, s46, 0x40080
	s_addc_u32 s31, s47, 0
	s_mov_b32 s70, -2
	s_mov_b64 s[44:45], 0
	s_cmp_eq_u32 s56, 1
	s_cbranch_scc1 .Lfa_10
	v_add_u32_e32 v153, s61, v147
	ds_read_b128 v[160:163], v153
	v_xor_b32_e32 v253, 64, v153
	ds_read_b128 v[164:167], v253
	ds_read_b128 v[168:171], v153 offset:2048
	ds_read_b128 v[172:175], v253 offset:2048
	v_add_u32_e32 v153, s62, v147
	ds_read_b128 v[176:179], v153
	v_xor_b32_e32 v253, 64, v153
	ds_read_b128 v[180:183], v253
	ds_read_b128 v[184:187], v153 offset:2048
	ds_read_b128 v[188:191], v253 offset:2048
	s_add_u32 s46, s30, 0xfffc0080
	s_addc_u32 s47, s31, -1
	s_and_b64 s[44:45], s[44:45], exec
	s_cselect_b32 s47, s25, s47
	s_cselect_b32 s46, s65, s46
	s_cselect_b32 s45, s66, s69
	s_cselect_b32 s44, s67, s68
	v_lshl_add_u64 v[154:155], s[30:31], 0, v[138:139]
	s_add_i32 m0, s52, 0xc000
	ds_read_b128 v[192:195], v150
	v_xor_b32_e32 v253, 64, v150
	ds_read_b128 v[196:199], v253
	ds_read_b128 v[200:203], v150 offset:2048
	ds_read_b128 v[204:207], v253 offset:2048
	ds_read_b128 v[208:211], v150 offset:4096
	ds_read_b128 v[212:215], v253 offset:4096
	ds_read_b128 v[216:219], v150 offset:6144
	ds_read_b128 v[220:223], v253 offset:6144
	global_load_lds_dwordx4 v[154:155], off
	v_lshl_add_u64 v[154:155], s[30:31], 0, v[136:137]
	s_add_i32 m0, s52, 0xe000
	s_nop 0
	global_load_lds_dwordx4 v[154:155], off
	s_waitcnt vmcnt(16)
	s_waitcnt lgkmcnt(0)
	s_barrier
	s_setprio 1
	s_waitcnt lgkmcnt(0)
	v_mfma_f32_16x16x32_bf16 v[124:127], v[160:163], v[192:195], 0
	v_mfma_f32_16x16x32_bf16 v[116:119], v[168:171], v[192:195], 0
	v_mfma_f32_16x16x32_bf16 v[108:111], v[160:163], v[200:203], 0
	v_mfma_f32_16x16x32_bf16 v[100:103], v[168:171], v[200:203], 0
	v_mfma_f32_16x16x32_bf16 v[92:95], v[160:163], v[208:211], 0
	v_mfma_f32_16x16x32_bf16 v[84:87], v[168:171], v[208:211], 0
	v_mfma_f32_16x16x32_bf16 v[76:79], v[160:163], v[216:219], 0
	v_mfma_f32_16x16x32_bf16 v[68:71], v[168:171], v[216:219], 0
	v_mfma_f32_16x16x32_bf16 v[124:127], v[164:167], v[196:199], v[124:127]
	v_mfma_f32_16x16x32_bf16 v[116:119], v[172:175], v[196:199], v[116:119]
	v_mfma_f32_16x16x32_bf16 v[108:111], v[164:167], v[204:207], v[108:111]
	v_mfma_f32_16x16x32_bf16 v[100:103], v[172:175], v[204:207], v[100:103]
	v_mfma_f32_16x16x32_bf16 v[92:95], v[164:167], v[212:215], v[92:95]
	v_mfma_f32_16x16x32_bf16 v[84:87], v[172:175], v[212:215], v[84:87]
	v_mfma_f32_16x16x32_bf16 v[76:79], v[164:167], v[220:223], v[76:79]
	v_mfma_f32_16x16x32_bf16 v[68:71], v[172:175], v[220:223], v[68:71]
	s_setprio 0
	s_setprio 1
	v_mfma_f32_16x16x32_bf16 v[120:123], v[176:179], v[192:195], 0
	v_mfma_f32_16x16x32_bf16 v[112:115], v[184:187], v[192:195], 0
	v_mfma_f32_16x16x32_bf16 v[104:107], v[176:179], v[200:203], 0
	v_mfma_f32_16x16x32_bf16 v[96:99], v[184:187], v[200:203], 0
	v_mfma_f32_16x16x32_bf16 v[88:91], v[176:179], v[208:211], 0
	v_mfma_f32_16x16x32_bf16 v[80:83], v[184:187], v[208:211], 0
	v_mfma_f32_16x16x32_bf16 v[72:75], v[176:179], v[216:219], 0
	v_mfma_f32_16x16x32_bf16 v[64:67], v[184:187], v[216:219], 0
	v_mfma_f32_16x16x32_bf16 v[120:123], v[180:183], v[196:199], v[120:123]
	v_mfma_f32_16x16x32_bf16 v[112:115], v[188:191], v[196:199], v[112:115]
	v_mfma_f32_16x16x32_bf16 v[104:107], v[180:183], v[204:207], v[104:107]
	v_mfma_f32_16x16x32_bf16 v[96:99], v[188:191], v[204:207], v[96:99]
	v_mfma_f32_16x16x32_bf16 v[88:91], v[180:183], v[212:215], v[88:91]
	v_mfma_f32_16x16x32_bf16 v[80:83], v[188:191], v[212:215], v[80:83]
	v_mfma_f32_16x16x32_bf16 v[72:75], v[180:183], v[220:223], v[72:75]
	v_mfma_f32_16x16x32_bf16 v[64:67], v[188:191], v[220:223], v[64:67]
	s_setprio 0
	s_barrier
	s_add_i32 s71, s61, s49
	v_lshl_add_u64 v[154:155], s[44:45], 0, v[132:133]
	s_mov_b32 m0, s71
	ds_read_b128 v[192:195], v150 offset:16384
	v_xor_b32_e32 v253, 64, v150
	ds_read_b128 v[196:199], v253 offset:16384
	ds_read_b128 v[200:203], v150 offset:18432
	ds_read_b128 v[204:207], v253 offset:18432
	ds_read_b128 v[208:211], v150 offset:20480
	ds_read_b128 v[212:215], v253 offset:20480
	ds_read_b128 v[216:219], v150 offset:22528
	ds_read_b128 v[220:223], v253 offset:22528
	global_load_lds_dwordx4 v[154:155], off
	s_add_i32 m0, s71, 0x2000
	s_add_u32 s72, s44, 0x40000
	v_lshl_add_u64 v[224:225], s[44:45], 0, v[128:129]
	s_addc_u32 s73, s45, 0
	s_add_i32 s71, s62, s49
	global_load_lds_dwordx4 v[224:225], off
	v_lshl_add_u64 v[226:227], s[72:73], 0, v[132:133]
	s_mov_b32 m0, s71
	v_lshl_add_u64 v[228:229], s[46:47], 0, v[130:131]
	global_load_lds_dwordx4 v[226:227], off
	v_lshl_add_u64 v[226:227], s[72:73], 0, v[128:129]
	s_add_i32 m0, s71, 0x2000
	s_nop 0
	global_load_lds_dwordx4 v[226:227], off
	v_lshl_add_u64 v[226:227], s[46:47], 0, v[134:135]
	s_mov_b32 m0, s52
	s_nop 0
	global_load_lds_dwordx4 v[226:227], off
	s_mov_b32 m0, s53
	s_nop 0
	global_load_lds_dwordx4 v[228:229], off
	s_waitcnt vmcnt(16)
	s_waitcnt lgkmcnt(0)
	s_barrier
	s_setprio 1
	s_waitcnt lgkmcnt(0)
	v_mfma_f32_16x16x32_bf16 v[60:63], v[160:163], v[192:195], 0
	v_mfma_f32_16x16x32_bf16 v[52:55], v[168:171], v[192:195], 0
	v_mfma_f32_16x16x32_bf16 v[44:47], v[160:163], v[200:203], 0
	v_mfma_f32_16x16x32_bf16 v[36:39], v[168:171], v[200:203], 0
	v_mfma_f32_16x16x32_bf16 v[28:31], v[160:163], v[208:211], 0
	v_mfma_f32_16x16x32_bf16 v[20:23], v[168:171], v[208:211], 0
	v_mfma_f32_16x16x32_bf16 v[12:15], v[160:163], v[216:219], 0
	v_mfma_f32_16x16x32_bf16 v[4:7], v[168:171], v[216:219], 0
	v_mfma_f32_16x16x32_bf16 v[60:63], v[164:167], v[196:199], v[60:63]
	v_mfma_f32_16x16x32_bf16 v[52:55], v[172:175], v[196:199], v[52:55]
	v_mfma_f32_16x16x32_bf16 v[44:47], v[164:167], v[204:207], v[44:47]
	v_mfma_f32_16x16x32_bf16 v[36:39], v[172:175], v[204:207], v[36:39]
	v_mfma_f32_16x16x32_bf16 v[28:31], v[164:167], v[212:215], v[28:31]
	v_mfma_f32_16x16x32_bf16 v[20:23], v[172:175], v[212:215], v[20:23]
	v_mfma_f32_16x16x32_bf16 v[12:15], v[164:167], v[220:223], v[12:15]
	v_mfma_f32_16x16x32_bf16 v[4:7], v[172:175], v[220:223], v[4:7]
	s_setprio 0
	s_setprio 1
	v_mfma_f32_16x16x32_bf16 v[56:59], v[176:179], v[192:195], 0
	v_mfma_f32_16x16x32_bf16 v[48:51], v[184:187], v[192:195], 0
	v_mfma_f32_16x16x32_bf16 v[40:43], v[176:179], v[200:203], 0
	v_mfma_f32_16x16x32_bf16 v[32:35], v[184:187], v[200:203], 0
	v_mfma_f32_16x16x32_bf16 v[24:27], v[176:179], v[208:211], 0
	v_mfma_f32_16x16x32_bf16 v[16:19], v[184:187], v[208:211], 0
	v_mfma_f32_16x16x32_bf16 v[8:11], v[176:179], v[216:219], 0
	v_mfma_f32_16x16x32_bf16 v[0:3], v[184:187], v[216:219], 0
	v_mfma_f32_16x16x32_bf16 v[56:59], v[180:183], v[196:199], v[56:59]
	v_mfma_f32_16x16x32_bf16 v[48:51], v[188:191], v[196:199], v[48:51]
	v_mfma_f32_16x16x32_bf16 v[40:43], v[180:183], v[204:207], v[40:43]
	v_mfma_f32_16x16x32_bf16 v[32:35], v[188:191], v[204:207], v[32:35]
	v_mfma_f32_16x16x32_bf16 v[24:27], v[180:183], v[212:215], v[24:27]
	v_mfma_f32_16x16x32_bf16 v[16:19], v[188:191], v[212:215], v[16:19]
	v_mfma_f32_16x16x32_bf16 v[8:11], v[180:183], v[220:223], v[8:11]
	v_mfma_f32_16x16x32_bf16 v[0:3], v[188:191], v[220:223], v[0:3]
	s_setprio 0
	s_barrier
	s_add_i32 s71, 0, 0x18000
	v_add_u32_e32 v153, s71, v147
	s_add_i32 s72, 0, 0x1c000
	ds_read_b128 v[160:163], v153
	v_xor_b32_e32 v253, 64, v153
	ds_read_b128 v[164:167], v253
	ds_read_b128 v[168:171], v153 offset:2048
	ds_read_b128 v[172:175], v253 offset:2048
	v_add_u32_e32 v153, s72, v147
	ds_read_b128 v[176:179], v153
	v_xor_b32_e32 v253, 64, v153
	ds_read_b128 v[180:183], v253
	ds_read_b128 v[184:187], v153 offset:2048
	ds_read_b128 v[188:191], v253 offset:2048
	s_add_u32 s46, s46, 0x40000
	s_addc_u32 s47, s47, 0
	s_mov_b32 m0, s54
	v_lshl_add_u64 v[230:231], s[46:47], 0, v[134:135]
	ds_read_b128 v[192:195], v150 offset:32768
	v_xor_b32_e32 v253, 64, v150
	ds_read_b128 v[196:199], v253 offset:32768
	ds_read_b128 v[200:203], v150 offset:34816
	ds_read_b128 v[204:207], v253 offset:34816
	ds_read_b128 v[208:211], v150 offset:36864
	ds_read_b128 v[212:215], v253 offset:36864
	ds_read_b128 v[216:219], v150 offset:38912
	ds_read_b128 v[220:223], v253 offset:38912
	global_load_lds_dwordx4 v[230:231], off
	v_lshl_add_u64 v[230:231], s[46:47], 0, v[130:131]
	s_mov_b32 m0, s55
	s_nop 0
	global_load_lds_dwordx4 v[230:231], off
	s_waitcnt vmcnt(8)
	s_waitcnt lgkmcnt(0)
	s_barrier
	s_setprio 1
	s_waitcnt lgkmcnt(0)
	v_mfma_f32_16x16x32_bf16 v[124:127], v[160:163], v[192:195], v[124:127]
	v_mfma_f32_16x16x32_bf16 v[124:127], v[164:167], v[196:199], v[124:127]
	v_mfma_f32_16x16x32_bf16 v[108:111], v[164:167], v[204:207], v[108:111]
	v_mfma_f32_16x16x32_bf16 v[108:111], v[160:163], v[200:203], v[108:111]
	v_mfma_f32_16x16x32_bf16 v[92:95], v[160:163], v[208:211], v[92:95]
	v_mfma_f32_16x16x32_bf16 v[92:95], v[164:167], v[212:215], v[92:95]
	v_mfma_f32_16x16x32_bf16 v[76:79], v[164:167], v[220:223], v[76:79]
	v_mfma_f32_16x16x32_bf16 v[76:79], v[160:163], v[216:219], v[76:79]
	v_mfma_f32_16x16x32_bf16 v[68:71], v[168:171], v[216:219], v[68:71]
	v_mfma_f32_16x16x32_bf16 v[68:71], v[172:175], v[220:223], v[68:71]
	v_mfma_f32_16x16x32_bf16 v[84:87], v[172:175], v[212:215], v[84:87]
	v_mfma_f32_16x16x32_bf16 v[84:87], v[168:171], v[208:211], v[84:87]
	v_mfma_f32_16x16x32_bf16 v[100:103], v[168:171], v[200:203], v[100:103]
	v_mfma_f32_16x16x32_bf16 v[100:103], v[172:175], v[204:207], v[100:103]
	v_mfma_f32_16x16x32_bf16 v[116:119], v[172:175], v[196:199], v[116:119]
	v_mfma_f32_16x16x32_bf16 v[116:119], v[168:171], v[192:195], v[116:119]
	s_setprio 0
	s_setprio 1
	v_mfma_f32_16x16x32_bf16 v[120:123], v[176:179], v[192:195], v[120:123]
	v_mfma_f32_16x16x32_bf16 v[120:123], v[180:183], v[196:199], v[120:123]
	v_mfma_f32_16x16x32_bf16 v[104:107], v[180:183], v[204:207], v[104:107]
	v_mfma_f32_16x16x32_bf16 v[104:107], v[176:179], v[200:203], v[104:107]
	v_mfma_f32_16x16x32_bf16 v[88:91], v[176:179], v[208:211], v[88:91]
	v_mfma_f32_16x16x32_bf16 v[88:91], v[180:183], v[212:215], v[88:91]
	v_mfma_f32_16x16x32_bf16 v[72:75], v[180:183], v[220:223], v[72:75]
	v_mfma_f32_16x16x32_bf16 v[72:75], v[176:179], v[216:219], v[72:75]
	v_mfma_f32_16x16x32_bf16 v[64:67], v[184:187], v[216:219], v[64:67]
	v_mfma_f32_16x16x32_bf16 v[64:67], v[188:191], v[220:223], v[64:67]
	v_mfma_f32_16x16x32_bf16 v[80:83], v[188:191], v[212:215], v[80:83]
	v_mfma_f32_16x16x32_bf16 v[80:83], v[184:187], v[208:211], v[80:83]
	v_mfma_f32_16x16x32_bf16 v[96:99], v[184:187], v[200:203], v[96:99]
	v_mfma_f32_16x16x32_bf16 v[96:99], v[188:191], v[204:207], v[96:99]
	v_mfma_f32_16x16x32_bf16 v[112:115], v[188:191], v[196:199], v[112:115]
	v_mfma_f32_16x16x32_bf16 v[112:115], v[184:187], v[192:195], v[112:115]
	s_setprio 0
	s_barrier
	s_add_i32 s46, s71, s49
	v_lshl_add_u64 v[154:155], v[154:155], 0, s[14:15]
	s_mov_b32 m0, s46
	ds_read_b128 v[192:195], v150 offset:49152
	v_xor_b32_e32 v253, 64, v150
	ds_read_b128 v[196:199], v253 offset:49152
	ds_read_b128 v[200:203], v150 offset:51200
	ds_read_b128 v[204:207], v253 offset:51200
	ds_read_b128 v[208:211], v150 offset:53248
	ds_read_b128 v[212:215], v253 offset:53248
	ds_read_b128 v[216:219], v150 offset:55296
	ds_read_b128 v[220:223], v253 offset:55296
	global_load_lds_dwordx4 v[154:155], off
	s_add_i32 m0, s46, 0x2000
	s_add_u32 s44, s44, 0x40080
	v_lshl_add_u64 v[154:155], v[224:225], 0, s[14:15]
	s_addc_u32 s45, s45, 0
	s_add_i32 s46, s72, s49
	global_load_lds_dwordx4 v[154:155], off
	v_lshl_add_u64 v[154:155], s[44:45], 0, v[132:133]
	s_mov_b32 m0, s46
	s_nop 0
	global_load_lds_dwordx4 v[154:155], off
	v_lshl_add_u64 v[154:155], s[44:45], 0, v[128:129]
	s_add_i32 m0, s46, 0x2000
	s_nop 0
	global_load_lds_dwordx4 v[154:155], off
	v_lshl_add_u64 v[154:155], v[226:227], 0, s[14:15]
	s_mov_b32 m0, s57
	s_nop 0
	global_load_lds_dwordx4 v[154:155], off
	v_lshl_add_u64 v[154:155], v[228:229], 0, s[14:15]
	s_mov_b32 m0, s58
	s_nop 0
	global_load_lds_dwordx4 v[154:155], off
	s_waitcnt vmcnt(8)
	s_waitcnt lgkmcnt(0)
	s_barrier
	s_setprio 1
	s_waitcnt lgkmcnt(0)
	v_mfma_f32_16x16x32_bf16 v[60:63], v[160:163], v[192:195], v[60:63]
	v_mfma_f32_16x16x32_bf16 v[60:63], v[164:167], v[196:199], v[60:63]
	v_mfma_f32_16x16x32_bf16 v[44:47], v[164:167], v[204:207], v[44:47]
	v_mfma_f32_16x16x32_bf16 v[44:47], v[160:163], v[200:203], v[44:47]
	v_mfma_f32_16x16x32_bf16 v[28:31], v[160:163], v[208:211], v[28:31]
	v_mfma_f32_16x16x32_bf16 v[28:31], v[164:167], v[212:215], v[28:31]
	v_mfma_f32_16x16x32_bf16 v[12:15], v[164:167], v[220:223], v[12:15]
	v_mfma_f32_16x16x32_bf16 v[12:15], v[160:163], v[216:219], v[12:15]
	v_mfma_f32_16x16x32_bf16 v[4:7], v[168:171], v[216:219], v[4:7]
	v_mfma_f32_16x16x32_bf16 v[4:7], v[172:175], v[220:223], v[4:7]
	v_mfma_f32_16x16x32_bf16 v[20:23], v[172:175], v[212:215], v[20:23]
	v_mfma_f32_16x16x32_bf16 v[20:23], v[168:171], v[208:211], v[20:23]
	v_mfma_f32_16x16x32_bf16 v[36:39], v[168:171], v[200:203], v[36:39]
	v_mfma_f32_16x16x32_bf16 v[36:39], v[172:175], v[204:207], v[36:39]
	v_mfma_f32_16x16x32_bf16 v[52:55], v[172:175], v[196:199], v[52:55]
	v_mfma_f32_16x16x32_bf16 v[52:55], v[168:171], v[192:195], v[52:55]
	s_setprio 0
	s_setprio 1
	v_mfma_f32_16x16x32_bf16 v[56:59], v[176:179], v[192:195], v[56:59]
	v_mfma_f32_16x16x32_bf16 v[56:59], v[180:183], v[196:199], v[56:59]
	v_mfma_f32_16x16x32_bf16 v[40:43], v[180:183], v[204:207], v[40:43]
	v_mfma_f32_16x16x32_bf16 v[40:43], v[176:179], v[200:203], v[40:43]
	v_mfma_f32_16x16x32_bf16 v[24:27], v[176:179], v[208:211], v[24:27]
	v_mfma_f32_16x16x32_bf16 v[24:27], v[180:183], v[212:215], v[24:27]
	v_mfma_f32_16x16x32_bf16 v[8:11], v[180:183], v[220:223], v[8:11]
	v_mfma_f32_16x16x32_bf16 v[8:11], v[176:179], v[216:219], v[8:11]
	v_mfma_f32_16x16x32_bf16 v[0:3], v[184:187], v[216:219], v[0:3]
	v_mfma_f32_16x16x32_bf16 v[0:3], v[188:191], v[220:223], v[0:3]
	v_mfma_f32_16x16x32_bf16 v[16:19], v[188:191], v[212:215], v[16:19]
	v_mfma_f32_16x16x32_bf16 v[16:19], v[184:187], v[208:211], v[16:19]
	v_mfma_f32_16x16x32_bf16 v[32:35], v[184:187], v[200:203], v[32:35]
	v_mfma_f32_16x16x32_bf16 v[32:35], v[188:191], v[204:207], v[32:35]
	v_mfma_f32_16x16x32_bf16 v[48:51], v[188:191], v[196:199], v[48:51]
	v_mfma_f32_16x16x32_bf16 v[48:51], v[184:187], v[192:195], v[48:51]
	s_setprio 0
	s_barrier
	s_add_i32 s70, s70, 2
	s_add_u32 s68, s68, 0x100
	s_addc_u32 s69, s69, 0
	s_add_u32 s30, s30, 0x100
	s_addc_u32 s31, s31, 0
	s_branch .LBB0_1098
.Lfa_10:
	v_add_u32_e32 v153, s61, v147
	ds_read_b128 v[160:163], v153
	v_xor_b32_e32 v253, 64, v153
	ds_read_b128 v[164:167], v253
	ds_read_b128 v[168:171], v153 offset:2048
	ds_read_b128 v[172:175], v253 offset:2048
	v_add_u32_e32 v153, s62, v147
	ds_read_b128 v[176:179], v153
	v_xor_b32_e32 v253, 64, v153
	ds_read_b128 v[180:183], v253
	ds_read_b128 v[184:187], v153 offset:2048
	ds_read_b128 v[188:191], v253 offset:2048
	s_add_u32 s46, s30, 0xfffc0080
	s_addc_u32 s47, s31, -1
	s_and_b64 s[44:45], s[44:45], exec
	s_cselect_b32 s47, s25, s47
	s_cselect_b32 s46, s65, s46
	s_cselect_b32 s45, s66, s69
	s_cselect_b32 s44, s67, s68
	v_lshl_add_u64 v[154:155], s[30:31], 0, v[138:139]
	s_add_i32 m0, s52, 0xc000
	ds_read_b128 v[192:195], v150
	v_xor_b32_e32 v253, 64, v150
	ds_read_b128 v[196:199], v253
	ds_read_b128 v[200:203], v150 offset:2048
	ds_read_b128 v[204:207], v253 offset:2048
	ds_read_b128 v[208:211], v150 offset:4096
	ds_read_b128 v[212:215], v253 offset:4096
	ds_read_b128 v[216:219], v150 offset:6144
	ds_read_b128 v[220:223], v253 offset:6144
	global_load_lds_dwordx4 v[154:155], off
	v_lshl_add_u64 v[154:155], s[30:31], 0, v[136:137]
	s_add_i32 m0, s52, 0xe000
	s_nop 0
	global_load_lds_dwordx4 v[154:155], off
	s_waitcnt vmcnt(8)
	s_waitcnt lgkmcnt(0)
	s_barrier
	s_setprio 1
	s_waitcnt lgkmcnt(0)
	v_mfma_f32_16x16x32_bf16 v[124:127], v[160:163], v[192:195], 0
	v_mfma_f32_16x16x32_bf16 v[116:119], v[168:171], v[192:195], 0
	v_mfma_f32_16x16x32_bf16 v[108:111], v[160:163], v[200:203], 0
	v_mfma_f32_16x16x32_bf16 v[100:103], v[168:171], v[200:203], 0
	v_mfma_f32_16x16x32_bf16 v[92:95], v[160:163], v[208:211], 0
	v_mfma_f32_16x16x32_bf16 v[84:87], v[168:171], v[208:211], 0
	v_mfma_f32_16x16x32_bf16 v[76:79], v[160:163], v[216:219], 0
	v_mfma_f32_16x16x32_bf16 v[68:71], v[168:171], v[216:219], 0
	v_mfma_f32_16x16x32_bf16 v[124:127], v[164:167], v[196:199], v[124:127]
	v_mfma_f32_16x16x32_bf16 v[116:119], v[172:175], v[196:199], v[116:119]
	v_mfma_f32_16x16x32_bf16 v[108:111], v[164:167], v[204:207], v[108:111]
	v_mfma_f32_16x16x32_bf16 v[100:103], v[172:175], v[204:207], v[100:103]
	v_mfma_f32_16x16x32_bf16 v[92:95], v[164:167], v[212:215], v[92:95]
	v_mfma_f32_16x16x32_bf16 v[84:87], v[172:175], v[212:215], v[84:87]
	v_mfma_f32_16x16x32_bf16 v[76:79], v[164:167], v[220:223], v[76:79]
	v_mfma_f32_16x16x32_bf16 v[68:71], v[172:175], v[220:223], v[68:71]
	s_setprio 0
	s_setprio 1
	v_mfma_f32_16x16x32_bf16 v[120:123], v[176:179], v[192:195], 0
	v_mfma_f32_16x16x32_bf16 v[112:115], v[184:187], v[192:195], 0
	v_mfma_f32_16x16x32_bf16 v[104:107], v[176:179], v[200:203], 0
	v_mfma_f32_16x16x32_bf16 v[96:99], v[184:187], v[200:203], 0
	v_mfma_f32_16x16x32_bf16 v[88:91], v[176:179], v[208:211], 0
	v_mfma_f32_16x16x32_bf16 v[80:83], v[184:187], v[208:211], 0
	v_mfma_f32_16x16x32_bf16 v[72:75], v[176:179], v[216:219], 0
	v_mfma_f32_16x16x32_bf16 v[64:67], v[184:187], v[216:219], 0
	v_mfma_f32_16x16x32_bf16 v[120:123], v[180:183], v[196:199], v[120:123]
	v_mfma_f32_16x16x32_bf16 v[112:115], v[188:191], v[196:199], v[112:115]
	v_mfma_f32_16x16x32_bf16 v[104:107], v[180:183], v[204:207], v[104:107]
	v_mfma_f32_16x16x32_bf16 v[96:99], v[188:191], v[204:207], v[96:99]
	v_mfma_f32_16x16x32_bf16 v[88:91], v[180:183], v[212:215], v[88:91]
	v_mfma_f32_16x16x32_bf16 v[80:83], v[188:191], v[212:215], v[80:83]
	v_mfma_f32_16x16x32_bf16 v[72:75], v[180:183], v[220:223], v[72:75]
	v_mfma_f32_16x16x32_bf16 v[64:67], v[188:191], v[220:223], v[64:67]
	s_setprio 0
	s_barrier
	s_add_i32 s71, s61, s49
	v_lshl_add_u64 v[154:155], s[44:45], 0, v[132:133]
	s_mov_b32 m0, s71
	ds_read_b128 v[192:195], v150 offset:16384
	v_xor_b32_e32 v253, 64, v150
	ds_read_b128 v[196:199], v253 offset:16384
	ds_read_b128 v[200:203], v150 offset:18432
	ds_read_b128 v[204:207], v253 offset:18432
	ds_read_b128 v[208:211], v150 offset:20480
	ds_read_b128 v[212:215], v253 offset:20480
	ds_read_b128 v[216:219], v150 offset:22528
	ds_read_b128 v[220:223], v253 offset:22528
	global_load_lds_dwordx4 v[154:155], off
	s_add_i32 m0, s71, 0x2000
	s_add_u32 s72, s44, 0x40000
	v_lshl_add_u64 v[224:225], s[44:45], 0, v[128:129]
	s_addc_u32 s73, s45, 0
	s_add_i32 s71, s62, s49
	global_load_lds_dwordx4 v[224:225], off
	v_lshl_add_u64 v[226:227], s[72:73], 0, v[132:133]
	s_mov_b32 m0, s71
	v_lshl_add_u64 v[228:229], s[46:47], 0, v[130:131]
	global_load_lds_dwordx4 v[226:227], off
	v_lshl_add_u64 v[226:227], s[72:73], 0, v[128:129]
	s_add_i32 m0, s71, 0x2000
	s_nop 0
	global_load_lds_dwordx4 v[226:227], off
	v_lshl_add_u64 v[226:227], s[46:47], 0, v[134:135]
	s_mov_b32 m0, s52
	s_nop 0
	global_load_lds_dwordx4 v[226:227], off
	s_mov_b32 m0, s53
	s_nop 0
	global_load_lds_dwordx4 v[228:229], off
	s_waitcnt vmcnt(8)
	s_waitcnt lgkmcnt(0)
	s_barrier
	s_setprio 1
	s_waitcnt lgkmcnt(0)
	v_mfma_f32_16x16x32_bf16 v[60:63], v[160:163], v[192:195], 0
	v_mfma_f32_16x16x32_bf16 v[52:55], v[168:171], v[192:195], 0
	v_mfma_f32_16x16x32_bf16 v[44:47], v[160:163], v[200:203], 0
	v_mfma_f32_16x16x32_bf16 v[36:39], v[168:171], v[200:203], 0
	v_mfma_f32_16x16x32_bf16 v[28:31], v[160:163], v[208:211], 0
	v_mfma_f32_16x16x32_bf16 v[20:23], v[168:171], v[208:211], 0
	v_mfma_f32_16x16x32_bf16 v[12:15], v[160:163], v[216:219], 0
	v_mfma_f32_16x16x32_bf16 v[4:7], v[168:171], v[216:219], 0
	v_mfma_f32_16x16x32_bf16 v[60:63], v[164:167], v[196:199], v[60:63]
	v_mfma_f32_16x16x32_bf16 v[52:55], v[172:175], v[196:199], v[52:55]
	v_mfma_f32_16x16x32_bf16 v[44:47], v[164:167], v[204:207], v[44:47]
	v_mfma_f32_16x16x32_bf16 v[36:39], v[172:175], v[204:207], v[36:39]
	v_mfma_f32_16x16x32_bf16 v[28:31], v[164:167], v[212:215], v[28:31]
	v_mfma_f32_16x16x32_bf16 v[20:23], v[172:175], v[212:215], v[20:23]
	v_mfma_f32_16x16x32_bf16 v[12:15], v[164:167], v[220:223], v[12:15]
	v_mfma_f32_16x16x32_bf16 v[4:7], v[172:175], v[220:223], v[4:7]
	s_setprio 0
	s_setprio 1
	v_mfma_f32_16x16x32_bf16 v[56:59], v[176:179], v[192:195], 0
	v_mfma_f32_16x16x32_bf16 v[48:51], v[184:187], v[192:195], 0
	v_mfma_f32_16x16x32_bf16 v[40:43], v[176:179], v[200:203], 0
	v_mfma_f32_16x16x32_bf16 v[32:35], v[184:187], v[200:203], 0
	v_mfma_f32_16x16x32_bf16 v[24:27], v[176:179], v[208:211], 0
	v_mfma_f32_16x16x32_bf16 v[16:19], v[184:187], v[208:211], 0
	v_mfma_f32_16x16x32_bf16 v[8:11], v[176:179], v[216:219], 0
	v_mfma_f32_16x16x32_bf16 v[0:3], v[184:187], v[216:219], 0
	v_mfma_f32_16x16x32_bf16 v[56:59], v[180:183], v[196:199], v[56:59]
	v_mfma_f32_16x16x32_bf16 v[48:51], v[188:191], v[196:199], v[48:51]
	v_mfma_f32_16x16x32_bf16 v[40:43], v[180:183], v[204:207], v[40:43]
	v_mfma_f32_16x16x32_bf16 v[32:35], v[188:191], v[204:207], v[32:35]
	v_mfma_f32_16x16x32_bf16 v[24:27], v[180:183], v[212:215], v[24:27]
	v_mfma_f32_16x16x32_bf16 v[16:19], v[188:191], v[212:215], v[16:19]
	v_mfma_f32_16x16x32_bf16 v[8:11], v[180:183], v[220:223], v[8:11]
	v_mfma_f32_16x16x32_bf16 v[0:3], v[188:191], v[220:223], v[0:3]
	s_setprio 0
	s_barrier
	s_add_i32 s71, 0, 0x18000
	v_add_u32_e32 v153, s71, v147
	s_add_i32 s72, 0, 0x1c000
	ds_read_b128 v[160:163], v153
	v_xor_b32_e32 v253, 64, v153
	ds_read_b128 v[164:167], v253
	ds_read_b128 v[168:171], v153 offset:2048
	ds_read_b128 v[172:175], v253 offset:2048
	v_add_u32_e32 v153, s72, v147
	ds_read_b128 v[176:179], v153
	v_xor_b32_e32 v253, 64, v153
	ds_read_b128 v[180:183], v253
	ds_read_b128 v[184:187], v153 offset:2048
	ds_read_b128 v[188:191], v253 offset:2048
	s_add_u32 s46, s46, 0x40000
	s_addc_u32 s47, s47, 0
	s_mov_b32 m0, s54
	v_lshl_add_u64 v[230:231], s[46:47], 0, v[134:135]
	ds_read_b128 v[192:195], v150 offset:32768
	v_xor_b32_e32 v253, 64, v150
	ds_read_b128 v[196:199], v253 offset:32768
	ds_read_b128 v[200:203], v150 offset:34816
	ds_read_b128 v[204:207], v253 offset:34816
	ds_read_b128 v[208:211], v150 offset:36864
	ds_read_b128 v[212:215], v253 offset:36864
	ds_read_b128 v[216:219], v150 offset:38912
	ds_read_b128 v[220:223], v253 offset:38912
	global_load_lds_dwordx4 v[230:231], off
	v_lshl_add_u64 v[230:231], s[46:47], 0, v[130:131]
	s_mov_b32 m0, s55
	s_nop 0
	global_load_lds_dwordx4 v[230:231], off
	s_waitcnt vmcnt(8)
	s_waitcnt lgkmcnt(0)
	s_barrier
	s_setprio 1
	s_waitcnt lgkmcnt(0)
	v_mfma_f32_16x16x32_bf16 v[124:127], v[160:163], v[192:195], v[124:127]
	v_mfma_f32_16x16x32_bf16 v[124:127], v[164:167], v[196:199], v[124:127]
	v_mfma_f32_16x16x32_bf16 v[108:111], v[164:167], v[204:207], v[108:111]
	v_mfma_f32_16x16x32_bf16 v[108:111], v[160:163], v[200:203], v[108:111]
	v_mfma_f32_16x16x32_bf16 v[92:95], v[160:163], v[208:211], v[92:95]
	v_mfma_f32_16x16x32_bf16 v[92:95], v[164:167], v[212:215], v[92:95]
	v_mfma_f32_16x16x32_bf16 v[76:79], v[164:167], v[220:223], v[76:79]
	v_mfma_f32_16x16x32_bf16 v[76:79], v[160:163], v[216:219], v[76:79]
	v_mfma_f32_16x16x32_bf16 v[68:71], v[168:171], v[216:219], v[68:71]
	v_mfma_f32_16x16x32_bf16 v[68:71], v[172:175], v[220:223], v[68:71]
	v_mfma_f32_16x16x32_bf16 v[84:87], v[172:175], v[212:215], v[84:87]
	v_mfma_f32_16x16x32_bf16 v[84:87], v[168:171], v[208:211], v[84:87]
	v_mfma_f32_16x16x32_bf16 v[100:103], v[168:171], v[200:203], v[100:103]
	v_mfma_f32_16x16x32_bf16 v[100:103], v[172:175], v[204:207], v[100:103]
	v_mfma_f32_16x16x32_bf16 v[116:119], v[172:175], v[196:199], v[116:119]
	v_mfma_f32_16x16x32_bf16 v[116:119], v[168:171], v[192:195], v[116:119]
	s_setprio 0
	s_setprio 1
	v_mfma_f32_16x16x32_bf16 v[120:123], v[176:179], v[192:195], v[120:123]
	v_mfma_f32_16x16x32_bf16 v[120:123], v[180:183], v[196:199], v[120:123]
	v_mfma_f32_16x16x32_bf16 v[104:107], v[180:183], v[204:207], v[104:107]
	v_mfma_f32_16x16x32_bf16 v[104:107], v[176:179], v[200:203], v[104:107]
	v_mfma_f32_16x16x32_bf16 v[88:91], v[176:179], v[208:211], v[88:91]
	v_mfma_f32_16x16x32_bf16 v[88:91], v[180:183], v[212:215], v[88:91]
	v_mfma_f32_16x16x32_bf16 v[72:75], v[180:183], v[220:223], v[72:75]
	v_mfma_f32_16x16x32_bf16 v[72:75], v[176:179], v[216:219], v[72:75]
	v_mfma_f32_16x16x32_bf16 v[64:67], v[184:187], v[216:219], v[64:67]
	v_mfma_f32_16x16x32_bf16 v[64:67], v[188:191], v[220:223], v[64:67]
	v_mfma_f32_16x16x32_bf16 v[80:83], v[188:191], v[212:215], v[80:83]
	v_mfma_f32_16x16x32_bf16 v[80:83], v[184:187], v[208:211], v[80:83]
	v_mfma_f32_16x16x32_bf16 v[96:99], v[184:187], v[200:203], v[96:99]
	v_mfma_f32_16x16x32_bf16 v[96:99], v[188:191], v[204:207], v[96:99]
	v_mfma_f32_16x16x32_bf16 v[112:115], v[188:191], v[196:199], v[112:115]
	v_mfma_f32_16x16x32_bf16 v[112:115], v[184:187], v[192:195], v[112:115]
	s_setprio 0
	s_barrier
	s_add_i32 s46, s71, s49
	v_lshl_add_u64 v[154:155], v[154:155], 0, s[14:15]
	s_mov_b32 m0, s46
	ds_read_b128 v[192:195], v150 offset:49152
	v_xor_b32_e32 v253, 64, v150
	ds_read_b128 v[196:199], v253 offset:49152
	ds_read_b128 v[200:203], v150 offset:51200
	ds_read_b128 v[204:207], v253 offset:51200
	ds_read_b128 v[208:211], v150 offset:53248
	ds_read_b128 v[212:215], v253 offset:53248
	ds_read_b128 v[216:219], v150 offset:55296
	ds_read_b128 v[220:223], v253 offset:55296
	global_load_lds_dwordx4 v[154:155], off
	s_add_i32 m0, s46, 0x2000
	s_add_u32 s44, s44, 0x40080
	v_lshl_add_u64 v[154:155], v[224:225], 0, s[14:15]
	s_addc_u32 s45, s45, 0
	s_add_i32 s46, s72, s49
	global_load_lds_dwordx4 v[154:155], off
	v_lshl_add_u64 v[154:155], s[44:45], 0, v[132:133]
	s_mov_b32 m0, s46
	s_nop 0
	global_load_lds_dwordx4 v[154:155], off
	v_lshl_add_u64 v[154:155], s[44:45], 0, v[128:129]
	s_add_i32 m0, s46, 0x2000
	s_nop 0
	global_load_lds_dwordx4 v[154:155], off
	v_lshl_add_u64 v[154:155], v[226:227], 0, s[14:15]
	s_mov_b32 m0, s57
	s_nop 0
	global_load_lds_dwordx4 v[154:155], off
	v_lshl_add_u64 v[154:155], v[228:229], 0, s[14:15]
	s_mov_b32 m0, s58
	s_nop 0
	global_load_lds_dwordx4 v[154:155], off
	s_waitcnt vmcnt(8)
	s_waitcnt lgkmcnt(0)
	s_barrier
	s_setprio 1
	s_waitcnt lgkmcnt(0)
	v_mfma_f32_16x16x32_bf16 v[60:63], v[160:163], v[192:195], v[60:63]
	v_mfma_f32_16x16x32_bf16 v[60:63], v[164:167], v[196:199], v[60:63]
	v_mfma_f32_16x16x32_bf16 v[44:47], v[164:167], v[204:207], v[44:47]
	v_mfma_f32_16x16x32_bf16 v[44:47], v[160:163], v[200:203], v[44:47]
	v_mfma_f32_16x16x32_bf16 v[28:31], v[160:163], v[208:211], v[28:31]
	v_mfma_f32_16x16x32_bf16 v[28:31], v[164:167], v[212:215], v[28:31]
	v_mfma_f32_16x16x32_bf16 v[12:15], v[164:167], v[220:223], v[12:15]
	v_mfma_f32_16x16x32_bf16 v[12:15], v[160:163], v[216:219], v[12:15]
	v_mfma_f32_16x16x32_bf16 v[4:7], v[168:171], v[216:219], v[4:7]
	v_mfma_f32_16x16x32_bf16 v[4:7], v[172:175], v[220:223], v[4:7]
	v_mfma_f32_16x16x32_bf16 v[20:23], v[172:175], v[212:215], v[20:23]
	v_mfma_f32_16x16x32_bf16 v[20:23], v[168:171], v[208:211], v[20:23]
	v_mfma_f32_16x16x32_bf16 v[36:39], v[168:171], v[200:203], v[36:39]
	v_mfma_f32_16x16x32_bf16 v[36:39], v[172:175], v[204:207], v[36:39]
	v_mfma_f32_16x16x32_bf16 v[52:55], v[172:175], v[196:199], v[52:55]
	v_mfma_f32_16x16x32_bf16 v[52:55], v[168:171], v[192:195], v[52:55]
	s_setprio 0
	s_setprio 1
	v_mfma_f32_16x16x32_bf16 v[56:59], v[176:179], v[192:195], v[56:59]
	v_mfma_f32_16x16x32_bf16 v[56:59], v[180:183], v[196:199], v[56:59]
	v_mfma_f32_16x16x32_bf16 v[40:43], v[180:183], v[204:207], v[40:43]
	v_mfma_f32_16x16x32_bf16 v[40:43], v[176:179], v[200:203], v[40:43]
	v_mfma_f32_16x16x32_bf16 v[24:27], v[176:179], v[208:211], v[24:27]
	v_mfma_f32_16x16x32_bf16 v[24:27], v[180:183], v[212:215], v[24:27]
	v_mfma_f32_16x16x32_bf16 v[8:11], v[180:183], v[220:223], v[8:11]
	v_mfma_f32_16x16x32_bf16 v[8:11], v[176:179], v[216:219], v[8:11]
	v_mfma_f32_16x16x32_bf16 v[0:3], v[184:187], v[216:219], v[0:3]
	v_mfma_f32_16x16x32_bf16 v[0:3], v[188:191], v[220:223], v[0:3]
	v_mfma_f32_16x16x32_bf16 v[16:19], v[188:191], v[212:215], v[16:19]
	v_mfma_f32_16x16x32_bf16 v[16:19], v[184:187], v[208:211], v[16:19]
	v_mfma_f32_16x16x32_bf16 v[32:35], v[184:187], v[200:203], v[32:35]
	v_mfma_f32_16x16x32_bf16 v[32:35], v[188:191], v[204:207], v[32:35]
	v_mfma_f32_16x16x32_bf16 v[48:51], v[188:191], v[196:199], v[48:51]
	v_mfma_f32_16x16x32_bf16 v[48:51], v[184:187], v[192:195], v[48:51]
	s_setprio 0
	s_barrier
	s_add_i32 s70, s70, 2
	s_add_u32 s68, s68, 0x100
	s_addc_u32 s69, s69, 0
	s_add_u32 s30, s30, 0x100
	s_addc_u32 s31, s31, 0
	s_branch .LBB0_1098
.LBB0_1097:
	v_add_u32_e32 v153, s61, v147
	ds_read_b128 v[160:163], v153
	v_xor_b32_e32 v253, 64, v153
	ds_read_b128 v[164:167], v253
	ds_read_b128 v[168:171], v153 offset:2048
	ds_read_b128 v[172:175], v253 offset:2048
	v_add_u32_e32 v153, s62, v147
	ds_read_b128 v[176:179], v153
	v_xor_b32_e32 v253, 64, v153
	ds_read_b128 v[180:183], v253
	ds_read_b128 v[184:187], v153 offset:2048
	ds_read_b128 v[188:191], v253 offset:2048
	s_add_u32 s46, s30, 0xfffc0080
	s_addc_u32 s47, s31, -1
	s_and_b64 s[44:45], s[44:45], exec
	s_cselect_b32 s47, s25, s47
	s_cselect_b32 s46, s65, s46
	s_cselect_b32 s45, s66, s69
	s_cselect_b32 s44, s67, s68
	v_lshl_add_u64 v[154:155], s[30:31], 0, v[138:139]
	s_add_i32 m0, s52, 0xc000
	ds_read_b128 v[192:195], v150
	v_xor_b32_e32 v253, 64, v150
	ds_read_b128 v[196:199], v253
	ds_read_b128 v[200:203], v150 offset:2048
	ds_read_b128 v[204:207], v253 offset:2048
	ds_read_b128 v[208:211], v150 offset:4096
	ds_read_b128 v[212:215], v253 offset:4096
	ds_read_b128 v[216:219], v150 offset:6144
	ds_read_b128 v[220:223], v253 offset:6144
	global_load_lds_dwordx4 v[154:155], off
	v_lshl_add_u64 v[154:155], s[30:31], 0, v[136:137]
	s_add_i32 m0, s52, 0xe000
	s_nop 0
	global_load_lds_dwordx4 v[154:155], off
	s_waitcnt vmcnt(8)
	s_waitcnt lgkmcnt(0)
	s_barrier
	s_setprio 1
	s_waitcnt lgkmcnt(0)
	v_mfma_f32_16x16x32_bf16 v[124:127], v[160:163], v[192:195], v[124:127]
	v_mfma_f32_16x16x32_bf16 v[124:127], v[164:167], v[196:199], v[124:127]
	v_mfma_f32_16x16x32_bf16 v[108:111], v[164:167], v[204:207], v[108:111]
	v_mfma_f32_16x16x32_bf16 v[108:111], v[160:163], v[200:203], v[108:111]
	v_mfma_f32_16x16x32_bf16 v[92:95], v[160:163], v[208:211], v[92:95]
	v_mfma_f32_16x16x32_bf16 v[92:95], v[164:167], v[212:215], v[92:95]
	v_mfma_f32_16x16x32_bf16 v[76:79], v[164:167], v[220:223], v[76:79]
	v_mfma_f32_16x16x32_bf16 v[76:79], v[160:163], v[216:219], v[76:79]
	v_mfma_f32_16x16x32_bf16 v[68:71], v[168:171], v[216:219], v[68:71]
	v_mfma_f32_16x16x32_bf16 v[68:71], v[172:175], v[220:223], v[68:71]
	v_mfma_f32_16x16x32_bf16 v[84:87], v[172:175], v[212:215], v[84:87]
	v_mfma_f32_16x16x32_bf16 v[84:87], v[168:171], v[208:211], v[84:87]
	v_mfma_f32_16x16x32_bf16 v[100:103], v[168:171], v[200:203], v[100:103]
	v_mfma_f32_16x16x32_bf16 v[100:103], v[172:175], v[204:207], v[100:103]
	v_mfma_f32_16x16x32_bf16 v[116:119], v[172:175], v[196:199], v[116:119]
	v_mfma_f32_16x16x32_bf16 v[116:119], v[168:171], v[192:195], v[116:119]
	s_setprio 0
	s_setprio 1
	v_mfma_f32_16x16x32_bf16 v[120:123], v[176:179], v[192:195], v[120:123]
	v_mfma_f32_16x16x32_bf16 v[120:123], v[180:183], v[196:199], v[120:123]
	v_mfma_f32_16x16x32_bf16 v[104:107], v[180:183], v[204:207], v[104:107]
	v_mfma_f32_16x16x32_bf16 v[104:107], v[176:179], v[200:203], v[104:107]
	v_mfma_f32_16x16x32_bf16 v[88:91], v[176:179], v[208:211], v[88:91]
	v_mfma_f32_16x16x32_bf16 v[88:91], v[180:183], v[212:215], v[88:91]
	v_mfma_f32_16x16x32_bf16 v[72:75], v[180:183], v[220:223], v[72:75]
	v_mfma_f32_16x16x32_bf16 v[72:75], v[176:179], v[216:219], v[72:75]
	v_mfma_f32_16x16x32_bf16 v[64:67], v[184:187], v[216:219], v[64:67]
	v_mfma_f32_16x16x32_bf16 v[64:67], v[188:191], v[220:223], v[64:67]
	v_mfma_f32_16x16x32_bf16 v[80:83], v[188:191], v[212:215], v[80:83]
	v_mfma_f32_16x16x32_bf16 v[80:83], v[184:187], v[208:211], v[80:83]
	v_mfma_f32_16x16x32_bf16 v[96:99], v[184:187], v[200:203], v[96:99]
	v_mfma_f32_16x16x32_bf16 v[96:99], v[188:191], v[204:207], v[96:99]
	v_mfma_f32_16x16x32_bf16 v[112:115], v[188:191], v[196:199], v[112:115]
	v_mfma_f32_16x16x32_bf16 v[112:115], v[184:187], v[192:195], v[112:115]
	s_setprio 0
	s_barrier
	s_add_i32 s71, s61, s49
	v_lshl_add_u64 v[154:155], s[44:45], 0, v[132:133]
	s_mov_b32 m0, s71
	ds_read_b128 v[192:195], v150 offset:16384
	v_xor_b32_e32 v253, 64, v150
	ds_read_b128 v[196:199], v253 offset:16384
	ds_read_b128 v[200:203], v150 offset:18432
	ds_read_b128 v[204:207], v253 offset:18432
	ds_read_b128 v[208:211], v150 offset:20480
	ds_read_b128 v[212:215], v253 offset:20480
	ds_read_b128 v[216:219], v150 offset:22528
	ds_read_b128 v[220:223], v253 offset:22528
	global_load_lds_dwordx4 v[154:155], off
	s_add_i32 m0, s71, 0x2000
	s_add_u32 s72, s44, 0x40000
	v_lshl_add_u64 v[224:225], s[44:45], 0, v[128:129]
	s_addc_u32 s73, s45, 0
	s_add_i32 s71, s62, s49
	global_load_lds_dwordx4 v[224:225], off
	v_lshl_add_u64 v[226:227], s[72:73], 0, v[132:133]
	s_mov_b32 m0, s71
	v_lshl_add_u64 v[228:229], s[46:47], 0, v[130:131]
	global_load_lds_dwordx4 v[226:227], off
	v_lshl_add_u64 v[226:227], s[72:73], 0, v[128:129]
	s_add_i32 m0, s71, 0x2000
	s_nop 0
	global_load_lds_dwordx4 v[226:227], off
	v_lshl_add_u64 v[226:227], s[46:47], 0, v[134:135]
	s_mov_b32 m0, s52
	s_nop 0
	global_load_lds_dwordx4 v[226:227], off
	s_mov_b32 m0, s53
	s_nop 0
	global_load_lds_dwordx4 v[228:229], off
	s_waitcnt vmcnt(8)
	s_waitcnt lgkmcnt(0)
	s_barrier
	s_setprio 1
	s_waitcnt lgkmcnt(0)
	v_mfma_f32_16x16x32_bf16 v[60:63], v[160:163], v[192:195], v[60:63]
	v_mfma_f32_16x16x32_bf16 v[60:63], v[164:167], v[196:199], v[60:63]
	v_mfma_f32_16x16x32_bf16 v[44:47], v[164:167], v[204:207], v[44:47]
	v_mfma_f32_16x16x32_bf16 v[44:47], v[160:163], v[200:203], v[44:47]
	v_mfma_f32_16x16x32_bf16 v[28:31], v[160:163], v[208:211], v[28:31]
	v_mfma_f32_16x16x32_bf16 v[28:31], v[164:167], v[212:215], v[28:31]
	v_mfma_f32_16x16x32_bf16 v[12:15], v[164:167], v[220:223], v[12:15]
	v_mfma_f32_16x16x32_bf16 v[12:15], v[160:163], v[216:219], v[12:15]
	v_mfma_f32_16x16x32_bf16 v[4:7], v[168:171], v[216:219], v[4:7]
	v_mfma_f32_16x16x32_bf16 v[4:7], v[172:175], v[220:223], v[4:7]
	v_mfma_f32_16x16x32_bf16 v[20:23], v[172:175], v[212:215], v[20:23]
	v_mfma_f32_16x16x32_bf16 v[20:23], v[168:171], v[208:211], v[20:23]
	v_mfma_f32_16x16x32_bf16 v[36:39], v[168:171], v[200:203], v[36:39]
	v_mfma_f32_16x16x32_bf16 v[36:39], v[172:175], v[204:207], v[36:39]
	v_mfma_f32_16x16x32_bf16 v[52:55], v[172:175], v[196:199], v[52:55]
	v_mfma_f32_16x16x32_bf16 v[52:55], v[168:171], v[192:195], v[52:55]
	s_setprio 0
	s_setprio 1
	v_mfma_f32_16x16x32_bf16 v[56:59], v[176:179], v[192:195], v[56:59]
	v_mfma_f32_16x16x32_bf16 v[56:59], v[180:183], v[196:199], v[56:59]
	v_mfma_f32_16x16x32_bf16 v[40:43], v[180:183], v[204:207], v[40:43]
	v_mfma_f32_16x16x32_bf16 v[40:43], v[176:179], v[200:203], v[40:43]
	v_mfma_f32_16x16x32_bf16 v[24:27], v[176:179], v[208:211], v[24:27]
	v_mfma_f32_16x16x32_bf16 v[24:27], v[180:183], v[212:215], v[24:27]
	v_mfma_f32_16x16x32_bf16 v[8:11], v[180:183], v[220:223], v[8:11]
	v_mfma_f32_16x16x32_bf16 v[8:11], v[176:179], v[216:219], v[8:11]
	v_mfma_f32_16x16x32_bf16 v[0:3], v[184:187], v[216:219], v[0:3]
	v_mfma_f32_16x16x32_bf16 v[0:3], v[188:191], v[220:223], v[0:3]
	v_mfma_f32_16x16x32_bf16 v[16:19], v[188:191], v[212:215], v[16:19]
	v_mfma_f32_16x16x32_bf16 v[16:19], v[184:187], v[208:211], v[16:19]
	v_mfma_f32_16x16x32_bf16 v[32:35], v[184:187], v[200:203], v[32:35]
	v_mfma_f32_16x16x32_bf16 v[32:35], v[188:191], v[204:207], v[32:35]
	v_mfma_f32_16x16x32_bf16 v[48:51], v[188:191], v[196:199], v[48:51]
	v_mfma_f32_16x16x32_bf16 v[48:51], v[184:187], v[192:195], v[48:51]
	s_setprio 0
	s_barrier
	s_add_i32 s71, 0, 0x18000
	v_add_u32_e32 v153, s71, v147
	s_add_i32 s72, 0, 0x1c000
	ds_read_b128 v[160:163], v153
	v_xor_b32_e32 v253, 64, v153
	ds_read_b128 v[164:167], v253
	ds_read_b128 v[168:171], v153 offset:2048
	ds_read_b128 v[172:175], v253 offset:2048
	v_add_u32_e32 v153, s72, v147
	ds_read_b128 v[176:179], v153
	v_xor_b32_e32 v253, 64, v153
	ds_read_b128 v[180:183], v253
	ds_read_b128 v[184:187], v153 offset:2048
	ds_read_b128 v[188:191], v253 offset:2048
	s_add_u32 s46, s46, 0x40000
	s_addc_u32 s47, s47, 0
	s_mov_b32 m0, s54
	v_lshl_add_u64 v[230:231], s[46:47], 0, v[134:135]
	ds_read_b128 v[192:195], v150 offset:32768
	v_xor_b32_e32 v253, 64, v150
	ds_read_b128 v[196:199], v253 offset:32768
	ds_read_b128 v[200:203], v150 offset:34816
	ds_read_b128 v[204:207], v253 offset:34816
	ds_read_b128 v[208:211], v150 offset:36864
	ds_read_b128 v[212:215], v253 offset:36864
	ds_read_b128 v[216:219], v150 offset:38912
	ds_read_b128 v[220:223], v253 offset:38912
	global_load_lds_dwordx4 v[230:231], off
	v_lshl_add_u64 v[230:231], s[46:47], 0, v[130:131]
	s_mov_b32 m0, s55
	s_nop 0
	global_load_lds_dwordx4 v[230:231], off
	s_waitcnt vmcnt(8)
	s_waitcnt lgkmcnt(0)
	s_barrier
	s_setprio 1
	s_waitcnt lgkmcnt(0)
	v_mfma_f32_16x16x32_bf16 v[124:127], v[160:163], v[192:195], v[124:127]
	v_mfma_f32_16x16x32_bf16 v[124:127], v[164:167], v[196:199], v[124:127]
	v_mfma_f32_16x16x32_bf16 v[108:111], v[164:167], v[204:207], v[108:111]
	v_mfma_f32_16x16x32_bf16 v[108:111], v[160:163], v[200:203], v[108:111]
	v_mfma_f32_16x16x32_bf16 v[92:95], v[160:163], v[208:211], v[92:95]
	v_mfma_f32_16x16x32_bf16 v[92:95], v[164:167], v[212:215], v[92:95]
	v_mfma_f32_16x16x32_bf16 v[76:79], v[164:167], v[220:223], v[76:79]
	v_mfma_f32_16x16x32_bf16 v[76:79], v[160:163], v[216:219], v[76:79]
	v_mfma_f32_16x16x32_bf16 v[68:71], v[168:171], v[216:219], v[68:71]
	v_mfma_f32_16x16x32_bf16 v[68:71], v[172:175], v[220:223], v[68:71]
	v_mfma_f32_16x16x32_bf16 v[84:87], v[172:175], v[212:215], v[84:87]
	v_mfma_f32_16x16x32_bf16 v[84:87], v[168:171], v[208:211], v[84:87]
	v_mfma_f32_16x16x32_bf16 v[100:103], v[168:171], v[200:203], v[100:103]
	v_mfma_f32_16x16x32_bf16 v[100:103], v[172:175], v[204:207], v[100:103]
	v_mfma_f32_16x16x32_bf16 v[116:119], v[172:175], v[196:199], v[116:119]
	v_mfma_f32_16x16x32_bf16 v[116:119], v[168:171], v[192:195], v[116:119]
	s_setprio 0
	s_setprio 1
	v_mfma_f32_16x16x32_bf16 v[120:123], v[176:179], v[192:195], v[120:123]
	v_mfma_f32_16x16x32_bf16 v[120:123], v[180:183], v[196:199], v[120:123]
	v_mfma_f32_16x16x32_bf16 v[104:107], v[180:183], v[204:207], v[104:107]
	v_mfma_f32_16x16x32_bf16 v[104:107], v[176:179], v[200:203], v[104:107]
	v_mfma_f32_16x16x32_bf16 v[88:91], v[176:179], v[208:211], v[88:91]
	v_mfma_f32_16x16x32_bf16 v[88:91], v[180:183], v[212:215], v[88:91]
	v_mfma_f32_16x16x32_bf16 v[72:75], v[180:183], v[220:223], v[72:75]
	v_mfma_f32_16x16x32_bf16 v[72:75], v[176:179], v[216:219], v[72:75]
	v_mfma_f32_16x16x32_bf16 v[64:67], v[184:187], v[216:219], v[64:67]
	v_mfma_f32_16x16x32_bf16 v[64:67], v[188:191], v[220:223], v[64:67]
	v_mfma_f32_16x16x32_bf16 v[80:83], v[188:191], v[212:215], v[80:83]
	v_mfma_f32_16x16x32_bf16 v[80:83], v[184:187], v[208:211], v[80:83]
	v_mfma_f32_16x16x32_bf16 v[96:99], v[184:187], v[200:203], v[96:99]
	v_mfma_f32_16x16x32_bf16 v[96:99], v[188:191], v[204:207], v[96:99]
	v_mfma_f32_16x16x32_bf16 v[112:115], v[188:191], v[196:199], v[112:115]
	v_mfma_f32_16x16x32_bf16 v[112:115], v[184:187], v[192:195], v[112:115]
	s_setprio 0
	s_barrier
	s_add_i32 s46, s71, s49
	v_lshl_add_u64 v[154:155], v[154:155], 0, s[14:15]
	s_mov_b32 m0, s46
	ds_read_b128 v[192:195], v150 offset:49152
	v_xor_b32_e32 v253, 64, v150
	ds_read_b128 v[196:199], v253 offset:49152
	ds_read_b128 v[200:203], v150 offset:51200
	ds_read_b128 v[204:207], v253 offset:51200
	ds_read_b128 v[208:211], v150 offset:53248
	ds_read_b128 v[212:215], v253 offset:53248
	ds_read_b128 v[216:219], v150 offset:55296
	ds_read_b128 v[220:223], v253 offset:55296
	global_load_lds_dwordx4 v[154:155], off
	s_add_i32 m0, s46, 0x2000
	s_add_u32 s44, s44, 0x40080
	v_lshl_add_u64 v[154:155], v[224:225], 0, s[14:15]
	s_addc_u32 s45, s45, 0
	s_add_i32 s46, s72, s49
	global_load_lds_dwordx4 v[154:155], off
	v_lshl_add_u64 v[154:155], s[44:45], 0, v[132:133]
	s_mov_b32 m0, s46
	s_nop 0
	global_load_lds_dwordx4 v[154:155], off
	v_lshl_add_u64 v[154:155], s[44:45], 0, v[128:129]
	s_add_i32 m0, s46, 0x2000
	s_nop 0
	global_load_lds_dwordx4 v[154:155], off
	v_lshl_add_u64 v[154:155], v[226:227], 0, s[14:15]
	s_mov_b32 m0, s57
	s_nop 0
	global_load_lds_dwordx4 v[154:155], off
	v_lshl_add_u64 v[154:155], v[228:229], 0, s[14:15]
	s_mov_b32 m0, s58
	s_nop 0
	global_load_lds_dwordx4 v[154:155], off
	s_waitcnt vmcnt(8)
	s_waitcnt lgkmcnt(0)
	s_barrier
	s_setprio 1
	s_waitcnt lgkmcnt(0)
	v_mfma_f32_16x16x32_bf16 v[60:63], v[160:163], v[192:195], v[60:63]
	v_mfma_f32_16x16x32_bf16 v[60:63], v[164:167], v[196:199], v[60:63]
	v_mfma_f32_16x16x32_bf16 v[44:47], v[164:167], v[204:207], v[44:47]
	v_mfma_f32_16x16x32_bf16 v[44:47], v[160:163], v[200:203], v[44:47]
	v_mfma_f32_16x16x32_bf16 v[28:31], v[160:163], v[208:211], v[28:31]
	v_mfma_f32_16x16x32_bf16 v[28:31], v[164:167], v[212:215], v[28:31]
	v_mfma_f32_16x16x32_bf16 v[12:15], v[164:167], v[220:223], v[12:15]
	v_mfma_f32_16x16x32_bf16 v[12:15], v[160:163], v[216:219], v[12:15]
	v_mfma_f32_16x16x32_bf16 v[4:7], v[168:171], v[216:219], v[4:7]
	v_mfma_f32_16x16x32_bf16 v[4:7], v[172:175], v[220:223], v[4:7]
	v_mfma_f32_16x16x32_bf16 v[20:23], v[172:175], v[212:215], v[20:23]
	v_mfma_f32_16x16x32_bf16 v[20:23], v[168:171], v[208:211], v[20:23]
	v_mfma_f32_16x16x32_bf16 v[36:39], v[168:171], v[200:203], v[36:39]
	v_mfma_f32_16x16x32_bf16 v[36:39], v[172:175], v[204:207], v[36:39]
	v_mfma_f32_16x16x32_bf16 v[52:55], v[172:175], v[196:199], v[52:55]
	v_mfma_f32_16x16x32_bf16 v[52:55], v[168:171], v[192:195], v[52:55]
	s_setprio 0
	s_setprio 1
	v_mfma_f32_16x16x32_bf16 v[56:59], v[176:179], v[192:195], v[56:59]
	v_mfma_f32_16x16x32_bf16 v[56:59], v[180:183], v[196:199], v[56:59]
	v_mfma_f32_16x16x32_bf16 v[40:43], v[180:183], v[204:207], v[40:43]
	v_mfma_f32_16x16x32_bf16 v[40:43], v[176:179], v[200:203], v[40:43]
	v_mfma_f32_16x16x32_bf16 v[24:27], v[176:179], v[208:211], v[24:27]
	v_mfma_f32_16x16x32_bf16 v[24:27], v[180:183], v[212:215], v[24:27]
	v_mfma_f32_16x16x32_bf16 v[8:11], v[180:183], v[220:223], v[8:11]
	v_mfma_f32_16x16x32_bf16 v[8:11], v[176:179], v[216:219], v[8:11]
	v_mfma_f32_16x16x32_bf16 v[0:3], v[184:187], v[216:219], v[0:3]
	v_mfma_f32_16x16x32_bf16 v[0:3], v[188:191], v[220:223], v[0:3]
	v_mfma_f32_16x16x32_bf16 v[16:19], v[188:191], v[212:215], v[16:19]
	v_mfma_f32_16x16x32_bf16 v[16:19], v[184:187], v[208:211], v[16:19]
	v_mfma_f32_16x16x32_bf16 v[32:35], v[184:187], v[200:203], v[32:35]
	v_mfma_f32_16x16x32_bf16 v[32:35], v[188:191], v[204:207], v[32:35]
	v_mfma_f32_16x16x32_bf16 v[48:51], v[188:191], v[196:199], v[48:51]
	v_mfma_f32_16x16x32_bf16 v[48:51], v[184:187], v[192:195], v[48:51]
	s_setprio 0
	s_barrier
	s_add_i32 s70, s70, 2
	s_add_u32 s68, s68, 0x100
	s_addc_u32 s69, s69, 0
	s_add_u32 s30, s30, 0x100
	s_addc_u32 s31, s31, 0
	s_cmp_gt_u32 s70, 13
	s_cbranch_scc1 .LBB0_1100

.Llast_10:
	v_add_u32_e32 v153, s61, v147
	ds_read_b128 v[160:163], v153
	v_xor_b32_e32 v253, 64, v153
	ds_read_b128 v[164:167], v253
	ds_read_b128 v[168:171], v153 offset:2048
	ds_read_b128 v[172:175], v253 offset:2048
	v_add_u32_e32 v153, s62, v147
	ds_read_b128 v[176:179], v153
	v_xor_b32_e32 v253, 64, v153
	ds_read_b128 v[180:183], v253
	ds_read_b128 v[184:187], v153 offset:2048
	ds_read_b128 v[188:191], v253 offset:2048
	s_add_u32 s46, s30, 0xfffc0080
	s_addc_u32 s47, s31, -1
	s_and_b64 s[44:45], s[44:45], exec
	s_cselect_b32 s47, s25, s47
	s_cselect_b32 s46, s65, s46
	s_cselect_b32 s45, s66, s69
	s_cselect_b32 s44, s67, s68
	v_lshl_add_u64 v[154:155], s[30:31], 0, v[138:139]
	s_add_i32 m0, s52, 0xc000
	ds_read_b128 v[192:195], v150
	v_xor_b32_e32 v253, 64, v150
	ds_read_b128 v[196:199], v253
	ds_read_b128 v[200:203], v150 offset:2048
	ds_read_b128 v[204:207], v253 offset:2048
	ds_read_b128 v[208:211], v150 offset:4096
	ds_read_b128 v[212:215], v253 offset:4096
	ds_read_b128 v[216:219], v150 offset:6144
	ds_read_b128 v[220:223], v253 offset:6144
	global_load_lds_dwordx4 v[154:155], off
	v_lshl_add_u64 v[154:155], s[30:31], 0, v[136:137]
	s_add_i32 m0, s52, 0xe000
	s_nop 0
	global_load_lds_dwordx4 v[154:155], off
	s_waitcnt vmcnt(8)
	s_waitcnt lgkmcnt(0)
	s_barrier
	s_setprio 1
	s_waitcnt lgkmcnt(0)
	v_mfma_f32_16x16x32_bf16 v[124:127], v[160:163], v[192:195], v[124:127]
	v_mfma_f32_16x16x32_bf16 v[124:127], v[164:167], v[196:199], v[124:127]
	v_mfma_f32_16x16x32_bf16 v[108:111], v[164:167], v[204:207], v[108:111]
	v_mfma_f32_16x16x32_bf16 v[108:111], v[160:163], v[200:203], v[108:111]
	v_mfma_f32_16x16x32_bf16 v[92:95], v[160:163], v[208:211], v[92:95]
	v_mfma_f32_16x16x32_bf16 v[92:95], v[164:167], v[212:215], v[92:95]
	v_mfma_f32_16x16x32_bf16 v[76:79], v[164:167], v[220:223], v[76:79]
	v_mfma_f32_16x16x32_bf16 v[76:79], v[160:163], v[216:219], v[76:79]
	v_mfma_f32_16x16x32_bf16 v[68:71], v[168:171], v[216:219], v[68:71]
	v_mfma_f32_16x16x32_bf16 v[68:71], v[172:175], v[220:223], v[68:71]
	v_mfma_f32_16x16x32_bf16 v[84:87], v[172:175], v[212:215], v[84:87]
	v_mfma_f32_16x16x32_bf16 v[84:87], v[168:171], v[208:211], v[84:87]
	v_mfma_f32_16x16x32_bf16 v[100:103], v[168:171], v[200:203], v[100:103]
	v_mfma_f32_16x16x32_bf16 v[100:103], v[172:175], v[204:207], v[100:103]
	v_mfma_f32_16x16x32_bf16 v[116:119], v[172:175], v[196:199], v[116:119]
	v_mfma_f32_16x16x32_bf16 v[116:119], v[168:171], v[192:195], v[116:119]
	s_setprio 0
	s_setprio 1
	v_mfma_f32_16x16x32_bf16 v[120:123], v[176:179], v[192:195], v[120:123]
	v_mfma_f32_16x16x32_bf16 v[120:123], v[180:183], v[196:199], v[120:123]
	v_mfma_f32_16x16x32_bf16 v[104:107], v[180:183], v[204:207], v[104:107]
	v_mfma_f32_16x16x32_bf16 v[104:107], v[176:179], v[200:203], v[104:107]
	v_mfma_f32_16x16x32_bf16 v[88:91], v[176:179], v[208:211], v[88:91]
	v_mfma_f32_16x16x32_bf16 v[88:91], v[180:183], v[212:215], v[88:91]
	v_mfma_f32_16x16x32_bf16 v[72:75], v[180:183], v[220:223], v[72:75]
	v_mfma_f32_16x16x32_bf16 v[72:75], v[176:179], v[216:219], v[72:75]
	v_mfma_f32_16x16x32_bf16 v[64:67], v[184:187], v[216:219], v[64:67]
	v_mfma_f32_16x16x32_bf16 v[64:67], v[188:191], v[220:223], v[64:67]
	v_mfma_f32_16x16x32_bf16 v[80:83], v[188:191], v[212:215], v[80:83]
	v_mfma_f32_16x16x32_bf16 v[80:83], v[184:187], v[208:211], v[80:83]
	v_mfma_f32_16x16x32_bf16 v[96:99], v[184:187], v[200:203], v[96:99]
	v_mfma_f32_16x16x32_bf16 v[96:99], v[188:191], v[204:207], v[96:99]
	v_mfma_f32_16x16x32_bf16 v[112:115], v[188:191], v[196:199], v[112:115]
	v_mfma_f32_16x16x32_bf16 v[112:115], v[184:187], v[192:195], v[112:115]
	s_setprio 0
	s_barrier
	s_add_i32 s71, s61, s49
	v_lshl_add_u64 v[154:155], s[44:45], 0, v[132:133]
	s_mov_b32 m0, s71
	ds_read_b128 v[192:195], v150 offset:16384
	v_xor_b32_e32 v253, 64, v150
	ds_read_b128 v[196:199], v253 offset:16384
	ds_read_b128 v[200:203], v150 offset:18432
	ds_read_b128 v[204:207], v253 offset:18432
	ds_read_b128 v[208:211], v150 offset:20480
	ds_read_b128 v[212:215], v253 offset:20480
	ds_read_b128 v[216:219], v150 offset:22528
	ds_read_b128 v[220:223], v253 offset:22528
	global_load_lds_dwordx4 v[154:155], off
	s_add_i32 m0, s71, 0x2000
	s_add_u32 s72, s44, 0x40000
	v_lshl_add_u64 v[224:225], s[44:45], 0, v[128:129]
	s_addc_u32 s73, s45, 0
	s_add_i32 s71, s62, s49
	global_load_lds_dwordx4 v[224:225], off
	v_lshl_add_u64 v[226:227], s[72:73], 0, v[132:133]
	s_mov_b32 m0, s71
	v_lshl_add_u64 v[228:229], s[46:47], 0, v[130:131]
	global_load_lds_dwordx4 v[226:227], off
	v_lshl_add_u64 v[226:227], s[72:73], 0, v[128:129]
	s_add_i32 m0, s71, 0x2000
	s_nop 0
	global_load_lds_dwordx4 v[226:227], off
	v_lshl_add_u64 v[226:227], s[46:47], 0, v[134:135]
	s_mov_b32 m0, s52
	s_nop 0
	global_load_lds_dwordx4 v[226:227], off
	s_mov_b32 m0, s53
	s_nop 0
	global_load_lds_dwordx4 v[228:229], off
	s_waitcnt vmcnt(8)
	s_waitcnt lgkmcnt(0)
	s_barrier
	s_setprio 1
	s_waitcnt lgkmcnt(0)
	v_mfma_f32_16x16x32_bf16 v[60:63], v[160:163], v[192:195], v[60:63]
	v_mfma_f32_16x16x32_bf16 v[60:63], v[164:167], v[196:199], v[60:63]
	v_mfma_f32_16x16x32_bf16 v[44:47], v[164:167], v[204:207], v[44:47]
	v_mfma_f32_16x16x32_bf16 v[44:47], v[160:163], v[200:203], v[44:47]
	v_mfma_f32_16x16x32_bf16 v[28:31], v[160:163], v[208:211], v[28:31]
	v_mfma_f32_16x16x32_bf16 v[28:31], v[164:167], v[212:215], v[28:31]
	v_mfma_f32_16x16x32_bf16 v[12:15], v[164:167], v[220:223], v[12:15]
	v_mfma_f32_16x16x32_bf16 v[12:15], v[160:163], v[216:219], v[12:15]
	v_mfma_f32_16x16x32_bf16 v[4:7], v[168:171], v[216:219], v[4:7]
	v_mfma_f32_16x16x32_bf16 v[4:7], v[172:175], v[220:223], v[4:7]
	v_mfma_f32_16x16x32_bf16 v[20:23], v[172:175], v[212:215], v[20:23]
	v_mfma_f32_16x16x32_bf16 v[20:23], v[168:171], v[208:211], v[20:23]
	v_mfma_f32_16x16x32_bf16 v[36:39], v[168:171], v[200:203], v[36:39]
	v_mfma_f32_16x16x32_bf16 v[36:39], v[172:175], v[204:207], v[36:39]
	v_mfma_f32_16x16x32_bf16 v[52:55], v[172:175], v[196:199], v[52:55]
	v_mfma_f32_16x16x32_bf16 v[52:55], v[168:171], v[192:195], v[52:55]
	s_setprio 0
	s_setprio 1
	v_mfma_f32_16x16x32_bf16 v[56:59], v[176:179], v[192:195], v[56:59]
	v_mfma_f32_16x16x32_bf16 v[56:59], v[180:183], v[196:199], v[56:59]
	v_mfma_f32_16x16x32_bf16 v[40:43], v[180:183], v[204:207], v[40:43]
	v_mfma_f32_16x16x32_bf16 v[40:43], v[176:179], v[200:203], v[40:43]
	v_mfma_f32_16x16x32_bf16 v[24:27], v[176:179], v[208:211], v[24:27]
	v_mfma_f32_16x16x32_bf16 v[24:27], v[180:183], v[212:215], v[24:27]
	v_mfma_f32_16x16x32_bf16 v[8:11], v[180:183], v[220:223], v[8:11]
	v_mfma_f32_16x16x32_bf16 v[8:11], v[176:179], v[216:219], v[8:11]
	v_mfma_f32_16x16x32_bf16 v[0:3], v[184:187], v[216:219], v[0:3]
	v_mfma_f32_16x16x32_bf16 v[0:3], v[188:191], v[220:223], v[0:3]
	v_mfma_f32_16x16x32_bf16 v[16:19], v[188:191], v[212:215], v[16:19]
	v_mfma_f32_16x16x32_bf16 v[16:19], v[184:187], v[208:211], v[16:19]
	v_mfma_f32_16x16x32_bf16 v[32:35], v[184:187], v[200:203], v[32:35]
	v_mfma_f32_16x16x32_bf16 v[32:35], v[188:191], v[204:207], v[32:35]
	v_mfma_f32_16x16x32_bf16 v[48:51], v[188:191], v[196:199], v[48:51]
	v_mfma_f32_16x16x32_bf16 v[48:51], v[184:187], v[192:195], v[48:51]
	s_setprio 0
	s_barrier
	s_add_i32 s71, 0, 0x18000
	v_add_u32_e32 v153, s71, v147
	s_add_i32 s72, 0, 0x1c000
	ds_read_b128 v[160:163], v153
	v_xor_b32_e32 v253, 64, v153
	ds_read_b128 v[164:167], v253
	ds_read_b128 v[168:171], v153 offset:2048
	ds_read_b128 v[172:175], v253 offset:2048
	v_add_u32_e32 v153, s72, v147
	ds_read_b128 v[176:179], v153
	v_xor_b32_e32 v253, 64, v153
	ds_read_b128 v[180:183], v253
	ds_read_b128 v[184:187], v153 offset:2048
	ds_read_b128 v[188:191], v253 offset:2048
	s_add_u32 s46, s46, 0x40000
	s_addc_u32 s47, s47, 0
	s_mov_b32 m0, s54
	v_lshl_add_u64 v[230:231], s[46:47], 0, v[134:135]
	ds_read_b128 v[192:195], v150 offset:32768
	v_xor_b32_e32 v253, 64, v150
	ds_read_b128 v[196:199], v253 offset:32768
	ds_read_b128 v[200:203], v150 offset:34816
	ds_read_b128 v[204:207], v253 offset:34816
	ds_read_b128 v[208:211], v150 offset:36864
	ds_read_b128 v[212:215], v253 offset:36864
	ds_read_b128 v[216:219], v150 offset:38912
	ds_read_b128 v[220:223], v253 offset:38912
	global_load_lds_dwordx4 v[230:231], off
	v_lshl_add_u64 v[230:231], s[46:47], 0, v[130:131]
	s_mov_b32 m0, s55
	s_nop 0
	global_load_lds_dwordx4 v[230:231], off
	s_waitcnt vmcnt(8)
	s_waitcnt lgkmcnt(0)
	s_barrier
	s_setprio 1
	s_waitcnt lgkmcnt(0)
	v_mfma_f32_16x16x32_bf16 v[124:127], v[160:163], v[192:195], v[124:127]
	v_mfma_f32_16x16x32_bf16 v[124:127], v[164:167], v[196:199], v[124:127]
	v_mfma_f32_16x16x32_bf16 v[108:111], v[164:167], v[204:207], v[108:111]
	v_mfma_f32_16x16x32_bf16 v[108:111], v[160:163], v[200:203], v[108:111]
	v_mfma_f32_16x16x32_bf16 v[92:95], v[160:163], v[208:211], v[92:95]
	v_mfma_f32_16x16x32_bf16 v[92:95], v[164:167], v[212:215], v[92:95]
	v_mfma_f32_16x16x32_bf16 v[76:79], v[164:167], v[220:223], v[76:79]
	v_mfma_f32_16x16x32_bf16 v[76:79], v[160:163], v[216:219], v[76:79]
	v_mfma_f32_16x16x32_bf16 v[68:71], v[168:171], v[216:219], v[68:71]
	v_mfma_f32_16x16x32_bf16 v[68:71], v[172:175], v[220:223], v[68:71]
	v_mfma_f32_16x16x32_bf16 v[84:87], v[172:175], v[212:215], v[84:87]
	v_mfma_f32_16x16x32_bf16 v[84:87], v[168:171], v[208:211], v[84:87]
	v_mfma_f32_16x16x32_bf16 v[100:103], v[168:171], v[200:203], v[100:103]
	v_mfma_f32_16x16x32_bf16 v[100:103], v[172:175], v[204:207], v[100:103]
	v_mfma_f32_16x16x32_bf16 v[116:119], v[172:175], v[196:199], v[116:119]
	v_mfma_f32_16x16x32_bf16 v[116:119], v[168:171], v[192:195], v[116:119]
	s_setprio 0
	s_setprio 1
	v_mfma_f32_16x16x32_bf16 v[120:123], v[176:179], v[192:195], v[120:123]
	v_mfma_f32_16x16x32_bf16 v[120:123], v[180:183], v[196:199], v[120:123]
	v_mfma_f32_16x16x32_bf16 v[104:107], v[180:183], v[204:207], v[104:107]
	v_mfma_f32_16x16x32_bf16 v[104:107], v[176:179], v[200:203], v[104:107]
	v_mfma_f32_16x16x32_bf16 v[88:91], v[176:179], v[208:211], v[88:91]
	v_mfma_f32_16x16x32_bf16 v[88:91], v[180:183], v[212:215], v[88:91]
	v_mfma_f32_16x16x32_bf16 v[72:75], v[180:183], v[220:223], v[72:75]
	v_mfma_f32_16x16x32_bf16 v[72:75], v[176:179], v[216:219], v[72:75]
	v_mfma_f32_16x16x32_bf16 v[64:67], v[184:187], v[216:219], v[64:67]
	v_mfma_f32_16x16x32_bf16 v[64:67], v[188:191], v[220:223], v[64:67]
	v_mfma_f32_16x16x32_bf16 v[80:83], v[188:191], v[212:215], v[80:83]
	v_mfma_f32_16x16x32_bf16 v[80:83], v[184:187], v[208:211], v[80:83]
	v_mfma_f32_16x16x32_bf16 v[96:99], v[184:187], v[200:203], v[96:99]
	v_mfma_f32_16x16x32_bf16 v[96:99], v[188:191], v[204:207], v[96:99]
	v_mfma_f32_16x16x32_bf16 v[112:115], v[188:191], v[196:199], v[112:115]
	v_mfma_f32_16x16x32_bf16 v[112:115], v[184:187], v[192:195], v[112:115]
	s_setprio 0
	s_barrier
	v_add_u32_e32 v234, 0x21000, v151
	ds_read_b128 v[236:239], v234
	ds_read_b128 v[240:243], v234 offset:256
	ds_read_b128 v[244:247], v234 offset:512
	ds_read_b128 v[248:251], v234 offset:768
	v_add_u32_e32 v235, s23, v146
	v_mul_u32_u24_e32 v235, 0x1600, v235
	v_lshl_or_b32 v234, s64, 7, v149
	v_lshl_add_u32 v235, v234, 1, v235
	s_add_i32 s46, s71, s49
	v_lshl_add_u64 v[154:155], v[154:155], 0, s[14:15]
	s_mov_b32 m0, s46
	ds_read_b128 v[192:195], v150 offset:49152
	v_xor_b32_e32 v253, 64, v150
	ds_read_b128 v[196:199], v253 offset:49152
	ds_read_b128 v[200:203], v150 offset:51200
	ds_read_b128 v[204:207], v253 offset:51200
	ds_read_b128 v[208:211], v150 offset:53248
	ds_read_b128 v[212:215], v253 offset:53248
	ds_read_b128 v[216:219], v150 offset:55296
	ds_read_b128 v[220:223], v253 offset:55296
	global_load_lds_dwordx4 v[154:155], off
	s_add_i32 m0, s46, 0x2000
	s_add_u32 s44, s44, 0x40080
	v_lshl_add_u64 v[154:155], v[224:225], 0, s[14:15]
	s_addc_u32 s45, s45, 0
	s_add_i32 s46, s72, s49
	global_load_lds_dwordx4 v[154:155], off
	v_lshl_add_u64 v[154:155], s[44:45], 0, v[132:133]
	s_mov_b32 m0, s46
	s_nop 0
	global_load_lds_dwordx4 v[154:155], off
	v_lshl_add_u64 v[154:155], s[44:45], 0, v[128:129]
	s_add_i32 m0, s46, 0x2000
	s_nop 0
	global_load_lds_dwordx4 v[154:155], off
	v_lshl_add_u64 v[154:155], v[226:227], 0, s[14:15]
	s_mov_b32 m0, s57
	s_nop 0
	global_load_lds_dwordx4 v[154:155], off
	v_lshl_add_u64 v[154:155], v[228:229], 0, s[14:15]
	s_mov_b32 m0, s58
	s_nop 0
	global_load_lds_dwordx4 v[154:155], off
	s_waitcnt lgkmcnt(8)
	v_add_f32_e32 v236, v236, v237
	v_add_f32_e32 v238, v238, v239
	v_add_f32_e32 v240, v240, v241
	v_add_f32_e32 v242, v242, v243
	v_add_f32_e32 v244, v244, v245
	v_add_f32_e32 v246, v246, v247
	v_add_f32_e32 v248, v248, v249
	v_add_f32_e32 v250, v250, v251
	v_add_f32_e32 v236, v236, v238
	v_add_f32_e32 v240, v240, v242
	v_add_f32_e32 v244, v244, v246
	v_add_f32_e32 v248, v248, v250
	v_fmamk_f32 v236, v236, 0x3a800000, v152
	v_fmamk_f32 v240, v240, 0x3a800000, v152
	v_fmamk_f32 v244, v244, 0x3a800000, v152
	v_fmamk_f32 v248, v248, 0x3a800000, v152
	v_rsq_f32_e32 v236, v236
	v_rsq_f32_e32 v240, v240
	v_rsq_f32_e32 v244, v244
	v_rsq_f32_e32 v248, v248
	v_mul_f32_e32 v252, 0xbfb8aa3b, v236
	v_mul_f32_e32 v254, v236, v236
	v_pk_mul_f32 v[120:121], v[124:125], v[120:121]
	v_pk_mul_f32 v[122:123], v[126:127], v[122:123]
	v_pk_mul_f32 v[112:113], v[116:117], v[112:113]
	v_pk_mul_f32 v[114:115], v[118:119], v[114:115]
	v_pk_mul_f32 v[124:125], v[124:125], v[252:253] op_sel_hi:[1,0]
	v_pk_mul_f32 v[126:127], v[126:127], v[252:253] op_sel_hi:[1,0]
	v_pk_mul_f32 v[116:117], v[116:117], v[252:253] op_sel_hi:[1,0]
	v_pk_mul_f32 v[118:119], v[118:119], v[252:253] op_sel_hi:[1,0]
	v_exp_f32_e32 v124, v124
	v_exp_f32_e32 v125, v125
	v_exp_f32_e32 v126, v126
	v_exp_f32_e32 v127, v127
	v_exp_f32_e32 v116, v116
	v_exp_f32_e32 v117, v117
	v_exp_f32_e32 v118, v118
	v_exp_f32_e32 v119, v119
	v_pk_add_f32 v[124:125], v[124:125], 1.0 op_sel_hi:[1,0]
	v_pk_add_f32 v[126:127], v[126:127], 1.0 op_sel_hi:[1,0]
	v_pk_add_f32 v[116:117], v[116:117], 1.0 op_sel_hi:[1,0]
	v_pk_add_f32 v[118:119], v[118:119], 1.0 op_sel_hi:[1,0]
	v_rcp_f32_e32 v124, v124
	v_rcp_f32_e32 v125, v125
	v_rcp_f32_e32 v126, v126
	v_rcp_f32_e32 v127, v127
	v_rcp_f32_e32 v116, v116
	v_rcp_f32_e32 v117, v117
	v_rcp_f32_e32 v118, v118
	v_rcp_f32_e32 v119, v119
	v_pk_mul_f32 v[120:121], v[120:121], v[254:255] op_sel_hi:[1,0]
	v_pk_mul_f32 v[122:123], v[122:123], v[254:255] op_sel_hi:[1,0]
	v_pk_mul_f32 v[112:113], v[112:113], v[254:255] op_sel_hi:[1,0]
	v_pk_mul_f32 v[114:115], v[114:115], v[254:255] op_sel_hi:[1,0]
	v_pk_mul_f32 v[120:121], v[120:121], v[124:125]
	v_pk_mul_f32 v[122:123], v[122:123], v[126:127]
	v_pk_mul_f32 v[112:113], v[112:113], v[116:117]
	v_pk_mul_f32 v[114:115], v[114:115], v[118:119]
	v_cvt_pk_bf16_f32 v120, v120, v121
	v_cvt_pk_bf16_f32 v121, v122, v123
	v_cvt_pk_bf16_f32 v122, v112, v113
	v_cvt_pk_bf16_f32 v123, v114, v115
	global_store_dwordx4 v235, v[120:123], s[10:11]
	v_add_u32_e32 v234, 0x16000, v235
	v_mul_f32_e32 v252, 0xbfb8aa3b, v240
	v_mul_f32_e32 v254, v240, v240
	v_pk_mul_f32 v[104:105], v[108:109], v[104:105]
	v_pk_mul_f32 v[106:107], v[110:111], v[106:107]
	v_pk_mul_f32 v[96:97], v[100:101], v[96:97]
	v_pk_mul_f32 v[98:99], v[102:103], v[98:99]
	v_pk_mul_f32 v[108:109], v[108:109], v[252:253] op_sel_hi:[1,0]
	v_pk_mul_f32 v[110:111], v[110:111], v[252:253] op_sel_hi:[1,0]
	v_pk_mul_f32 v[100:101], v[100:101], v[252:253] op_sel_hi:[1,0]
	v_pk_mul_f32 v[102:103], v[102:103], v[252:253] op_sel_hi:[1,0]
	v_exp_f32_e32 v108, v108
	v_exp_f32_e32 v109, v109
	v_exp_f32_e32 v110, v110
	v_exp_f32_e32 v111, v111
	v_exp_f32_e32 v100, v100
	v_exp_f32_e32 v101, v101
	v_exp_f32_e32 v102, v102
	v_exp_f32_e32 v103, v103
	v_pk_add_f32 v[108:109], v[108:109], 1.0 op_sel_hi:[1,0]
	v_pk_add_f32 v[110:111], v[110:111], 1.0 op_sel_hi:[1,0]
	v_pk_add_f32 v[100:101], v[100:101], 1.0 op_sel_hi:[1,0]
	v_pk_add_f32 v[102:103], v[102:103], 1.0 op_sel_hi:[1,0]
	v_rcp_f32_e32 v108, v108
	v_rcp_f32_e32 v109, v109
	v_rcp_f32_e32 v110, v110
	v_rcp_f32_e32 v111, v111
	v_rcp_f32_e32 v100, v100
	v_rcp_f32_e32 v101, v101
	v_rcp_f32_e32 v102, v102
	v_rcp_f32_e32 v103, v103
	v_pk_mul_f32 v[104:105], v[104:105], v[254:255] op_sel_hi:[1,0]
	v_pk_mul_f32 v[106:107], v[106:107], v[254:255] op_sel_hi:[1,0]
	v_pk_mul_f32 v[96:97], v[96:97], v[254:255] op_sel_hi:[1,0]
	v_pk_mul_f32 v[98:99], v[98:99], v[254:255] op_sel_hi:[1,0]
	v_pk_mul_f32 v[104:105], v[104:105], v[108:109]
	v_pk_mul_f32 v[106:107], v[106:107], v[110:111]
	v_pk_mul_f32 v[96:97], v[96:97], v[100:101]
	v_pk_mul_f32 v[98:99], v[98:99], v[102:103]
	v_cvt_pk_bf16_f32 v104, v104, v105
	v_cvt_pk_bf16_f32 v105, v106, v107
	v_cvt_pk_bf16_f32 v106, v96, v97
	v_cvt_pk_bf16_f32 v107, v98, v99
	global_store_dwordx4 v234, v[104:107], s[10:11]
	v_add_u32_e32 v235, 0x16000, v234
	v_mul_f32_e32 v252, 0xbfb8aa3b, v244
	v_mul_f32_e32 v254, v244, v244
	v_pk_mul_f32 v[88:89], v[92:93], v[88:89]
	v_pk_mul_f32 v[90:91], v[94:95], v[90:91]
	v_pk_mul_f32 v[80:81], v[84:85], v[80:81]
	v_pk_mul_f32 v[82:83], v[86:87], v[82:83]
	v_pk_mul_f32 v[92:93], v[92:93], v[252:253] op_sel_hi:[1,0]
	v_pk_mul_f32 v[94:95], v[94:95], v[252:253] op_sel_hi:[1,0]
	v_pk_mul_f32 v[84:85], v[84:85], v[252:253] op_sel_hi:[1,0]
	v_pk_mul_f32 v[86:87], v[86:87], v[252:253] op_sel_hi:[1,0]
	v_exp_f32_e32 v92, v92
	v_exp_f32_e32 v93, v93
	v_exp_f32_e32 v94, v94
	v_exp_f32_e32 v95, v95
	v_exp_f32_e32 v84, v84
	v_exp_f32_e32 v85, v85
	v_exp_f32_e32 v86, v86
	v_exp_f32_e32 v87, v87
	v_pk_add_f32 v[92:93], v[92:93], 1.0 op_sel_hi:[1,0]
	v_pk_add_f32 v[94:95], v[94:95], 1.0 op_sel_hi:[1,0]
	v_pk_add_f32 v[84:85], v[84:85], 1.0 op_sel_hi:[1,0]
	v_pk_add_f32 v[86:87], v[86:87], 1.0 op_sel_hi:[1,0]
	v_rcp_f32_e32 v92, v92
	v_rcp_f32_e32 v93, v93
	v_rcp_f32_e32 v94, v94
	v_rcp_f32_e32 v95, v95
	v_rcp_f32_e32 v84, v84
	v_rcp_f32_e32 v85, v85
	v_rcp_f32_e32 v86, v86
	v_rcp_f32_e32 v87, v87
	v_pk_mul_f32 v[88:89], v[88:89], v[254:255] op_sel_hi:[1,0]
	v_pk_mul_f32 v[90:91], v[90:91], v[254:255] op_sel_hi:[1,0]
	v_pk_mul_f32 v[80:81], v[80:81], v[254:255] op_sel_hi:[1,0]
	v_pk_mul_f32 v[82:83], v[82:83], v[254:255] op_sel_hi:[1,0]
	v_pk_mul_f32 v[88:89], v[88:89], v[92:93]
	v_pk_mul_f32 v[90:91], v[90:91], v[94:95]
	v_pk_mul_f32 v[80:81], v[80:81], v[84:85]
	v_pk_mul_f32 v[82:83], v[82:83], v[86:87]
	v_cvt_pk_bf16_f32 v88, v88, v89
	v_cvt_pk_bf16_f32 v89, v90, v91
	v_cvt_pk_bf16_f32 v90, v80, v81
	v_cvt_pk_bf16_f32 v91, v82, v83
	global_store_dwordx4 v235, v[88:91], s[10:11]
	v_add_u32_e32 v234, 0x16000, v235
	v_mul_f32_e32 v252, 0xbfb8aa3b, v248
	v_mul_f32_e32 v254, v248, v248
	v_pk_mul_f32 v[72:73], v[76:77], v[72:73]
	v_pk_mul_f32 v[74:75], v[78:79], v[74:75]
	v_pk_mul_f32 v[64:65], v[68:69], v[64:65]
	v_pk_mul_f32 v[66:67], v[70:71], v[66:67]
	v_pk_mul_f32 v[76:77], v[76:77], v[252:253] op_sel_hi:[1,0]
	v_pk_mul_f32 v[78:79], v[78:79], v[252:253] op_sel_hi:[1,0]
	v_pk_mul_f32 v[68:69], v[68:69], v[252:253] op_sel_hi:[1,0]
	v_pk_mul_f32 v[70:71], v[70:71], v[252:253] op_sel_hi:[1,0]
	v_exp_f32_e32 v76, v76
	v_exp_f32_e32 v77, v77
	v_exp_f32_e32 v78, v78
	v_exp_f32_e32 v79, v79
	v_exp_f32_e32 v68, v68
	v_exp_f32_e32 v69, v69
	v_exp_f32_e32 v70, v70
	v_exp_f32_e32 v71, v71
	v_pk_add_f32 v[76:77], v[76:77], 1.0 op_sel_hi:[1,0]
	v_pk_add_f32 v[78:79], v[78:79], 1.0 op_sel_hi:[1,0]
	v_pk_add_f32 v[68:69], v[68:69], 1.0 op_sel_hi:[1,0]
	v_pk_add_f32 v[70:71], v[70:71], 1.0 op_sel_hi:[1,0]
	v_rcp_f32_e32 v76, v76
	v_rcp_f32_e32 v77, v77
	v_rcp_f32_e32 v78, v78
	v_rcp_f32_e32 v79, v79
	v_rcp_f32_e32 v68, v68
	v_rcp_f32_e32 v69, v69
	v_rcp_f32_e32 v70, v70
	v_rcp_f32_e32 v71, v71
	v_pk_mul_f32 v[72:73], v[72:73], v[254:255] op_sel_hi:[1,0]
	v_pk_mul_f32 v[74:75], v[74:75], v[254:255] op_sel_hi:[1,0]
	v_pk_mul_f32 v[64:65], v[64:65], v[254:255] op_sel_hi:[1,0]
	v_pk_mul_f32 v[66:67], v[66:67], v[254:255] op_sel_hi:[1,0]
	v_pk_mul_f32 v[72:73], v[72:73], v[76:77]
	v_pk_mul_f32 v[74:75], v[74:75], v[78:79]
	v_pk_mul_f32 v[64:65], v[64:65], v[68:69]
	v_pk_mul_f32 v[66:67], v[66:67], v[70:71]
	v_cvt_pk_bf16_f32 v72, v72, v73
	v_cvt_pk_bf16_f32 v73, v74, v75
	v_cvt_pk_bf16_f32 v74, v64, v65
	v_cvt_pk_bf16_f32 v75, v66, v67
	global_store_dwordx4 v234, v[72:75], s[10:11]
	s_waitcnt vmcnt(12)
	s_waitcnt lgkmcnt(0)
	s_barrier
	s_setprio 1
	s_waitcnt lgkmcnt(0)
	v_mfma_f32_16x16x32_bf16 v[60:63], v[160:163], v[192:195], v[60:63]
	v_mfma_f32_16x16x32_bf16 v[60:63], v[164:167], v[196:199], v[60:63]
	v_mfma_f32_16x16x32_bf16 v[44:47], v[164:167], v[204:207], v[44:47]
	v_mfma_f32_16x16x32_bf16 v[44:47], v[160:163], v[200:203], v[44:47]
	v_mfma_f32_16x16x32_bf16 v[28:31], v[160:163], v[208:211], v[28:31]
	v_mfma_f32_16x16x32_bf16 v[28:31], v[164:167], v[212:215], v[28:31]
	v_mfma_f32_16x16x32_bf16 v[12:15], v[164:167], v[220:223], v[12:15]
	v_mfma_f32_16x16x32_bf16 v[12:15], v[160:163], v[216:219], v[12:15]
	v_mfma_f32_16x16x32_bf16 v[4:7], v[168:171], v[216:219], v[4:7]
	v_mfma_f32_16x16x32_bf16 v[4:7], v[172:175], v[220:223], v[4:7]
	v_mfma_f32_16x16x32_bf16 v[20:23], v[172:175], v[212:215], v[20:23]
	v_mfma_f32_16x16x32_bf16 v[20:23], v[168:171], v[208:211], v[20:23]
	v_mfma_f32_16x16x32_bf16 v[36:39], v[168:171], v[200:203], v[36:39]
	v_mfma_f32_16x16x32_bf16 v[36:39], v[172:175], v[204:207], v[36:39]
	v_mfma_f32_16x16x32_bf16 v[52:55], v[172:175], v[196:199], v[52:55]
	v_mfma_f32_16x16x32_bf16 v[52:55], v[168:171], v[192:195], v[52:55]
	s_setprio 0
	s_setprio 1
	v_mfma_f32_16x16x32_bf16 v[56:59], v[176:179], v[192:195], v[56:59]
	v_mfma_f32_16x16x32_bf16 v[56:59], v[180:183], v[196:199], v[56:59]
	v_mfma_f32_16x16x32_bf16 v[40:43], v[180:183], v[204:207], v[40:43]
	v_mfma_f32_16x16x32_bf16 v[40:43], v[176:179], v[200:203], v[40:43]
	v_mfma_f32_16x16x32_bf16 v[24:27], v[176:179], v[208:211], v[24:27]
	v_mfma_f32_16x16x32_bf16 v[24:27], v[180:183], v[212:215], v[24:27]
	v_mfma_f32_16x16x32_bf16 v[8:11], v[180:183], v[220:223], v[8:11]
	v_mfma_f32_16x16x32_bf16 v[8:11], v[176:179], v[216:219], v[8:11]
	v_mfma_f32_16x16x32_bf16 v[0:3], v[184:187], v[216:219], v[0:3]
	v_mfma_f32_16x16x32_bf16 v[0:3], v[188:191], v[220:223], v[0:3]
	v_mfma_f32_16x16x32_bf16 v[16:19], v[188:191], v[212:215], v[16:19]
	v_mfma_f32_16x16x32_bf16 v[16:19], v[184:187], v[208:211], v[16:19]
	v_mfma_f32_16x16x32_bf16 v[32:35], v[184:187], v[200:203], v[32:35]
	v_mfma_f32_16x16x32_bf16 v[32:35], v[188:191], v[204:207], v[32:35]
	v_mfma_f32_16x16x32_bf16 v[48:51], v[188:191], v[196:199], v[48:51]
	v_mfma_f32_16x16x32_bf16 v[48:51], v[184:187], v[192:195], v[48:51]
	s_setprio 0
	s_barrier
	s_add_i32 s70, s70, 2
	s_add_u32 s68, s68, 0x100
	s_addc_u32 s69, s69, 0
	s_add_u32 s30, s30, 0x100
	s_addc_u32 s31, s31, 0

.LBB0_1180:
	s_add_u32 s72, s50, 0x100
	s_addc_u32 s73, s51, 0
	s_mov_b32 s74, -2
	s_waitcnt lgkmcnt(0)
	s_cmp_eq_u32 s63, 1
	s_cbranch_scc1 .Lfa_11
	ds_read_b128 v[128:131], v188
	v_xor_b32_e32 v253, 64, v188
	ds_read_b128 v[132:135], v253
	ds_read_b128 v[136:139], v188 offset:2048
	ds_read_b128 v[140:143], v253 offset:2048
	ds_read_b128 v[144:147], v189
	v_xor_b32_e32 v253, 64, v189
	ds_read_b128 v[148:151], v253
	ds_read_b128 v[172:175], v189 offset:2048
	ds_read_b128 v[176:179], v253 offset:2048
	s_add_u32 s50, s48, 0x100
	s_addc_u32 s51, s49, 0
	s_cmp_eq_u32 s74, 40
	s_cselect_b32 s55, s11, s51
	s_cselect_b32 s54, s10, s50
	s_cselect_b32 s53, s47, s73
	s_cselect_b32 s52, s46, s72
	v_lshl_add_u64 v[220:221], s[48:49], 0, v[166:167]
	s_add_i32 m0, s59, 0xc000
	ds_read_b128 v[180:183], v190
	v_xor_b32_e32 v253, 64, v190
	ds_read_b128 v[192:195], v253
	ds_read_b128 v[196:199], v190 offset:2048
	ds_read_b128 v[200:203], v253 offset:2048
	ds_read_b128 v[204:207], v190 offset:4096
	ds_read_b128 v[208:211], v253 offset:4096
	ds_read_b128 v[212:215], v190 offset:6144
	ds_read_b128 v[216:219], v253 offset:6144
	global_load_lds_dwordx4 v[220:221], off
	v_lshl_add_u64 v[220:221], s[48:49], 0, v[164:165]
	s_add_i32 m0, s59, 0xe000
	s_nop 0
	global_load_lds_dwordx4 v[220:221], off
	s_waitcnt vmcnt(24)
	s_waitcnt lgkmcnt(0)
	s_barrier
	s_setprio 1
	s_waitcnt lgkmcnt(0)
	v_mfma_f32_16x16x32_bf16 v[124:127], v[128:131], v[180:183], 0
	v_mfma_f32_16x16x32_bf16 v[120:123], v[136:139], v[180:183], 0
	v_mfma_f32_16x16x32_bf16 v[108:111], v[128:131], v[196:199], 0
	v_mfma_f32_16x16x32_bf16 v[104:107], v[136:139], v[196:199], 0
	v_mfma_f32_16x16x32_bf16 v[92:95], v[128:131], v[204:207], 0
	v_mfma_f32_16x16x32_bf16 v[88:91], v[136:139], v[204:207], 0
	v_mfma_f32_16x16x32_bf16 v[76:79], v[128:131], v[212:215], 0
	v_mfma_f32_16x16x32_bf16 v[72:75], v[136:139], v[212:215], 0
	v_mfma_f32_16x16x32_bf16 v[124:127], v[132:135], v[192:195], v[124:127]
	v_mfma_f32_16x16x32_bf16 v[120:123], v[140:143], v[192:195], v[120:123]
	v_mfma_f32_16x16x32_bf16 v[108:111], v[132:135], v[200:203], v[108:111]
	v_mfma_f32_16x16x32_bf16 v[104:107], v[140:143], v[200:203], v[104:107]
	v_mfma_f32_16x16x32_bf16 v[92:95], v[132:135], v[208:211], v[92:95]
	v_mfma_f32_16x16x32_bf16 v[88:91], v[140:143], v[208:211], v[88:91]
	v_mfma_f32_16x16x32_bf16 v[76:79], v[132:135], v[216:219], v[76:79]
	v_mfma_f32_16x16x32_bf16 v[72:75], v[140:143], v[216:219], v[72:75]
	s_setprio 0
	s_setprio 1
	v_mfma_f32_16x16x32_bf16 v[116:119], v[144:147], v[180:183], 0
	v_mfma_f32_16x16x32_bf16 v[112:115], v[172:175], v[180:183], 0
	v_mfma_f32_16x16x32_bf16 v[100:103], v[144:147], v[196:199], 0
	v_mfma_f32_16x16x32_bf16 v[96:99], v[172:175], v[196:199], 0
	v_mfma_f32_16x16x32_bf16 v[84:87], v[144:147], v[204:207], 0
	v_mfma_f32_16x16x32_bf16 v[80:83], v[172:175], v[204:207], 0
	v_mfma_f32_16x16x32_bf16 v[68:71], v[144:147], v[212:215], 0
	v_mfma_f32_16x16x32_bf16 v[64:67], v[172:175], v[212:215], 0
	v_mfma_f32_16x16x32_bf16 v[116:119], v[148:151], v[192:195], v[116:119]
	v_mfma_f32_16x16x32_bf16 v[112:115], v[176:179], v[192:195], v[112:115]
	v_mfma_f32_16x16x32_bf16 v[100:103], v[148:151], v[200:203], v[100:103]
	v_mfma_f32_16x16x32_bf16 v[96:99], v[176:179], v[200:203], v[96:99]
	v_mfma_f32_16x16x32_bf16 v[84:87], v[148:151], v[208:211], v[84:87]
	v_mfma_f32_16x16x32_bf16 v[80:83], v[176:179], v[208:211], v[80:83]
	v_mfma_f32_16x16x32_bf16 v[68:71], v[148:151], v[216:219], v[68:71]
	v_mfma_f32_16x16x32_bf16 v[64:67], v[176:179], v[216:219], v[64:67]
	s_setprio 0
	s_barrier
	s_add_i32 s48, s68, s58
	v_lshl_add_u64 v[220:221], s[52:53], 0, v[154:155]
	s_mov_b32 m0, s48
	ds_read_b128 v[180:183], v190 offset:16384
	v_xor_b32_e32 v253, 64, v190
	ds_read_b128 v[192:195], v253 offset:16384
	ds_read_b128 v[196:199], v190 offset:18432
	ds_read_b128 v[200:203], v253 offset:18432
	ds_read_b128 v[204:207], v190 offset:20480
	ds_read_b128 v[208:211], v253 offset:20480
	ds_read_b128 v[212:215], v190 offset:22528
	ds_read_b128 v[216:219], v253 offset:22528
	global_load_lds_dwordx4 v[220:221], off
	s_add_i32 m0, s48, 0x2000
	s_add_u32 s48, s52, 0xb0000
	v_lshl_add_u64 v[222:223], s[52:53], 0, v[162:163]
	s_addc_u32 s49, s53, 0
	s_add_i32 s75, s69, s58
	global_load_lds_dwordx4 v[222:223], off
	v_lshl_add_u64 v[224:225], s[48:49], 0, v[154:155]
	s_mov_b32 m0, s75
	v_lshl_add_u64 v[226:227], s[54:55], 0, v[160:161]
	global_load_lds_dwordx4 v[224:225], off
	v_lshl_add_u64 v[224:225], s[48:49], 0, v[162:163]
	s_add_i32 m0, s75, 0x2000
	s_nop 0
	global_load_lds_dwordx4 v[224:225], off
	v_lshl_add_u64 v[224:225], s[54:55], 0, v[152:153]
	s_mov_b32 m0, s59
	s_nop 0
	global_load_lds_dwordx4 v[224:225], off
	s_mov_b32 m0, s60
	s_nop 0
	global_load_lds_dwordx4 v[226:227], off
	s_waitcnt vmcnt(24)
	s_waitcnt lgkmcnt(0)
	s_barrier
	s_setprio 1
	s_waitcnt lgkmcnt(0)
	v_mfma_f32_16x16x32_bf16 v[60:63], v[128:131], v[180:183], 0
	v_mfma_f32_16x16x32_bf16 v[56:59], v[136:139], v[180:183], 0
	v_mfma_f32_16x16x32_bf16 v[44:47], v[128:131], v[196:199], 0
	v_mfma_f32_16x16x32_bf16 v[40:43], v[136:139], v[196:199], 0
	v_mfma_f32_16x16x32_bf16 v[28:31], v[128:131], v[204:207], 0
	v_mfma_f32_16x16x32_bf16 v[24:27], v[136:139], v[204:207], 0
	v_mfma_f32_16x16x32_bf16 v[12:15], v[128:131], v[212:215], 0
	v_mfma_f32_16x16x32_bf16 v[8:11], v[136:139], v[212:215], 0
	v_mfma_f32_16x16x32_bf16 v[60:63], v[132:135], v[192:195], v[60:63]
	v_mfma_f32_16x16x32_bf16 v[56:59], v[140:143], v[192:195], v[56:59]
	v_mfma_f32_16x16x32_bf16 v[44:47], v[132:135], v[200:203], v[44:47]
	v_mfma_f32_16x16x32_bf16 v[40:43], v[140:143], v[200:203], v[40:43]
	v_mfma_f32_16x16x32_bf16 v[28:31], v[132:135], v[208:211], v[28:31]
	v_mfma_f32_16x16x32_bf16 v[24:27], v[140:143], v[208:211], v[24:27]
	v_mfma_f32_16x16x32_bf16 v[12:15], v[132:135], v[216:219], v[12:15]
	v_mfma_f32_16x16x32_bf16 v[8:11], v[140:143], v[216:219], v[8:11]
	s_setprio 0
	s_setprio 1
	v_mfma_f32_16x16x32_bf16 v[52:55], v[144:147], v[180:183], 0
	v_mfma_f32_16x16x32_bf16 v[48:51], v[172:175], v[180:183], 0
	v_mfma_f32_16x16x32_bf16 v[36:39], v[144:147], v[196:199], 0
	v_mfma_f32_16x16x32_bf16 v[32:35], v[172:175], v[196:199], 0
	v_mfma_f32_16x16x32_bf16 v[20:23], v[144:147], v[204:207], 0
	v_mfma_f32_16x16x32_bf16 v[16:19], v[172:175], v[204:207], 0
	v_mfma_f32_16x16x32_bf16 v[4:7], v[144:147], v[212:215], 0
	v_mfma_f32_16x16x32_bf16 v[0:3], v[172:175], v[212:215], 0
	v_mfma_f32_16x16x32_bf16 v[52:55], v[148:151], v[192:195], v[52:55]
	v_mfma_f32_16x16x32_bf16 v[48:51], v[176:179], v[192:195], v[48:51]
	v_mfma_f32_16x16x32_bf16 v[36:39], v[148:151], v[200:203], v[36:39]
	v_mfma_f32_16x16x32_bf16 v[32:35], v[176:179], v[200:203], v[32:35]
	v_mfma_f32_16x16x32_bf16 v[20:23], v[148:151], v[208:211], v[20:23]
	v_mfma_f32_16x16x32_bf16 v[16:19], v[176:179], v[208:211], v[16:19]
	v_mfma_f32_16x16x32_bf16 v[4:7], v[148:151], v[216:219], v[4:7]
	v_mfma_f32_16x16x32_bf16 v[0:3], v[176:179], v[216:219], v[0:3]
	s_setprio 0
	s_barrier
	s_add_i32 s75, 0, 0x18000
	s_add_i32 s76, 0, 0x1c000
	v_add_u32_e32 v140, s75, v185
	v_add_u32_e32 v176, s76, v185
	ds_read_b128 v[128:131], v140
	v_xor_b32_e32 v253, 64, v140
	ds_read_b128 v[132:135], v253
	ds_read_b128 v[136:139], v140 offset:2048
	ds_read_b128 v[140:143], v253 offset:2048
	ds_read_b128 v[144:147], v176
	v_xor_b32_e32 v253, 64, v176
	ds_read_b128 v[148:151], v253
	ds_read_b128 v[172:175], v176 offset:2048
	ds_read_b128 v[176:179], v253 offset:2048
	s_add_u32 s48, s54, 0xb0000
	s_addc_u32 s49, s55, 0
	s_mov_b32 m0, s61
	v_lshl_add_u64 v[228:229], s[48:49], 0, v[152:153]
	ds_read_b128 v[180:183], v190 offset:32768
	v_xor_b32_e32 v253, 64, v190
	ds_read_b128 v[192:195], v253 offset:32768
	ds_read_b128 v[196:199], v190 offset:34816
	ds_read_b128 v[200:203], v253 offset:34816
	ds_read_b128 v[204:207], v190 offset:36864
	ds_read_b128 v[208:211], v253 offset:36864
	ds_read_b128 v[212:215], v190 offset:38912
	ds_read_b128 v[216:219], v253 offset:38912
	global_load_lds_dwordx4 v[228:229], off
	v_lshl_add_u64 v[228:229], s[48:49], 0, v[160:161]
	s_mov_b32 m0, s62
	s_nop 0
	global_load_lds_dwordx4 v[228:229], off
	s_waitcnt vmcnt(8)
	s_waitcnt lgkmcnt(0)
	s_barrier
	s_setprio 1
	s_waitcnt lgkmcnt(0)
	v_mfma_f32_16x16x32_bf16 v[124:127], v[128:131], v[180:183], v[124:127]
	v_mfma_f32_16x16x32_bf16 v[124:127], v[132:135], v[192:195], v[124:127]
	v_mfma_f32_16x16x32_bf16 v[108:111], v[132:135], v[200:203], v[108:111]
	v_mfma_f32_16x16x32_bf16 v[108:111], v[128:131], v[196:199], v[108:111]
	v_mfma_f32_16x16x32_bf16 v[92:95], v[128:131], v[204:207], v[92:95]
	v_mfma_f32_16x16x32_bf16 v[92:95], v[132:135], v[208:211], v[92:95]
	v_mfma_f32_16x16x32_bf16 v[76:79], v[132:135], v[216:219], v[76:79]
	v_mfma_f32_16x16x32_bf16 v[76:79], v[128:131], v[212:215], v[76:79]
	v_mfma_f32_16x16x32_bf16 v[72:75], v[136:139], v[212:215], v[72:75]
	v_mfma_f32_16x16x32_bf16 v[72:75], v[140:143], v[216:219], v[72:75]
	v_mfma_f32_16x16x32_bf16 v[88:91], v[140:143], v[208:211], v[88:91]
	v_mfma_f32_16x16x32_bf16 v[88:91], v[136:139], v[204:207], v[88:91]
	v_mfma_f32_16x16x32_bf16 v[104:107], v[136:139], v[196:199], v[104:107]
	v_mfma_f32_16x16x32_bf16 v[104:107], v[140:143], v[200:203], v[104:107]
	v_mfma_f32_16x16x32_bf16 v[120:123], v[140:143], v[192:195], v[120:123]
	v_mfma_f32_16x16x32_bf16 v[120:123], v[136:139], v[180:183], v[120:123]
	s_setprio 0
	s_setprio 1
	v_mfma_f32_16x16x32_bf16 v[116:119], v[144:147], v[180:183], v[116:119]
	v_mfma_f32_16x16x32_bf16 v[116:119], v[148:151], v[192:195], v[116:119]
	v_mfma_f32_16x16x32_bf16 v[100:103], v[148:151], v[200:203], v[100:103]
	v_mfma_f32_16x16x32_bf16 v[100:103], v[144:147], v[196:199], v[100:103]
	v_mfma_f32_16x16x32_bf16 v[84:87], v[144:147], v[204:207], v[84:87]
	v_mfma_f32_16x16x32_bf16 v[84:87], v[148:151], v[208:211], v[84:87]
	v_mfma_f32_16x16x32_bf16 v[68:71], v[148:151], v[216:219], v[68:71]
	v_mfma_f32_16x16x32_bf16 v[68:71], v[144:147], v[212:215], v[68:71]
	v_mfma_f32_16x16x32_bf16 v[64:67], v[172:175], v[212:215], v[64:67]
	v_mfma_f32_16x16x32_bf16 v[64:67], v[176:179], v[216:219], v[64:67]
	v_mfma_f32_16x16x32_bf16 v[80:83], v[176:179], v[208:211], v[80:83]
	v_mfma_f32_16x16x32_bf16 v[80:83], v[172:175], v[204:207], v[80:83]
	v_mfma_f32_16x16x32_bf16 v[96:99], v[172:175], v[196:199], v[96:99]
	v_mfma_f32_16x16x32_bf16 v[96:99], v[176:179], v[200:203], v[96:99]
	v_mfma_f32_16x16x32_bf16 v[112:115], v[176:179], v[192:195], v[112:115]
	v_mfma_f32_16x16x32_bf16 v[112:115], v[172:175], v[180:183], v[112:115]
	s_setprio 0
	s_barrier
	s_add_i32 s48, s75, s58
	v_lshl_add_u64 v[220:221], v[220:221], 0, s[22:23]
	s_mov_b32 m0, s48
	ds_read_b128 v[180:183], v190 offset:49152
	v_xor_b32_e32 v253, 64, v190
	ds_read_b128 v[192:195], v253 offset:49152
	ds_read_b128 v[196:199], v190 offset:51200
	ds_read_b128 v[200:203], v253 offset:51200
	ds_read_b128 v[204:207], v190 offset:53248
	ds_read_b128 v[208:211], v253 offset:53248
	ds_read_b128 v[212:215], v190 offset:55296
	ds_read_b128 v[216:219], v253 offset:55296
	global_load_lds_dwordx4 v[220:221], off
	s_add_i32 m0, s48, 0x2000
	s_add_u32 s48, s52, 0xb0080
	v_lshl_add_u64 v[220:221], v[222:223], 0, s[22:23]
	s_addc_u32 s49, s53, 0
	s_add_i32 s52, s76, s58
	global_load_lds_dwordx4 v[220:221], off
	v_lshl_add_u64 v[220:221], s[48:49], 0, v[154:155]
	s_mov_b32 m0, s52
	s_nop 0
	global_load_lds_dwordx4 v[220:221], off
	v_lshl_add_u64 v[220:221], s[48:49], 0, v[162:163]
	s_add_i32 m0, s52, 0x2000
	s_nop 0
	global_load_lds_dwordx4 v[220:221], off
	v_lshl_add_u64 v[220:221], v[224:225], 0, s[22:23]
	s_mov_b32 m0, s3
	s_nop 0
	global_load_lds_dwordx4 v[220:221], off
	v_lshl_add_u64 v[220:221], v[226:227], 0, s[22:23]
	s_mov_b32 m0, s64
	s_nop 0
	global_load_lds_dwordx4 v[220:221], off
	s_waitcnt vmcnt(8)
	s_waitcnt lgkmcnt(0)
	s_barrier
	s_setprio 1
	s_waitcnt lgkmcnt(0)
	v_mfma_f32_16x16x32_bf16 v[60:63], v[128:131], v[180:183], v[60:63]
	v_mfma_f32_16x16x32_bf16 v[60:63], v[132:135], v[192:195], v[60:63]
	v_mfma_f32_16x16x32_bf16 v[44:47], v[132:135], v[200:203], v[44:47]
	v_mfma_f32_16x16x32_bf16 v[44:47], v[128:131], v[196:199], v[44:47]
	v_mfma_f32_16x16x32_bf16 v[28:31], v[128:131], v[204:207], v[28:31]
	v_mfma_f32_16x16x32_bf16 v[28:31], v[132:135], v[208:211], v[28:31]
	v_mfma_f32_16x16x32_bf16 v[12:15], v[132:135], v[216:219], v[12:15]
	v_mfma_f32_16x16x32_bf16 v[12:15], v[128:131], v[212:215], v[12:15]
	v_mfma_f32_16x16x32_bf16 v[8:11], v[136:139], v[212:215], v[8:11]
	v_mfma_f32_16x16x32_bf16 v[8:11], v[140:143], v[216:219], v[8:11]
	v_mfma_f32_16x16x32_bf16 v[24:27], v[140:143], v[208:211], v[24:27]
	v_mfma_f32_16x16x32_bf16 v[24:27], v[136:139], v[204:207], v[24:27]
	v_mfma_f32_16x16x32_bf16 v[40:43], v[136:139], v[196:199], v[40:43]
	v_mfma_f32_16x16x32_bf16 v[40:43], v[140:143], v[200:203], v[40:43]
	v_mfma_f32_16x16x32_bf16 v[56:59], v[140:143], v[192:195], v[56:59]
	v_mfma_f32_16x16x32_bf16 v[56:59], v[136:139], v[180:183], v[56:59]
	s_setprio 0
	s_setprio 1
	v_mfma_f32_16x16x32_bf16 v[52:55], v[144:147], v[180:183], v[52:55]
	v_mfma_f32_16x16x32_bf16 v[52:55], v[148:151], v[192:195], v[52:55]
	v_mfma_f32_16x16x32_bf16 v[36:39], v[148:151], v[200:203], v[36:39]
	v_mfma_f32_16x16x32_bf16 v[36:39], v[144:147], v[196:199], v[36:39]
	v_mfma_f32_16x16x32_bf16 v[20:23], v[144:147], v[204:207], v[20:23]
	v_mfma_f32_16x16x32_bf16 v[20:23], v[148:151], v[208:211], v[20:23]
	v_mfma_f32_16x16x32_bf16 v[4:7], v[148:151], v[216:219], v[4:7]
	v_mfma_f32_16x16x32_bf16 v[4:7], v[144:147], v[212:215], v[4:7]
	v_mfma_f32_16x16x32_bf16 v[0:3], v[172:175], v[212:215], v[0:3]
	v_mfma_f32_16x16x32_bf16 v[0:3], v[176:179], v[216:219], v[0:3]
	v_mfma_f32_16x16x32_bf16 v[16:19], v[176:179], v[208:211], v[16:19]
	v_mfma_f32_16x16x32_bf16 v[16:19], v[172:175], v[204:207], v[16:19]
	v_mfma_f32_16x16x32_bf16 v[32:35], v[172:175], v[196:199], v[32:35]
	v_mfma_f32_16x16x32_bf16 v[32:35], v[176:179], v[200:203], v[32:35]
	v_mfma_f32_16x16x32_bf16 v[48:51], v[176:179], v[192:195], v[48:51]
	v_mfma_f32_16x16x32_bf16 v[48:51], v[172:175], v[180:183], v[48:51]
	s_setprio 0
	s_barrier
	s_add_i32 s74, s74, 2
	s_add_u32 s72, s72, 0x100
	s_addc_u32 s73, s73, 0
	s_cmp_gt_u32 s74, 41
	s_mov_b64 s[48:49], s[50:51]
	s_branch .LBB0_1181
.Lfa_11:
	ds_read_b128 v[128:131], v188
	v_xor_b32_e32 v253, 64, v188
	ds_read_b128 v[132:135], v253
	ds_read_b128 v[136:139], v188 offset:2048
	ds_read_b128 v[140:143], v253 offset:2048
	ds_read_b128 v[144:147], v189
	v_xor_b32_e32 v253, 64, v189
	ds_read_b128 v[148:151], v253
	ds_read_b128 v[172:175], v189 offset:2048
	ds_read_b128 v[176:179], v253 offset:2048
	s_add_u32 s50, s48, 0x100
	s_addc_u32 s51, s49, 0
	s_cmp_eq_u32 s74, 40
	s_cselect_b32 s55, s11, s51
	s_cselect_b32 s54, s10, s50
	s_cselect_b32 s53, s47, s73
	s_cselect_b32 s52, s46, s72
	v_lshl_add_u64 v[220:221], s[48:49], 0, v[166:167]
	s_add_i32 m0, s59, 0xc000
	ds_read_b128 v[180:183], v190
	v_xor_b32_e32 v253, 64, v190
	ds_read_b128 v[192:195], v253
	ds_read_b128 v[196:199], v190 offset:2048
	ds_read_b128 v[200:203], v253 offset:2048
	ds_read_b128 v[204:207], v190 offset:4096
	ds_read_b128 v[208:211], v253 offset:4096
	ds_read_b128 v[212:215], v190 offset:6144
	ds_read_b128 v[216:219], v253 offset:6144
	global_load_lds_dwordx4 v[220:221], off
	v_lshl_add_u64 v[220:221], s[48:49], 0, v[164:165]
	s_add_i32 m0, s59, 0xe000
	s_nop 0
	global_load_lds_dwordx4 v[220:221], off
	s_waitcnt vmcnt(8)
	s_waitcnt lgkmcnt(0)
	s_barrier
	s_setprio 1
	s_waitcnt lgkmcnt(0)
	v_mfma_f32_16x16x32_bf16 v[124:127], v[128:131], v[180:183], 0
	v_mfma_f32_16x16x32_bf16 v[120:123], v[136:139], v[180:183], 0
	v_mfma_f32_16x16x32_bf16 v[108:111], v[128:131], v[196:199], 0
	v_mfma_f32_16x16x32_bf16 v[104:107], v[136:139], v[196:199], 0
	v_mfma_f32_16x16x32_bf16 v[92:95], v[128:131], v[204:207], 0
	v_mfma_f32_16x16x32_bf16 v[88:91], v[136:139], v[204:207], 0
	v_mfma_f32_16x16x32_bf16 v[76:79], v[128:131], v[212:215], 0
	v_mfma_f32_16x16x32_bf16 v[72:75], v[136:139], v[212:215], 0
	v_mfma_f32_16x16x32_bf16 v[124:127], v[132:135], v[192:195], v[124:127]
	v_mfma_f32_16x16x32_bf16 v[120:123], v[140:143], v[192:195], v[120:123]
	v_mfma_f32_16x16x32_bf16 v[108:111], v[132:135], v[200:203], v[108:111]
	v_mfma_f32_16x16x32_bf16 v[104:107], v[140:143], v[200:203], v[104:107]
	v_mfma_f32_16x16x32_bf16 v[92:95], v[132:135], v[208:211], v[92:95]
	v_mfma_f32_16x16x32_bf16 v[88:91], v[140:143], v[208:211], v[88:91]
	v_mfma_f32_16x16x32_bf16 v[76:79], v[132:135], v[216:219], v[76:79]
	v_mfma_f32_16x16x32_bf16 v[72:75], v[140:143], v[216:219], v[72:75]
	s_setprio 0
	s_setprio 1
	v_mfma_f32_16x16x32_bf16 v[116:119], v[144:147], v[180:183], 0
	v_mfma_f32_16x16x32_bf16 v[112:115], v[172:175], v[180:183], 0
	v_mfma_f32_16x16x32_bf16 v[100:103], v[144:147], v[196:199], 0
	v_mfma_f32_16x16x32_bf16 v[96:99], v[172:175], v[196:199], 0
	v_mfma_f32_16x16x32_bf16 v[84:87], v[144:147], v[204:207], 0
	v_mfma_f32_16x16x32_bf16 v[80:83], v[172:175], v[204:207], 0
	v_mfma_f32_16x16x32_bf16 v[68:71], v[144:147], v[212:215], 0
	v_mfma_f32_16x16x32_bf16 v[64:67], v[172:175], v[212:215], 0
	v_mfma_f32_16x16x32_bf16 v[116:119], v[148:151], v[192:195], v[116:119]
	v_mfma_f32_16x16x32_bf16 v[112:115], v[176:179], v[192:195], v[112:115]
	v_mfma_f32_16x16x32_bf16 v[100:103], v[148:151], v[200:203], v[100:103]
	v_mfma_f32_16x16x32_bf16 v[96:99], v[176:179], v[200:203], v[96:99]
	v_mfma_f32_16x16x32_bf16 v[84:87], v[148:151], v[208:211], v[84:87]
	v_mfma_f32_16x16x32_bf16 v[80:83], v[176:179], v[208:211], v[80:83]
	v_mfma_f32_16x16x32_bf16 v[68:71], v[148:151], v[216:219], v[68:71]
	v_mfma_f32_16x16x32_bf16 v[64:67], v[176:179], v[216:219], v[64:67]
	s_setprio 0
	s_barrier
	s_add_i32 s48, s68, s58
	v_lshl_add_u64 v[220:221], s[52:53], 0, v[154:155]
	s_mov_b32 m0, s48
	ds_read_b128 v[180:183], v190 offset:16384
	v_xor_b32_e32 v253, 64, v190
	ds_read_b128 v[192:195], v253 offset:16384
	ds_read_b128 v[196:199], v190 offset:18432
	ds_read_b128 v[200:203], v253 offset:18432
	ds_read_b128 v[204:207], v190 offset:20480
	ds_read_b128 v[208:211], v253 offset:20480
	ds_read_b128 v[212:215], v190 offset:22528
	ds_read_b128 v[216:219], v253 offset:22528
	global_load_lds_dwordx4 v[220:221], off
	s_add_i32 m0, s48, 0x2000
	s_add_u32 s48, s52, 0xb0000
	v_lshl_add_u64 v[222:223], s[52:53], 0, v[162:163]
	s_addc_u32 s49, s53, 0
	s_add_i32 s75, s69, s58
	global_load_lds_dwordx4 v[222:223], off
	v_lshl_add_u64 v[224:225], s[48:49], 0, v[154:155]
	s_mov_b32 m0, s75
	v_lshl_add_u64 v[226:227], s[54:55], 0, v[160:161]
	global_load_lds_dwordx4 v[224:225], off
	v_lshl_add_u64 v[224:225], s[48:49], 0, v[162:163]
	s_add_i32 m0, s75, 0x2000
	s_nop 0
	global_load_lds_dwordx4 v[224:225], off
	v_lshl_add_u64 v[224:225], s[54:55], 0, v[152:153]
	s_mov_b32 m0, s59
	s_nop 0
	global_load_lds_dwordx4 v[224:225], off
	s_mov_b32 m0, s60
	s_nop 0
	global_load_lds_dwordx4 v[226:227], off
	s_waitcnt vmcnt(8)
	s_waitcnt lgkmcnt(0)
	s_barrier
	s_setprio 1
	s_waitcnt lgkmcnt(0)
	v_mfma_f32_16x16x32_bf16 v[60:63], v[128:131], v[180:183], 0
	v_mfma_f32_16x16x32_bf16 v[56:59], v[136:139], v[180:183], 0
	v_mfma_f32_16x16x32_bf16 v[44:47], v[128:131], v[196:199], 0
	v_mfma_f32_16x16x32_bf16 v[40:43], v[136:139], v[196:199], 0
	v_mfma_f32_16x16x32_bf16 v[28:31], v[128:131], v[204:207], 0
	v_mfma_f32_16x16x32_bf16 v[24:27], v[136:139], v[204:207], 0
	v_mfma_f32_16x16x32_bf16 v[12:15], v[128:131], v[212:215], 0
	v_mfma_f32_16x16x32_bf16 v[8:11], v[136:139], v[212:215], 0
	v_mfma_f32_16x16x32_bf16 v[60:63], v[132:135], v[192:195], v[60:63]
	v_mfma_f32_16x16x32_bf16 v[56:59], v[140:143], v[192:195], v[56:59]
	v_mfma_f32_16x16x32_bf16 v[44:47], v[132:135], v[200:203], v[44:47]
	v_mfma_f32_16x16x32_bf16 v[40:43], v[140:143], v[200:203], v[40:43]
	v_mfma_f32_16x16x32_bf16 v[28:31], v[132:135], v[208:211], v[28:31]
	v_mfma_f32_16x16x32_bf16 v[24:27], v[140:143], v[208:211], v[24:27]
	v_mfma_f32_16x16x32_bf16 v[12:15], v[132:135], v[216:219], v[12:15]
	v_mfma_f32_16x16x32_bf16 v[8:11], v[140:143], v[216:219], v[8:11]
	s_setprio 0
	s_setprio 1
	v_mfma_f32_16x16x32_bf16 v[52:55], v[144:147], v[180:183], 0
	v_mfma_f32_16x16x32_bf16 v[48:51], v[172:175], v[180:183], 0
	v_mfma_f32_16x16x32_bf16 v[36:39], v[144:147], v[196:199], 0
	v_mfma_f32_16x16x32_bf16 v[32:35], v[172:175], v[196:199], 0
	v_mfma_f32_16x16x32_bf16 v[20:23], v[144:147], v[204:207], 0
	v_mfma_f32_16x16x32_bf16 v[16:19], v[172:175], v[204:207], 0
	v_mfma_f32_16x16x32_bf16 v[4:7], v[144:147], v[212:215], 0
	v_mfma_f32_16x16x32_bf16 v[0:3], v[172:175], v[212:215], 0
	v_mfma_f32_16x16x32_bf16 v[52:55], v[148:151], v[192:195], v[52:55]
	v_mfma_f32_16x16x32_bf16 v[48:51], v[176:179], v[192:195], v[48:51]
	v_mfma_f32_16x16x32_bf16 v[36:39], v[148:151], v[200:203], v[36:39]
	v_mfma_f32_16x16x32_bf16 v[32:35], v[176:179], v[200:203], v[32:35]
	v_mfma_f32_16x16x32_bf16 v[20:23], v[148:151], v[208:211], v[20:23]
	v_mfma_f32_16x16x32_bf16 v[16:19], v[176:179], v[208:211], v[16:19]
	v_mfma_f32_16x16x32_bf16 v[4:7], v[148:151], v[216:219], v[4:7]
	v_mfma_f32_16x16x32_bf16 v[0:3], v[176:179], v[216:219], v[0:3]
	s_setprio 0
	s_barrier
	s_add_i32 s75, 0, 0x18000
	s_add_i32 s76, 0, 0x1c000
	v_add_u32_e32 v140, s75, v185
	v_add_u32_e32 v176, s76, v185
	ds_read_b128 v[128:131], v140
	v_xor_b32_e32 v253, 64, v140
	ds_read_b128 v[132:135], v253
	ds_read_b128 v[136:139], v140 offset:2048
	ds_read_b128 v[140:143], v253 offset:2048
	ds_read_b128 v[144:147], v176
	v_xor_b32_e32 v253, 64, v176
	ds_read_b128 v[148:151], v253
	ds_read_b128 v[172:175], v176 offset:2048
	ds_read_b128 v[176:179], v253 offset:2048
	s_add_u32 s48, s54, 0xb0000
	s_addc_u32 s49, s55, 0
	s_mov_b32 m0, s61
	v_lshl_add_u64 v[228:229], s[48:49], 0, v[152:153]
	ds_read_b128 v[180:183], v190 offset:32768
	v_xor_b32_e32 v253, 64, v190
	ds_read_b128 v[192:195], v253 offset:32768
	ds_read_b128 v[196:199], v190 offset:34816
	ds_read_b128 v[200:203], v253 offset:34816
	ds_read_b128 v[204:207], v190 offset:36864
	ds_read_b128 v[208:211], v253 offset:36864
	ds_read_b128 v[212:215], v190 offset:38912
	ds_read_b128 v[216:219], v253 offset:38912
	global_load_lds_dwordx4 v[228:229], off
	v_lshl_add_u64 v[228:229], s[48:49], 0, v[160:161]
	s_mov_b32 m0, s62
	s_nop 0
	global_load_lds_dwordx4 v[228:229], off
	s_waitcnt vmcnt(8)
	s_waitcnt lgkmcnt(0)
	s_barrier
	s_setprio 1
	s_waitcnt lgkmcnt(0)
	v_mfma_f32_16x16x32_bf16 v[124:127], v[128:131], v[180:183], v[124:127]
	v_mfma_f32_16x16x32_bf16 v[124:127], v[132:135], v[192:195], v[124:127]
	v_mfma_f32_16x16x32_bf16 v[108:111], v[132:135], v[200:203], v[108:111]
	v_mfma_f32_16x16x32_bf16 v[108:111], v[128:131], v[196:199], v[108:111]
	v_mfma_f32_16x16x32_bf16 v[92:95], v[128:131], v[204:207], v[92:95]
	v_mfma_f32_16x16x32_bf16 v[92:95], v[132:135], v[208:211], v[92:95]
	v_mfma_f32_16x16x32_bf16 v[76:79], v[132:135], v[216:219], v[76:79]
	v_mfma_f32_16x16x32_bf16 v[76:79], v[128:131], v[212:215], v[76:79]
	v_mfma_f32_16x16x32_bf16 v[72:75], v[136:139], v[212:215], v[72:75]
	v_mfma_f32_16x16x32_bf16 v[72:75], v[140:143], v[216:219], v[72:75]
	v_mfma_f32_16x16x32_bf16 v[88:91], v[140:143], v[208:211], v[88:91]
	v_mfma_f32_16x16x32_bf16 v[88:91], v[136:139], v[204:207], v[88:91]
	v_mfma_f32_16x16x32_bf16 v[104:107], v[136:139], v[196:199], v[104:107]
	v_mfma_f32_16x16x32_bf16 v[104:107], v[140:143], v[200:203], v[104:107]
	v_mfma_f32_16x16x32_bf16 v[120:123], v[140:143], v[192:195], v[120:123]
	v_mfma_f32_16x16x32_bf16 v[120:123], v[136:139], v[180:183], v[120:123]
	s_setprio 0
	s_setprio 1
	v_mfma_f32_16x16x32_bf16 v[116:119], v[144:147], v[180:183], v[116:119]
	v_mfma_f32_16x16x32_bf16 v[116:119], v[148:151], v[192:195], v[116:119]
	v_mfma_f32_16x16x32_bf16 v[100:103], v[148:151], v[200:203], v[100:103]
	v_mfma_f32_16x16x32_bf16 v[100:103], v[144:147], v[196:199], v[100:103]
	v_mfma_f32_16x16x32_bf16 v[84:87], v[144:147], v[204:207], v[84:87]
	v_mfma_f32_16x16x32_bf16 v[84:87], v[148:151], v[208:211], v[84:87]
	v_mfma_f32_16x16x32_bf16 v[68:71], v[148:151], v[216:219], v[68:71]
	v_mfma_f32_16x16x32_bf16 v[68:71], v[144:147], v[212:215], v[68:71]
	v_mfma_f32_16x16x32_bf16 v[64:67], v[172:175], v[212:215], v[64:67]
	v_mfma_f32_16x16x32_bf16 v[64:67], v[176:179], v[216:219], v[64:67]
	v_mfma_f32_16x16x32_bf16 v[80:83], v[176:179], v[208:211], v[80:83]
	v_mfma_f32_16x16x32_bf16 v[80:83], v[172:175], v[204:207], v[80:83]
	v_mfma_f32_16x16x32_bf16 v[96:99], v[172:175], v[196:199], v[96:99]
	v_mfma_f32_16x16x32_bf16 v[96:99], v[176:179], v[200:203], v[96:99]
	v_mfma_f32_16x16x32_bf16 v[112:115], v[176:179], v[192:195], v[112:115]
	v_mfma_f32_16x16x32_bf16 v[112:115], v[172:175], v[180:183], v[112:115]
	s_setprio 0
	s_barrier
	s_add_i32 s48, s75, s58
	v_lshl_add_u64 v[220:221], v[220:221], 0, s[22:23]
	s_mov_b32 m0, s48
	ds_read_b128 v[180:183], v190 offset:49152
	v_xor_b32_e32 v253, 64, v190
	ds_read_b128 v[192:195], v253 offset:49152
	ds_read_b128 v[196:199], v190 offset:51200
	ds_read_b128 v[200:203], v253 offset:51200
	ds_read_b128 v[204:207], v190 offset:53248
	ds_read_b128 v[208:211], v253 offset:53248
	ds_read_b128 v[212:215], v190 offset:55296
	ds_read_b128 v[216:219], v253 offset:55296
	global_load_lds_dwordx4 v[220:221], off
	s_add_i32 m0, s48, 0x2000
	s_add_u32 s48, s52, 0xb0080
	v_lshl_add_u64 v[220:221], v[222:223], 0, s[22:23]
	s_addc_u32 s49, s53, 0
	s_add_i32 s52, s76, s58
	global_load_lds_dwordx4 v[220:221], off
	v_lshl_add_u64 v[220:221], s[48:49], 0, v[154:155]
	s_mov_b32 m0, s52
	s_nop 0
	global_load_lds_dwordx4 v[220:221], off
	v_lshl_add_u64 v[220:221], s[48:49], 0, v[162:163]
	s_add_i32 m0, s52, 0x2000
	s_nop 0
	global_load_lds_dwordx4 v[220:221], off
	v_lshl_add_u64 v[220:221], v[224:225], 0, s[22:23]
	s_mov_b32 m0, s3
	s_nop 0
	global_load_lds_dwordx4 v[220:221], off
	v_lshl_add_u64 v[220:221], v[226:227], 0, s[22:23]
	s_mov_b32 m0, s64
	s_nop 0
	global_load_lds_dwordx4 v[220:221], off
	s_waitcnt vmcnt(8)
	s_waitcnt lgkmcnt(0)
	s_barrier
	s_setprio 1
	s_waitcnt lgkmcnt(0)
	v_mfma_f32_16x16x32_bf16 v[60:63], v[128:131], v[180:183], v[60:63]
	v_mfma_f32_16x16x32_bf16 v[60:63], v[132:135], v[192:195], v[60:63]
	v_mfma_f32_16x16x32_bf16 v[44:47], v[132:135], v[200:203], v[44:47]
	v_mfma_f32_16x16x32_bf16 v[44:47], v[128:131], v[196:199], v[44:47]
	v_mfma_f32_16x16x32_bf16 v[28:31], v[128:131], v[204:207], v[28:31]
	v_mfma_f32_16x16x32_bf16 v[28:31], v[132:135], v[208:211], v[28:31]
	v_mfma_f32_16x16x32_bf16 v[12:15], v[132:135], v[216:219], v[12:15]
	v_mfma_f32_16x16x32_bf16 v[12:15], v[128:131], v[212:215], v[12:15]
	v_mfma_f32_16x16x32_bf16 v[8:11], v[136:139], v[212:215], v[8:11]
	v_mfma_f32_16x16x32_bf16 v[8:11], v[140:143], v[216:219], v[8:11]
	v_mfma_f32_16x16x32_bf16 v[24:27], v[140:143], v[208:211], v[24:27]
	v_mfma_f32_16x16x32_bf16 v[24:27], v[136:139], v[204:207], v[24:27]
	v_mfma_f32_16x16x32_bf16 v[40:43], v[136:139], v[196:199], v[40:43]
	v_mfma_f32_16x16x32_bf16 v[40:43], v[140:143], v[200:203], v[40:43]
	v_mfma_f32_16x16x32_bf16 v[56:59], v[140:143], v[192:195], v[56:59]
	v_mfma_f32_16x16x32_bf16 v[56:59], v[136:139], v[180:183], v[56:59]
	s_setprio 0
	s_setprio 1
	v_mfma_f32_16x16x32_bf16 v[52:55], v[144:147], v[180:183], v[52:55]
	v_mfma_f32_16x16x32_bf16 v[52:55], v[148:151], v[192:195], v[52:55]
	v_mfma_f32_16x16x32_bf16 v[36:39], v[148:151], v[200:203], v[36:39]
	v_mfma_f32_16x16x32_bf16 v[36:39], v[144:147], v[196:199], v[36:39]
	v_mfma_f32_16x16x32_bf16 v[20:23], v[144:147], v[204:207], v[20:23]
	v_mfma_f32_16x16x32_bf16 v[20:23], v[148:151], v[208:211], v[20:23]
	v_mfma_f32_16x16x32_bf16 v[4:7], v[148:151], v[216:219], v[4:7]
	v_mfma_f32_16x16x32_bf16 v[4:7], v[144:147], v[212:215], v[4:7]
	v_mfma_f32_16x16x32_bf16 v[0:3], v[172:175], v[212:215], v[0:3]
	v_mfma_f32_16x16x32_bf16 v[0:3], v[176:179], v[216:219], v[0:3]
	v_mfma_f32_16x16x32_bf16 v[16:19], v[176:179], v[208:211], v[16:19]
	v_mfma_f32_16x16x32_bf16 v[16:19], v[172:175], v[204:207], v[16:19]
	v_mfma_f32_16x16x32_bf16 v[32:35], v[172:175], v[196:199], v[32:35]
	v_mfma_f32_16x16x32_bf16 v[32:35], v[176:179], v[200:203], v[32:35]
	v_mfma_f32_16x16x32_bf16 v[48:51], v[176:179], v[192:195], v[48:51]
	v_mfma_f32_16x16x32_bf16 v[48:51], v[172:175], v[180:183], v[48:51]
	s_setprio 0
	s_barrier
	s_add_i32 s74, s74, 2
	s_add_u32 s72, s72, 0x100
	s_addc_u32 s73, s73, 0
	s_cmp_gt_u32 s74, 41
	s_mov_b64 s[48:49], s[50:51]
.LBB0_1181:
	ds_read_b128 v[128:131], v188
	v_xor_b32_e32 v253, 64, v188
	ds_read_b128 v[132:135], v253
	ds_read_b128 v[136:139], v188 offset:2048
	ds_read_b128 v[140:143], v253 offset:2048
	ds_read_b128 v[144:147], v189
	v_xor_b32_e32 v253, 64, v189
	ds_read_b128 v[148:151], v253
	ds_read_b128 v[172:175], v189 offset:2048
	ds_read_b128 v[176:179], v253 offset:2048
	s_add_u32 s50, s48, 0x100
	s_addc_u32 s51, s49, 0
	s_cmp_eq_u32 s74, 40
	s_cselect_b32 s55, s11, s51
	s_cselect_b32 s54, s10, s50
	s_cselect_b32 s53, s47, s73
	s_cselect_b32 s52, s46, s72
	v_lshl_add_u64 v[220:221], s[48:49], 0, v[166:167]
	s_add_i32 m0, s59, 0xc000
	ds_read_b128 v[180:183], v190
	v_xor_b32_e32 v253, 64, v190
	ds_read_b128 v[192:195], v253
	ds_read_b128 v[196:199], v190 offset:2048
	ds_read_b128 v[200:203], v253 offset:2048
	ds_read_b128 v[204:207], v190 offset:4096
	ds_read_b128 v[208:211], v253 offset:4096
	ds_read_b128 v[212:215], v190 offset:6144
	ds_read_b128 v[216:219], v253 offset:6144
	global_load_lds_dwordx4 v[220:221], off
	v_lshl_add_u64 v[220:221], s[48:49], 0, v[164:165]
	s_add_i32 m0, s59, 0xe000
	s_nop 0
	global_load_lds_dwordx4 v[220:221], off
	s_waitcnt vmcnt(8)
	s_waitcnt lgkmcnt(0)
	s_barrier
	s_setprio 1
	s_waitcnt lgkmcnt(0)
	v_mfma_f32_16x16x32_bf16 v[124:127], v[128:131], v[180:183], v[124:127]
	v_mfma_f32_16x16x32_bf16 v[124:127], v[132:135], v[192:195], v[124:127]
	v_mfma_f32_16x16x32_bf16 v[108:111], v[132:135], v[200:203], v[108:111]
	v_mfma_f32_16x16x32_bf16 v[108:111], v[128:131], v[196:199], v[108:111]
	v_mfma_f32_16x16x32_bf16 v[92:95], v[128:131], v[204:207], v[92:95]
	v_mfma_f32_16x16x32_bf16 v[92:95], v[132:135], v[208:211], v[92:95]
	v_mfma_f32_16x16x32_bf16 v[76:79], v[132:135], v[216:219], v[76:79]
	v_mfma_f32_16x16x32_bf16 v[76:79], v[128:131], v[212:215], v[76:79]
	v_mfma_f32_16x16x32_bf16 v[72:75], v[136:139], v[212:215], v[72:75]
	v_mfma_f32_16x16x32_bf16 v[72:75], v[140:143], v[216:219], v[72:75]
	v_mfma_f32_16x16x32_bf16 v[88:91], v[140:143], v[208:211], v[88:91]
	v_mfma_f32_16x16x32_bf16 v[88:91], v[136:139], v[204:207], v[88:91]
	v_mfma_f32_16x16x32_bf16 v[104:107], v[136:139], v[196:199], v[104:107]
	v_mfma_f32_16x16x32_bf16 v[104:107], v[140:143], v[200:203], v[104:107]
	v_mfma_f32_16x16x32_bf16 v[120:123], v[140:143], v[192:195], v[120:123]
	v_mfma_f32_16x16x32_bf16 v[120:123], v[136:139], v[180:183], v[120:123]
	s_setprio 0
	s_setprio 1
	v_mfma_f32_16x16x32_bf16 v[116:119], v[144:147], v[180:183], v[116:119]
	v_mfma_f32_16x16x32_bf16 v[116:119], v[148:151], v[192:195], v[116:119]
	v_mfma_f32_16x16x32_bf16 v[100:103], v[148:151], v[200:203], v[100:103]
	v_mfma_f32_16x16x32_bf16 v[100:103], v[144:147], v[196:199], v[100:103]
	v_mfma_f32_16x16x32_bf16 v[84:87], v[144:147], v[204:207], v[84:87]
	v_mfma_f32_16x16x32_bf16 v[84:87], v[148:151], v[208:211], v[84:87]
	v_mfma_f32_16x16x32_bf16 v[68:71], v[148:151], v[216:219], v[68:71]
	v_mfma_f32_16x16x32_bf16 v[68:71], v[144:147], v[212:215], v[68:71]
	v_mfma_f32_16x16x32_bf16 v[64:67], v[172:175], v[212:215], v[64:67]
	v_mfma_f32_16x16x32_bf16 v[64:67], v[176:179], v[216:219], v[64:67]
	v_mfma_f32_16x16x32_bf16 v[80:83], v[176:179], v[208:211], v[80:83]
	v_mfma_f32_16x16x32_bf16 v[80:83], v[172:175], v[204:207], v[80:83]
	v_mfma_f32_16x16x32_bf16 v[96:99], v[172:175], v[196:199], v[96:99]
	v_mfma_f32_16x16x32_bf16 v[96:99], v[176:179], v[200:203], v[96:99]
	v_mfma_f32_16x16x32_bf16 v[112:115], v[176:179], v[192:195], v[112:115]
	v_mfma_f32_16x16x32_bf16 v[112:115], v[172:175], v[180:183], v[112:115]
	s_setprio 0
	s_barrier
	s_add_i32 s48, s68, s58
	v_lshl_add_u64 v[220:221], s[52:53], 0, v[154:155]
	s_mov_b32 m0, s48
	ds_read_b128 v[180:183], v190 offset:16384
	v_xor_b32_e32 v253, 64, v190
	ds_read_b128 v[192:195], v253 offset:16384
	ds_read_b128 v[196:199], v190 offset:18432
	ds_read_b128 v[200:203], v253 offset:18432
	ds_read_b128 v[204:207], v190 offset:20480
	ds_read_b128 v[208:211], v253 offset:20480
	ds_read_b128 v[212:215], v190 offset:22528
	ds_read_b128 v[216:219], v253 offset:22528
	global_load_lds_dwordx4 v[220:221], off
	s_add_i32 m0, s48, 0x2000
	s_add_u32 s48, s52, 0xb0000
	v_lshl_add_u64 v[222:223], s[52:53], 0, v[162:163]
	s_addc_u32 s49, s53, 0
	s_add_i32 s75, s69, s58
	global_load_lds_dwordx4 v[222:223], off
	v_lshl_add_u64 v[224:225], s[48:49], 0, v[154:155]
	s_mov_b32 m0, s75
	v_lshl_add_u64 v[226:227], s[54:55], 0, v[160:161]
	global_load_lds_dwordx4 v[224:225], off
	v_lshl_add_u64 v[224:225], s[48:49], 0, v[162:163]
	s_add_i32 m0, s75, 0x2000
	s_nop 0
	global_load_lds_dwordx4 v[224:225], off
	v_lshl_add_u64 v[224:225], s[54:55], 0, v[152:153]
	s_mov_b32 m0, s59
	s_nop 0
	global_load_lds_dwordx4 v[224:225], off
	s_mov_b32 m0, s60
	s_nop 0
	global_load_lds_dwordx4 v[226:227], off
	s_waitcnt vmcnt(8)
	s_waitcnt lgkmcnt(0)
	s_barrier
	s_setprio 1
	s_waitcnt lgkmcnt(0)
	v_mfma_f32_16x16x32_bf16 v[60:63], v[128:131], v[180:183], v[60:63]
	v_mfma_f32_16x16x32_bf16 v[60:63], v[132:135], v[192:195], v[60:63]
	v_mfma_f32_16x16x32_bf16 v[44:47], v[132:135], v[200:203], v[44:47]
	v_mfma_f32_16x16x32_bf16 v[44:47], v[128:131], v[196:199], v[44:47]
	v_mfma_f32_16x16x32_bf16 v[28:31], v[128:131], v[204:207], v[28:31]
	v_mfma_f32_16x16x32_bf16 v[28:31], v[132:135], v[208:211], v[28:31]
	v_mfma_f32_16x16x32_bf16 v[12:15], v[132:135], v[216:219], v[12:15]
	v_mfma_f32_16x16x32_bf16 v[12:15], v[128:131], v[212:215], v[12:15]
	v_mfma_f32_16x16x32_bf16 v[8:11], v[136:139], v[212:215], v[8:11]
	v_mfma_f32_16x16x32_bf16 v[8:11], v[140:143], v[216:219], v[8:11]
	v_mfma_f32_16x16x32_bf16 v[24:27], v[140:143], v[208:211], v[24:27]
	v_mfma_f32_16x16x32_bf16 v[24:27], v[136:139], v[204:207], v[24:27]
	v_mfma_f32_16x16x32_bf16 v[40:43], v[136:139], v[196:199], v[40:43]
	v_mfma_f32_16x16x32_bf16 v[40:43], v[140:143], v[200:203], v[40:43]
	v_mfma_f32_16x16x32_bf16 v[56:59], v[140:143], v[192:195], v[56:59]
	v_mfma_f32_16x16x32_bf16 v[56:59], v[136:139], v[180:183], v[56:59]
	s_setprio 0
	s_setprio 1
	v_mfma_f32_16x16x32_bf16 v[52:55], v[144:147], v[180:183], v[52:55]
	v_mfma_f32_16x16x32_bf16 v[52:55], v[148:151], v[192:195], v[52:55]
	v_mfma_f32_16x16x32_bf16 v[36:39], v[148:151], v[200:203], v[36:39]
	v_mfma_f32_16x16x32_bf16 v[36:39], v[144:147], v[196:199], v[36:39]
	v_mfma_f32_16x16x32_bf16 v[20:23], v[144:147], v[204:207], v[20:23]
	v_mfma_f32_16x16x32_bf16 v[20:23], v[148:151], v[208:211], v[20:23]
	v_mfma_f32_16x16x32_bf16 v[4:7], v[148:151], v[216:219], v[4:7]
	v_mfma_f32_16x16x32_bf16 v[4:7], v[144:147], v[212:215], v[4:7]
	v_mfma_f32_16x16x32_bf16 v[0:3], v[172:175], v[212:215], v[0:3]
	v_mfma_f32_16x16x32_bf16 v[0:3], v[176:179], v[216:219], v[0:3]
	v_mfma_f32_16x16x32_bf16 v[16:19], v[176:179], v[208:211], v[16:19]
	v_mfma_f32_16x16x32_bf16 v[16:19], v[172:175], v[204:207], v[16:19]
	v_mfma_f32_16x16x32_bf16 v[32:35], v[172:175], v[196:199], v[32:35]
	v_mfma_f32_16x16x32_bf16 v[32:35], v[176:179], v[200:203], v[32:35]
	v_mfma_f32_16x16x32_bf16 v[48:51], v[176:179], v[192:195], v[48:51]
	v_mfma_f32_16x16x32_bf16 v[48:51], v[172:175], v[180:183], v[48:51]
	s_setprio 0
	s_barrier
	s_add_i32 s75, 0, 0x18000
	s_add_i32 s76, 0, 0x1c000
	v_add_u32_e32 v140, s75, v185
	v_add_u32_e32 v176, s76, v185
	ds_read_b128 v[128:131], v140
	v_xor_b32_e32 v253, 64, v140
	ds_read_b128 v[132:135], v253
	ds_read_b128 v[136:139], v140 offset:2048
	ds_read_b128 v[140:143], v253 offset:2048
	ds_read_b128 v[144:147], v176
	v_xor_b32_e32 v253, 64, v176
	ds_read_b128 v[148:151], v253
	ds_read_b128 v[172:175], v176 offset:2048
	ds_read_b128 v[176:179], v253 offset:2048
	s_add_u32 s48, s54, 0xb0000
	s_addc_u32 s49, s55, 0
	s_mov_b32 m0, s61
	v_lshl_add_u64 v[228:229], s[48:49], 0, v[152:153]
	ds_read_b128 v[180:183], v190 offset:32768
	v_xor_b32_e32 v253, 64, v190
	ds_read_b128 v[192:195], v253 offset:32768
	ds_read_b128 v[196:199], v190 offset:34816
	ds_read_b128 v[200:203], v253 offset:34816
	ds_read_b128 v[204:207], v190 offset:36864
	ds_read_b128 v[208:211], v253 offset:36864
	ds_read_b128 v[212:215], v190 offset:38912
	ds_read_b128 v[216:219], v253 offset:38912
	global_load_lds_dwordx4 v[228:229], off
	v_lshl_add_u64 v[228:229], s[48:49], 0, v[160:161]
	s_mov_b32 m0, s62
	s_nop 0
	global_load_lds_dwordx4 v[228:229], off
	s_waitcnt vmcnt(8)
	s_waitcnt lgkmcnt(0)
	s_barrier
	s_setprio 1
	s_waitcnt lgkmcnt(0)
	v_mfma_f32_16x16x32_bf16 v[124:127], v[128:131], v[180:183], v[124:127]
	v_mfma_f32_16x16x32_bf16 v[124:127], v[132:135], v[192:195], v[124:127]
	v_mfma_f32_16x16x32_bf16 v[108:111], v[132:135], v[200:203], v[108:111]
	v_mfma_f32_16x16x32_bf16 v[108:111], v[128:131], v[196:199], v[108:111]
	v_mfma_f32_16x16x32_bf16 v[92:95], v[128:131], v[204:207], v[92:95]
	v_mfma_f32_16x16x32_bf16 v[92:95], v[132:135], v[208:211], v[92:95]
	v_mfma_f32_16x16x32_bf16 v[76:79], v[132:135], v[216:219], v[76:79]
	v_mfma_f32_16x16x32_bf16 v[76:79], v[128:131], v[212:215], v[76:79]
	v_mfma_f32_16x16x32_bf16 v[72:75], v[136:139], v[212:215], v[72:75]
	v_mfma_f32_16x16x32_bf16 v[72:75], v[140:143], v[216:219], v[72:75]
	v_mfma_f32_16x16x32_bf16 v[88:91], v[140:143], v[208:211], v[88:91]
	v_mfma_f32_16x16x32_bf16 v[88:91], v[136:139], v[204:207], v[88:91]
	v_mfma_f32_16x16x32_bf16 v[104:107], v[136:139], v[196:199], v[104:107]
	v_mfma_f32_16x16x32_bf16 v[104:107], v[140:143], v[200:203], v[104:107]
	v_mfma_f32_16x16x32_bf16 v[120:123], v[140:143], v[192:195], v[120:123]
	v_mfma_f32_16x16x32_bf16 v[120:123], v[136:139], v[180:183], v[120:123]
	s_setprio 0
	s_setprio 1
	v_mfma_f32_16x16x32_bf16 v[116:119], v[144:147], v[180:183], v[116:119]
	v_mfma_f32_16x16x32_bf16 v[116:119], v[148:151], v[192:195], v[116:119]
	v_mfma_f32_16x16x32_bf16 v[100:103], v[148:151], v[200:203], v[100:103]
	v_mfma_f32_16x16x32_bf16 v[100:103], v[144:147], v[196:199], v[100:103]
	v_mfma_f32_16x16x32_bf16 v[84:87], v[144:147], v[204:207], v[84:87]
	v_mfma_f32_16x16x32_bf16 v[84:87], v[148:151], v[208:211], v[84:87]
	v_mfma_f32_16x16x32_bf16 v[68:71], v[148:151], v[216:219], v[68:71]
	v_mfma_f32_16x16x32_bf16 v[68:71], v[144:147], v[212:215], v[68:71]
	v_mfma_f32_16x16x32_bf16 v[64:67], v[172:175], v[212:215], v[64:67]
	v_mfma_f32_16x16x32_bf16 v[64:67], v[176:179], v[216:219], v[64:67]
	v_mfma_f32_16x16x32_bf16 v[80:83], v[176:179], v[208:211], v[80:83]
	v_mfma_f32_16x16x32_bf16 v[80:83], v[172:175], v[204:207], v[80:83]
	v_mfma_f32_16x16x32_bf16 v[96:99], v[172:175], v[196:199], v[96:99]
	v_mfma_f32_16x16x32_bf16 v[96:99], v[176:179], v[200:203], v[96:99]
	v_mfma_f32_16x16x32_bf16 v[112:115], v[176:179], v[192:195], v[112:115]
	v_mfma_f32_16x16x32_bf16 v[112:115], v[172:175], v[180:183], v[112:115]
	s_setprio 0
	s_barrier
	s_add_i32 s48, s75, s58
	v_lshl_add_u64 v[220:221], v[220:221], 0, s[22:23]
	s_mov_b32 m0, s48
	ds_read_b128 v[180:183], v190 offset:49152
	v_xor_b32_e32 v253, 64, v190
	ds_read_b128 v[192:195], v253 offset:49152
	ds_read_b128 v[196:199], v190 offset:51200
	ds_read_b128 v[200:203], v253 offset:51200
	ds_read_b128 v[204:207], v190 offset:53248
	ds_read_b128 v[208:211], v253 offset:53248
	ds_read_b128 v[212:215], v190 offset:55296
	ds_read_b128 v[216:219], v253 offset:55296
	global_load_lds_dwordx4 v[220:221], off
	s_add_i32 m0, s48, 0x2000
	s_add_u32 s48, s52, 0xb0080
	v_lshl_add_u64 v[220:221], v[222:223], 0, s[22:23]
	s_addc_u32 s49, s53, 0
	s_add_i32 s52, s76, s58
	global_load_lds_dwordx4 v[220:221], off
	v_lshl_add_u64 v[220:221], s[48:49], 0, v[154:155]
	s_mov_b32 m0, s52
	s_nop 0
	global_load_lds_dwordx4 v[220:221], off
	v_lshl_add_u64 v[220:221], s[48:49], 0, v[162:163]
	s_add_i32 m0, s52, 0x2000
	s_nop 0
	global_load_lds_dwordx4 v[220:221], off
	v_lshl_add_u64 v[220:221], v[224:225], 0, s[22:23]
	s_mov_b32 m0, s3
	s_nop 0
	global_load_lds_dwordx4 v[220:221], off
	v_lshl_add_u64 v[220:221], v[226:227], 0, s[22:23]
	s_mov_b32 m0, s64
	s_nop 0
	global_load_lds_dwordx4 v[220:221], off
	s_waitcnt vmcnt(8)
	s_waitcnt lgkmcnt(0)
	s_barrier
	s_setprio 1
	s_waitcnt lgkmcnt(0)
	v_mfma_f32_16x16x32_bf16 v[60:63], v[128:131], v[180:183], v[60:63]
	v_mfma_f32_16x16x32_bf16 v[60:63], v[132:135], v[192:195], v[60:63]
	v_mfma_f32_16x16x32_bf16 v[44:47], v[132:135], v[200:203], v[44:47]
	v_mfma_f32_16x16x32_bf16 v[44:47], v[128:131], v[196:199], v[44:47]
	v_mfma_f32_16x16x32_bf16 v[28:31], v[128:131], v[204:207], v[28:31]
	v_mfma_f32_16x16x32_bf16 v[28:31], v[132:135], v[208:211], v[28:31]
	v_mfma_f32_16x16x32_bf16 v[12:15], v[132:135], v[216:219], v[12:15]
	v_mfma_f32_16x16x32_bf16 v[12:15], v[128:131], v[212:215], v[12:15]
	v_mfma_f32_16x16x32_bf16 v[8:11], v[136:139], v[212:215], v[8:11]
	v_mfma_f32_16x16x32_bf16 v[8:11], v[140:143], v[216:219], v[8:11]
	v_mfma_f32_16x16x32_bf16 v[24:27], v[140:143], v[208:211], v[24:27]
	v_mfma_f32_16x16x32_bf16 v[24:27], v[136:139], v[204:207], v[24:27]
	v_mfma_f32_16x16x32_bf16 v[40:43], v[136:139], v[196:199], v[40:43]
	v_mfma_f32_16x16x32_bf16 v[40:43], v[140:143], v[200:203], v[40:43]
	v_mfma_f32_16x16x32_bf16 v[56:59], v[140:143], v[192:195], v[56:59]
	v_mfma_f32_16x16x32_bf16 v[56:59], v[136:139], v[180:183], v[56:59]
	s_setprio 0
	s_setprio 1
	v_mfma_f32_16x16x32_bf16 v[52:55], v[144:147], v[180:183], v[52:55]
	v_mfma_f32_16x16x32_bf16 v[52:55], v[148:151], v[192:195], v[52:55]
	v_mfma_f32_16x16x32_bf16 v[36:39], v[148:151], v[200:203], v[36:39]
	v_mfma_f32_16x16x32_bf16 v[36:39], v[144:147], v[196:199], v[36:39]
	v_mfma_f32_16x16x32_bf16 v[20:23], v[144:147], v[204:207], v[20:23]
	v_mfma_f32_16x16x32_bf16 v[20:23], v[148:151], v[208:211], v[20:23]
	v_mfma_f32_16x16x32_bf16 v[4:7], v[148:151], v[216:219], v[4:7]
	v_mfma_f32_16x16x32_bf16 v[4:7], v[144:147], v[212:215], v[4:7]
	v_mfma_f32_16x16x32_bf16 v[0:3], v[172:175], v[212:215], v[0:3]
	v_mfma_f32_16x16x32_bf16 v[0:3], v[176:179], v[216:219], v[0:3]
	v_mfma_f32_16x16x32_bf16 v[16:19], v[176:179], v[208:211], v[16:19]
	v_mfma_f32_16x16x32_bf16 v[16:19], v[172:175], v[204:207], v[16:19]
	v_mfma_f32_16x16x32_bf16 v[32:35], v[172:175], v[196:199], v[32:35]
	v_mfma_f32_16x16x32_bf16 v[32:35], v[176:179], v[200:203], v[32:35]
	v_mfma_f32_16x16x32_bf16 v[48:51], v[176:179], v[192:195], v[48:51]
	v_mfma_f32_16x16x32_bf16 v[48:51], v[172:175], v[180:183], v[48:51]
	s_setprio 0
	s_barrier
	s_add_i32 s74, s74, 2
	s_add_u32 s72, s72, 0x100
	s_addc_u32 s73, s73, 0
	s_cmp_gt_u32 s74, 41
	s_mov_b64 s[48:49], s[50:51]
	s_cbranch_scc0 .LBB0_1181
	s_and_b64 vcc, exec, s[24:25]
	s_cbranch_vccz .LBB0_1184
	s_barrier
